# Hyena FFT twiddles: constant-angle twiddles (last pass) as literals, per-butterfly twiddles of the first two passes derived from W(0) by a constant complex multiply instead of v_cos/v_sin (56 -> 12 tr
# speedup vs baseline: 1.0020x; 1.0020x over previous
; DI f32x2 cmul(f32x2 a, f32x2 b) { return mkf2(a.x * b.x - a.y * b.y, a.x * b.y + a.y * b.x); }
; DI void fft8192(f32x2* buf, const f32x2* __restrict__ tw) {
;     ...
;   for (int ls = 0; ls < 12; ls += 2) {
;     const int s = 1 << ls;
;     f32x2 a[8], b[8], c[8], d[8];
;     __syncthreads();
; #pragma unroll
;     for (int e = 0; e < 8; ++e) {
;       const int i = tid + 256 * e;
;       const int pi = SW(i);
;       a[e] = buf[pi]; b[e] = buf[pi + 2048]; c[e] = buf[pi + 4096]; d[e] = buf[pi + 6144];
;     }
;     __syncthreads();
; #pragma unroll
;     for (int e = 0; e < 8; ++e) {
;       const int i = tid + 256 * e;
;       const int q = i & (s - 1);
;       const int ps = i - q;
;       const float rev = (float)ps * (1.f / 8192.f);
;       const f32x2 w1 = mkf2(__builtin_amdgcn_cosf(rev), -__builtin_amdgcn_sinf(rev));
;       const f32x2 w2 = cmul(w1, w1), w3 = cmul(w1, w2);
;       const f32x2 apc = mkf2(a[e].x + c[e].x, a[e].y + c[e].y), amc = mkf2(a[e].x - c[e].x, a[e].y - c[e].y);
;       const f32x2 bpd = mkf2(b[e].x + d[e].x, b[e].y + d[e].y), bmd = mkf2(b[e].x - d[e].x, b[e].y - d[e].y);
;       const int o = 4 * i - 3 * q;
;       buf[SW(o)] = mkf2(apc.x + bpd.x, apc.y + bpd.y);
;       buf[SW(o + s)] = cmul(w1, mkf2(amc.x + bmd.y, amc.y - bmd.x));
;       buf[SW(o + 2 * s)] = cmul(w2, mkf2(apc.x - bpd.x, apc.y - bpd.y));
;       buf[SW(o + 3 * s)] = cmul(w3, mkf2(amc.x - bmd.y, amc.y + bmd.x));
;     }
.LBB0_933:
	v_bfe_i32 v166, v0, 5, 1
	v_bfe_i32 v168, v0, 6, 1
	v_and_b32_e32 v166, 5, v166
	v_and_b32_e32 v168, 26, v168
	v_xor_b32_e32 v166, v166, v168
	v_xor_b32_e32 v166, v166, v0
	v_lshlrev_b32_e32 v154, 3, v166
	s_waitcnt lgkmcnt(0)
	s_barrier
	ds_read2st64_b64 v[2:5], v154 offset0:0 offset1:32
	ds_read2st64_b64 v[6:9], v154 offset0:64 offset1:96
	ds_read2st64_b64 v[10:13], v154 offset0:4 offset1:36
	ds_read2st64_b64 v[14:17], v154 offset0:68 offset1:100
	ds_read2st64_b64 v[18:21], v154 offset0:8 offset1:40
	ds_read2st64_b64 v[22:25], v154 offset0:72 offset1:104
	ds_read2st64_b64 v[26:29], v154 offset0:12 offset1:44
	ds_read2st64_b64 v[30:33], v154 offset0:76 offset1:108
	ds_read2st64_b64 v[34:37], v154 offset0:16 offset1:48
	ds_read2st64_b64 v[38:41], v154 offset0:80 offset1:112
	ds_read2st64_b64 v[42:45], v154 offset0:20 offset1:52
	ds_read2st64_b64 v[46:49], v154 offset0:84 offset1:116
	ds_read2st64_b64 v[50:53], v154 offset0:24 offset1:56
	ds_read2st64_b64 v[54:57], v154 offset0:88 offset1:120
	ds_read2st64_b64 v[58:61], v154 offset0:28 offset1:60
	ds_read2st64_b64 v[62:65], v154 offset0:92 offset1:124
	v_cvt_f32_u32_e32 v201, v0
	v_and_b32_e32 v166, 15, v0
	v_lshlrev_b32_e32 v166, 3, v166
	v_lshl_add_u32 v164, v0, 7, v166
	v_mul_f32_e32 v201, 0x39000000, v201
	v_cos_f32_e32 v210, v201
	v_sin_f32_e64 v211, -v201
	s_nop 0
	v_mov_b32_e32 v224, v210
	v_mov_b32_e32 v225, v211
	s_waitcnt lgkmcnt(14)
	v_pk_add_f32 v[202:203], v[2:3], v[6:7]
	v_pk_add_f32 v[2:3], v[2:3], v[6:7] neg_lo:[0,1] neg_hi:[0,1]
	v_pk_add_f32 v[204:205], v[4:5], v[8:9]
	v_pk_add_f32 v[4:5], v[4:5], v[8:9] neg_lo:[0,1] neg_hi:[0,1]
	v_pk_add_f32 v[6:7], v[202:203], v[204:205]
	v_pk_add_f32 v[8:9], v[202:203], v[204:205] neg_lo:[0,1] neg_hi:[0,1]
	v_pk_add_f32 v[202:203], v[2:3], v[4:5] op_sel:[0,1] op_sel_hi:[1,0] neg_hi:[0,1]
	v_pk_add_f32 v[204:205], v[2:3], v[4:5] op_sel:[0,1] op_sel_hi:[1,0] neg_lo:[0,1]
	v_pk_mul_f32 v[206:207], v[210:211], v[210:211] op_sel:[1,1] op_sel_hi:[1,0]
	v_pk_fma_f32 v[212:213], v[210:211], v[210:211], v[206:207] op_sel_hi:[0,1,1] neg_lo:[0,0,1]
	v_pk_mul_f32 v[206:207], v[210:211], v[212:213] op_sel:[1,1] op_sel_hi:[1,0]
	v_pk_fma_f32 v[220:221], v[210:211], v[212:213], v[206:207] op_sel_hi:[0,1,1] neg_lo:[0,0,1]
	v_pk_mul_f32 v[2:3], v[210:211], v[202:203] op_sel:[1,1] op_sel_hi:[1,0]
	v_pk_fma_f32 v[2:3], v[210:211], v[202:203], v[2:3] op_sel_hi:[0,1,1] neg_lo:[0,0,1]
	v_pk_mul_f32 v[4:5], v[212:213], v[8:9] op_sel:[1,1] op_sel_hi:[1,0]
	v_pk_fma_f32 v[4:5], v[212:213], v[8:9], v[4:5] op_sel_hi:[0,1,1] neg_lo:[0,0,1]
	v_pk_mul_f32 v[8:9], v[220:221], v[204:205] op_sel:[1,1] op_sel_hi:[1,0]
	v_pk_fma_f32 v[8:9], v[220:221], v[204:205], v[8:9] op_sel_hi:[0,1,1] neg_lo:[0,0,1]
	v_mul_f32_e32 v210, 0x3f7b14be, v224
	v_mul_f32_e32 v211, 0xbe47c5c2, v224
	v_fmac_f32_e32 v210, 0x3e47c5c2, v225
	v_fmac_f32_e32 v211, 0x3f7b14be, v225
	s_waitcnt lgkmcnt(12)
	v_pk_add_f32 v[202:203], v[10:11], v[14:15]
	v_pk_add_f32 v[10:11], v[10:11], v[14:15] neg_lo:[0,1] neg_hi:[0,1]
	v_pk_add_f32 v[204:205], v[12:13], v[16:17]
	v_pk_add_f32 v[12:13], v[12:13], v[16:17] neg_lo:[0,1] neg_hi:[0,1]
	v_pk_add_f32 v[14:15], v[202:203], v[204:205]
	v_pk_add_f32 v[16:17], v[202:203], v[204:205] neg_lo:[0,1] neg_hi:[0,1]
	v_pk_add_f32 v[202:203], v[10:11], v[12:13] op_sel:[0,1] op_sel_hi:[1,0] neg_hi:[0,1]
	v_pk_add_f32 v[204:205], v[10:11], v[12:13] op_sel:[0,1] op_sel_hi:[1,0] neg_lo:[0,1]
	v_pk_mul_f32 v[206:207], v[210:211], v[210:211] op_sel:[1,1] op_sel_hi:[1,0]
	v_pk_fma_f32 v[212:213], v[210:211], v[210:211], v[206:207] op_sel_hi:[0,1,1] neg_lo:[0,0,1]
	v_pk_mul_f32 v[206:207], v[210:211], v[212:213] op_sel:[1,1] op_sel_hi:[1,0]
	v_pk_fma_f32 v[220:221], v[210:211], v[212:213], v[206:207] op_sel_hi:[0,1,1] neg_lo:[0,0,1]
	v_pk_mul_f32 v[10:11], v[210:211], v[202:203] op_sel:[1,1] op_sel_hi:[1,0]
	v_pk_fma_f32 v[10:11], v[210:211], v[202:203], v[10:11] op_sel_hi:[0,1,1] neg_lo:[0,0,1]
	v_pk_mul_f32 v[12:13], v[212:213], v[16:17] op_sel:[1,1] op_sel_hi:[1,0]
	v_pk_fma_f32 v[12:13], v[212:213], v[16:17], v[12:13] op_sel_hi:[0,1,1] neg_lo:[0,0,1]
	v_pk_mul_f32 v[16:17], v[220:221], v[204:205] op_sel:[1,1] op_sel_hi:[1,0]
	v_pk_fma_f32 v[16:17], v[220:221], v[204:205], v[16:17] op_sel_hi:[0,1,1] neg_lo:[0,0,1]
	v_mul_f32_e32 v210, 0x3f6c835e, v224
	v_mul_f32_e32 v211, 0xbec3ef15, v224
	v_fmac_f32_e32 v210, 0x3ec3ef15, v225
	v_fmac_f32_e32 v211, 0x3f6c835e, v225
	s_waitcnt lgkmcnt(10)
	v_pk_add_f32 v[202:203], v[18:19], v[22:23]
	v_pk_add_f32 v[18:19], v[18:19], v[22:23] neg_lo:[0,1] neg_hi:[0,1]
	v_pk_add_f32 v[204:205], v[20:21], v[24:25]
	v_pk_add_f32 v[20:21], v[20:21], v[24:25] neg_lo:[0,1] neg_hi:[0,1]
	v_pk_add_f32 v[22:23], v[202:203], v[204:205]
	v_pk_add_f32 v[24:25], v[202:203], v[204:205] neg_lo:[0,1] neg_hi:[0,1]
	v_pk_add_f32 v[202:203], v[18:19], v[20:21] op_sel:[0,1] op_sel_hi:[1,0] neg_hi:[0,1]
	v_pk_add_f32 v[204:205], v[18:19], v[20:21] op_sel:[0,1] op_sel_hi:[1,0] neg_lo:[0,1]
	v_pk_mul_f32 v[206:207], v[210:211], v[210:211] op_sel:[1,1] op_sel_hi:[1,0]
	v_pk_fma_f32 v[212:213], v[210:211], v[210:211], v[206:207] op_sel_hi:[0,1,1] neg_lo:[0,0,1]
	v_pk_mul_f32 v[206:207], v[210:211], v[212:213] op_sel:[1,1] op_sel_hi:[1,0]
	v_pk_fma_f32 v[220:221], v[210:211], v[212:213], v[206:207] op_sel_hi:[0,1,1] neg_lo:[0,0,1]
	v_pk_mul_f32 v[18:19], v[210:211], v[202:203] op_sel:[1,1] op_sel_hi:[1,0]
	v_pk_fma_f32 v[18:19], v[210:211], v[202:203], v[18:19] op_sel_hi:[0,1,1] neg_lo:[0,0,1]
	v_pk_mul_f32 v[20:21], v[212:213], v[24:25] op_sel:[1,1] op_sel_hi:[1,0]
	v_pk_fma_f32 v[20:21], v[212:213], v[24:25], v[20:21] op_sel_hi:[0,1,1] neg_lo:[0,0,1]
	v_pk_mul_f32 v[24:25], v[220:221], v[204:205] op_sel:[1,1] op_sel_hi:[1,0]
	v_pk_fma_f32 v[24:25], v[220:221], v[204:205], v[24:25] op_sel_hi:[0,1,1] neg_lo:[0,0,1]
	v_mul_f32_e32 v210, 0x3f54db31, v224
	v_mul_f32_e32 v211, 0xbf0e39da, v224
	v_fmac_f32_e32 v210, 0x3f0e39da, v225
	v_fmac_f32_e32 v211, 0x3f54db31, v225
	s_waitcnt lgkmcnt(8)
; DI f32x2 cmul(f32x2 a, f32x2 b) { return mkf2(a.x * b.x - a.y * b.y, a.x * b.y + a.y * b.x); }
; DI void fft8192(f32x2* buf, const f32x2* __restrict__ tw) {
;     ...
;   for (int ls = 0; ls < 12; ls += 2) {
;     const int s = 1 << ls;
;     f32x2 a[8], b[8], c[8], d[8];
;     __syncthreads();
; #pragma unroll
;     for (int e = 0; e < 8; ++e) {
;       const int i = tid + 256 * e;
;       const int pi = SW(i);
;       a[e] = buf[pi]; b[e] = buf[pi + 2048]; c[e] = buf[pi + 4096]; d[e] = buf[pi + 6144];
;     }
;     __syncthreads();
; #pragma unroll
;     for (int e = 0; e < 8; ++e) {
;       const int i = tid + 256 * e;
;       const int q = i & (s - 1);
;       const int ps = i - q;
;       const float rev = (float)ps * (1.f / 8192.f);
;       const f32x2 w1 = mkf2(__builtin_amdgcn_cosf(rev), -__builtin_amdgcn_sinf(rev));
;       const f32x2 w2 = cmul(w1, w1), w3 = cmul(w1, w2);
;       const f32x2 apc = mkf2(a[e].x + c[e].x, a[e].y + c[e].y), amc = mkf2(a[e].x - c[e].x, a[e].y - c[e].y);
;       const f32x2 bpd = mkf2(b[e].x + d[e].x, b[e].y + d[e].y), bmd = mkf2(b[e].x - d[e].x, b[e].y - d[e].y);
;       const int o = 4 * i - 3 * q;
;       buf[SW(o)] = mkf2(apc.x + bpd.x, apc.y + bpd.y);
;       buf[SW(o + s)] = cmul(w1, mkf2(amc.x + bmd.y, amc.y - bmd.x));
;       buf[SW(o + 2 * s)] = cmul(w2, mkf2(apc.x - bpd.x, apc.y - bpd.y));
;       buf[SW(o + 3 * s)] = cmul(w3, mkf2(amc.x - bmd.y, amc.y + bmd.x));
;     }
	v_pk_add_f32 v[202:203], v[26:27], v[30:31]
	v_pk_add_f32 v[26:27], v[26:27], v[30:31] neg_lo:[0,1] neg_hi:[0,1]
	v_pk_add_f32 v[204:205], v[28:29], v[32:33]
	v_pk_add_f32 v[28:29], v[28:29], v[32:33] neg_lo:[0,1] neg_hi:[0,1]
	v_pk_add_f32 v[30:31], v[202:203], v[204:205]
	v_pk_add_f32 v[32:33], v[202:203], v[204:205] neg_lo:[0,1] neg_hi:[0,1]
	v_pk_add_f32 v[202:203], v[26:27], v[28:29] op_sel:[0,1] op_sel_hi:[1,0] neg_hi:[0,1]
	v_pk_add_f32 v[204:205], v[26:27], v[28:29] op_sel:[0,1] op_sel_hi:[1,0] neg_lo:[0,1]
	v_pk_mul_f32 v[206:207], v[210:211], v[210:211] op_sel:[1,1] op_sel_hi:[1,0]
	v_pk_fma_f32 v[212:213], v[210:211], v[210:211], v[206:207] op_sel_hi:[0,1,1] neg_lo:[0,0,1]
	v_pk_mul_f32 v[206:207], v[210:211], v[212:213] op_sel:[1,1] op_sel_hi:[1,0]
	v_pk_fma_f32 v[220:221], v[210:211], v[212:213], v[206:207] op_sel_hi:[0,1,1] neg_lo:[0,0,1]
	v_pk_mul_f32 v[26:27], v[210:211], v[202:203] op_sel:[1,1] op_sel_hi:[1,0]
	v_pk_fma_f32 v[26:27], v[210:211], v[202:203], v[26:27] op_sel_hi:[0,1,1] neg_lo:[0,0,1]
	v_pk_mul_f32 v[28:29], v[212:213], v[32:33] op_sel:[1,1] op_sel_hi:[1,0]
	v_pk_fma_f32 v[28:29], v[212:213], v[32:33], v[28:29] op_sel_hi:[0,1,1] neg_lo:[0,0,1]
	v_pk_mul_f32 v[32:33], v[220:221], v[204:205] op_sel:[1,1] op_sel_hi:[1,0]
	v_pk_fma_f32 v[32:33], v[220:221], v[204:205], v[32:33] op_sel_hi:[0,1,1] neg_lo:[0,0,1]
	v_mul_f32_e32 v210, 0x3f3504f3, v224
	v_mul_f32_e32 v211, 0xbf3504f3, v224
	v_fmac_f32_e32 v210, 0x3f3504f3, v225
	v_fmac_f32_e32 v211, 0x3f3504f3, v225
	s_waitcnt lgkmcnt(6)
	v_pk_add_f32 v[202:203], v[34:35], v[38:39]
	v_pk_add_f32 v[34:35], v[34:35], v[38:39] neg_lo:[0,1] neg_hi:[0,1]
	v_pk_add_f32 v[204:205], v[36:37], v[40:41]
	v_pk_add_f32 v[36:37], v[36:37], v[40:41] neg_lo:[0,1] neg_hi:[0,1]
	v_pk_add_f32 v[38:39], v[202:203], v[204:205]
	v_pk_add_f32 v[40:41], v[202:203], v[204:205] neg_lo:[0,1] neg_hi:[0,1]
	v_pk_add_f32 v[202:203], v[34:35], v[36:37] op_sel:[0,1] op_sel_hi:[1,0] neg_hi:[0,1]
	v_pk_add_f32 v[204:205], v[34:35], v[36:37] op_sel:[0,1] op_sel_hi:[1,0] neg_lo:[0,1]
	v_pk_mul_f32 v[206:207], v[210:211], v[210:211] op_sel:[1,1] op_sel_hi:[1,0]
	v_pk_fma_f32 v[212:213], v[210:211], v[210:211], v[206:207] op_sel_hi:[0,1,1] neg_lo:[0,0,1]
	v_pk_mul_f32 v[206:207], v[210:211], v[212:213] op_sel:[1,1] op_sel_hi:[1,0]
	v_pk_fma_f32 v[220:221], v[210:211], v[212:213], v[206:207] op_sel_hi:[0,1,1] neg_lo:[0,0,1]
	v_pk_mul_f32 v[34:35], v[210:211], v[202:203] op_sel:[1,1] op_sel_hi:[1,0]
	v_pk_fma_f32 v[34:35], v[210:211], v[202:203], v[34:35] op_sel_hi:[0,1,1] neg_lo:[0,0,1]
	v_pk_mul_f32 v[36:37], v[212:213], v[40:41] op_sel:[1,1] op_sel_hi:[1,0]
	v_pk_fma_f32 v[36:37], v[212:213], v[40:41], v[36:37] op_sel_hi:[0,1,1] neg_lo:[0,0,1]
	v_pk_mul_f32 v[40:41], v[220:221], v[204:205] op_sel:[1,1] op_sel_hi:[1,0]
	v_pk_fma_f32 v[40:41], v[220:221], v[204:205], v[40:41] op_sel_hi:[0,1,1] neg_lo:[0,0,1]
	v_mul_f32_e32 v210, 0x3f0e39da, v224
	v_mul_f32_e32 v211, 0xbf54db31, v224
	v_fmac_f32_e32 v210, 0x3f54db31, v225
	v_fmac_f32_e32 v211, 0x3f0e39da, v225
	s_waitcnt lgkmcnt(4)
	v_pk_add_f32 v[202:203], v[42:43], v[46:47]
	v_pk_add_f32 v[42:43], v[42:43], v[46:47] neg_lo:[0,1] neg_hi:[0,1]
	v_pk_add_f32 v[204:205], v[44:45], v[48:49]
	v_pk_add_f32 v[44:45], v[44:45], v[48:49] neg_lo:[0,1] neg_hi:[0,1]
	v_pk_add_f32 v[46:47], v[202:203], v[204:205]
	v_pk_add_f32 v[48:49], v[202:203], v[204:205] neg_lo:[0,1] neg_hi:[0,1]
	v_pk_add_f32 v[202:203], v[42:43], v[44:45] op_sel:[0,1] op_sel_hi:[1,0] neg_hi:[0,1]
	v_pk_add_f32 v[204:205], v[42:43], v[44:45] op_sel:[0,1] op_sel_hi:[1,0] neg_lo:[0,1]
	v_pk_mul_f32 v[206:207], v[210:211], v[210:211] op_sel:[1,1] op_sel_hi:[1,0]
	v_pk_fma_f32 v[212:213], v[210:211], v[210:211], v[206:207] op_sel_hi:[0,1,1] neg_lo:[0,0,1]
	v_pk_mul_f32 v[206:207], v[210:211], v[212:213] op_sel:[1,1] op_sel_hi:[1,0]
	v_pk_fma_f32 v[220:221], v[210:211], v[212:213], v[206:207] op_sel_hi:[0,1,1] neg_lo:[0,0,1]
	v_pk_mul_f32 v[42:43], v[210:211], v[202:203] op_sel:[1,1] op_sel_hi:[1,0]
	v_pk_fma_f32 v[42:43], v[210:211], v[202:203], v[42:43] op_sel_hi:[0,1,1] neg_lo:[0,0,1]
	v_pk_mul_f32 v[44:45], v[212:213], v[48:49] op_sel:[1,1] op_sel_hi:[1,0]
	v_pk_fma_f32 v[44:45], v[212:213], v[48:49], v[44:45] op_sel_hi:[0,1,1] neg_lo:[0,0,1]
	v_pk_mul_f32 v[48:49], v[220:221], v[204:205] op_sel:[1,1] op_sel_hi:[1,0]
	v_pk_fma_f32 v[48:49], v[220:221], v[204:205], v[48:49] op_sel_hi:[0,1,1] neg_lo:[0,0,1]
	v_mul_f32_e32 v210, 0x3ec3ef15, v224
	v_mul_f32_e32 v211, 0xbf6c835e, v224
	v_fmac_f32_e32 v210, 0x3f6c835e, v225
	v_fmac_f32_e32 v211, 0x3ec3ef15, v225
	s_waitcnt lgkmcnt(2)
	v_pk_add_f32 v[202:203], v[50:51], v[54:55]
	v_pk_add_f32 v[50:51], v[50:51], v[54:55] neg_lo:[0,1] neg_hi:[0,1]
	v_pk_add_f32 v[204:205], v[52:53], v[56:57]
	v_pk_add_f32 v[52:53], v[52:53], v[56:57] neg_lo:[0,1] neg_hi:[0,1]
	v_pk_add_f32 v[54:55], v[202:203], v[204:205]
	v_pk_add_f32 v[56:57], v[202:203], v[204:205] neg_lo:[0,1] neg_hi:[0,1]
	v_pk_add_f32 v[202:203], v[50:51], v[52:53] op_sel:[0,1] op_sel_hi:[1,0] neg_hi:[0,1]
	v_pk_add_f32 v[204:205], v[50:51], v[52:53] op_sel:[0,1] op_sel_hi:[1,0] neg_lo:[0,1]
	v_pk_mul_f32 v[206:207], v[210:211], v[210:211] op_sel:[1,1] op_sel_hi:[1,0]
	v_pk_fma_f32 v[212:213], v[210:211], v[210:211], v[206:207] op_sel_hi:[0,1,1] neg_lo:[0,0,1]
	v_pk_mul_f32 v[206:207], v[210:211], v[212:213] op_sel:[1,1] op_sel_hi:[1,0]
	v_pk_fma_f32 v[220:221], v[210:211], v[212:213], v[206:207] op_sel_hi:[0,1,1] neg_lo:[0,0,1]
	v_pk_mul_f32 v[50:51], v[210:211], v[202:203] op_sel:[1,1] op_sel_hi:[1,0]
	v_pk_fma_f32 v[50:51], v[210:211], v[202:203], v[50:51] op_sel_hi:[0,1,1] neg_lo:[0,0,1]
	v_pk_mul_f32 v[52:53], v[212:213], v[56:57] op_sel:[1,1] op_sel_hi:[1,0]
	v_pk_fma_f32 v[52:53], v[212:213], v[56:57], v[52:53] op_sel_hi:[0,1,1] neg_lo:[0,0,1]
	v_pk_mul_f32 v[56:57], v[220:221], v[204:205] op_sel:[1,1] op_sel_hi:[1,0]
	v_pk_fma_f32 v[56:57], v[220:221], v[204:205], v[56:57] op_sel_hi:[0,1,1] neg_lo:[0,0,1]
	v_mul_f32_e32 v210, 0x3e47c5c2, v224
	v_mul_f32_e32 v211, 0xbf7b14be, v224
	v_fmac_f32_e32 v210, 0x3f7b14be, v225
	v_fmac_f32_e32 v211, 0x3e47c5c2, v225
	s_waitcnt lgkmcnt(0)
; DI f32x2 cmul(f32x2 a, f32x2 b) { return mkf2(a.x * b.x - a.y * b.y, a.x * b.y + a.y * b.x); }
; DI void fft8192(f32x2* buf, const f32x2* __restrict__ tw) {
;     ...
;   for (int ls = 0; ls < 12; ls += 2) {
;     const int s = 1 << ls;
;     f32x2 a[8], b[8], c[8], d[8];
;     __syncthreads();
; #pragma unroll
;     for (int e = 0; e < 8; ++e) {
;       const int i = tid + 256 * e;
;       const int pi = SW(i);
;       a[e] = buf[pi]; b[e] = buf[pi + 2048]; c[e] = buf[pi + 4096]; d[e] = buf[pi + 6144];
;     }
;     __syncthreads();
; #pragma unroll
;     for (int e = 0; e < 8; ++e) {
;       const int i = tid + 256 * e;
;       const int q = i & (s - 1);
;       const int ps = i - q;
;       const float rev = (float)ps * (1.f / 8192.f);
;       const f32x2 w1 = mkf2(__builtin_amdgcn_cosf(rev), -__builtin_amdgcn_sinf(rev));
;       const f32x2 w2 = cmul(w1, w1), w3 = cmul(w1, w2);
;       const f32x2 apc = mkf2(a[e].x + c[e].x, a[e].y + c[e].y), amc = mkf2(a[e].x - c[e].x, a[e].y - c[e].y);
;       const f32x2 bpd = mkf2(b[e].x + d[e].x, b[e].y + d[e].y), bmd = mkf2(b[e].x - d[e].x, b[e].y - d[e].y);
;       const int o = 4 * i - 3 * q;
;       buf[SW(o)] = mkf2(apc.x + bpd.x, apc.y + bpd.y);
;       buf[SW(o + s)] = cmul(w1, mkf2(amc.x + bmd.y, amc.y - bmd.x));
;       buf[SW(o + 2 * s)] = cmul(w2, mkf2(apc.x - bpd.x, apc.y - bpd.y));
;       buf[SW(o + 3 * s)] = cmul(w3, mkf2(amc.x - bmd.y, amc.y + bmd.x));
;     }
	v_pk_add_f32 v[202:203], v[58:59], v[62:63]
	v_pk_add_f32 v[58:59], v[58:59], v[62:63] neg_lo:[0,1] neg_hi:[0,1]
	v_pk_add_f32 v[204:205], v[60:61], v[64:65]
	v_pk_add_f32 v[60:61], v[60:61], v[64:65] neg_lo:[0,1] neg_hi:[0,1]
	v_pk_add_f32 v[62:63], v[202:203], v[204:205]
	v_pk_add_f32 v[64:65], v[202:203], v[204:205] neg_lo:[0,1] neg_hi:[0,1]
	v_pk_add_f32 v[202:203], v[58:59], v[60:61] op_sel:[0,1] op_sel_hi:[1,0] neg_hi:[0,1]
	v_pk_add_f32 v[204:205], v[58:59], v[60:61] op_sel:[0,1] op_sel_hi:[1,0] neg_lo:[0,1]
	v_pk_mul_f32 v[206:207], v[210:211], v[210:211] op_sel:[1,1] op_sel_hi:[1,0]
	v_pk_fma_f32 v[212:213], v[210:211], v[210:211], v[206:207] op_sel_hi:[0,1,1] neg_lo:[0,0,1]
	v_pk_mul_f32 v[206:207], v[210:211], v[212:213] op_sel:[1,1] op_sel_hi:[1,0]
	v_pk_fma_f32 v[220:221], v[210:211], v[212:213], v[206:207] op_sel_hi:[0,1,1] neg_lo:[0,0,1]
	v_pk_mul_f32 v[58:59], v[210:211], v[202:203] op_sel:[1,1] op_sel_hi:[1,0]
	v_pk_fma_f32 v[58:59], v[210:211], v[202:203], v[58:59] op_sel_hi:[0,1,1] neg_lo:[0,0,1]
	v_pk_mul_f32 v[60:61], v[212:213], v[64:65] op_sel:[1,1] op_sel_hi:[1,0]
	v_pk_fma_f32 v[60:61], v[212:213], v[64:65], v[60:61] op_sel_hi:[0,1,1] neg_lo:[0,0,1]
	v_pk_mul_f32 v[64:65], v[220:221], v[204:205] op_sel:[1,1] op_sel_hi:[1,0]
	v_pk_fma_f32 v[64:65], v[220:221], v[204:205], v[64:65] op_sel_hi:[0,1,1] neg_lo:[0,0,1]
	s_barrier
	v_mul_f32_e32 v214, 4.0, v201
	v_cos_f32_e32 v224, v214
	v_sin_f32_e64 v225, -v214
	s_nop 0
	v_pk_mul_f32 v[206:207], v[224:225], v[224:225] op_sel:[1,1] op_sel_hi:[1,0]
	v_pk_fma_f32 v[226:227], v[224:225], v[224:225], v[206:207] op_sel_hi:[0,1,1] neg_lo:[0,0,1]
	v_pk_mul_f32 v[206:207], v[224:225], v[226:227] op_sel:[1,1] op_sel_hi:[1,0]
	v_pk_fma_f32 v[230:231], v[224:225], v[226:227], v[206:207] op_sel_hi:[0,1,1] neg_lo:[0,0,1]
	v_pk_add_f32 v[202:203], v[6:7], v[38:39]
	v_pk_add_f32 v[6:7], v[6:7], v[38:39] neg_lo:[0,1] neg_hi:[0,1]
	v_pk_add_f32 v[204:205], v[22:23], v[54:55]
	v_pk_add_f32 v[22:23], v[22:23], v[54:55] neg_lo:[0,1] neg_hi:[0,1]
	v_pk_add_f32 v[38:39], v[202:203], v[204:205]
	v_pk_add_f32 v[54:55], v[202:203], v[204:205] neg_lo:[0,1] neg_hi:[0,1]
	v_pk_add_f32 v[202:203], v[6:7], v[22:23] op_sel:[0,1] op_sel_hi:[1,0] neg_hi:[0,1]
	v_pk_add_f32 v[204:205], v[6:7], v[22:23] op_sel:[0,1] op_sel_hi:[1,0] neg_lo:[0,1]
	v_pk_mul_f32 v[6:7], v[224:225], v[202:203] op_sel:[1,1] op_sel_hi:[1,0]
	v_pk_fma_f32 v[6:7], v[224:225], v[202:203], v[6:7] op_sel_hi:[0,1,1] neg_lo:[0,0,1]
	v_pk_mul_f32 v[22:23], v[226:227], v[54:55] op_sel:[1,1] op_sel_hi:[1,0]
	v_pk_fma_f32 v[22:23], v[226:227], v[54:55], v[22:23] op_sel_hi:[0,1,1] neg_lo:[0,0,1]
	v_pk_mul_f32 v[54:55], v[230:231], v[204:205] op_sel:[1,1] op_sel_hi:[1,0]
	v_pk_fma_f32 v[54:55], v[230:231], v[204:205], v[54:55] op_sel_hi:[0,1,1] neg_lo:[0,0,1]
	v_pk_add_f32 v[202:203], v[2:3], v[34:35]
	v_pk_add_f32 v[2:3], v[2:3], v[34:35] neg_lo:[0,1] neg_hi:[0,1]
	v_pk_add_f32 v[204:205], v[18:19], v[50:51]
	v_pk_add_f32 v[18:19], v[18:19], v[50:51] neg_lo:[0,1] neg_hi:[0,1]
	v_pk_add_f32 v[34:35], v[202:203], v[204:205]
	v_pk_add_f32 v[50:51], v[202:203], v[204:205] neg_lo:[0,1] neg_hi:[0,1]
	v_pk_add_f32 v[202:203], v[2:3], v[18:19] op_sel:[0,1] op_sel_hi:[1,0] neg_hi:[0,1]
	v_pk_add_f32 v[204:205], v[2:3], v[18:19] op_sel:[0,1] op_sel_hi:[1,0] neg_lo:[0,1]
	v_pk_mul_f32 v[2:3], v[224:225], v[202:203] op_sel:[1,1] op_sel_hi:[1,0]
	v_pk_fma_f32 v[2:3], v[224:225], v[202:203], v[2:3] op_sel_hi:[0,1,1] neg_lo:[0,0,1]
	v_pk_mul_f32 v[18:19], v[226:227], v[50:51] op_sel:[1,1] op_sel_hi:[1,0]
	v_pk_fma_f32 v[18:19], v[226:227], v[50:51], v[18:19] op_sel_hi:[0,1,1] neg_lo:[0,0,1]
	v_pk_mul_f32 v[50:51], v[230:231], v[204:205] op_sel:[1,1] op_sel_hi:[1,0]
	v_pk_fma_f32 v[50:51], v[230:231], v[204:205], v[50:51] op_sel_hi:[0,1,1] neg_lo:[0,0,1]
	v_pk_add_f32 v[202:203], v[4:5], v[36:37]
	v_pk_add_f32 v[4:5], v[4:5], v[36:37] neg_lo:[0,1] neg_hi:[0,1]
	v_pk_add_f32 v[204:205], v[20:21], v[52:53]
	v_pk_add_f32 v[20:21], v[20:21], v[52:53] neg_lo:[0,1] neg_hi:[0,1]
	v_pk_add_f32 v[36:37], v[202:203], v[204:205]
	v_pk_add_f32 v[52:53], v[202:203], v[204:205] neg_lo:[0,1] neg_hi:[0,1]
	v_pk_add_f32 v[202:203], v[4:5], v[20:21] op_sel:[0,1] op_sel_hi:[1,0] neg_hi:[0,1]
	v_pk_add_f32 v[204:205], v[4:5], v[20:21] op_sel:[0,1] op_sel_hi:[1,0] neg_lo:[0,1]
	v_pk_mul_f32 v[4:5], v[224:225], v[202:203] op_sel:[1,1] op_sel_hi:[1,0]
	v_pk_fma_f32 v[4:5], v[224:225], v[202:203], v[4:5] op_sel_hi:[0,1,1] neg_lo:[0,0,1]
	v_pk_mul_f32 v[20:21], v[226:227], v[52:53] op_sel:[1,1] op_sel_hi:[1,0]
	v_pk_fma_f32 v[20:21], v[226:227], v[52:53], v[20:21] op_sel_hi:[0,1,1] neg_lo:[0,0,1]
	v_pk_mul_f32 v[52:53], v[230:231], v[204:205] op_sel:[1,1] op_sel_hi:[1,0]
	v_pk_fma_f32 v[52:53], v[230:231], v[204:205], v[52:53] op_sel_hi:[0,1,1] neg_lo:[0,0,1]
	v_pk_add_f32 v[202:203], v[8:9], v[40:41]
	v_pk_add_f32 v[8:9], v[8:9], v[40:41] neg_lo:[0,1] neg_hi:[0,1]
	v_pk_add_f32 v[204:205], v[24:25], v[56:57]
	v_pk_add_f32 v[24:25], v[24:25], v[56:57] neg_lo:[0,1] neg_hi:[0,1]
	v_pk_add_f32 v[40:41], v[202:203], v[204:205]
	v_pk_add_f32 v[56:57], v[202:203], v[204:205] neg_lo:[0,1] neg_hi:[0,1]
	v_pk_add_f32 v[202:203], v[8:9], v[24:25] op_sel:[0,1] op_sel_hi:[1,0] neg_hi:[0,1]
	v_pk_add_f32 v[204:205], v[8:9], v[24:25] op_sel:[0,1] op_sel_hi:[1,0] neg_lo:[0,1]
	v_pk_mul_f32 v[8:9], v[224:225], v[202:203] op_sel:[1,1] op_sel_hi:[1,0]
	v_pk_fma_f32 v[8:9], v[224:225], v[202:203], v[8:9] op_sel_hi:[0,1,1] neg_lo:[0,0,1]
	v_pk_mul_f32 v[24:25], v[226:227], v[56:57] op_sel:[1,1] op_sel_hi:[1,0]
	v_pk_fma_f32 v[24:25], v[226:227], v[56:57], v[24:25] op_sel_hi:[0,1,1] neg_lo:[0,0,1]
; DI f32x2 cmul(f32x2 a, f32x2 b) { return mkf2(a.x * b.x - a.y * b.y, a.x * b.y + a.y * b.x); }
; DI void fft8192(f32x2* buf, const f32x2* __restrict__ tw) {
;     ...
;   for (int ls = 0; ls < 12; ls += 2) {
;     const int s = 1 << ls;
;     f32x2 a[8], b[8], c[8], d[8];
;     __syncthreads();
; #pragma unroll
;     for (int e = 0; e < 8; ++e) {
;       const int i = tid + 256 * e;
;       const int pi = SW(i);
;       a[e] = buf[pi]; b[e] = buf[pi + 2048]; c[e] = buf[pi + 4096]; d[e] = buf[pi + 6144];
;     }
;     __syncthreads();
; #pragma unroll
;     for (int e = 0; e < 8; ++e) {
;       const int i = tid + 256 * e;
;       const int q = i & (s - 1);
;       const int ps = i - q;
;       const float rev = (float)ps * (1.f / 8192.f);
;       const f32x2 w1 = mkf2(__builtin_amdgcn_cosf(rev), -__builtin_amdgcn_sinf(rev));
;       const f32x2 w2 = cmul(w1, w1), w3 = cmul(w1, w2);
;       const f32x2 apc = mkf2(a[e].x + c[e].x, a[e].y + c[e].y), amc = mkf2(a[e].x - c[e].x, a[e].y - c[e].y);
;       const f32x2 bpd = mkf2(b[e].x + d[e].x, b[e].y + d[e].y), bmd = mkf2(b[e].x - d[e].x, b[e].y - d[e].y);
;       const int o = 4 * i - 3 * q;
;       buf[SW(o)] = mkf2(apc.x + bpd.x, apc.y + bpd.y);
;       buf[SW(o + s)] = cmul(w1, mkf2(amc.x + bmd.y, amc.y - bmd.x));
;       buf[SW(o + 2 * s)] = cmul(w2, mkf2(apc.x - bpd.x, apc.y - bpd.y));
;       buf[SW(o + 3 * s)] = cmul(w3, mkf2(amc.x - bmd.y, amc.y + bmd.x));
;     }
	v_pk_mul_f32 v[56:57], v[230:231], v[204:205] op_sel:[1,1] op_sel_hi:[1,0]
	v_pk_fma_f32 v[56:57], v[230:231], v[204:205], v[56:57] op_sel_hi:[0,1,1] neg_lo:[0,0,1]
	v_mul_f32_e32 v214, 4.0, v201
	v_add_f32_e32 v214, 0x3e000000, v214
	v_cos_f32_e32 v224, v214
	v_sin_f32_e64 v225, -v214
	s_nop 0
	v_pk_mul_f32 v[206:207], v[224:225], v[224:225] op_sel:[1,1] op_sel_hi:[1,0]
	v_pk_fma_f32 v[226:227], v[224:225], v[224:225], v[206:207] op_sel_hi:[0,1,1] neg_lo:[0,0,1]
	v_pk_mul_f32 v[206:207], v[224:225], v[226:227] op_sel:[1,1] op_sel_hi:[1,0]
	v_pk_fma_f32 v[230:231], v[224:225], v[226:227], v[206:207] op_sel_hi:[0,1,1] neg_lo:[0,0,1]
	v_pk_add_f32 v[202:203], v[14:15], v[46:47]
	v_pk_add_f32 v[14:15], v[14:15], v[46:47] neg_lo:[0,1] neg_hi:[0,1]
	v_pk_add_f32 v[204:205], v[30:31], v[62:63]
	v_pk_add_f32 v[30:31], v[30:31], v[62:63] neg_lo:[0,1] neg_hi:[0,1]
	v_pk_add_f32 v[46:47], v[202:203], v[204:205]
	v_pk_add_f32 v[62:63], v[202:203], v[204:205] neg_lo:[0,1] neg_hi:[0,1]
	v_pk_add_f32 v[202:203], v[14:15], v[30:31] op_sel:[0,1] op_sel_hi:[1,0] neg_hi:[0,1]
	v_pk_add_f32 v[204:205], v[14:15], v[30:31] op_sel:[0,1] op_sel_hi:[1,0] neg_lo:[0,1]
	v_pk_mul_f32 v[14:15], v[224:225], v[202:203] op_sel:[1,1] op_sel_hi:[1,0]
	v_pk_fma_f32 v[14:15], v[224:225], v[202:203], v[14:15] op_sel_hi:[0,1,1] neg_lo:[0,0,1]
	v_pk_mul_f32 v[30:31], v[226:227], v[62:63] op_sel:[1,1] op_sel_hi:[1,0]
	v_pk_fma_f32 v[30:31], v[226:227], v[62:63], v[30:31] op_sel_hi:[0,1,1] neg_lo:[0,0,1]
	v_pk_mul_f32 v[62:63], v[230:231], v[204:205] op_sel:[1,1] op_sel_hi:[1,0]
	v_pk_fma_f32 v[62:63], v[230:231], v[204:205], v[62:63] op_sel_hi:[0,1,1] neg_lo:[0,0,1]
	v_pk_add_f32 v[202:203], v[10:11], v[42:43]
	v_pk_add_f32 v[10:11], v[10:11], v[42:43] neg_lo:[0,1] neg_hi:[0,1]
	v_pk_add_f32 v[204:205], v[26:27], v[58:59]
	v_pk_add_f32 v[26:27], v[26:27], v[58:59] neg_lo:[0,1] neg_hi:[0,1]
	v_pk_add_f32 v[42:43], v[202:203], v[204:205]
	v_pk_add_f32 v[58:59], v[202:203], v[204:205] neg_lo:[0,1] neg_hi:[0,1]
	v_pk_add_f32 v[202:203], v[10:11], v[26:27] op_sel:[0,1] op_sel_hi:[1,0] neg_hi:[0,1]
	v_pk_add_f32 v[204:205], v[10:11], v[26:27] op_sel:[0,1] op_sel_hi:[1,0] neg_lo:[0,1]
	v_pk_mul_f32 v[10:11], v[224:225], v[202:203] op_sel:[1,1] op_sel_hi:[1,0]
	v_pk_fma_f32 v[10:11], v[224:225], v[202:203], v[10:11] op_sel_hi:[0,1,1] neg_lo:[0,0,1]
	v_pk_mul_f32 v[26:27], v[226:227], v[58:59] op_sel:[1,1] op_sel_hi:[1,0]
	v_pk_fma_f32 v[26:27], v[226:227], v[58:59], v[26:27] op_sel_hi:[0,1,1] neg_lo:[0,0,1]
	v_pk_mul_f32 v[58:59], v[230:231], v[204:205] op_sel:[1,1] op_sel_hi:[1,0]
	v_pk_fma_f32 v[58:59], v[230:231], v[204:205], v[58:59] op_sel_hi:[0,1,1] neg_lo:[0,0,1]
	v_pk_add_f32 v[202:203], v[12:13], v[44:45]
	v_pk_add_f32 v[12:13], v[12:13], v[44:45] neg_lo:[0,1] neg_hi:[0,1]
	v_pk_add_f32 v[204:205], v[28:29], v[60:61]
	v_pk_add_f32 v[28:29], v[28:29], v[60:61] neg_lo:[0,1] neg_hi:[0,1]
	v_pk_add_f32 v[44:45], v[202:203], v[204:205]
	v_pk_add_f32 v[60:61], v[202:203], v[204:205] neg_lo:[0,1] neg_hi:[0,1]
	v_pk_add_f32 v[202:203], v[12:13], v[28:29] op_sel:[0,1] op_sel_hi:[1,0] neg_hi:[0,1]
	v_pk_add_f32 v[204:205], v[12:13], v[28:29] op_sel:[0,1] op_sel_hi:[1,0] neg_lo:[0,1]
	v_pk_mul_f32 v[12:13], v[224:225], v[202:203] op_sel:[1,1] op_sel_hi:[1,0]
	v_pk_fma_f32 v[12:13], v[224:225], v[202:203], v[12:13] op_sel_hi:[0,1,1] neg_lo:[0,0,1]
	v_pk_mul_f32 v[28:29], v[226:227], v[60:61] op_sel:[1,1] op_sel_hi:[1,0]
	v_pk_fma_f32 v[28:29], v[226:227], v[60:61], v[28:29] op_sel_hi:[0,1,1] neg_lo:[0,0,1]
	v_pk_mul_f32 v[60:61], v[230:231], v[204:205] op_sel:[1,1] op_sel_hi:[1,0]
	v_pk_fma_f32 v[60:61], v[230:231], v[204:205], v[60:61] op_sel_hi:[0,1,1] neg_lo:[0,0,1]
	v_pk_add_f32 v[202:203], v[16:17], v[48:49]
	v_pk_add_f32 v[16:17], v[16:17], v[48:49] neg_lo:[0,1] neg_hi:[0,1]
	v_pk_add_f32 v[204:205], v[32:33], v[64:65]
	v_pk_add_f32 v[32:33], v[32:33], v[64:65] neg_lo:[0,1] neg_hi:[0,1]
	v_pk_add_f32 v[48:49], v[202:203], v[204:205]
	v_pk_add_f32 v[64:65], v[202:203], v[204:205] neg_lo:[0,1] neg_hi:[0,1]
	v_pk_add_f32 v[202:203], v[16:17], v[32:33] op_sel:[0,1] op_sel_hi:[1,0] neg_hi:[0,1]
	v_pk_add_f32 v[204:205], v[16:17], v[32:33] op_sel:[0,1] op_sel_hi:[1,0] neg_lo:[0,1]
	v_pk_mul_f32 v[16:17], v[224:225], v[202:203] op_sel:[1,1] op_sel_hi:[1,0]
	v_pk_fma_f32 v[16:17], v[224:225], v[202:203], v[16:17] op_sel_hi:[0,1,1] neg_lo:[0,0,1]
	v_pk_mul_f32 v[32:33], v[226:227], v[64:65] op_sel:[1,1] op_sel_hi:[1,0]
	v_pk_fma_f32 v[32:33], v[226:227], v[64:65], v[32:33] op_sel_hi:[0,1,1] neg_lo:[0,0,1]
	v_pk_mul_f32 v[64:65], v[230:231], v[204:205] op_sel:[1,1] op_sel_hi:[1,0]
	v_pk_fma_f32 v[64:65], v[230:231], v[204:205], v[64:65] op_sel_hi:[0,1,1] neg_lo:[0,0,1]
	ds_write_b64 v164, v[38:39] offset:0
	v_xor_b32_e32 v156, 8, v164
	ds_write_b64 v156, v[34:35] offset:0
	v_xor_b32_e32 v158, 16, v164
	ds_write_b64 v158, v[36:37] offset:0
	v_xor_b32_e32 v160, 24, v164
	ds_write_b64 v160, v[40:41] offset:0
	v_xor_b32_e32 v162, 32, v164
	ds_write_b64 v162, v[6:7] offset:0
	v_xor_b32_e32 v156, 40, v164
	ds_write_b64 v156, v[2:3] offset:0
	v_xor_b32_e32 v158, 48, v164
	ds_write_b64 v158, v[4:5] offset:0
	v_xor_b32_e32 v160, 56, v164
	ds_write_b64 v160, v[8:9] offset:0
	v_xor_b32_e32 v162, 64, v164
	ds_write_b64 v162, v[22:23] offset:0
	v_xor_b32_e32 v156, 0x48, v164
	ds_write_b64 v156, v[18:19] offset:0
	v_xor_b32_e32 v158, 0x50, v164
	ds_write_b64 v158, v[20:21] offset:0
	v_xor_b32_e32 v160, 0x58, v164
	ds_write_b64 v160, v[24:25] offset:0
	v_xor_b32_e32 v162, 0x60, v164
	ds_write_b64 v162, v[54:55] offset:0
	v_xor_b32_e32 v156, 0x68, v164
	ds_write_b64 v156, v[50:51] offset:0
	v_xor_b32_e32 v158, 0x70, v164
	ds_write_b64 v158, v[52:53] offset:0
	v_xor_b32_e32 v160, 0x78, v164
	ds_write_b64 v160, v[56:57] offset:0
	ds_write_b64 v164, v[46:47] offset:32768
	v_xor_b32_e32 v162, 8, v164
	ds_write_b64 v162, v[42:43] offset:32768
	v_xor_b32_e32 v156, 16, v164
	ds_write_b64 v156, v[44:45] offset:32768
	v_xor_b32_e32 v158, 24, v164
	ds_write_b64 v158, v[48:49] offset:32768
	v_xor_b32_e32 v160, 32, v164
	ds_write_b64 v160, v[14:15] offset:32768
	v_xor_b32_e32 v162, 40, v164
	ds_write_b64 v162, v[10:11] offset:32768
	v_xor_b32_e32 v156, 48, v164
	ds_write_b64 v156, v[12:13] offset:32768
	v_xor_b32_e32 v158, 56, v164
	ds_write_b64 v158, v[16:17] offset:32768
	v_xor_b32_e32 v160, 64, v164
	ds_write_b64 v160, v[30:31] offset:32768
	v_xor_b32_e32 v162, 0x48, v164
	ds_write_b64 v162, v[26:27] offset:32768
	v_xor_b32_e32 v156, 0x50, v164
	ds_write_b64 v156, v[28:29] offset:32768
	v_xor_b32_e32 v158, 0x58, v164
	ds_write_b64 v158, v[32:33] offset:32768
	v_xor_b32_e32 v160, 0x60, v164
	ds_write_b64 v160, v[62:63] offset:32768
	v_xor_b32_e32 v162, 0x68, v164
	ds_write_b64 v162, v[58:59] offset:32768
	v_xor_b32_e32 v156, 0x70, v164
	ds_write_b64 v156, v[60:61] offset:32768
	v_xor_b32_e32 v158, 0x78, v164
	ds_write_b64 v158, v[64:65] offset:32768
	s_waitcnt lgkmcnt(0)
	s_barrier
; DI f32x2 cmul(f32x2 a, f32x2 b) { return mkf2(a.x * b.x - a.y * b.y, a.x * b.y + a.y * b.x); }
; DI void fft8192(f32x2* buf, const f32x2* __restrict__ tw) {
;     ...
;   for (int ls = 0; ls < 12; ls += 2) {
;     const int s = 1 << ls;
;     f32x2 a[8], b[8], c[8], d[8];
;     __syncthreads();
; #pragma unroll
;     for (int e = 0; e < 8; ++e) {
;       const int i = tid + 256 * e;
;       const int pi = SW(i);
;       a[e] = buf[pi]; b[e] = buf[pi + 2048]; c[e] = buf[pi + 4096]; d[e] = buf[pi + 6144];
;     }
;     __syncthreads();
; #pragma unroll
;     for (int e = 0; e < 8; ++e) {
;       const int i = tid + 256 * e;
;       const int q = i & (s - 1);
;       const int ps = i - q;
;       const float rev = (float)ps * (1.f / 8192.f);
;       const f32x2 w1 = mkf2(__builtin_amdgcn_cosf(rev), -__builtin_amdgcn_sinf(rev));
;       const f32x2 w2 = cmul(w1, w1), w3 = cmul(w1, w2);
;       const f32x2 apc = mkf2(a[e].x + c[e].x, a[e].y + c[e].y), amc = mkf2(a[e].x - c[e].x, a[e].y - c[e].y);
;       const f32x2 bpd = mkf2(b[e].x + d[e].x, b[e].y + d[e].y), bmd = mkf2(b[e].x - d[e].x, b[e].y - d[e].y);
;       const int o = 4 * i - 3 * q;
;       buf[SW(o)] = mkf2(apc.x + bpd.x, apc.y + bpd.y);
;       buf[SW(o + s)] = cmul(w1, mkf2(amc.x + bmd.y, amc.y - bmd.x));
;       buf[SW(o + 2 * s)] = cmul(w2, mkf2(apc.x - bpd.x, apc.y - bpd.y));
;       buf[SW(o + 3 * s)] = cmul(w3, mkf2(amc.x - bmd.y, amc.y + bmd.x));
;     }
	v_bfe_i32 v166, v0, 4, 4
	v_and_b32_e32 v166, 15, v166
	v_xor_b32_e32 v166, v166, v0
	v_lshlrev_b32_e32 v164, 3, v166
	ds_read2st64_b64 v[2:5], v164 offset0:0 offset1:32
	ds_read2st64_b64 v[6:9], v164 offset0:64 offset1:96
	ds_read2st64_b64 v[10:13], v164 offset0:4 offset1:36
	ds_read2st64_b64 v[14:17], v164 offset0:68 offset1:100
	ds_read2st64_b64 v[18:21], v164 offset0:8 offset1:40
	ds_read2st64_b64 v[22:25], v164 offset0:72 offset1:104
	ds_read2st64_b64 v[26:29], v164 offset0:12 offset1:44
	ds_read2st64_b64 v[30:33], v164 offset0:76 offset1:108
	ds_read2st64_b64 v[34:37], v164 offset0:16 offset1:48
	ds_read2st64_b64 v[38:41], v164 offset0:80 offset1:112
	ds_read2st64_b64 v[42:45], v164 offset0:20 offset1:52
	ds_read2st64_b64 v[46:49], v164 offset0:84 offset1:116
	ds_read2st64_b64 v[50:53], v164 offset0:24 offset1:56
	ds_read2st64_b64 v[54:57], v164 offset0:88 offset1:120
	ds_read2st64_b64 v[58:61], v164 offset0:28 offset1:60
	ds_read2st64_b64 v[62:65], v164 offset0:92 offset1:124
	v_and_b32_e32 v166, 15, v0
	v_sub_u32_e32 v168, v0, v166
	v_cvt_f32_u32_e32 v201, v168
	v_lshl_add_u32 v164, v168, 4, v166
	v_lshlrev_b32_e32 v164, 3, v164
	v_mul_f32_e32 v201, 0x39000000, v201
	v_cos_f32_e32 v210, v201
	v_sin_f32_e64 v211, -v201
	s_nop 0
	v_mov_b32_e32 v224, v210
	v_mov_b32_e32 v225, v211
	s_waitcnt lgkmcnt(14)
	v_pk_add_f32 v[202:203], v[2:3], v[6:7]
	v_pk_add_f32 v[2:3], v[2:3], v[6:7] neg_lo:[0,1] neg_hi:[0,1]
	v_pk_add_f32 v[204:205], v[4:5], v[8:9]
	v_pk_add_f32 v[4:5], v[4:5], v[8:9] neg_lo:[0,1] neg_hi:[0,1]
	v_pk_add_f32 v[6:7], v[202:203], v[204:205]
	v_pk_add_f32 v[8:9], v[202:203], v[204:205] neg_lo:[0,1] neg_hi:[0,1]
	v_pk_add_f32 v[202:203], v[2:3], v[4:5] op_sel:[0,1] op_sel_hi:[1,0] neg_hi:[0,1]
	v_pk_add_f32 v[204:205], v[2:3], v[4:5] op_sel:[0,1] op_sel_hi:[1,0] neg_lo:[0,1]
	v_pk_mul_f32 v[206:207], v[210:211], v[210:211] op_sel:[1,1] op_sel_hi:[1,0]
	v_pk_fma_f32 v[212:213], v[210:211], v[210:211], v[206:207] op_sel_hi:[0,1,1] neg_lo:[0,0,1]
	v_pk_mul_f32 v[206:207], v[210:211], v[212:213] op_sel:[1,1] op_sel_hi:[1,0]
	v_pk_fma_f32 v[220:221], v[210:211], v[212:213], v[206:207] op_sel_hi:[0,1,1] neg_lo:[0,0,1]
	v_pk_mul_f32 v[2:3], v[210:211], v[202:203] op_sel:[1,1] op_sel_hi:[1,0]
	v_pk_fma_f32 v[2:3], v[210:211], v[202:203], v[2:3] op_sel_hi:[0,1,1] neg_lo:[0,0,1]
	v_pk_mul_f32 v[4:5], v[212:213], v[8:9] op_sel:[1,1] op_sel_hi:[1,0]
	v_pk_fma_f32 v[4:5], v[212:213], v[8:9], v[4:5] op_sel_hi:[0,1,1] neg_lo:[0,0,1]
	v_pk_mul_f32 v[8:9], v[220:221], v[204:205] op_sel:[1,1] op_sel_hi:[1,0]
	v_pk_fma_f32 v[8:9], v[220:221], v[204:205], v[8:9] op_sel_hi:[0,1,1] neg_lo:[0,0,1]
	v_mul_f32_e32 v210, 0x3f7b14be, v224
	v_mul_f32_e32 v211, 0xbe47c5c2, v224
	v_fmac_f32_e32 v210, 0x3e47c5c2, v225
	v_fmac_f32_e32 v211, 0x3f7b14be, v225
	s_waitcnt lgkmcnt(12)
	v_pk_add_f32 v[202:203], v[10:11], v[14:15]
	v_pk_add_f32 v[10:11], v[10:11], v[14:15] neg_lo:[0,1] neg_hi:[0,1]
	v_pk_add_f32 v[204:205], v[12:13], v[16:17]
	v_pk_add_f32 v[12:13], v[12:13], v[16:17] neg_lo:[0,1] neg_hi:[0,1]
	v_pk_add_f32 v[14:15], v[202:203], v[204:205]
	v_pk_add_f32 v[16:17], v[202:203], v[204:205] neg_lo:[0,1] neg_hi:[0,1]
	v_pk_add_f32 v[202:203], v[10:11], v[12:13] op_sel:[0,1] op_sel_hi:[1,0] neg_hi:[0,1]
	v_pk_add_f32 v[204:205], v[10:11], v[12:13] op_sel:[0,1] op_sel_hi:[1,0] neg_lo:[0,1]
	v_pk_mul_f32 v[206:207], v[210:211], v[210:211] op_sel:[1,1] op_sel_hi:[1,0]
	v_pk_fma_f32 v[212:213], v[210:211], v[210:211], v[206:207] op_sel_hi:[0,1,1] neg_lo:[0,0,1]
	v_pk_mul_f32 v[206:207], v[210:211], v[212:213] op_sel:[1,1] op_sel_hi:[1,0]
	v_pk_fma_f32 v[220:221], v[210:211], v[212:213], v[206:207] op_sel_hi:[0,1,1] neg_lo:[0,0,1]
	v_pk_mul_f32 v[10:11], v[210:211], v[202:203] op_sel:[1,1] op_sel_hi:[1,0]
	v_pk_fma_f32 v[10:11], v[210:211], v[202:203], v[10:11] op_sel_hi:[0,1,1] neg_lo:[0,0,1]
	v_pk_mul_f32 v[12:13], v[212:213], v[16:17] op_sel:[1,1] op_sel_hi:[1,0]
	v_pk_fma_f32 v[12:13], v[212:213], v[16:17], v[12:13] op_sel_hi:[0,1,1] neg_lo:[0,0,1]
	v_pk_mul_f32 v[16:17], v[220:221], v[204:205] op_sel:[1,1] op_sel_hi:[1,0]
	v_pk_fma_f32 v[16:17], v[220:221], v[204:205], v[16:17] op_sel_hi:[0,1,1] neg_lo:[0,0,1]
	v_mul_f32_e32 v210, 0x3f6c835e, v224
	v_mul_f32_e32 v211, 0xbec3ef15, v224
	v_fmac_f32_e32 v210, 0x3ec3ef15, v225
	v_fmac_f32_e32 v211, 0x3f6c835e, v225
	s_waitcnt lgkmcnt(10)
	v_pk_add_f32 v[202:203], v[18:19], v[22:23]
	v_pk_add_f32 v[18:19], v[18:19], v[22:23] neg_lo:[0,1] neg_hi:[0,1]
	v_pk_add_f32 v[204:205], v[20:21], v[24:25]
	v_pk_add_f32 v[20:21], v[20:21], v[24:25] neg_lo:[0,1] neg_hi:[0,1]
	v_pk_add_f32 v[22:23], v[202:203], v[204:205]
	v_pk_add_f32 v[24:25], v[202:203], v[204:205] neg_lo:[0,1] neg_hi:[0,1]
	v_pk_add_f32 v[202:203], v[18:19], v[20:21] op_sel:[0,1] op_sel_hi:[1,0] neg_hi:[0,1]
	v_pk_add_f32 v[204:205], v[18:19], v[20:21] op_sel:[0,1] op_sel_hi:[1,0] neg_lo:[0,1]
	v_pk_mul_f32 v[206:207], v[210:211], v[210:211] op_sel:[1,1] op_sel_hi:[1,0]
	v_pk_fma_f32 v[212:213], v[210:211], v[210:211], v[206:207] op_sel_hi:[0,1,1] neg_lo:[0,0,1]
	v_pk_mul_f32 v[206:207], v[210:211], v[212:213] op_sel:[1,1] op_sel_hi:[1,0]
	v_pk_fma_f32 v[220:221], v[210:211], v[212:213], v[206:207] op_sel_hi:[0,1,1] neg_lo:[0,0,1]
	v_pk_mul_f32 v[18:19], v[210:211], v[202:203] op_sel:[1,1] op_sel_hi:[1,0]
	v_pk_fma_f32 v[18:19], v[210:211], v[202:203], v[18:19] op_sel_hi:[0,1,1] neg_lo:[0,0,1]
	v_pk_mul_f32 v[20:21], v[212:213], v[24:25] op_sel:[1,1] op_sel_hi:[1,0]
	v_pk_fma_f32 v[20:21], v[212:213], v[24:25], v[20:21] op_sel_hi:[0,1,1] neg_lo:[0,0,1]
	v_pk_mul_f32 v[24:25], v[220:221], v[204:205] op_sel:[1,1] op_sel_hi:[1,0]
	v_pk_fma_f32 v[24:25], v[220:221], v[204:205], v[24:25] op_sel_hi:[0,1,1] neg_lo:[0,0,1]
	v_mul_f32_e32 v210, 0x3f54db31, v224
	v_mul_f32_e32 v211, 0xbf0e39da, v224
	v_fmac_f32_e32 v210, 0x3f0e39da, v225
	v_fmac_f32_e32 v211, 0x3f54db31, v225
	s_waitcnt lgkmcnt(8)
; DI f32x2 cmul(f32x2 a, f32x2 b) { return mkf2(a.x * b.x - a.y * b.y, a.x * b.y + a.y * b.x); }
; DI void fft8192(f32x2* buf, const f32x2* __restrict__ tw) {
;     ...
;   for (int ls = 0; ls < 12; ls += 2) {
;     const int s = 1 << ls;
;     f32x2 a[8], b[8], c[8], d[8];
;     __syncthreads();
; #pragma unroll
;     for (int e = 0; e < 8; ++e) {
;       const int i = tid + 256 * e;
;       const int pi = SW(i);
;       a[e] = buf[pi]; b[e] = buf[pi + 2048]; c[e] = buf[pi + 4096]; d[e] = buf[pi + 6144];
;     }
;     __syncthreads();
; #pragma unroll
;     for (int e = 0; e < 8; ++e) {
;       const int i = tid + 256 * e;
;       const int q = i & (s - 1);
;       const int ps = i - q;
;       const float rev = (float)ps * (1.f / 8192.f);
;       const f32x2 w1 = mkf2(__builtin_amdgcn_cosf(rev), -__builtin_amdgcn_sinf(rev));
;       const f32x2 w2 = cmul(w1, w1), w3 = cmul(w1, w2);
;       const f32x2 apc = mkf2(a[e].x + c[e].x, a[e].y + c[e].y), amc = mkf2(a[e].x - c[e].x, a[e].y - c[e].y);
;       const f32x2 bpd = mkf2(b[e].x + d[e].x, b[e].y + d[e].y), bmd = mkf2(b[e].x - d[e].x, b[e].y - d[e].y);
;       const int o = 4 * i - 3 * q;
;       buf[SW(o)] = mkf2(apc.x + bpd.x, apc.y + bpd.y);
;       buf[SW(o + s)] = cmul(w1, mkf2(amc.x + bmd.y, amc.y - bmd.x));
;       buf[SW(o + 2 * s)] = cmul(w2, mkf2(apc.x - bpd.x, apc.y - bpd.y));
;       buf[SW(o + 3 * s)] = cmul(w3, mkf2(amc.x - bmd.y, amc.y + bmd.x));
;     }
	v_pk_add_f32 v[202:203], v[26:27], v[30:31]
	v_pk_add_f32 v[26:27], v[26:27], v[30:31] neg_lo:[0,1] neg_hi:[0,1]
	v_pk_add_f32 v[204:205], v[28:29], v[32:33]
	v_pk_add_f32 v[28:29], v[28:29], v[32:33] neg_lo:[0,1] neg_hi:[0,1]
	v_pk_add_f32 v[30:31], v[202:203], v[204:205]
	v_pk_add_f32 v[32:33], v[202:203], v[204:205] neg_lo:[0,1] neg_hi:[0,1]
	v_pk_add_f32 v[202:203], v[26:27], v[28:29] op_sel:[0,1] op_sel_hi:[1,0] neg_hi:[0,1]
	v_pk_add_f32 v[204:205], v[26:27], v[28:29] op_sel:[0,1] op_sel_hi:[1,0] neg_lo:[0,1]
	v_pk_mul_f32 v[206:207], v[210:211], v[210:211] op_sel:[1,1] op_sel_hi:[1,0]
	v_pk_fma_f32 v[212:213], v[210:211], v[210:211], v[206:207] op_sel_hi:[0,1,1] neg_lo:[0,0,1]
	v_pk_mul_f32 v[206:207], v[210:211], v[212:213] op_sel:[1,1] op_sel_hi:[1,0]
	v_pk_fma_f32 v[220:221], v[210:211], v[212:213], v[206:207] op_sel_hi:[0,1,1] neg_lo:[0,0,1]
	v_pk_mul_f32 v[26:27], v[210:211], v[202:203] op_sel:[1,1] op_sel_hi:[1,0]
	v_pk_fma_f32 v[26:27], v[210:211], v[202:203], v[26:27] op_sel_hi:[0,1,1] neg_lo:[0,0,1]
	v_pk_mul_f32 v[28:29], v[212:213], v[32:33] op_sel:[1,1] op_sel_hi:[1,0]
	v_pk_fma_f32 v[28:29], v[212:213], v[32:33], v[28:29] op_sel_hi:[0,1,1] neg_lo:[0,0,1]
	v_pk_mul_f32 v[32:33], v[220:221], v[204:205] op_sel:[1,1] op_sel_hi:[1,0]
	v_pk_fma_f32 v[32:33], v[220:221], v[204:205], v[32:33] op_sel_hi:[0,1,1] neg_lo:[0,0,1]
	v_mul_f32_e32 v210, 0x3f3504f3, v224
	v_mul_f32_e32 v211, 0xbf3504f3, v224
	v_fmac_f32_e32 v210, 0x3f3504f3, v225
	v_fmac_f32_e32 v211, 0x3f3504f3, v225
	s_waitcnt lgkmcnt(6)
	v_pk_add_f32 v[202:203], v[34:35], v[38:39]
	v_pk_add_f32 v[34:35], v[34:35], v[38:39] neg_lo:[0,1] neg_hi:[0,1]
	v_pk_add_f32 v[204:205], v[36:37], v[40:41]
	v_pk_add_f32 v[36:37], v[36:37], v[40:41] neg_lo:[0,1] neg_hi:[0,1]
	v_pk_add_f32 v[38:39], v[202:203], v[204:205]
	v_pk_add_f32 v[40:41], v[202:203], v[204:205] neg_lo:[0,1] neg_hi:[0,1]
	v_pk_add_f32 v[202:203], v[34:35], v[36:37] op_sel:[0,1] op_sel_hi:[1,0] neg_hi:[0,1]
	v_pk_add_f32 v[204:205], v[34:35], v[36:37] op_sel:[0,1] op_sel_hi:[1,0] neg_lo:[0,1]
	v_pk_mul_f32 v[206:207], v[210:211], v[210:211] op_sel:[1,1] op_sel_hi:[1,0]
	v_pk_fma_f32 v[212:213], v[210:211], v[210:211], v[206:207] op_sel_hi:[0,1,1] neg_lo:[0,0,1]
	v_pk_mul_f32 v[206:207], v[210:211], v[212:213] op_sel:[1,1] op_sel_hi:[1,0]
	v_pk_fma_f32 v[220:221], v[210:211], v[212:213], v[206:207] op_sel_hi:[0,1,1] neg_lo:[0,0,1]
	v_pk_mul_f32 v[34:35], v[210:211], v[202:203] op_sel:[1,1] op_sel_hi:[1,0]
	v_pk_fma_f32 v[34:35], v[210:211], v[202:203], v[34:35] op_sel_hi:[0,1,1] neg_lo:[0,0,1]
	v_pk_mul_f32 v[36:37], v[212:213], v[40:41] op_sel:[1,1] op_sel_hi:[1,0]
	v_pk_fma_f32 v[36:37], v[212:213], v[40:41], v[36:37] op_sel_hi:[0,1,1] neg_lo:[0,0,1]
	v_pk_mul_f32 v[40:41], v[220:221], v[204:205] op_sel:[1,1] op_sel_hi:[1,0]
	v_pk_fma_f32 v[40:41], v[220:221], v[204:205], v[40:41] op_sel_hi:[0,1,1] neg_lo:[0,0,1]
	v_mul_f32_e32 v210, 0x3f0e39da, v224
	v_mul_f32_e32 v211, 0xbf54db31, v224
	v_fmac_f32_e32 v210, 0x3f54db31, v225
	v_fmac_f32_e32 v211, 0x3f0e39da, v225
	s_waitcnt lgkmcnt(4)
	v_pk_add_f32 v[202:203], v[42:43], v[46:47]
	v_pk_add_f32 v[42:43], v[42:43], v[46:47] neg_lo:[0,1] neg_hi:[0,1]
	v_pk_add_f32 v[204:205], v[44:45], v[48:49]
	v_pk_add_f32 v[44:45], v[44:45], v[48:49] neg_lo:[0,1] neg_hi:[0,1]
	v_pk_add_f32 v[46:47], v[202:203], v[204:205]
	v_pk_add_f32 v[48:49], v[202:203], v[204:205] neg_lo:[0,1] neg_hi:[0,1]
	v_pk_add_f32 v[202:203], v[42:43], v[44:45] op_sel:[0,1] op_sel_hi:[1,0] neg_hi:[0,1]
	v_pk_add_f32 v[204:205], v[42:43], v[44:45] op_sel:[0,1] op_sel_hi:[1,0] neg_lo:[0,1]
	v_pk_mul_f32 v[206:207], v[210:211], v[210:211] op_sel:[1,1] op_sel_hi:[1,0]
	v_pk_fma_f32 v[212:213], v[210:211], v[210:211], v[206:207] op_sel_hi:[0,1,1] neg_lo:[0,0,1]
	v_pk_mul_f32 v[206:207], v[210:211], v[212:213] op_sel:[1,1] op_sel_hi:[1,0]
	v_pk_fma_f32 v[220:221], v[210:211], v[212:213], v[206:207] op_sel_hi:[0,1,1] neg_lo:[0,0,1]
	v_pk_mul_f32 v[42:43], v[210:211], v[202:203] op_sel:[1,1] op_sel_hi:[1,0]
	v_pk_fma_f32 v[42:43], v[210:211], v[202:203], v[42:43] op_sel_hi:[0,1,1] neg_lo:[0,0,1]
	v_pk_mul_f32 v[44:45], v[212:213], v[48:49] op_sel:[1,1] op_sel_hi:[1,0]
	v_pk_fma_f32 v[44:45], v[212:213], v[48:49], v[44:45] op_sel_hi:[0,1,1] neg_lo:[0,0,1]
	v_pk_mul_f32 v[48:49], v[220:221], v[204:205] op_sel:[1,1] op_sel_hi:[1,0]
	v_pk_fma_f32 v[48:49], v[220:221], v[204:205], v[48:49] op_sel_hi:[0,1,1] neg_lo:[0,0,1]
	v_mul_f32_e32 v210, 0x3ec3ef15, v224
	v_mul_f32_e32 v211, 0xbf6c835e, v224
	v_fmac_f32_e32 v210, 0x3f6c835e, v225
	v_fmac_f32_e32 v211, 0x3ec3ef15, v225
	s_waitcnt lgkmcnt(2)
	v_pk_add_f32 v[202:203], v[50:51], v[54:55]
	v_pk_add_f32 v[50:51], v[50:51], v[54:55] neg_lo:[0,1] neg_hi:[0,1]
	v_pk_add_f32 v[204:205], v[52:53], v[56:57]
	v_pk_add_f32 v[52:53], v[52:53], v[56:57] neg_lo:[0,1] neg_hi:[0,1]
	v_pk_add_f32 v[54:55], v[202:203], v[204:205]
	v_pk_add_f32 v[56:57], v[202:203], v[204:205] neg_lo:[0,1] neg_hi:[0,1]
	v_pk_add_f32 v[202:203], v[50:51], v[52:53] op_sel:[0,1] op_sel_hi:[1,0] neg_hi:[0,1]
	v_pk_add_f32 v[204:205], v[50:51], v[52:53] op_sel:[0,1] op_sel_hi:[1,0] neg_lo:[0,1]
	v_pk_mul_f32 v[206:207], v[210:211], v[210:211] op_sel:[1,1] op_sel_hi:[1,0]
	v_pk_fma_f32 v[212:213], v[210:211], v[210:211], v[206:207] op_sel_hi:[0,1,1] neg_lo:[0,0,1]
	v_pk_mul_f32 v[206:207], v[210:211], v[212:213] op_sel:[1,1] op_sel_hi:[1,0]
	v_pk_fma_f32 v[220:221], v[210:211], v[212:213], v[206:207] op_sel_hi:[0,1,1] neg_lo:[0,0,1]
	v_pk_mul_f32 v[50:51], v[210:211], v[202:203] op_sel:[1,1] op_sel_hi:[1,0]
	v_pk_fma_f32 v[50:51], v[210:211], v[202:203], v[50:51] op_sel_hi:[0,1,1] neg_lo:[0,0,1]
	v_pk_mul_f32 v[52:53], v[212:213], v[56:57] op_sel:[1,1] op_sel_hi:[1,0]
	v_pk_fma_f32 v[52:53], v[212:213], v[56:57], v[52:53] op_sel_hi:[0,1,1] neg_lo:[0,0,1]
	v_pk_mul_f32 v[56:57], v[220:221], v[204:205] op_sel:[1,1] op_sel_hi:[1,0]
	v_pk_fma_f32 v[56:57], v[220:221], v[204:205], v[56:57] op_sel_hi:[0,1,1] neg_lo:[0,0,1]
	v_mul_f32_e32 v210, 0x3e47c5c2, v224
	v_mul_f32_e32 v211, 0xbf7b14be, v224
	v_fmac_f32_e32 v210, 0x3f7b14be, v225
	v_fmac_f32_e32 v211, 0x3e47c5c2, v225
	s_waitcnt lgkmcnt(0)
; DI f32x2 cmul(f32x2 a, f32x2 b) { return mkf2(a.x * b.x - a.y * b.y, a.x * b.y + a.y * b.x); }
; DI void fft8192(f32x2* buf, const f32x2* __restrict__ tw) {
;     ...
; #pragma unroll
;     for (int e = 0; e < 8; ++e) {
;       const int i = tid + 256 * e;
;       const int q = i & (s - 1);
;       const int ps = i - q;
;       const float rev = (float)ps * (1.f / 8192.f);
;       const f32x2 w1 = mkf2(__builtin_amdgcn_cosf(rev), -__builtin_amdgcn_sinf(rev));
;       const f32x2 w2 = cmul(w1, w1), w3 = cmul(w1, w2);
;       const f32x2 apc = mkf2(a[e].x + c[e].x, a[e].y + c[e].y), amc = mkf2(a[e].x - c[e].x, a[e].y - c[e].y);
;       const f32x2 bpd = mkf2(b[e].x + d[e].x, b[e].y + d[e].y), bmd = mkf2(b[e].x - d[e].x, b[e].y - d[e].y);
;       const int o = 4 * i - 3 * q;
;       buf[SW(o)] = mkf2(apc.x + bpd.x, apc.y + bpd.y);
;       buf[SW(o + s)] = cmul(w1, mkf2(amc.x + bmd.y, amc.y - bmd.x));
;       buf[SW(o + 2 * s)] = cmul(w2, mkf2(apc.x - bpd.x, apc.y - bpd.y));
;       buf[SW(o + 3 * s)] = cmul(w3, mkf2(amc.x - bmd.y, amc.y + bmd.x));
;     }
	v_pk_add_f32 v[202:203], v[58:59], v[62:63]
	v_pk_add_f32 v[58:59], v[58:59], v[62:63] neg_lo:[0,1] neg_hi:[0,1]
	v_pk_add_f32 v[204:205], v[60:61], v[64:65]
	v_pk_add_f32 v[60:61], v[60:61], v[64:65] neg_lo:[0,1] neg_hi:[0,1]
	v_pk_add_f32 v[62:63], v[202:203], v[204:205]
	v_pk_add_f32 v[64:65], v[202:203], v[204:205] neg_lo:[0,1] neg_hi:[0,1]
	v_pk_add_f32 v[202:203], v[58:59], v[60:61] op_sel:[0,1] op_sel_hi:[1,0] neg_hi:[0,1]
	v_pk_add_f32 v[204:205], v[58:59], v[60:61] op_sel:[0,1] op_sel_hi:[1,0] neg_lo:[0,1]
	v_pk_mul_f32 v[206:207], v[210:211], v[210:211] op_sel:[1,1] op_sel_hi:[1,0]
	v_pk_fma_f32 v[212:213], v[210:211], v[210:211], v[206:207] op_sel_hi:[0,1,1] neg_lo:[0,0,1]
	v_pk_mul_f32 v[206:207], v[210:211], v[212:213] op_sel:[1,1] op_sel_hi:[1,0]
	v_pk_fma_f32 v[220:221], v[210:211], v[212:213], v[206:207] op_sel_hi:[0,1,1] neg_lo:[0,0,1]
	v_pk_mul_f32 v[58:59], v[210:211], v[202:203] op_sel:[1,1] op_sel_hi:[1,0]
	v_pk_fma_f32 v[58:59], v[210:211], v[202:203], v[58:59] op_sel_hi:[0,1,1] neg_lo:[0,0,1]
	v_pk_mul_f32 v[60:61], v[212:213], v[64:65] op_sel:[1,1] op_sel_hi:[1,0]
	v_pk_fma_f32 v[60:61], v[212:213], v[64:65], v[60:61] op_sel_hi:[0,1,1] neg_lo:[0,0,1]
	v_pk_mul_f32 v[64:65], v[220:221], v[204:205] op_sel:[1,1] op_sel_hi:[1,0]
	v_pk_fma_f32 v[64:65], v[220:221], v[204:205], v[64:65] op_sel_hi:[0,1,1] neg_lo:[0,0,1]
	s_barrier
	v_mul_f32_e32 v214, 4.0, v201
	v_cos_f32_e32 v224, v214
	v_sin_f32_e64 v225, -v214
	s_nop 0
	v_pk_mul_f32 v[206:207], v[224:225], v[224:225] op_sel:[1,1] op_sel_hi:[1,0]
	v_pk_fma_f32 v[226:227], v[224:225], v[224:225], v[206:207] op_sel_hi:[0,1,1] neg_lo:[0,0,1]
	v_pk_mul_f32 v[206:207], v[224:225], v[226:227] op_sel:[1,1] op_sel_hi:[1,0]
	v_pk_fma_f32 v[230:231], v[224:225], v[226:227], v[206:207] op_sel_hi:[0,1,1] neg_lo:[0,0,1]
	v_pk_add_f32 v[202:203], v[6:7], v[38:39]
	v_pk_add_f32 v[6:7], v[6:7], v[38:39] neg_lo:[0,1] neg_hi:[0,1]
	v_pk_add_f32 v[204:205], v[22:23], v[54:55]
	v_pk_add_f32 v[22:23], v[22:23], v[54:55] neg_lo:[0,1] neg_hi:[0,1]
	v_pk_add_f32 v[38:39], v[202:203], v[204:205]
	v_pk_add_f32 v[54:55], v[202:203], v[204:205] neg_lo:[0,1] neg_hi:[0,1]
	v_pk_add_f32 v[202:203], v[6:7], v[22:23] op_sel:[0,1] op_sel_hi:[1,0] neg_hi:[0,1]
	v_pk_add_f32 v[204:205], v[6:7], v[22:23] op_sel:[0,1] op_sel_hi:[1,0] neg_lo:[0,1]
	v_pk_mul_f32 v[6:7], v[224:225], v[202:203] op_sel:[1,1] op_sel_hi:[1,0]
	v_pk_fma_f32 v[6:7], v[224:225], v[202:203], v[6:7] op_sel_hi:[0,1,1] neg_lo:[0,0,1]
	v_pk_mul_f32 v[22:23], v[226:227], v[54:55] op_sel:[1,1] op_sel_hi:[1,0]
	v_pk_fma_f32 v[22:23], v[226:227], v[54:55], v[22:23] op_sel_hi:[0,1,1] neg_lo:[0,0,1]
	v_pk_mul_f32 v[54:55], v[230:231], v[204:205] op_sel:[1,1] op_sel_hi:[1,0]
	v_pk_fma_f32 v[54:55], v[230:231], v[204:205], v[54:55] op_sel_hi:[0,1,1] neg_lo:[0,0,1]
	v_pk_add_f32 v[202:203], v[2:3], v[34:35]
	v_pk_add_f32 v[2:3], v[2:3], v[34:35] neg_lo:[0,1] neg_hi:[0,1]
	v_pk_add_f32 v[204:205], v[18:19], v[50:51]
	v_pk_add_f32 v[18:19], v[18:19], v[50:51] neg_lo:[0,1] neg_hi:[0,1]
	v_pk_add_f32 v[34:35], v[202:203], v[204:205]
	v_pk_add_f32 v[50:51], v[202:203], v[204:205] neg_lo:[0,1] neg_hi:[0,1]
	v_pk_add_f32 v[202:203], v[2:3], v[18:19] op_sel:[0,1] op_sel_hi:[1,0] neg_hi:[0,1]
	v_pk_add_f32 v[204:205], v[2:3], v[18:19] op_sel:[0,1] op_sel_hi:[1,0] neg_lo:[0,1]
	v_pk_mul_f32 v[2:3], v[224:225], v[202:203] op_sel:[1,1] op_sel_hi:[1,0]
	v_pk_fma_f32 v[2:3], v[224:225], v[202:203], v[2:3] op_sel_hi:[0,1,1] neg_lo:[0,0,1]
	v_pk_mul_f32 v[18:19], v[226:227], v[50:51] op_sel:[1,1] op_sel_hi:[1,0]
	v_pk_fma_f32 v[18:19], v[226:227], v[50:51], v[18:19] op_sel_hi:[0,1,1] neg_lo:[0,0,1]
	v_pk_mul_f32 v[50:51], v[230:231], v[204:205] op_sel:[1,1] op_sel_hi:[1,0]
	v_pk_fma_f32 v[50:51], v[230:231], v[204:205], v[50:51] op_sel_hi:[0,1,1] neg_lo:[0,0,1]
	v_pk_add_f32 v[202:203], v[4:5], v[36:37]
	v_pk_add_f32 v[4:5], v[4:5], v[36:37] neg_lo:[0,1] neg_hi:[0,1]
	v_pk_add_f32 v[204:205], v[20:21], v[52:53]
	v_pk_add_f32 v[20:21], v[20:21], v[52:53] neg_lo:[0,1] neg_hi:[0,1]
	v_pk_add_f32 v[36:37], v[202:203], v[204:205]
	v_pk_add_f32 v[52:53], v[202:203], v[204:205] neg_lo:[0,1] neg_hi:[0,1]
	v_pk_add_f32 v[202:203], v[4:5], v[20:21] op_sel:[0,1] op_sel_hi:[1,0] neg_hi:[0,1]
	v_pk_add_f32 v[204:205], v[4:5], v[20:21] op_sel:[0,1] op_sel_hi:[1,0] neg_lo:[0,1]
	v_pk_mul_f32 v[4:5], v[224:225], v[202:203] op_sel:[1,1] op_sel_hi:[1,0]
	v_pk_fma_f32 v[4:5], v[224:225], v[202:203], v[4:5] op_sel_hi:[0,1,1] neg_lo:[0,0,1]
	v_pk_mul_f32 v[20:21], v[226:227], v[52:53] op_sel:[1,1] op_sel_hi:[1,0]
	v_pk_fma_f32 v[20:21], v[226:227], v[52:53], v[20:21] op_sel_hi:[0,1,1] neg_lo:[0,0,1]
	v_pk_mul_f32 v[52:53], v[230:231], v[204:205] op_sel:[1,1] op_sel_hi:[1,0]
	v_pk_fma_f32 v[52:53], v[230:231], v[204:205], v[52:53] op_sel_hi:[0,1,1] neg_lo:[0,0,1]
	v_pk_add_f32 v[202:203], v[8:9], v[40:41]
	v_pk_add_f32 v[8:9], v[8:9], v[40:41] neg_lo:[0,1] neg_hi:[0,1]
	v_pk_add_f32 v[204:205], v[24:25], v[56:57]
	v_pk_add_f32 v[24:25], v[24:25], v[56:57] neg_lo:[0,1] neg_hi:[0,1]
	v_pk_add_f32 v[40:41], v[202:203], v[204:205]
	v_pk_add_f32 v[56:57], v[202:203], v[204:205] neg_lo:[0,1] neg_hi:[0,1]
	v_pk_add_f32 v[202:203], v[8:9], v[24:25] op_sel:[0,1] op_sel_hi:[1,0] neg_hi:[0,1]
	v_pk_add_f32 v[204:205], v[8:9], v[24:25] op_sel:[0,1] op_sel_hi:[1,0] neg_lo:[0,1]
	v_pk_mul_f32 v[8:9], v[224:225], v[202:203] op_sel:[1,1] op_sel_hi:[1,0]
	v_pk_fma_f32 v[8:9], v[224:225], v[202:203], v[8:9] op_sel_hi:[0,1,1] neg_lo:[0,0,1]
	v_pk_mul_f32 v[24:25], v[226:227], v[56:57] op_sel:[1,1] op_sel_hi:[1,0]
	v_pk_fma_f32 v[24:25], v[226:227], v[56:57], v[24:25] op_sel_hi:[0,1,1] neg_lo:[0,0,1]
; DI f32x2 cmul(f32x2 a, f32x2 b) { return mkf2(a.x * b.x - a.y * b.y, a.x * b.y + a.y * b.x); }
; DI void fft8192(f32x2* buf, const f32x2* __restrict__ tw) {
;     ...
; #pragma unroll
;     for (int e = 0; e < 8; ++e) {
;       const int i = tid + 256 * e;
;       const int q = i & (s - 1);
;       const int ps = i - q;
;       const float rev = (float)ps * (1.f / 8192.f);
;       const f32x2 w1 = mkf2(__builtin_amdgcn_cosf(rev), -__builtin_amdgcn_sinf(rev));
;       const f32x2 w2 = cmul(w1, w1), w3 = cmul(w1, w2);
;       const f32x2 apc = mkf2(a[e].x + c[e].x, a[e].y + c[e].y), amc = mkf2(a[e].x - c[e].x, a[e].y - c[e].y);
;       const f32x2 bpd = mkf2(b[e].x + d[e].x, b[e].y + d[e].y), bmd = mkf2(b[e].x - d[e].x, b[e].y - d[e].y);
;       const int o = 4 * i - 3 * q;
;       buf[SW(o)] = mkf2(apc.x + bpd.x, apc.y + bpd.y);
;       buf[SW(o + s)] = cmul(w1, mkf2(amc.x + bmd.y, amc.y - bmd.x));
;       buf[SW(o + 2 * s)] = cmul(w2, mkf2(apc.x - bpd.x, apc.y - bpd.y));
;       buf[SW(o + 3 * s)] = cmul(w3, mkf2(amc.x - bmd.y, amc.y + bmd.x));
;     }
	v_pk_mul_f32 v[56:57], v[230:231], v[204:205] op_sel:[1,1] op_sel_hi:[1,0]
	v_pk_fma_f32 v[56:57], v[230:231], v[204:205], v[56:57] op_sel_hi:[0,1,1] neg_lo:[0,0,1]
	v_mul_f32_e32 v214, 4.0, v201
	v_add_f32_e32 v214, 0x3e000000, v214
	v_cos_f32_e32 v224, v214
	v_sin_f32_e64 v225, -v214
	s_nop 0
	v_pk_mul_f32 v[206:207], v[224:225], v[224:225] op_sel:[1,1] op_sel_hi:[1,0]
	v_pk_fma_f32 v[226:227], v[224:225], v[224:225], v[206:207] op_sel_hi:[0,1,1] neg_lo:[0,0,1]
	v_pk_mul_f32 v[206:207], v[224:225], v[226:227] op_sel:[1,1] op_sel_hi:[1,0]
	v_pk_fma_f32 v[230:231], v[224:225], v[226:227], v[206:207] op_sel_hi:[0,1,1] neg_lo:[0,0,1]
	v_pk_add_f32 v[202:203], v[14:15], v[46:47]
	v_pk_add_f32 v[14:15], v[14:15], v[46:47] neg_lo:[0,1] neg_hi:[0,1]
	v_pk_add_f32 v[204:205], v[30:31], v[62:63]
	v_pk_add_f32 v[30:31], v[30:31], v[62:63] neg_lo:[0,1] neg_hi:[0,1]
	v_pk_add_f32 v[46:47], v[202:203], v[204:205]
	v_pk_add_f32 v[62:63], v[202:203], v[204:205] neg_lo:[0,1] neg_hi:[0,1]
	v_pk_add_f32 v[202:203], v[14:15], v[30:31] op_sel:[0,1] op_sel_hi:[1,0] neg_hi:[0,1]
	v_pk_add_f32 v[204:205], v[14:15], v[30:31] op_sel:[0,1] op_sel_hi:[1,0] neg_lo:[0,1]
	v_pk_mul_f32 v[14:15], v[224:225], v[202:203] op_sel:[1,1] op_sel_hi:[1,0]
	v_pk_fma_f32 v[14:15], v[224:225], v[202:203], v[14:15] op_sel_hi:[0,1,1] neg_lo:[0,0,1]
	v_pk_mul_f32 v[30:31], v[226:227], v[62:63] op_sel:[1,1] op_sel_hi:[1,0]
	v_pk_fma_f32 v[30:31], v[226:227], v[62:63], v[30:31] op_sel_hi:[0,1,1] neg_lo:[0,0,1]
	v_pk_mul_f32 v[62:63], v[230:231], v[204:205] op_sel:[1,1] op_sel_hi:[1,0]
	v_pk_fma_f32 v[62:63], v[230:231], v[204:205], v[62:63] op_sel_hi:[0,1,1] neg_lo:[0,0,1]
	v_pk_add_f32 v[202:203], v[10:11], v[42:43]
	v_pk_add_f32 v[10:11], v[10:11], v[42:43] neg_lo:[0,1] neg_hi:[0,1]
	v_pk_add_f32 v[204:205], v[26:27], v[58:59]
	v_pk_add_f32 v[26:27], v[26:27], v[58:59] neg_lo:[0,1] neg_hi:[0,1]
	v_pk_add_f32 v[42:43], v[202:203], v[204:205]
	v_pk_add_f32 v[58:59], v[202:203], v[204:205] neg_lo:[0,1] neg_hi:[0,1]
	v_pk_add_f32 v[202:203], v[10:11], v[26:27] op_sel:[0,1] op_sel_hi:[1,0] neg_hi:[0,1]
	v_pk_add_f32 v[204:205], v[10:11], v[26:27] op_sel:[0,1] op_sel_hi:[1,0] neg_lo:[0,1]
	v_pk_mul_f32 v[10:11], v[224:225], v[202:203] op_sel:[1,1] op_sel_hi:[1,0]
	v_pk_fma_f32 v[10:11], v[224:225], v[202:203], v[10:11] op_sel_hi:[0,1,1] neg_lo:[0,0,1]
	v_pk_mul_f32 v[26:27], v[226:227], v[58:59] op_sel:[1,1] op_sel_hi:[1,0]
	v_pk_fma_f32 v[26:27], v[226:227], v[58:59], v[26:27] op_sel_hi:[0,1,1] neg_lo:[0,0,1]
	v_pk_mul_f32 v[58:59], v[230:231], v[204:205] op_sel:[1,1] op_sel_hi:[1,0]
	v_pk_fma_f32 v[58:59], v[230:231], v[204:205], v[58:59] op_sel_hi:[0,1,1] neg_lo:[0,0,1]
	v_pk_add_f32 v[202:203], v[12:13], v[44:45]
	v_pk_add_f32 v[12:13], v[12:13], v[44:45] neg_lo:[0,1] neg_hi:[0,1]
	v_pk_add_f32 v[204:205], v[28:29], v[60:61]
	v_pk_add_f32 v[28:29], v[28:29], v[60:61] neg_lo:[0,1] neg_hi:[0,1]
	v_pk_add_f32 v[44:45], v[202:203], v[204:205]
	v_pk_add_f32 v[60:61], v[202:203], v[204:205] neg_lo:[0,1] neg_hi:[0,1]
	v_pk_add_f32 v[202:203], v[12:13], v[28:29] op_sel:[0,1] op_sel_hi:[1,0] neg_hi:[0,1]
	v_pk_add_f32 v[204:205], v[12:13], v[28:29] op_sel:[0,1] op_sel_hi:[1,0] neg_lo:[0,1]
	v_pk_mul_f32 v[12:13], v[224:225], v[202:203] op_sel:[1,1] op_sel_hi:[1,0]
	v_pk_fma_f32 v[12:13], v[224:225], v[202:203], v[12:13] op_sel_hi:[0,1,1] neg_lo:[0,0,1]
	v_pk_mul_f32 v[28:29], v[226:227], v[60:61] op_sel:[1,1] op_sel_hi:[1,0]
	v_pk_fma_f32 v[28:29], v[226:227], v[60:61], v[28:29] op_sel_hi:[0,1,1] neg_lo:[0,0,1]
	v_pk_mul_f32 v[60:61], v[230:231], v[204:205] op_sel:[1,1] op_sel_hi:[1,0]
	v_pk_fma_f32 v[60:61], v[230:231], v[204:205], v[60:61] op_sel_hi:[0,1,1] neg_lo:[0,0,1]
	v_pk_add_f32 v[202:203], v[16:17], v[48:49]
	v_pk_add_f32 v[16:17], v[16:17], v[48:49] neg_lo:[0,1] neg_hi:[0,1]
	v_pk_add_f32 v[204:205], v[32:33], v[64:65]
	v_pk_add_f32 v[32:33], v[32:33], v[64:65] neg_lo:[0,1] neg_hi:[0,1]
	v_pk_add_f32 v[48:49], v[202:203], v[204:205]
	v_pk_add_f32 v[64:65], v[202:203], v[204:205] neg_lo:[0,1] neg_hi:[0,1]
	v_pk_add_f32 v[202:203], v[16:17], v[32:33] op_sel:[0,1] op_sel_hi:[1,0] neg_hi:[0,1]
	v_pk_add_f32 v[204:205], v[16:17], v[32:33] op_sel:[0,1] op_sel_hi:[1,0] neg_lo:[0,1]
	v_pk_mul_f32 v[16:17], v[224:225], v[202:203] op_sel:[1,1] op_sel_hi:[1,0]
	v_pk_fma_f32 v[16:17], v[224:225], v[202:203], v[16:17] op_sel_hi:[0,1,1] neg_lo:[0,0,1]
	v_pk_mul_f32 v[32:33], v[226:227], v[64:65] op_sel:[1,1] op_sel_hi:[1,0]
	v_pk_fma_f32 v[32:33], v[226:227], v[64:65], v[32:33] op_sel_hi:[0,1,1] neg_lo:[0,0,1]
	v_pk_mul_f32 v[64:65], v[230:231], v[204:205] op_sel:[1,1] op_sel_hi:[1,0]
	v_pk_fma_f32 v[64:65], v[230:231], v[204:205], v[64:65] op_sel_hi:[0,1,1] neg_lo:[0,0,1]
	ds_write_b64 v164, v[38:39] offset:0
	v_xor_b32_e32 v156, 0x80, v164
	ds_write_b64 v156, v[34:35] offset:0
	v_xor_b32_e32 v158, 0x128, v164
	ds_write_b64 v158, v[36:37] offset:0
	v_xor_b32_e32 v160, 0x1a8, v164
	ds_write_b64 v160, v[40:41] offset:0
	v_xor_b32_e32 v162, 0x2d0, v164
	ds_write_b64 v162, v[6:7] offset:0
	v_xor_b32_e32 v156, 0x250, v164
	ds_write_b64 v156, v[2:3] offset:0
	v_xor_b32_e32 v158, 0x3f8, v164
	ds_write_b64 v158, v[4:5] offset:0
	v_xor_b32_e32 v160, 0x378, v164
	ds_write_b64 v160, v[8:9] offset:0
	v_xor_b32_e32 v162, 0x400, v164
	ds_write_b64 v162, v[22:23] offset:0
	v_xor_b32_e32 v156, 0x480, v164
	ds_write_b64 v156, v[18:19] offset:0
	v_xor_b32_e32 v158, 0x528, v164
	ds_write_b64 v158, v[20:21] offset:0
	v_xor_b32_e32 v160, 0x5a8, v164
	ds_write_b64 v160, v[24:25] offset:0
	v_xor_b32_e32 v162, 0x6d0, v164
	ds_write_b64 v162, v[54:55] offset:0
	v_xor_b32_e32 v156, 0x650, v164
	ds_write_b64 v156, v[50:51] offset:0
	v_xor_b32_e32 v158, 0x7f8, v164
	ds_write_b64 v158, v[52:53] offset:0
	v_xor_b32_e32 v160, 0x778, v164
	ds_write_b64 v160, v[56:57] offset:0
	ds_write_b64 v164, v[46:47] offset:32768
	v_xor_b32_e32 v162, 0x80, v164
	ds_write_b64 v162, v[42:43] offset:32768
	v_xor_b32_e32 v156, 0x128, v164
	ds_write_b64 v156, v[44:45] offset:32768
	v_xor_b32_e32 v158, 0x1a8, v164
	ds_write_b64 v158, v[48:49] offset:32768
	v_xor_b32_e32 v160, 0x2d0, v164
	ds_write_b64 v160, v[14:15] offset:32768
	v_xor_b32_e32 v162, 0x250, v164
	ds_write_b64 v162, v[10:11] offset:32768
	v_xor_b32_e32 v156, 0x3f8, v164
	ds_write_b64 v156, v[12:13] offset:32768
	v_xor_b32_e32 v158, 0x378, v164
	ds_write_b64 v158, v[16:17] offset:32768
	v_xor_b32_e32 v160, 0x400, v164
	ds_write_b64 v160, v[30:31] offset:32768
	v_xor_b32_e32 v162, 0x480, v164
	ds_write_b64 v162, v[26:27] offset:32768
	v_xor_b32_e32 v156, 0x528, v164
	ds_write_b64 v156, v[28:29] offset:32768
	v_xor_b32_e32 v158, 0x5a8, v164
	ds_write_b64 v158, v[32:33] offset:32768
	v_xor_b32_e32 v160, 0x6d0, v164
	ds_write_b64 v160, v[62:63] offset:32768
	v_xor_b32_e32 v162, 0x650, v164
	ds_write_b64 v162, v[58:59] offset:32768
	v_xor_b32_e32 v156, 0x7f8, v164
	ds_write_b64 v156, v[60:61] offset:32768
	v_xor_b32_e32 v158, 0x778, v164
	ds_write_b64 v158, v[64:65] offset:32768
	s_waitcnt lgkmcnt(0)
	s_barrier
; DI f32x2 cmul(f32x2 a, f32x2 b) { return mkf2(a.x * b.x - a.y * b.y, a.x * b.y + a.y * b.x); }
; DI void fft8192(f32x2* buf, const f32x2* __restrict__ tw) {
;     ...
;     __syncthreads();
; #pragma unroll
;     for (int e = 0; e < 8; ++e) {
;       const int i = tid + 256 * e;
;       const int pi = SW(i);
;       a[e] = buf[pi]; b[e] = buf[pi + 2048]; c[e] = buf[pi + 4096]; d[e] = buf[pi + 6144];
;     }
;     __syncthreads();
; #pragma unroll
;     for (int e = 0; e < 8; ++e) {
;       const int i = tid + 256 * e;
;       const int q = i & (s - 1);
;       const int ps = i - q;
;       const float rev = (float)ps * (1.f / 8192.f);
;       const f32x2 w1 = mkf2(__builtin_amdgcn_cosf(rev), -__builtin_amdgcn_sinf(rev));
;       const f32x2 w2 = cmul(w1, w1), w3 = cmul(w1, w2);
;       const f32x2 apc = mkf2(a[e].x + c[e].x, a[e].y + c[e].y), amc = mkf2(a[e].x - c[e].x, a[e].y - c[e].y);
;       const f32x2 bpd = mkf2(b[e].x + d[e].x, b[e].y + d[e].y), bmd = mkf2(b[e].x - d[e].x, b[e].y - d[e].y);
;       const int o = 4 * i - 3 * q;
;       buf[SW(o)] = mkf2(apc.x + bpd.x, apc.y + bpd.y);
;       buf[SW(o + s)] = cmul(w1, mkf2(amc.x + bmd.y, amc.y - bmd.x));
;       buf[SW(o + 2 * s)] = cmul(w2, mkf2(apc.x - bpd.x, apc.y - bpd.y));
;       buf[SW(o + 3 * s)] = cmul(w3, mkf2(amc.x - bmd.y, amc.y + bmd.x));
;     }
	ds_read2st64_b64 v[2:5], v154 offset0:0 offset1:32
	ds_read2st64_b64 v[6:9], v154 offset0:64 offset1:96
	ds_read2st64_b64 v[10:13], v154 offset0:4 offset1:36
	ds_read2st64_b64 v[14:17], v154 offset0:68 offset1:100
	ds_read2st64_b64 v[18:21], v154 offset0:8 offset1:40
	ds_read2st64_b64 v[22:25], v154 offset0:72 offset1:104
	ds_read2st64_b64 v[26:29], v154 offset0:12 offset1:44
	ds_read2st64_b64 v[30:33], v154 offset0:76 offset1:108
	ds_read2st64_b64 v[34:37], v154 offset0:16 offset1:48
	ds_read2st64_b64 v[38:41], v154 offset0:80 offset1:112
	ds_read2st64_b64 v[42:45], v154 offset0:20 offset1:52
	ds_read2st64_b64 v[46:49], v154 offset0:84 offset1:116
	ds_read2st64_b64 v[50:53], v154 offset0:24 offset1:56
	ds_read2st64_b64 v[54:57], v154 offset0:88 offset1:120
	ds_read2st64_b64 v[58:61], v154 offset0:28 offset1:60
	ds_read2st64_b64 v[62:65], v154 offset0:92 offset1:124
	s_waitcnt lgkmcnt(14)
	v_pk_add_f32 v[202:203], v[2:3], v[6:7]
	v_pk_add_f32 v[2:3], v[2:3], v[6:7] neg_lo:[0,1] neg_hi:[0,1]
	v_pk_add_f32 v[204:205], v[4:5], v[8:9]
	v_pk_add_f32 v[4:5], v[4:5], v[8:9] neg_lo:[0,1] neg_hi:[0,1]
	v_pk_add_f32 v[6:7], v[202:203], v[204:205]
	v_pk_add_f32 v[8:9], v[202:203], v[204:205] neg_lo:[0,1] neg_hi:[0,1]
	v_pk_add_f32 v[202:203], v[2:3], v[4:5] op_sel:[0,1] op_sel_hi:[1,0] neg_hi:[0,1]
	v_pk_add_f32 v[4:5], v[2:3], v[4:5] op_sel:[0,1] op_sel_hi:[1,0] neg_lo:[0,1]
	v_pk_mov_b32 v[2:3], v[202:203], v[202:203] op_sel:[0,1]
	v_mov_b32_e32 v210, 0x3f7b14be
	v_mov_b32_e32 v211, 0xbe47c5c2
	v_mov_b32_e32 v212, 0x3f6c835e
	v_mov_b32_e32 v213, 0xbec3ef15
	v_mov_b32_e32 v220, 0x3f54db31
	v_mov_b32_e32 v221, 0xbf0e39da
	s_waitcnt lgkmcnt(12)
	v_pk_add_f32 v[202:203], v[10:11], v[14:15]
	v_pk_add_f32 v[10:11], v[10:11], v[14:15] neg_lo:[0,1] neg_hi:[0,1]
	v_pk_add_f32 v[204:205], v[12:13], v[16:17]
	v_pk_add_f32 v[12:13], v[12:13], v[16:17] neg_lo:[0,1] neg_hi:[0,1]
	v_pk_add_f32 v[14:15], v[202:203], v[204:205]
	v_pk_add_f32 v[16:17], v[202:203], v[204:205] neg_lo:[0,1] neg_hi:[0,1]
	v_pk_add_f32 v[202:203], v[10:11], v[12:13] op_sel:[0,1] op_sel_hi:[1,0] neg_hi:[0,1]
	v_pk_add_f32 v[204:205], v[10:11], v[12:13] op_sel:[0,1] op_sel_hi:[1,0] neg_lo:[0,1]
	v_pk_mul_f32 v[10:11], v[210:211], v[202:203] op_sel:[1,1] op_sel_hi:[1,0]
	v_pk_fma_f32 v[10:11], v[210:211], v[202:203], v[10:11] op_sel_hi:[0,1,1] neg_lo:[0,0,1]
	v_pk_mul_f32 v[12:13], v[212:213], v[16:17] op_sel:[1,1] op_sel_hi:[1,0]
	v_pk_fma_f32 v[12:13], v[212:213], v[16:17], v[12:13] op_sel_hi:[0,1,1] neg_lo:[0,0,1]
	v_pk_mul_f32 v[16:17], v[220:221], v[204:205] op_sel:[1,1] op_sel_hi:[1,0]
	v_pk_fma_f32 v[16:17], v[220:221], v[204:205], v[16:17] op_sel_hi:[0,1,1] neg_lo:[0,0,1]
	v_mov_b32_e32 v210, 0x3f6c835e
	v_mov_b32_e32 v211, 0xbec3ef15
	v_mov_b32_e32 v212, 0x3f3504f3
	v_mov_b32_e32 v213, 0xbf3504f3
	v_mov_b32_e32 v220, 0x3ec3ef15
	v_mov_b32_e32 v221, 0xbf6c835e
	s_waitcnt lgkmcnt(10)
	v_pk_add_f32 v[202:203], v[18:19], v[22:23]
	v_pk_add_f32 v[18:19], v[18:19], v[22:23] neg_lo:[0,1] neg_hi:[0,1]
	v_pk_add_f32 v[204:205], v[20:21], v[24:25]
	v_pk_add_f32 v[20:21], v[20:21], v[24:25] neg_lo:[0,1] neg_hi:[0,1]
	v_pk_add_f32 v[22:23], v[202:203], v[204:205]
	v_pk_add_f32 v[24:25], v[202:203], v[204:205] neg_lo:[0,1] neg_hi:[0,1]
	v_pk_add_f32 v[202:203], v[18:19], v[20:21] op_sel:[0,1] op_sel_hi:[1,0] neg_hi:[0,1]
	v_pk_add_f32 v[204:205], v[18:19], v[20:21] op_sel:[0,1] op_sel_hi:[1,0] neg_lo:[0,1]
	v_pk_mul_f32 v[18:19], v[210:211], v[202:203] op_sel:[1,1] op_sel_hi:[1,0]
	v_pk_fma_f32 v[18:19], v[210:211], v[202:203], v[18:19] op_sel_hi:[0,1,1] neg_lo:[0,0,1]
	v_pk_mul_f32 v[20:21], v[212:213], v[24:25] op_sel:[1,1] op_sel_hi:[1,0]
	v_pk_fma_f32 v[20:21], v[212:213], v[24:25], v[20:21] op_sel_hi:[0,1,1] neg_lo:[0,0,1]
	v_pk_mul_f32 v[24:25], v[220:221], v[204:205] op_sel:[1,1] op_sel_hi:[1,0]
	v_pk_fma_f32 v[24:25], v[220:221], v[204:205], v[24:25] op_sel_hi:[0,1,1] neg_lo:[0,0,1]
	v_mov_b32_e32 v210, 0x3f54db31
	v_mov_b32_e32 v211, 0xbf0e39da
	v_mov_b32_e32 v212, 0x3ec3ef15
	v_mov_b32_e32 v213, 0xbf6c835e
	v_mov_b32_e32 v220, 0xbe47c5c2
	v_mov_b32_e32 v221, 0xbf7b14be
	s_waitcnt lgkmcnt(8)
	v_pk_add_f32 v[202:203], v[26:27], v[30:31]
	v_pk_add_f32 v[26:27], v[26:27], v[30:31] neg_lo:[0,1] neg_hi:[0,1]
	v_pk_add_f32 v[204:205], v[28:29], v[32:33]
	v_pk_add_f32 v[28:29], v[28:29], v[32:33] neg_lo:[0,1] neg_hi:[0,1]
	v_pk_add_f32 v[30:31], v[202:203], v[204:205]
	v_pk_add_f32 v[32:33], v[202:203], v[204:205] neg_lo:[0,1] neg_hi:[0,1]
	v_pk_add_f32 v[202:203], v[26:27], v[28:29] op_sel:[0,1] op_sel_hi:[1,0] neg_hi:[0,1]
	v_pk_add_f32 v[204:205], v[26:27], v[28:29] op_sel:[0,1] op_sel_hi:[1,0] neg_lo:[0,1]
	v_pk_mul_f32 v[26:27], v[210:211], v[202:203] op_sel:[1,1] op_sel_hi:[1,0]
	v_pk_fma_f32 v[26:27], v[210:211], v[202:203], v[26:27] op_sel_hi:[0,1,1] neg_lo:[0,0,1]
	v_pk_mul_f32 v[28:29], v[212:213], v[32:33] op_sel:[1,1] op_sel_hi:[1,0]
	v_pk_fma_f32 v[28:29], v[212:213], v[32:33], v[28:29] op_sel_hi:[0,1,1] neg_lo:[0,0,1]
	v_pk_mul_f32 v[32:33], v[220:221], v[204:205] op_sel:[1,1] op_sel_hi:[1,0]
	v_pk_fma_f32 v[32:33], v[220:221], v[204:205], v[32:33] op_sel_hi:[0,1,1] neg_lo:[0,0,1]
	v_mov_b32_e32 v210, 0x3f3504f3
	v_mov_b32_e32 v211, 0xbf3504f3
	v_mov_b32_e32 v212, 0x248d3132
	v_mov_b32_e32 v213, 0xbf800000
	v_mov_b32_e32 v220, 0xbf3504f3
	v_mov_b32_e32 v221, 0xbf3504f3
	s_waitcnt lgkmcnt(6)
; DI f32x2 cmul(f32x2 a, f32x2 b) { return mkf2(a.x * b.x - a.y * b.y, a.x * b.y + a.y * b.x); }
; DI void fft8192(f32x2* buf, const f32x2* __restrict__ tw) {
;     ...
; #pragma unroll
;     for (int e = 0; e < 8; ++e) {
;       const int i = tid + 256 * e;
;       const int q = i & (s - 1);
;       const int ps = i - q;
;       const float rev = (float)ps * (1.f / 8192.f);
;       const f32x2 w1 = mkf2(__builtin_amdgcn_cosf(rev), -__builtin_amdgcn_sinf(rev));
;       const f32x2 w2 = cmul(w1, w1), w3 = cmul(w1, w2);
;       const f32x2 apc = mkf2(a[e].x + c[e].x, a[e].y + c[e].y), amc = mkf2(a[e].x - c[e].x, a[e].y - c[e].y);
;       const f32x2 bpd = mkf2(b[e].x + d[e].x, b[e].y + d[e].y), bmd = mkf2(b[e].x - d[e].x, b[e].y - d[e].y);
;       const int o = 4 * i - 3 * q;
;       buf[SW(o)] = mkf2(apc.x + bpd.x, apc.y + bpd.y);
;       buf[SW(o + s)] = cmul(w1, mkf2(amc.x + bmd.y, amc.y - bmd.x));
;       buf[SW(o + 2 * s)] = cmul(w2, mkf2(apc.x - bpd.x, apc.y - bpd.y));
;       buf[SW(o + 3 * s)] = cmul(w3, mkf2(amc.x - bmd.y, amc.y + bmd.x));
;     }
	v_pk_add_f32 v[202:203], v[34:35], v[38:39]
	v_pk_add_f32 v[34:35], v[34:35], v[38:39] neg_lo:[0,1] neg_hi:[0,1]
	v_pk_add_f32 v[204:205], v[36:37], v[40:41]
	v_pk_add_f32 v[36:37], v[36:37], v[40:41] neg_lo:[0,1] neg_hi:[0,1]
	v_pk_add_f32 v[38:39], v[202:203], v[204:205]
	v_pk_add_f32 v[40:41], v[202:203], v[204:205] neg_lo:[0,1] neg_hi:[0,1]
	v_pk_add_f32 v[202:203], v[34:35], v[36:37] op_sel:[0,1] op_sel_hi:[1,0] neg_hi:[0,1]
	v_pk_add_f32 v[204:205], v[34:35], v[36:37] op_sel:[0,1] op_sel_hi:[1,0] neg_lo:[0,1]
	v_pk_mul_f32 v[34:35], v[210:211], v[202:203] op_sel:[1,1] op_sel_hi:[1,0]
	v_pk_fma_f32 v[34:35], v[210:211], v[202:203], v[34:35] op_sel_hi:[0,1,1] neg_lo:[0,0,1]
	v_pk_mul_f32 v[36:37], v[212:213], v[40:41] op_sel:[1,1] op_sel_hi:[1,0]
	v_pk_fma_f32 v[36:37], v[212:213], v[40:41], v[36:37] op_sel_hi:[0,1,1] neg_lo:[0,0,1]
	v_pk_mul_f32 v[40:41], v[220:221], v[204:205] op_sel:[1,1] op_sel_hi:[1,0]
	v_pk_fma_f32 v[40:41], v[220:221], v[204:205], v[40:41] op_sel_hi:[0,1,1] neg_lo:[0,0,1]
	v_mov_b32_e32 v210, 0x3f0e39da
	v_mov_b32_e32 v211, 0xbf54db31
	v_mov_b32_e32 v212, 0xbec3ef15
	v_mov_b32_e32 v213, 0xbf6c835e
	v_mov_b32_e32 v220, 0xbf7b14be
	v_mov_b32_e32 v221, 0xbe47c5c2
	s_waitcnt lgkmcnt(4)
	v_pk_add_f32 v[202:203], v[42:43], v[46:47]
	v_pk_add_f32 v[42:43], v[42:43], v[46:47] neg_lo:[0,1] neg_hi:[0,1]
	v_pk_add_f32 v[204:205], v[44:45], v[48:49]
	v_pk_add_f32 v[44:45], v[44:45], v[48:49] neg_lo:[0,1] neg_hi:[0,1]
	v_pk_add_f32 v[46:47], v[202:203], v[204:205]
	v_pk_add_f32 v[48:49], v[202:203], v[204:205] neg_lo:[0,1] neg_hi:[0,1]
	v_pk_add_f32 v[202:203], v[42:43], v[44:45] op_sel:[0,1] op_sel_hi:[1,0] neg_hi:[0,1]
	v_pk_add_f32 v[204:205], v[42:43], v[44:45] op_sel:[0,1] op_sel_hi:[1,0] neg_lo:[0,1]
	v_pk_mul_f32 v[42:43], v[210:211], v[202:203] op_sel:[1,1] op_sel_hi:[1,0]
	v_pk_fma_f32 v[42:43], v[210:211], v[202:203], v[42:43] op_sel_hi:[0,1,1] neg_lo:[0,0,1]
	v_pk_mul_f32 v[44:45], v[212:213], v[48:49] op_sel:[1,1] op_sel_hi:[1,0]
	v_pk_fma_f32 v[44:45], v[212:213], v[48:49], v[44:45] op_sel_hi:[0,1,1] neg_lo:[0,0,1]
	v_pk_mul_f32 v[48:49], v[220:221], v[204:205] op_sel:[1,1] op_sel_hi:[1,0]
	v_pk_fma_f32 v[48:49], v[220:221], v[204:205], v[48:49] op_sel_hi:[0,1,1] neg_lo:[0,0,1]
	v_mov_b32_e32 v210, 0x3ec3ef15
	v_mov_b32_e32 v211, 0xbf6c835e
	v_mov_b32_e32 v212, 0xbf3504f3
	v_mov_b32_e32 v213, 0xbf3504f3
	v_mov_b32_e32 v220, 0xbf6c835e
	v_mov_b32_e32 v221, 0x3ec3ef15
	s_waitcnt lgkmcnt(2)
	v_pk_add_f32 v[202:203], v[50:51], v[54:55]
	v_pk_add_f32 v[50:51], v[50:51], v[54:55] neg_lo:[0,1] neg_hi:[0,1]
	v_pk_add_f32 v[204:205], v[52:53], v[56:57]
	v_pk_add_f32 v[52:53], v[52:53], v[56:57] neg_lo:[0,1] neg_hi:[0,1]
	v_pk_add_f32 v[54:55], v[202:203], v[204:205]
	v_pk_add_f32 v[56:57], v[202:203], v[204:205] neg_lo:[0,1] neg_hi:[0,1]
	v_pk_add_f32 v[202:203], v[50:51], v[52:53] op_sel:[0,1] op_sel_hi:[1,0] neg_hi:[0,1]
	v_pk_add_f32 v[204:205], v[50:51], v[52:53] op_sel:[0,1] op_sel_hi:[1,0] neg_lo:[0,1]
	v_pk_mul_f32 v[50:51], v[210:211], v[202:203] op_sel:[1,1] op_sel_hi:[1,0]
	v_pk_fma_f32 v[50:51], v[210:211], v[202:203], v[50:51] op_sel_hi:[0,1,1] neg_lo:[0,0,1]
	v_pk_mul_f32 v[52:53], v[212:213], v[56:57] op_sel:[1,1] op_sel_hi:[1,0]
	v_pk_fma_f32 v[52:53], v[212:213], v[56:57], v[52:53] op_sel_hi:[0,1,1] neg_lo:[0,0,1]
	v_pk_mul_f32 v[56:57], v[220:221], v[204:205] op_sel:[1,1] op_sel_hi:[1,0]
	v_pk_fma_f32 v[56:57], v[220:221], v[204:205], v[56:57] op_sel_hi:[0,1,1] neg_lo:[0,0,1]
	v_mov_b32_e32 v210, 0x3e47c5c2
	v_mov_b32_e32 v211, 0xbf7b14be
	v_mov_b32_e32 v212, 0xbf6c835e
	v_mov_b32_e32 v213, 0xbec3ef15
	v_mov_b32_e32 v220, 0xbf0e39da
	v_mov_b32_e32 v221, 0x3f54db31
	s_waitcnt lgkmcnt(0)
	v_pk_add_f32 v[202:203], v[58:59], v[62:63]
	v_pk_add_f32 v[58:59], v[58:59], v[62:63] neg_lo:[0,1] neg_hi:[0,1]
	v_pk_add_f32 v[204:205], v[60:61], v[64:65]
	v_pk_add_f32 v[60:61], v[60:61], v[64:65] neg_lo:[0,1] neg_hi:[0,1]
	v_pk_add_f32 v[62:63], v[202:203], v[204:205]
	v_pk_add_f32 v[64:65], v[202:203], v[204:205] neg_lo:[0,1] neg_hi:[0,1]
	v_pk_add_f32 v[202:203], v[58:59], v[60:61] op_sel:[0,1] op_sel_hi:[1,0] neg_hi:[0,1]
	v_pk_add_f32 v[204:205], v[58:59], v[60:61] op_sel:[0,1] op_sel_hi:[1,0] neg_lo:[0,1]
	v_pk_mul_f32 v[58:59], v[210:211], v[202:203] op_sel:[1,1] op_sel_hi:[1,0]
	v_pk_fma_f32 v[58:59], v[210:211], v[202:203], v[58:59] op_sel_hi:[0,1,1] neg_lo:[0,0,1]
	v_pk_mul_f32 v[60:61], v[212:213], v[64:65] op_sel:[1,1] op_sel_hi:[1,0]
	v_pk_fma_f32 v[60:61], v[212:213], v[64:65], v[60:61] op_sel_hi:[0,1,1] neg_lo:[0,0,1]
	v_pk_mul_f32 v[64:65], v[220:221], v[204:205] op_sel:[1,1] op_sel_hi:[1,0]
	v_pk_fma_f32 v[64:65], v[220:221], v[204:205], v[64:65] op_sel_hi:[0,1,1] neg_lo:[0,0,1]
	s_barrier
; DI f32x2 cmul(f32x2 a, f32x2 b) { return mkf2(a.x * b.x - a.y * b.y, a.x * b.y + a.y * b.x); }
; DI void fft8192(f32x2* buf, const f32x2* __restrict__ tw) {
;     ...
; #pragma unroll
;     for (int e = 0; e < 8; ++e) {
;       const int i = tid + 256 * e;
;       const int q = i & (s - 1);
;       const int ps = i - q;
;       const float rev = (float)ps * (1.f / 8192.f);
;       const f32x2 w1 = mkf2(__builtin_amdgcn_cosf(rev), -__builtin_amdgcn_sinf(rev));
;       const f32x2 w2 = cmul(w1, w1), w3 = cmul(w1, w2);
;       const f32x2 apc = mkf2(a[e].x + c[e].x, a[e].y + c[e].y), amc = mkf2(a[e].x - c[e].x, a[e].y - c[e].y);
;       const f32x2 bpd = mkf2(b[e].x + d[e].x, b[e].y + d[e].y), bmd = mkf2(b[e].x - d[e].x, b[e].y - d[e].y);
;       const int o = 4 * i - 3 * q;
;       buf[SW(o)] = mkf2(apc.x + bpd.x, apc.y + bpd.y);
;       buf[SW(o + s)] = cmul(w1, mkf2(amc.x + bmd.y, amc.y - bmd.x));
;       buf[SW(o + 2 * s)] = cmul(w2, mkf2(apc.x - bpd.x, apc.y - bpd.y));
;       buf[SW(o + 3 * s)] = cmul(w3, mkf2(amc.x - bmd.y, amc.y + bmd.x));
;     }
	v_pk_add_f32 v[202:203], v[6:7], v[38:39]
	v_pk_add_f32 v[6:7], v[6:7], v[38:39] neg_lo:[0,1] neg_hi:[0,1]
	v_pk_add_f32 v[204:205], v[22:23], v[54:55]
	v_pk_add_f32 v[22:23], v[22:23], v[54:55] neg_lo:[0,1] neg_hi:[0,1]
	v_pk_add_f32 v[38:39], v[202:203], v[204:205]
	v_pk_add_f32 v[54:55], v[202:203], v[204:205] neg_lo:[0,1] neg_hi:[0,1]
	v_pk_add_f32 v[202:203], v[6:7], v[22:23] op_sel:[0,1] op_sel_hi:[1,0] neg_hi:[0,1]
	v_pk_add_f32 v[22:23], v[6:7], v[22:23] op_sel:[0,1] op_sel_hi:[1,0] neg_lo:[0,1]
	v_pk_mov_b32 v[6:7], v[202:203], v[202:203] op_sel:[0,1]
	v_pk_add_f32 v[202:203], v[2:3], v[34:35]
	v_pk_add_f32 v[2:3], v[2:3], v[34:35] neg_lo:[0,1] neg_hi:[0,1]
	v_pk_add_f32 v[204:205], v[18:19], v[50:51]
	v_pk_add_f32 v[18:19], v[18:19], v[50:51] neg_lo:[0,1] neg_hi:[0,1]
	v_pk_add_f32 v[34:35], v[202:203], v[204:205]
	v_pk_add_f32 v[50:51], v[202:203], v[204:205] neg_lo:[0,1] neg_hi:[0,1]
	v_pk_add_f32 v[202:203], v[2:3], v[18:19] op_sel:[0,1] op_sel_hi:[1,0] neg_hi:[0,1]
	v_pk_add_f32 v[18:19], v[2:3], v[18:19] op_sel:[0,1] op_sel_hi:[1,0] neg_lo:[0,1]
	v_pk_mov_b32 v[2:3], v[202:203], v[202:203] op_sel:[0,1]
	v_pk_add_f32 v[202:203], v[8:9], v[36:37]
	v_pk_add_f32 v[8:9], v[8:9], v[36:37] neg_lo:[0,1] neg_hi:[0,1]
	v_pk_add_f32 v[204:205], v[20:21], v[52:53]
	v_pk_add_f32 v[20:21], v[20:21], v[52:53] neg_lo:[0,1] neg_hi:[0,1]
	v_pk_add_f32 v[36:37], v[202:203], v[204:205]
	v_pk_add_f32 v[52:53], v[202:203], v[204:205] neg_lo:[0,1] neg_hi:[0,1]
	v_pk_add_f32 v[202:203], v[8:9], v[20:21] op_sel:[0,1] op_sel_hi:[1,0] neg_hi:[0,1]
	v_pk_add_f32 v[20:21], v[8:9], v[20:21] op_sel:[0,1] op_sel_hi:[1,0] neg_lo:[0,1]
	v_pk_mov_b32 v[8:9], v[202:203], v[202:203] op_sel:[0,1]
	v_pk_add_f32 v[202:203], v[4:5], v[40:41]
	v_pk_add_f32 v[4:5], v[4:5], v[40:41] neg_lo:[0,1] neg_hi:[0,1]
	v_pk_add_f32 v[204:205], v[24:25], v[56:57]
	v_pk_add_f32 v[24:25], v[24:25], v[56:57] neg_lo:[0,1] neg_hi:[0,1]
	v_pk_add_f32 v[40:41], v[202:203], v[204:205]
	v_pk_add_f32 v[56:57], v[202:203], v[204:205] neg_lo:[0,1] neg_hi:[0,1]
	v_pk_add_f32 v[202:203], v[4:5], v[24:25] op_sel:[0,1] op_sel_hi:[1,0] neg_hi:[0,1]
	v_pk_add_f32 v[24:25], v[4:5], v[24:25] op_sel:[0,1] op_sel_hi:[1,0] neg_lo:[0,1]
	v_pk_mov_b32 v[4:5], v[202:203], v[202:203] op_sel:[0,1]
	v_mov_b32_e32 v224, 0x3f3504f3
	v_mov_b32_e32 v225, 0xbf3504f3
	v_mov_b32_e32 v226, 0x248d3132
	v_mov_b32_e32 v227, 0xbf800000
	v_mov_b32_e32 v230, 0xbf3504f3
	v_mov_b32_e32 v231, 0xbf3504f3
	v_pk_add_f32 v[202:203], v[14:15], v[46:47]
	v_pk_add_f32 v[14:15], v[14:15], v[46:47] neg_lo:[0,1] neg_hi:[0,1]
	v_pk_add_f32 v[204:205], v[30:31], v[62:63]
	v_pk_add_f32 v[30:31], v[30:31], v[62:63] neg_lo:[0,1] neg_hi:[0,1]
	v_pk_add_f32 v[46:47], v[202:203], v[204:205]
	v_pk_add_f32 v[62:63], v[202:203], v[204:205] neg_lo:[0,1] neg_hi:[0,1]
	v_pk_add_f32 v[202:203], v[14:15], v[30:31] op_sel:[0,1] op_sel_hi:[1,0] neg_hi:[0,1]
	v_pk_add_f32 v[204:205], v[14:15], v[30:31] op_sel:[0,1] op_sel_hi:[1,0] neg_lo:[0,1]
	v_pk_mul_f32 v[14:15], v[224:225], v[202:203] op_sel:[1,1] op_sel_hi:[1,0]
	v_pk_fma_f32 v[14:15], v[224:225], v[202:203], v[14:15] op_sel_hi:[0,1,1] neg_lo:[0,0,1]
	v_pk_mul_f32 v[30:31], v[226:227], v[62:63] op_sel:[1,1] op_sel_hi:[1,0]
	v_pk_fma_f32 v[30:31], v[226:227], v[62:63], v[30:31] op_sel_hi:[0,1,1] neg_lo:[0,0,1]
	v_pk_mul_f32 v[62:63], v[230:231], v[204:205] op_sel:[1,1] op_sel_hi:[1,0]
	v_pk_fma_f32 v[62:63], v[230:231], v[204:205], v[62:63] op_sel_hi:[0,1,1] neg_lo:[0,0,1]
	v_pk_add_f32 v[202:203], v[10:11], v[42:43]
	v_pk_add_f32 v[10:11], v[10:11], v[42:43] neg_lo:[0,1] neg_hi:[0,1]
	v_pk_add_f32 v[204:205], v[26:27], v[58:59]
	v_pk_add_f32 v[26:27], v[26:27], v[58:59] neg_lo:[0,1] neg_hi:[0,1]
	v_pk_add_f32 v[42:43], v[202:203], v[204:205]
	v_pk_add_f32 v[58:59], v[202:203], v[204:205] neg_lo:[0,1] neg_hi:[0,1]
	v_pk_add_f32 v[202:203], v[10:11], v[26:27] op_sel:[0,1] op_sel_hi:[1,0] neg_hi:[0,1]
	v_pk_add_f32 v[204:205], v[10:11], v[26:27] op_sel:[0,1] op_sel_hi:[1,0] neg_lo:[0,1]
	v_pk_mul_f32 v[10:11], v[224:225], v[202:203] op_sel:[1,1] op_sel_hi:[1,0]
	v_pk_fma_f32 v[10:11], v[224:225], v[202:203], v[10:11] op_sel_hi:[0,1,1] neg_lo:[0,0,1]
	v_pk_mul_f32 v[26:27], v[226:227], v[58:59] op_sel:[1,1] op_sel_hi:[1,0]
	v_pk_fma_f32 v[26:27], v[226:227], v[58:59], v[26:27] op_sel_hi:[0,1,1] neg_lo:[0,0,1]
	v_pk_mul_f32 v[58:59], v[230:231], v[204:205] op_sel:[1,1] op_sel_hi:[1,0]
	v_pk_fma_f32 v[58:59], v[230:231], v[204:205], v[58:59] op_sel_hi:[0,1,1] neg_lo:[0,0,1]
	v_pk_add_f32 v[202:203], v[12:13], v[44:45]
	v_pk_add_f32 v[12:13], v[12:13], v[44:45] neg_lo:[0,1] neg_hi:[0,1]
	v_pk_add_f32 v[204:205], v[28:29], v[60:61]
	v_pk_add_f32 v[28:29], v[28:29], v[60:61] neg_lo:[0,1] neg_hi:[0,1]
	v_pk_add_f32 v[44:45], v[202:203], v[204:205]
	v_pk_add_f32 v[60:61], v[202:203], v[204:205] neg_lo:[0,1] neg_hi:[0,1]
	v_pk_add_f32 v[202:203], v[12:13], v[28:29] op_sel:[0,1] op_sel_hi:[1,0] neg_hi:[0,1]
	v_pk_add_f32 v[204:205], v[12:13], v[28:29] op_sel:[0,1] op_sel_hi:[1,0] neg_lo:[0,1]
	v_pk_mul_f32 v[12:13], v[224:225], v[202:203] op_sel:[1,1] op_sel_hi:[1,0]
	v_pk_fma_f32 v[12:13], v[224:225], v[202:203], v[12:13] op_sel_hi:[0,1,1] neg_lo:[0,0,1]
	v_pk_mul_f32 v[28:29], v[226:227], v[60:61] op_sel:[1,1] op_sel_hi:[1,0]
	v_pk_fma_f32 v[28:29], v[226:227], v[60:61], v[28:29] op_sel_hi:[0,1,1] neg_lo:[0,0,1]
	v_pk_mul_f32 v[60:61], v[230:231], v[204:205] op_sel:[1,1] op_sel_hi:[1,0]
	v_pk_fma_f32 v[60:61], v[230:231], v[204:205], v[60:61] op_sel_hi:[0,1,1] neg_lo:[0,0,1]
	v_pk_add_f32 v[202:203], v[16:17], v[48:49]
	v_pk_add_f32 v[16:17], v[16:17], v[48:49] neg_lo:[0,1] neg_hi:[0,1]
; DI void fft8192(f32x2* buf, const f32x2* __restrict__ tw) {
;     ...
;   {
;     f32x2 a[16], b[16];
;     __syncthreads();
; #pragma unroll
;     for (int e = 0; e < 16; ++e) { const int pi = SW(tid + 256 * e); a[e] = buf[pi]; b[e] = buf[pi + 4096]; }
;     __syncthreads();
; #pragma unroll
;     for (int e = 0; e < 16; ++e) {
;       const int pi = SW(tid + 256 * e);
;       buf[pi] = mkf2(a[e].x + b[e].x, a[e].y + b[e].y);
;       buf[pi + 4096] = mkf2(a[e].x - b[e].x, a[e].y - b[e].y);
;     }
;     __syncthreads();
;   }
; DI void hyena_unit(KP p, int l, int c, char* smem) {
;     ...
;     for (int j = 0; j < 32; ++j) KF[j] = buf[SW(tid + 256 * j)];
;     const int gcol = (o == 0 ? 512 : 1024) + c;
;     const float gw0 = cw[gcol], gw1 = cw[1536 + gcol], gw2 = cw[3072 + gcol], gb = cb[gcol];
;     const float vw0 = cw[c], vw1 = cw[1536 + c], vw2 = cw[3072 + c], vb = cb[c];
	v_pk_add_f32 v[204:205], v[32:33], v[64:65]
	v_pk_add_f32 v[32:33], v[32:33], v[64:65] neg_lo:[0,1] neg_hi:[0,1]
	v_pk_add_f32 v[48:49], v[202:203], v[204:205]
	v_pk_add_f32 v[64:65], v[202:203], v[204:205] neg_lo:[0,1] neg_hi:[0,1]
	v_pk_add_f32 v[202:203], v[16:17], v[32:33] op_sel:[0,1] op_sel_hi:[1,0] neg_hi:[0,1]
	v_pk_add_f32 v[204:205], v[16:17], v[32:33] op_sel:[0,1] op_sel_hi:[1,0] neg_lo:[0,1]
	v_pk_mul_f32 v[16:17], v[224:225], v[202:203] op_sel:[1,1] op_sel_hi:[1,0]
	v_pk_fma_f32 v[16:17], v[224:225], v[202:203], v[16:17] op_sel_hi:[0,1,1] neg_lo:[0,0,1]
	v_pk_mul_f32 v[32:33], v[226:227], v[64:65] op_sel:[1,1] op_sel_hi:[1,0]
	v_pk_fma_f32 v[32:33], v[226:227], v[64:65], v[32:33] op_sel_hi:[0,1,1] neg_lo:[0,0,1]
	v_pk_mul_f32 v[64:65], v[230:231], v[204:205] op_sel:[1,1] op_sel_hi:[1,0]
	v_pk_fma_f32 v[64:65], v[230:231], v[204:205], v[64:65] op_sel_hi:[0,1,1] neg_lo:[0,0,1]
	v_pk_add_f32 v[202:203], v[38:39], v[46:47]
	v_pk_add_f32 v[46:47], v[38:39], v[46:47] neg_lo:[0,1] neg_hi:[0,1]
	v_pk_add_f32 v[204:205], v[34:35], v[42:43]
	v_pk_add_f32 v[42:43], v[34:35], v[42:43] neg_lo:[0,1] neg_hi:[0,1]
	v_pk_add_f32 v[206:207], v[36:37], v[44:45]
	v_pk_add_f32 v[44:45], v[36:37], v[44:45] neg_lo:[0,1] neg_hi:[0,1]
	v_pk_add_f32 v[208:209], v[40:41], v[48:49]
	v_pk_add_f32 v[48:49], v[40:41], v[48:49] neg_lo:[0,1] neg_hi:[0,1]
	v_pk_add_f32 v[210:211], v[6:7], v[14:15]
	v_pk_add_f32 v[14:15], v[6:7], v[14:15] neg_lo:[0,1] neg_hi:[0,1]
	v_pk_add_f32 v[212:213], v[2:3], v[10:11]
	v_pk_add_f32 v[10:11], v[2:3], v[10:11] neg_lo:[0,1] neg_hi:[0,1]
	v_pk_add_f32 v[220:221], v[8:9], v[12:13]
	v_pk_add_f32 v[12:13], v[8:9], v[12:13] neg_lo:[0,1] neg_hi:[0,1]
	v_pk_add_f32 v[224:225], v[4:5], v[16:17]
	v_pk_add_f32 v[16:17], v[4:5], v[16:17] neg_lo:[0,1] neg_hi:[0,1]
	v_pk_add_f32 v[226:227], v[54:55], v[30:31]
	v_pk_add_f32 v[30:31], v[54:55], v[30:31] neg_lo:[0,1] neg_hi:[0,1]
	v_pk_add_f32 v[230:231], v[50:51], v[26:27]
	v_pk_add_f32 v[26:27], v[50:51], v[26:27] neg_lo:[0,1] neg_hi:[0,1]
	v_pk_add_f32 v[232:233], v[52:53], v[28:29]
	v_pk_add_f32 v[28:29], v[52:53], v[28:29] neg_lo:[0,1] neg_hi:[0,1]
	v_pk_add_f32 v[236:237], v[56:57], v[32:33]
	v_pk_add_f32 v[32:33], v[56:57], v[32:33] neg_lo:[0,1] neg_hi:[0,1]
	v_pk_add_f32 v[238:239], v[22:23], v[62:63]
	v_pk_add_f32 v[62:63], v[22:23], v[62:63] neg_lo:[0,1] neg_hi:[0,1]
	v_pk_add_f32 v[240:241], v[18:19], v[58:59]
	v_pk_add_f32 v[58:59], v[18:19], v[58:59] neg_lo:[0,1] neg_hi:[0,1]
	v_pk_add_f32 v[244:245], v[20:21], v[60:61]
	v_pk_add_f32 v[60:61], v[20:21], v[60:61] neg_lo:[0,1] neg_hi:[0,1]
	v_pk_add_f32 v[246:247], v[24:25], v[64:65]
	v_pk_add_f32 v[64:65], v[24:25], v[64:65] neg_lo:[0,1] neg_hi:[0,1]
	ds_write2st64_b64 v154, v[202:203], v[46:47] offset0:0 offset1:64
	ds_write2st64_b64 v154, v[204:205], v[42:43] offset0:4 offset1:68
	ds_write2st64_b64 v154, v[206:207], v[44:45] offset0:8 offset1:72
	ds_write2st64_b64 v154, v[208:209], v[48:49] offset0:12 offset1:76
	ds_write2st64_b64 v154, v[210:211], v[14:15] offset0:16 offset1:80
	ds_write2st64_b64 v154, v[212:213], v[10:11] offset0:20 offset1:84
	ds_write2st64_b64 v154, v[220:221], v[12:13] offset0:24 offset1:88
	ds_write2st64_b64 v154, v[224:225], v[16:17] offset0:28 offset1:92
	ds_write2st64_b64 v154, v[226:227], v[30:31] offset0:32 offset1:96
	ds_write2st64_b64 v154, v[230:231], v[26:27] offset0:36 offset1:100
	ds_write2st64_b64 v154, v[232:233], v[28:29] offset0:40 offset1:104
	ds_write2st64_b64 v154, v[236:237], v[32:33] offset0:44 offset1:108
	ds_write2st64_b64 v154, v[238:239], v[62:63] offset0:48 offset1:112
	ds_write2st64_b64 v154, v[240:241], v[58:59] offset0:52 offset1:116
	ds_write2st64_b64 v154, v[244:245], v[60:61] offset0:56 offset1:120
	ds_write2st64_b64 v154, v[246:247], v[64:65] offset0:60 offset1:124
	s_and_b64 s[2:3], s[96:97], exec
	s_cselect_b32 s4, 0x200, s62
	s_add_i32 s21, s4, s86
	s_lshl_b32 s5, s4, 2
	s_add_u32 s2, s88, s5
	v_mov_b32_e32 v2, s5
	s_waitcnt lgkmcnt(0)
	s_barrier
	s_addc_u32 s3, s89, 0
	global_load_dword v74, v2, s[88:89]
	global_load_dword v195, v2, s[94:95]
	global_load_dword v196, v235, s[2:3] offset:2048
	global_load_dword v75, v229, s[2:3]
	global_load_dword v76, v199, s[88:89]
	global_load_dword v197, v199, s[90:91]
	global_load_dword v77, v199, s[92:93]
	global_load_dword v200, v199, s[94:95]
	ds_read_b64 v[78:79], v157
	ds_read_b64 v[80:81], v159
	ds_read_b64 v[82:83], v161
	ds_read_b64 v[84:85], v163
	ds_read_b64 v[86:87], v165
	ds_read_b64 v[88:89], v167
	ds_read_b64 v[90:91], v169
	ds_read_b64 v[92:93], v170
	ds_read_b64 v[94:95], v171
	ds_read_b64 v[96:97], v172
	ds_read_b64 v[98:99], v173
	ds_read_b64 v[100:101], v174
	ds_read_b64 v[102:103], v175
	ds_read_b64 v[104:105], v176
	ds_read_b64 v[106:107], v177
	ds_read_b64 v[108:109], v178
	ds_read_b64 v[110:111], v179
	ds_read_b64 v[112:113], v180
	ds_read_b64 v[114:115], v181
	ds_read_b64 v[116:117], v182
	ds_read_b64 v[118:119], v183
	ds_read_b64 v[120:121], v184
	ds_read_b64 v[122:123], v185
	ds_read_b64 v[124:125], v186
	ds_read_b64 v[126:127], v187
	ds_read_b64 v[128:129], v188
	ds_read_b64 v[130:131], v189
	ds_read_b64 v[132:133], v190
	ds_read_b64 v[134:135], v191
	ds_read_b64 v[136:137], v192
	ds_read_b64 v[138:139], v193
	ds_read_b64 v[140:141], v194
	s_waitcnt lgkmcnt(5)
	v_pk_mov_b32 v[142:143], v[130:131], v[130:131] op_sel:[1,0]
	s_waitcnt lgkmcnt(4)
	v_pk_mov_b32 v[144:145], v[132:133], v[132:133] op_sel:[1,0]
	s_waitcnt lgkmcnt(3)
	v_pk_mov_b32 v[146:147], v[134:135], v[134:135] op_sel:[1,0]
	s_waitcnt lgkmcnt(2)
	v_pk_mov_b32 v[148:149], v[136:137], v[136:137] op_sel:[1,0]
	s_waitcnt lgkmcnt(1)
	v_pk_mov_b32 v[150:151], v[138:139], v[138:139] op_sel:[1,0]
	s_waitcnt lgkmcnt(0)
	v_pk_mov_b32 v[152:153], v[140:141], v[140:141] op_sel:[1,0]
	s_add_i32 s77, s40, s4
	s_mov_b32 s83, 0
	s_mov_b64 s[6:7], -1
	s_branch .LBB0_937

; DI f32x2 cmul(f32x2 a, f32x2 b) { return mkf2(a.x * b.x - a.y * b.y, a.x * b.y + a.y * b.x); }
; DI void fft8192(f32x2* buf, const f32x2* __restrict__ tw) {
;     ...
;     __syncthreads();
; #pragma unroll
;     for (int e = 0; e < 8; ++e) {
;       const int i = tid + 256 * e;
;       const int pi = SW(i);
;       a[e] = buf[pi]; b[e] = buf[pi + 2048]; c[e] = buf[pi + 4096]; d[e] = buf[pi + 6144];
;     }
;     __syncthreads();
; #pragma unroll
;     for (int e = 0; e < 8; ++e) {
;       const int i = tid + 256 * e;
;       const int q = i & (s - 1);
;       const int ps = i - q;
;       const float rev = (float)ps * (1.f / 8192.f);
;       const f32x2 w1 = mkf2(__builtin_amdgcn_cosf(rev), -__builtin_amdgcn_sinf(rev));
;       const f32x2 w2 = cmul(w1, w1), w3 = cmul(w1, w2);
;       const f32x2 apc = mkf2(a[e].x + c[e].x, a[e].y + c[e].y), amc = mkf2(a[e].x - c[e].x, a[e].y - c[e].y);
;       const f32x2 bpd = mkf2(b[e].x + d[e].x, b[e].y + d[e].y), bmd = mkf2(b[e].x - d[e].x, b[e].y - d[e].y);
;       const int o = 4 * i - 3 * q;
;       buf[SW(o)] = mkf2(apc.x + bpd.x, apc.y + bpd.y);
;       buf[SW(o + s)] = cmul(w1, mkf2(amc.x + bmd.y, amc.y - bmd.x));
;       buf[SW(o + 2 * s)] = cmul(w2, mkf2(apc.x - bpd.x, apc.y - bpd.y));
;       buf[SW(o + 3 * s)] = cmul(w3, mkf2(amc.x - bmd.y, amc.y + bmd.x));
;     }
.Lhy_inA_done:
.LBB0_987:
	v_bfe_i32 v166, v0, 5, 1
	v_bfe_i32 v168, v0, 6, 1
	v_and_b32_e32 v166, 5, v166
	v_and_b32_e32 v168, 26, v168
	v_xor_b32_e32 v166, v166, v168
	v_xor_b32_e32 v166, v166, v0
	v_lshlrev_b32_e32 v154, 3, v166
	s_waitcnt lgkmcnt(0)
	s_barrier
	ds_read2st64_b64 v[2:5], v154 offset0:0 offset1:32
	ds_read2st64_b64 v[10:13], v154 offset0:4 offset1:36
	ds_read2st64_b64 v[18:21], v154 offset0:8 offset1:40
	ds_read2st64_b64 v[26:29], v154 offset0:12 offset1:44
	ds_read2st64_b64 v[34:37], v154 offset0:16 offset1:48
	ds_read2st64_b64 v[42:45], v154 offset0:20 offset1:52
	ds_read2st64_b64 v[50:53], v154 offset0:24 offset1:56
	ds_read2st64_b64 v[58:61], v154 offset0:28 offset1:60
	v_cvt_f32_u32_e32 v201, v0
	v_and_b32_e32 v166, 15, v0
	v_lshlrev_b32_e32 v166, 3, v166
	v_lshl_add_u32 v164, v0, 7, v166
	v_mul_f32_e32 v201, 0x39000000, v201
	v_cos_f32_e32 v210, v201
	v_sin_f32_e64 v211, -v201
	s_nop 0
	v_mov_b32_e32 v224, v210
	v_mov_b32_e32 v225, v211
	s_waitcnt lgkmcnt(7)
	v_pk_add_f32 v[6:7], v[2:3], v[4:5]
	v_pk_add_f32 v[8:9], v[2:3], v[4:5] neg_lo:[0,1] neg_hi:[0,1]
	v_pk_add_f32 v[202:203], v[2:3], v[4:5] op_sel:[0,1] op_sel_hi:[1,0] neg_hi:[0,1]
	v_pk_add_f32 v[204:205], v[2:3], v[4:5] op_sel:[0,1] op_sel_hi:[1,0] neg_lo:[0,1]
	v_pk_mul_f32 v[206:207], v[210:211], v[210:211] op_sel:[1,1] op_sel_hi:[1,0]
	v_pk_fma_f32 v[212:213], v[210:211], v[210:211], v[206:207] op_sel_hi:[0,1,1] neg_lo:[0,0,1]
	v_pk_mul_f32 v[206:207], v[210:211], v[212:213] op_sel:[1,1] op_sel_hi:[1,0]
	v_pk_fma_f32 v[220:221], v[210:211], v[212:213], v[206:207] op_sel_hi:[0,1,1] neg_lo:[0,0,1]
	v_pk_mul_f32 v[2:3], v[210:211], v[202:203] op_sel:[1,1] op_sel_hi:[1,0]
	v_pk_fma_f32 v[2:3], v[210:211], v[202:203], v[2:3] op_sel_hi:[0,1,1] neg_lo:[0,0,1]
	v_pk_mul_f32 v[4:5], v[212:213], v[8:9] op_sel:[1,1] op_sel_hi:[1,0]
	v_pk_fma_f32 v[4:5], v[212:213], v[8:9], v[4:5] op_sel_hi:[0,1,1] neg_lo:[0,0,1]
	v_pk_mul_f32 v[8:9], v[220:221], v[204:205] op_sel:[1,1] op_sel_hi:[1,0]
	v_pk_fma_f32 v[8:9], v[220:221], v[204:205], v[8:9] op_sel_hi:[0,1,1] neg_lo:[0,0,1]
	v_mul_f32_e32 v210, 0x3f7b14be, v224
	v_mul_f32_e32 v211, 0xbe47c5c2, v224
	v_fmac_f32_e32 v210, 0x3e47c5c2, v225
	v_fmac_f32_e32 v211, 0x3f7b14be, v225
	s_waitcnt lgkmcnt(6)
	v_pk_add_f32 v[14:15], v[10:11], v[12:13]
	v_pk_add_f32 v[16:17], v[10:11], v[12:13] neg_lo:[0,1] neg_hi:[0,1]
	v_pk_add_f32 v[202:203], v[10:11], v[12:13] op_sel:[0,1] op_sel_hi:[1,0] neg_hi:[0,1]
	v_pk_add_f32 v[204:205], v[10:11], v[12:13] op_sel:[0,1] op_sel_hi:[1,0] neg_lo:[0,1]
	v_pk_mul_f32 v[206:207], v[210:211], v[210:211] op_sel:[1,1] op_sel_hi:[1,0]
	v_pk_fma_f32 v[212:213], v[210:211], v[210:211], v[206:207] op_sel_hi:[0,1,1] neg_lo:[0,0,1]
	v_pk_mul_f32 v[206:207], v[210:211], v[212:213] op_sel:[1,1] op_sel_hi:[1,0]
	v_pk_fma_f32 v[220:221], v[210:211], v[212:213], v[206:207] op_sel_hi:[0,1,1] neg_lo:[0,0,1]
	v_pk_mul_f32 v[10:11], v[210:211], v[202:203] op_sel:[1,1] op_sel_hi:[1,0]
	v_pk_fma_f32 v[10:11], v[210:211], v[202:203], v[10:11] op_sel_hi:[0,1,1] neg_lo:[0,0,1]
	v_pk_mul_f32 v[12:13], v[212:213], v[16:17] op_sel:[1,1] op_sel_hi:[1,0]
	v_pk_fma_f32 v[12:13], v[212:213], v[16:17], v[12:13] op_sel_hi:[0,1,1] neg_lo:[0,0,1]
	v_pk_mul_f32 v[16:17], v[220:221], v[204:205] op_sel:[1,1] op_sel_hi:[1,0]
	v_pk_fma_f32 v[16:17], v[220:221], v[204:205], v[16:17] op_sel_hi:[0,1,1] neg_lo:[0,0,1]
	v_mul_f32_e32 v210, 0x3f6c835e, v224
	v_mul_f32_e32 v211, 0xbec3ef15, v224
	v_fmac_f32_e32 v210, 0x3ec3ef15, v225
	v_fmac_f32_e32 v211, 0x3f6c835e, v225
	s_waitcnt lgkmcnt(5)
	v_pk_add_f32 v[22:23], v[18:19], v[20:21]
	v_pk_add_f32 v[24:25], v[18:19], v[20:21] neg_lo:[0,1] neg_hi:[0,1]
	v_pk_add_f32 v[202:203], v[18:19], v[20:21] op_sel:[0,1] op_sel_hi:[1,0] neg_hi:[0,1]
	v_pk_add_f32 v[204:205], v[18:19], v[20:21] op_sel:[0,1] op_sel_hi:[1,0] neg_lo:[0,1]
	v_pk_mul_f32 v[206:207], v[210:211], v[210:211] op_sel:[1,1] op_sel_hi:[1,0]
	v_pk_fma_f32 v[212:213], v[210:211], v[210:211], v[206:207] op_sel_hi:[0,1,1] neg_lo:[0,0,1]
	v_pk_mul_f32 v[206:207], v[210:211], v[212:213] op_sel:[1,1] op_sel_hi:[1,0]
	v_pk_fma_f32 v[220:221], v[210:211], v[212:213], v[206:207] op_sel_hi:[0,1,1] neg_lo:[0,0,1]
	v_pk_mul_f32 v[18:19], v[210:211], v[202:203] op_sel:[1,1] op_sel_hi:[1,0]
	v_pk_fma_f32 v[18:19], v[210:211], v[202:203], v[18:19] op_sel_hi:[0,1,1] neg_lo:[0,0,1]
	v_pk_mul_f32 v[20:21], v[212:213], v[24:25] op_sel:[1,1] op_sel_hi:[1,0]
	v_pk_fma_f32 v[20:21], v[212:213], v[24:25], v[20:21] op_sel_hi:[0,1,1] neg_lo:[0,0,1]
	v_pk_mul_f32 v[24:25], v[220:221], v[204:205] op_sel:[1,1] op_sel_hi:[1,0]
	v_pk_fma_f32 v[24:25], v[220:221], v[204:205], v[24:25] op_sel_hi:[0,1,1] neg_lo:[0,0,1]
	v_mul_f32_e32 v210, 0x3f54db31, v224
	v_mul_f32_e32 v211, 0xbf0e39da, v224
	v_fmac_f32_e32 v210, 0x3f0e39da, v225
	v_fmac_f32_e32 v211, 0x3f54db31, v225
	s_waitcnt lgkmcnt(4)
	v_pk_add_f32 v[30:31], v[26:27], v[28:29]
	v_pk_add_f32 v[32:33], v[26:27], v[28:29] neg_lo:[0,1] neg_hi:[0,1]
	v_pk_add_f32 v[202:203], v[26:27], v[28:29] op_sel:[0,1] op_sel_hi:[1,0] neg_hi:[0,1]
	v_pk_add_f32 v[204:205], v[26:27], v[28:29] op_sel:[0,1] op_sel_hi:[1,0] neg_lo:[0,1]
	v_pk_mul_f32 v[206:207], v[210:211], v[210:211] op_sel:[1,1] op_sel_hi:[1,0]
	v_pk_fma_f32 v[212:213], v[210:211], v[210:211], v[206:207] op_sel_hi:[0,1,1] neg_lo:[0,0,1]
	v_pk_mul_f32 v[206:207], v[210:211], v[212:213] op_sel:[1,1] op_sel_hi:[1,0]
	v_pk_fma_f32 v[220:221], v[210:211], v[212:213], v[206:207] op_sel_hi:[0,1,1] neg_lo:[0,0,1]
	v_pk_mul_f32 v[26:27], v[210:211], v[202:203] op_sel:[1,1] op_sel_hi:[1,0]
	v_pk_fma_f32 v[26:27], v[210:211], v[202:203], v[26:27] op_sel_hi:[0,1,1] neg_lo:[0,0,1]
	v_pk_mul_f32 v[28:29], v[212:213], v[32:33] op_sel:[1,1] op_sel_hi:[1,0]
	v_pk_fma_f32 v[28:29], v[212:213], v[32:33], v[28:29] op_sel_hi:[0,1,1] neg_lo:[0,0,1]
	v_pk_mul_f32 v[32:33], v[220:221], v[204:205] op_sel:[1,1] op_sel_hi:[1,0]
	v_pk_fma_f32 v[32:33], v[220:221], v[204:205], v[32:33] op_sel_hi:[0,1,1] neg_lo:[0,0,1]
	v_mul_f32_e32 v210, 0x3f3504f3, v224
	v_mul_f32_e32 v211, 0xbf3504f3, v224
	v_fmac_f32_e32 v210, 0x3f3504f3, v225
	v_fmac_f32_e32 v211, 0x3f3504f3, v225
	s_waitcnt lgkmcnt(3)
; DI f32x2 cmul(f32x2 a, f32x2 b) { return mkf2(a.x * b.x - a.y * b.y, a.x * b.y + a.y * b.x); }
; DI void fft8192(f32x2* buf, const f32x2* __restrict__ tw) {
;     ...
; #pragma unroll
;     for (int e = 0; e < 8; ++e) {
;       const int i = tid + 256 * e;
;       const int q = i & (s - 1);
;       const int ps = i - q;
;       const float rev = (float)ps * (1.f / 8192.f);
;       const f32x2 w1 = mkf2(__builtin_amdgcn_cosf(rev), -__builtin_amdgcn_sinf(rev));
;       const f32x2 w2 = cmul(w1, w1), w3 = cmul(w1, w2);
;       const f32x2 apc = mkf2(a[e].x + c[e].x, a[e].y + c[e].y), amc = mkf2(a[e].x - c[e].x, a[e].y - c[e].y);
;       const f32x2 bpd = mkf2(b[e].x + d[e].x, b[e].y + d[e].y), bmd = mkf2(b[e].x - d[e].x, b[e].y - d[e].y);
;       const int o = 4 * i - 3 * q;
;       buf[SW(o)] = mkf2(apc.x + bpd.x, apc.y + bpd.y);
;       buf[SW(o + s)] = cmul(w1, mkf2(amc.x + bmd.y, amc.y - bmd.x));
;       buf[SW(o + 2 * s)] = cmul(w2, mkf2(apc.x - bpd.x, apc.y - bpd.y));
;       buf[SW(o + 3 * s)] = cmul(w3, mkf2(amc.x - bmd.y, amc.y + bmd.x));
;     }
	v_pk_add_f32 v[38:39], v[34:35], v[36:37]
	v_pk_add_f32 v[40:41], v[34:35], v[36:37] neg_lo:[0,1] neg_hi:[0,1]
	v_pk_add_f32 v[202:203], v[34:35], v[36:37] op_sel:[0,1] op_sel_hi:[1,0] neg_hi:[0,1]
	v_pk_add_f32 v[204:205], v[34:35], v[36:37] op_sel:[0,1] op_sel_hi:[1,0] neg_lo:[0,1]
	v_pk_mul_f32 v[206:207], v[210:211], v[210:211] op_sel:[1,1] op_sel_hi:[1,0]
	v_pk_fma_f32 v[212:213], v[210:211], v[210:211], v[206:207] op_sel_hi:[0,1,1] neg_lo:[0,0,1]
	v_pk_mul_f32 v[206:207], v[210:211], v[212:213] op_sel:[1,1] op_sel_hi:[1,0]
	v_pk_fma_f32 v[220:221], v[210:211], v[212:213], v[206:207] op_sel_hi:[0,1,1] neg_lo:[0,0,1]
	v_pk_mul_f32 v[34:35], v[210:211], v[202:203] op_sel:[1,1] op_sel_hi:[1,0]
	v_pk_fma_f32 v[34:35], v[210:211], v[202:203], v[34:35] op_sel_hi:[0,1,1] neg_lo:[0,0,1]
	v_pk_mul_f32 v[36:37], v[212:213], v[40:41] op_sel:[1,1] op_sel_hi:[1,0]
	v_pk_fma_f32 v[36:37], v[212:213], v[40:41], v[36:37] op_sel_hi:[0,1,1] neg_lo:[0,0,1]
	v_pk_mul_f32 v[40:41], v[220:221], v[204:205] op_sel:[1,1] op_sel_hi:[1,0]
	v_pk_fma_f32 v[40:41], v[220:221], v[204:205], v[40:41] op_sel_hi:[0,1,1] neg_lo:[0,0,1]
	v_mul_f32_e32 v210, 0x3f0e39da, v224
	v_mul_f32_e32 v211, 0xbf54db31, v224
	v_fmac_f32_e32 v210, 0x3f54db31, v225
	v_fmac_f32_e32 v211, 0x3f0e39da, v225
	s_waitcnt lgkmcnt(2)
	v_pk_add_f32 v[46:47], v[42:43], v[44:45]
	v_pk_add_f32 v[48:49], v[42:43], v[44:45] neg_lo:[0,1] neg_hi:[0,1]
	v_pk_add_f32 v[202:203], v[42:43], v[44:45] op_sel:[0,1] op_sel_hi:[1,0] neg_hi:[0,1]
	v_pk_add_f32 v[204:205], v[42:43], v[44:45] op_sel:[0,1] op_sel_hi:[1,0] neg_lo:[0,1]
	v_pk_mul_f32 v[206:207], v[210:211], v[210:211] op_sel:[1,1] op_sel_hi:[1,0]
	v_pk_fma_f32 v[212:213], v[210:211], v[210:211], v[206:207] op_sel_hi:[0,1,1] neg_lo:[0,0,1]
	v_pk_mul_f32 v[206:207], v[210:211], v[212:213] op_sel:[1,1] op_sel_hi:[1,0]
	v_pk_fma_f32 v[220:221], v[210:211], v[212:213], v[206:207] op_sel_hi:[0,1,1] neg_lo:[0,0,1]
	v_pk_mul_f32 v[42:43], v[210:211], v[202:203] op_sel:[1,1] op_sel_hi:[1,0]
	v_pk_fma_f32 v[42:43], v[210:211], v[202:203], v[42:43] op_sel_hi:[0,1,1] neg_lo:[0,0,1]
	v_pk_mul_f32 v[44:45], v[212:213], v[48:49] op_sel:[1,1] op_sel_hi:[1,0]
	v_pk_fma_f32 v[44:45], v[212:213], v[48:49], v[44:45] op_sel_hi:[0,1,1] neg_lo:[0,0,1]
	v_pk_mul_f32 v[48:49], v[220:221], v[204:205] op_sel:[1,1] op_sel_hi:[1,0]
	v_pk_fma_f32 v[48:49], v[220:221], v[204:205], v[48:49] op_sel_hi:[0,1,1] neg_lo:[0,0,1]
	v_mul_f32_e32 v210, 0x3ec3ef15, v224
	v_mul_f32_e32 v211, 0xbf6c835e, v224
	v_fmac_f32_e32 v210, 0x3f6c835e, v225
	v_fmac_f32_e32 v211, 0x3ec3ef15, v225
	s_waitcnt lgkmcnt(1)
	v_pk_add_f32 v[54:55], v[50:51], v[52:53]
	v_pk_add_f32 v[56:57], v[50:51], v[52:53] neg_lo:[0,1] neg_hi:[0,1]
	v_pk_add_f32 v[202:203], v[50:51], v[52:53] op_sel:[0,1] op_sel_hi:[1,0] neg_hi:[0,1]
	v_pk_add_f32 v[204:205], v[50:51], v[52:53] op_sel:[0,1] op_sel_hi:[1,0] neg_lo:[0,1]
	v_pk_mul_f32 v[206:207], v[210:211], v[210:211] op_sel:[1,1] op_sel_hi:[1,0]
	v_pk_fma_f32 v[212:213], v[210:211], v[210:211], v[206:207] op_sel_hi:[0,1,1] neg_lo:[0,0,1]
	v_pk_mul_f32 v[206:207], v[210:211], v[212:213] op_sel:[1,1] op_sel_hi:[1,0]
	v_pk_fma_f32 v[220:221], v[210:211], v[212:213], v[206:207] op_sel_hi:[0,1,1] neg_lo:[0,0,1]
	v_pk_mul_f32 v[50:51], v[210:211], v[202:203] op_sel:[1,1] op_sel_hi:[1,0]
	v_pk_fma_f32 v[50:51], v[210:211], v[202:203], v[50:51] op_sel_hi:[0,1,1] neg_lo:[0,0,1]
	v_pk_mul_f32 v[52:53], v[212:213], v[56:57] op_sel:[1,1] op_sel_hi:[1,0]
	v_pk_fma_f32 v[52:53], v[212:213], v[56:57], v[52:53] op_sel_hi:[0,1,1] neg_lo:[0,0,1]
	v_pk_mul_f32 v[56:57], v[220:221], v[204:205] op_sel:[1,1] op_sel_hi:[1,0]
	v_pk_fma_f32 v[56:57], v[220:221], v[204:205], v[56:57] op_sel_hi:[0,1,1] neg_lo:[0,0,1]
	v_mul_f32_e32 v210, 0x3e47c5c2, v224
	v_mul_f32_e32 v211, 0xbf7b14be, v224
	v_fmac_f32_e32 v210, 0x3f7b14be, v225
	v_fmac_f32_e32 v211, 0x3e47c5c2, v225
	s_waitcnt lgkmcnt(0)
	v_pk_add_f32 v[62:63], v[58:59], v[60:61]
	v_pk_add_f32 v[64:65], v[58:59], v[60:61] neg_lo:[0,1] neg_hi:[0,1]
	v_pk_add_f32 v[202:203], v[58:59], v[60:61] op_sel:[0,1] op_sel_hi:[1,0] neg_hi:[0,1]
	v_pk_add_f32 v[204:205], v[58:59], v[60:61] op_sel:[0,1] op_sel_hi:[1,0] neg_lo:[0,1]
	v_pk_mul_f32 v[206:207], v[210:211], v[210:211] op_sel:[1,1] op_sel_hi:[1,0]
	v_pk_fma_f32 v[212:213], v[210:211], v[210:211], v[206:207] op_sel_hi:[0,1,1] neg_lo:[0,0,1]
	v_pk_mul_f32 v[206:207], v[210:211], v[212:213] op_sel:[1,1] op_sel_hi:[1,0]
	v_pk_fma_f32 v[220:221], v[210:211], v[212:213], v[206:207] op_sel_hi:[0,1,1] neg_lo:[0,0,1]
	v_pk_mul_f32 v[58:59], v[210:211], v[202:203] op_sel:[1,1] op_sel_hi:[1,0]
	v_pk_fma_f32 v[58:59], v[210:211], v[202:203], v[58:59] op_sel_hi:[0,1,1] neg_lo:[0,0,1]
	v_pk_mul_f32 v[60:61], v[212:213], v[64:65] op_sel:[1,1] op_sel_hi:[1,0]
	v_pk_fma_f32 v[60:61], v[212:213], v[64:65], v[60:61] op_sel_hi:[0,1,1] neg_lo:[0,0,1]
	v_pk_mul_f32 v[64:65], v[220:221], v[204:205] op_sel:[1,1] op_sel_hi:[1,0]
	v_pk_fma_f32 v[64:65], v[220:221], v[204:205], v[64:65] op_sel_hi:[0,1,1] neg_lo:[0,0,1]
	s_barrier
; DI f32x2 cmul(f32x2 a, f32x2 b) { return mkf2(a.x * b.x - a.y * b.y, a.x * b.y + a.y * b.x); }
; DI void fft8192(f32x2* buf, const f32x2* __restrict__ tw) {
;     ...
; #pragma unroll
;     for (int e = 0; e < 8; ++e) {
;       const int i = tid + 256 * e;
;       const int q = i & (s - 1);
;       const int ps = i - q;
;       const float rev = (float)ps * (1.f / 8192.f);
;       const f32x2 w1 = mkf2(__builtin_amdgcn_cosf(rev), -__builtin_amdgcn_sinf(rev));
;       const f32x2 w2 = cmul(w1, w1), w3 = cmul(w1, w2);
;       const f32x2 apc = mkf2(a[e].x + c[e].x, a[e].y + c[e].y), amc = mkf2(a[e].x - c[e].x, a[e].y - c[e].y);
;       const f32x2 bpd = mkf2(b[e].x + d[e].x, b[e].y + d[e].y), bmd = mkf2(b[e].x - d[e].x, b[e].y - d[e].y);
;       const int o = 4 * i - 3 * q;
;       buf[SW(o)] = mkf2(apc.x + bpd.x, apc.y + bpd.y);
;       buf[SW(o + s)] = cmul(w1, mkf2(amc.x + bmd.y, amc.y - bmd.x));
;       buf[SW(o + 2 * s)] = cmul(w2, mkf2(apc.x - bpd.x, apc.y - bpd.y));
;       buf[SW(o + 3 * s)] = cmul(w3, mkf2(amc.x - bmd.y, amc.y + bmd.x));
;     }
	v_mul_f32_e32 v214, 4.0, v201
	v_cos_f32_e32 v224, v214
	v_sin_f32_e64 v225, -v214
	s_nop 0
	v_pk_mul_f32 v[206:207], v[224:225], v[224:225] op_sel:[1,1] op_sel_hi:[1,0]
	v_pk_fma_f32 v[226:227], v[224:225], v[224:225], v[206:207] op_sel_hi:[0,1,1] neg_lo:[0,0,1]
	v_pk_mul_f32 v[206:207], v[224:225], v[226:227] op_sel:[1,1] op_sel_hi:[1,0]
	v_pk_fma_f32 v[230:231], v[224:225], v[226:227], v[206:207] op_sel_hi:[0,1,1] neg_lo:[0,0,1]
	v_pk_add_f32 v[202:203], v[6:7], v[38:39]
	v_pk_add_f32 v[6:7], v[6:7], v[38:39] neg_lo:[0,1] neg_hi:[0,1]
	v_pk_add_f32 v[204:205], v[22:23], v[54:55]
	v_pk_add_f32 v[22:23], v[22:23], v[54:55] neg_lo:[0,1] neg_hi:[0,1]
	v_pk_add_f32 v[38:39], v[202:203], v[204:205]
	v_pk_add_f32 v[54:55], v[202:203], v[204:205] neg_lo:[0,1] neg_hi:[0,1]
	v_pk_add_f32 v[202:203], v[6:7], v[22:23] op_sel:[0,1] op_sel_hi:[1,0] neg_hi:[0,1]
	v_pk_add_f32 v[204:205], v[6:7], v[22:23] op_sel:[0,1] op_sel_hi:[1,0] neg_lo:[0,1]
	v_pk_mul_f32 v[6:7], v[224:225], v[202:203] op_sel:[1,1] op_sel_hi:[1,0]
	v_pk_fma_f32 v[6:7], v[224:225], v[202:203], v[6:7] op_sel_hi:[0,1,1] neg_lo:[0,0,1]
	v_pk_mul_f32 v[22:23], v[226:227], v[54:55] op_sel:[1,1] op_sel_hi:[1,0]
	v_pk_fma_f32 v[22:23], v[226:227], v[54:55], v[22:23] op_sel_hi:[0,1,1] neg_lo:[0,0,1]
	v_pk_mul_f32 v[54:55], v[230:231], v[204:205] op_sel:[1,1] op_sel_hi:[1,0]
	v_pk_fma_f32 v[54:55], v[230:231], v[204:205], v[54:55] op_sel_hi:[0,1,1] neg_lo:[0,0,1]
	v_pk_add_f32 v[202:203], v[2:3], v[34:35]
	v_pk_add_f32 v[2:3], v[2:3], v[34:35] neg_lo:[0,1] neg_hi:[0,1]
	v_pk_add_f32 v[204:205], v[18:19], v[50:51]
	v_pk_add_f32 v[18:19], v[18:19], v[50:51] neg_lo:[0,1] neg_hi:[0,1]
	v_pk_add_f32 v[34:35], v[202:203], v[204:205]
	v_pk_add_f32 v[50:51], v[202:203], v[204:205] neg_lo:[0,1] neg_hi:[0,1]
	v_pk_add_f32 v[202:203], v[2:3], v[18:19] op_sel:[0,1] op_sel_hi:[1,0] neg_hi:[0,1]
	v_pk_add_f32 v[204:205], v[2:3], v[18:19] op_sel:[0,1] op_sel_hi:[1,0] neg_lo:[0,1]
	v_pk_mul_f32 v[2:3], v[224:225], v[202:203] op_sel:[1,1] op_sel_hi:[1,0]
	v_pk_fma_f32 v[2:3], v[224:225], v[202:203], v[2:3] op_sel_hi:[0,1,1] neg_lo:[0,0,1]
	v_pk_mul_f32 v[18:19], v[226:227], v[50:51] op_sel:[1,1] op_sel_hi:[1,0]
	v_pk_fma_f32 v[18:19], v[226:227], v[50:51], v[18:19] op_sel_hi:[0,1,1] neg_lo:[0,0,1]
	v_pk_mul_f32 v[50:51], v[230:231], v[204:205] op_sel:[1,1] op_sel_hi:[1,0]
	v_pk_fma_f32 v[50:51], v[230:231], v[204:205], v[50:51] op_sel_hi:[0,1,1] neg_lo:[0,0,1]
	v_pk_add_f32 v[202:203], v[4:5], v[36:37]
	v_pk_add_f32 v[4:5], v[4:5], v[36:37] neg_lo:[0,1] neg_hi:[0,1]
	v_pk_add_f32 v[204:205], v[20:21], v[52:53]
	v_pk_add_f32 v[20:21], v[20:21], v[52:53] neg_lo:[0,1] neg_hi:[0,1]
	v_pk_add_f32 v[36:37], v[202:203], v[204:205]
	v_pk_add_f32 v[52:53], v[202:203], v[204:205] neg_lo:[0,1] neg_hi:[0,1]
	v_pk_add_f32 v[202:203], v[4:5], v[20:21] op_sel:[0,1] op_sel_hi:[1,0] neg_hi:[0,1]
	v_pk_add_f32 v[204:205], v[4:5], v[20:21] op_sel:[0,1] op_sel_hi:[1,0] neg_lo:[0,1]
	v_pk_mul_f32 v[4:5], v[224:225], v[202:203] op_sel:[1,1] op_sel_hi:[1,0]
	v_pk_fma_f32 v[4:5], v[224:225], v[202:203], v[4:5] op_sel_hi:[0,1,1] neg_lo:[0,0,1]
	v_pk_mul_f32 v[20:21], v[226:227], v[52:53] op_sel:[1,1] op_sel_hi:[1,0]
	v_pk_fma_f32 v[20:21], v[226:227], v[52:53], v[20:21] op_sel_hi:[0,1,1] neg_lo:[0,0,1]
	v_pk_mul_f32 v[52:53], v[230:231], v[204:205] op_sel:[1,1] op_sel_hi:[1,0]
	v_pk_fma_f32 v[52:53], v[230:231], v[204:205], v[52:53] op_sel_hi:[0,1,1] neg_lo:[0,0,1]
	v_pk_add_f32 v[202:203], v[8:9], v[40:41]
	v_pk_add_f32 v[8:9], v[8:9], v[40:41] neg_lo:[0,1] neg_hi:[0,1]
	v_pk_add_f32 v[204:205], v[24:25], v[56:57]
	v_pk_add_f32 v[24:25], v[24:25], v[56:57] neg_lo:[0,1] neg_hi:[0,1]
	v_pk_add_f32 v[40:41], v[202:203], v[204:205]
	v_pk_add_f32 v[56:57], v[202:203], v[204:205] neg_lo:[0,1] neg_hi:[0,1]
	v_pk_add_f32 v[202:203], v[8:9], v[24:25] op_sel:[0,1] op_sel_hi:[1,0] neg_hi:[0,1]
	v_pk_add_f32 v[204:205], v[8:9], v[24:25] op_sel:[0,1] op_sel_hi:[1,0] neg_lo:[0,1]
	v_pk_mul_f32 v[8:9], v[224:225], v[202:203] op_sel:[1,1] op_sel_hi:[1,0]
	v_pk_fma_f32 v[8:9], v[224:225], v[202:203], v[8:9] op_sel_hi:[0,1,1] neg_lo:[0,0,1]
	v_pk_mul_f32 v[24:25], v[226:227], v[56:57] op_sel:[1,1] op_sel_hi:[1,0]
	v_pk_fma_f32 v[24:25], v[226:227], v[56:57], v[24:25] op_sel_hi:[0,1,1] neg_lo:[0,0,1]
	v_pk_mul_f32 v[56:57], v[230:231], v[204:205] op_sel:[1,1] op_sel_hi:[1,0]
	v_pk_fma_f32 v[56:57], v[230:231], v[204:205], v[56:57] op_sel_hi:[0,1,1] neg_lo:[0,0,1]
	v_mul_f32_e32 v214, 4.0, v201
	v_add_f32_e32 v214, 0x3e000000, v214
	v_cos_f32_e32 v224, v214
	v_sin_f32_e64 v225, -v214
	s_nop 0
	v_pk_mul_f32 v[206:207], v[224:225], v[224:225] op_sel:[1,1] op_sel_hi:[1,0]
	v_pk_fma_f32 v[226:227], v[224:225], v[224:225], v[206:207] op_sel_hi:[0,1,1] neg_lo:[0,0,1]
	v_pk_mul_f32 v[206:207], v[224:225], v[226:227] op_sel:[1,1] op_sel_hi:[1,0]
	v_pk_fma_f32 v[230:231], v[224:225], v[226:227], v[206:207] op_sel_hi:[0,1,1] neg_lo:[0,0,1]
	v_pk_add_f32 v[202:203], v[14:15], v[46:47]
	v_pk_add_f32 v[14:15], v[14:15], v[46:47] neg_lo:[0,1] neg_hi:[0,1]
	v_pk_add_f32 v[204:205], v[30:31], v[62:63]
	v_pk_add_f32 v[30:31], v[30:31], v[62:63] neg_lo:[0,1] neg_hi:[0,1]
	v_pk_add_f32 v[46:47], v[202:203], v[204:205]
	v_pk_add_f32 v[62:63], v[202:203], v[204:205] neg_lo:[0,1] neg_hi:[0,1]
	v_pk_add_f32 v[202:203], v[14:15], v[30:31] op_sel:[0,1] op_sel_hi:[1,0] neg_hi:[0,1]
	v_pk_add_f32 v[204:205], v[14:15], v[30:31] op_sel:[0,1] op_sel_hi:[1,0] neg_lo:[0,1]
	v_pk_mul_f32 v[14:15], v[224:225], v[202:203] op_sel:[1,1] op_sel_hi:[1,0]
	v_pk_fma_f32 v[14:15], v[224:225], v[202:203], v[14:15] op_sel_hi:[0,1,1] neg_lo:[0,0,1]
	v_pk_mul_f32 v[30:31], v[226:227], v[62:63] op_sel:[1,1] op_sel_hi:[1,0]
; DI f32x2 cmul(f32x2 a, f32x2 b) { return mkf2(a.x * b.x - a.y * b.y, a.x * b.y + a.y * b.x); }
; DI void fft8192(f32x2* buf, const f32x2* __restrict__ tw) {
;     ...
; #pragma unroll
;     for (int e = 0; e < 8; ++e) {
;       const int i = tid + 256 * e;
;       const int q = i & (s - 1);
;       const int ps = i - q;
;       const float rev = (float)ps * (1.f / 8192.f);
;       const f32x2 w1 = mkf2(__builtin_amdgcn_cosf(rev), -__builtin_amdgcn_sinf(rev));
;       const f32x2 w2 = cmul(w1, w1), w3 = cmul(w1, w2);
;       const f32x2 apc = mkf2(a[e].x + c[e].x, a[e].y + c[e].y), amc = mkf2(a[e].x - c[e].x, a[e].y - c[e].y);
;       const f32x2 bpd = mkf2(b[e].x + d[e].x, b[e].y + d[e].y), bmd = mkf2(b[e].x - d[e].x, b[e].y - d[e].y);
;       const int o = 4 * i - 3 * q;
;       buf[SW(o)] = mkf2(apc.x + bpd.x, apc.y + bpd.y);
;       buf[SW(o + s)] = cmul(w1, mkf2(amc.x + bmd.y, amc.y - bmd.x));
;       buf[SW(o + 2 * s)] = cmul(w2, mkf2(apc.x - bpd.x, apc.y - bpd.y));
;       buf[SW(o + 3 * s)] = cmul(w3, mkf2(amc.x - bmd.y, amc.y + bmd.x));
;     }
	v_pk_fma_f32 v[30:31], v[226:227], v[62:63], v[30:31] op_sel_hi:[0,1,1] neg_lo:[0,0,1]
	v_pk_mul_f32 v[62:63], v[230:231], v[204:205] op_sel:[1,1] op_sel_hi:[1,0]
	v_pk_fma_f32 v[62:63], v[230:231], v[204:205], v[62:63] op_sel_hi:[0,1,1] neg_lo:[0,0,1]
	v_pk_add_f32 v[202:203], v[10:11], v[42:43]
	v_pk_add_f32 v[10:11], v[10:11], v[42:43] neg_lo:[0,1] neg_hi:[0,1]
	v_pk_add_f32 v[204:205], v[26:27], v[58:59]
	v_pk_add_f32 v[26:27], v[26:27], v[58:59] neg_lo:[0,1] neg_hi:[0,1]
	v_pk_add_f32 v[42:43], v[202:203], v[204:205]
	v_pk_add_f32 v[58:59], v[202:203], v[204:205] neg_lo:[0,1] neg_hi:[0,1]
	v_pk_add_f32 v[202:203], v[10:11], v[26:27] op_sel:[0,1] op_sel_hi:[1,0] neg_hi:[0,1]
	v_pk_add_f32 v[204:205], v[10:11], v[26:27] op_sel:[0,1] op_sel_hi:[1,0] neg_lo:[0,1]
	v_pk_mul_f32 v[10:11], v[224:225], v[202:203] op_sel:[1,1] op_sel_hi:[1,0]
	v_pk_fma_f32 v[10:11], v[224:225], v[202:203], v[10:11] op_sel_hi:[0,1,1] neg_lo:[0,0,1]
	v_pk_mul_f32 v[26:27], v[226:227], v[58:59] op_sel:[1,1] op_sel_hi:[1,0]
	v_pk_fma_f32 v[26:27], v[226:227], v[58:59], v[26:27] op_sel_hi:[0,1,1] neg_lo:[0,0,1]
	v_pk_mul_f32 v[58:59], v[230:231], v[204:205] op_sel:[1,1] op_sel_hi:[1,0]
	v_pk_fma_f32 v[58:59], v[230:231], v[204:205], v[58:59] op_sel_hi:[0,1,1] neg_lo:[0,0,1]
	v_pk_add_f32 v[202:203], v[12:13], v[44:45]
	v_pk_add_f32 v[12:13], v[12:13], v[44:45] neg_lo:[0,1] neg_hi:[0,1]
	v_pk_add_f32 v[204:205], v[28:29], v[60:61]
	v_pk_add_f32 v[28:29], v[28:29], v[60:61] neg_lo:[0,1] neg_hi:[0,1]
	v_pk_add_f32 v[44:45], v[202:203], v[204:205]
	v_pk_add_f32 v[60:61], v[202:203], v[204:205] neg_lo:[0,1] neg_hi:[0,1]
	v_pk_add_f32 v[202:203], v[12:13], v[28:29] op_sel:[0,1] op_sel_hi:[1,0] neg_hi:[0,1]
	v_pk_add_f32 v[204:205], v[12:13], v[28:29] op_sel:[0,1] op_sel_hi:[1,0] neg_lo:[0,1]
	v_pk_mul_f32 v[12:13], v[224:225], v[202:203] op_sel:[1,1] op_sel_hi:[1,0]
	v_pk_fma_f32 v[12:13], v[224:225], v[202:203], v[12:13] op_sel_hi:[0,1,1] neg_lo:[0,0,1]
	v_pk_mul_f32 v[28:29], v[226:227], v[60:61] op_sel:[1,1] op_sel_hi:[1,0]
	v_pk_fma_f32 v[28:29], v[226:227], v[60:61], v[28:29] op_sel_hi:[0,1,1] neg_lo:[0,0,1]
	v_pk_mul_f32 v[60:61], v[230:231], v[204:205] op_sel:[1,1] op_sel_hi:[1,0]
	v_pk_fma_f32 v[60:61], v[230:231], v[204:205], v[60:61] op_sel_hi:[0,1,1] neg_lo:[0,0,1]
	v_pk_add_f32 v[202:203], v[16:17], v[48:49]
	v_pk_add_f32 v[16:17], v[16:17], v[48:49] neg_lo:[0,1] neg_hi:[0,1]
	v_pk_add_f32 v[204:205], v[32:33], v[64:65]
	v_pk_add_f32 v[32:33], v[32:33], v[64:65] neg_lo:[0,1] neg_hi:[0,1]
	v_pk_add_f32 v[48:49], v[202:203], v[204:205]
	v_pk_add_f32 v[64:65], v[202:203], v[204:205] neg_lo:[0,1] neg_hi:[0,1]
	v_pk_add_f32 v[202:203], v[16:17], v[32:33] op_sel:[0,1] op_sel_hi:[1,0] neg_hi:[0,1]
	v_pk_add_f32 v[204:205], v[16:17], v[32:33] op_sel:[0,1] op_sel_hi:[1,0] neg_lo:[0,1]
	v_pk_mul_f32 v[16:17], v[224:225], v[202:203] op_sel:[1,1] op_sel_hi:[1,0]
	v_pk_fma_f32 v[16:17], v[224:225], v[202:203], v[16:17] op_sel_hi:[0,1,1] neg_lo:[0,0,1]
	v_pk_mul_f32 v[32:33], v[226:227], v[64:65] op_sel:[1,1] op_sel_hi:[1,0]
	v_pk_fma_f32 v[32:33], v[226:227], v[64:65], v[32:33] op_sel_hi:[0,1,1] neg_lo:[0,0,1]
	v_pk_mul_f32 v[64:65], v[230:231], v[204:205] op_sel:[1,1] op_sel_hi:[1,0]
	v_pk_fma_f32 v[64:65], v[230:231], v[204:205], v[64:65] op_sel_hi:[0,1,1] neg_lo:[0,0,1]
	ds_write_b64 v164, v[38:39] offset:0
	v_xor_b32_e32 v156, 8, v164
	ds_write_b64 v156, v[34:35] offset:0
	v_xor_b32_e32 v158, 16, v164
	ds_write_b64 v158, v[36:37] offset:0
	v_xor_b32_e32 v160, 24, v164
	ds_write_b64 v160, v[40:41] offset:0
	v_xor_b32_e32 v162, 32, v164
	ds_write_b64 v162, v[6:7] offset:0
	v_xor_b32_e32 v156, 40, v164
	ds_write_b64 v156, v[2:3] offset:0
	v_xor_b32_e32 v158, 48, v164
	ds_write_b64 v158, v[4:5] offset:0
	v_xor_b32_e32 v160, 56, v164
	ds_write_b64 v160, v[8:9] offset:0
	v_xor_b32_e32 v162, 64, v164
	ds_write_b64 v162, v[22:23] offset:0
	v_xor_b32_e32 v156, 0x48, v164
	ds_write_b64 v156, v[18:19] offset:0
	v_xor_b32_e32 v158, 0x50, v164
	ds_write_b64 v158, v[20:21] offset:0
	v_xor_b32_e32 v160, 0x58, v164
	ds_write_b64 v160, v[24:25] offset:0
	v_xor_b32_e32 v162, 0x60, v164
	ds_write_b64 v162, v[54:55] offset:0
	v_xor_b32_e32 v156, 0x68, v164
	ds_write_b64 v156, v[50:51] offset:0
	v_xor_b32_e32 v158, 0x70, v164
	ds_write_b64 v158, v[52:53] offset:0
	v_xor_b32_e32 v160, 0x78, v164
	ds_write_b64 v160, v[56:57] offset:0
	ds_write_b64 v164, v[46:47] offset:32768
	v_xor_b32_e32 v162, 8, v164
	ds_write_b64 v162, v[42:43] offset:32768
	v_xor_b32_e32 v156, 16, v164
	ds_write_b64 v156, v[44:45] offset:32768
	v_xor_b32_e32 v158, 24, v164
	ds_write_b64 v158, v[48:49] offset:32768
	v_xor_b32_e32 v160, 32, v164
	ds_write_b64 v160, v[14:15] offset:32768
	v_xor_b32_e32 v162, 40, v164
	ds_write_b64 v162, v[10:11] offset:32768
	v_xor_b32_e32 v156, 48, v164
	ds_write_b64 v156, v[12:13] offset:32768
	v_xor_b32_e32 v158, 56, v164
	ds_write_b64 v158, v[16:17] offset:32768
	v_xor_b32_e32 v160, 64, v164
	ds_write_b64 v160, v[30:31] offset:32768
	v_xor_b32_e32 v162, 0x48, v164
	ds_write_b64 v162, v[26:27] offset:32768
	v_xor_b32_e32 v156, 0x50, v164
	ds_write_b64 v156, v[28:29] offset:32768
	v_xor_b32_e32 v158, 0x58, v164
	ds_write_b64 v158, v[32:33] offset:32768
	v_xor_b32_e32 v160, 0x60, v164
	ds_write_b64 v160, v[62:63] offset:32768
	v_xor_b32_e32 v162, 0x68, v164
	ds_write_b64 v162, v[58:59] offset:32768
	v_xor_b32_e32 v156, 0x70, v164
	ds_write_b64 v156, v[60:61] offset:32768
	v_xor_b32_e32 v158, 0x78, v164
	ds_write_b64 v158, v[64:65] offset:32768
	s_waitcnt lgkmcnt(0)
	s_barrier
; DI f32x2 cmul(f32x2 a, f32x2 b) { return mkf2(a.x * b.x - a.y * b.y, a.x * b.y + a.y * b.x); }
; DI void fft8192(f32x2* buf, const f32x2* __restrict__ tw) {
;     ...
;     __syncthreads();
; #pragma unroll
;     for (int e = 0; e < 8; ++e) {
;       const int i = tid + 256 * e;
;       const int pi = SW(i);
;       a[e] = buf[pi]; b[e] = buf[pi + 2048]; c[e] = buf[pi + 4096]; d[e] = buf[pi + 6144];
;     }
;     __syncthreads();
; #pragma unroll
;     for (int e = 0; e < 8; ++e) {
;       const int i = tid + 256 * e;
;       const int q = i & (s - 1);
;       const int ps = i - q;
;       const float rev = (float)ps * (1.f / 8192.f);
;       const f32x2 w1 = mkf2(__builtin_amdgcn_cosf(rev), -__builtin_amdgcn_sinf(rev));
;       const f32x2 w2 = cmul(w1, w1), w3 = cmul(w1, w2);
;       const f32x2 apc = mkf2(a[e].x + c[e].x, a[e].y + c[e].y), amc = mkf2(a[e].x - c[e].x, a[e].y - c[e].y);
;       const f32x2 bpd = mkf2(b[e].x + d[e].x, b[e].y + d[e].y), bmd = mkf2(b[e].x - d[e].x, b[e].y - d[e].y);
;       const int o = 4 * i - 3 * q;
;       buf[SW(o)] = mkf2(apc.x + bpd.x, apc.y + bpd.y);
;       buf[SW(o + s)] = cmul(w1, mkf2(amc.x + bmd.y, amc.y - bmd.x));
;       buf[SW(o + 2 * s)] = cmul(w2, mkf2(apc.x - bpd.x, apc.y - bpd.y));
;       buf[SW(o + 3 * s)] = cmul(w3, mkf2(amc.x - bmd.y, amc.y + bmd.x));
;     }
	v_bfe_i32 v166, v0, 4, 4
	v_and_b32_e32 v166, 15, v166
	v_xor_b32_e32 v166, v166, v0
	v_lshlrev_b32_e32 v164, 3, v166
	ds_read2st64_b64 v[2:5], v164 offset0:0 offset1:32
	ds_read2st64_b64 v[6:9], v164 offset0:64 offset1:96
	ds_read2st64_b64 v[10:13], v164 offset0:4 offset1:36
	ds_read2st64_b64 v[14:17], v164 offset0:68 offset1:100
	ds_read2st64_b64 v[18:21], v164 offset0:8 offset1:40
	ds_read2st64_b64 v[22:25], v164 offset0:72 offset1:104
	ds_read2st64_b64 v[26:29], v164 offset0:12 offset1:44
	ds_read2st64_b64 v[30:33], v164 offset0:76 offset1:108
	ds_read2st64_b64 v[34:37], v164 offset0:16 offset1:48
	ds_read2st64_b64 v[38:41], v164 offset0:80 offset1:112
	ds_read2st64_b64 v[42:45], v164 offset0:20 offset1:52
	ds_read2st64_b64 v[46:49], v164 offset0:84 offset1:116
	ds_read2st64_b64 v[50:53], v164 offset0:24 offset1:56
	ds_read2st64_b64 v[54:57], v164 offset0:88 offset1:120
	ds_read2st64_b64 v[58:61], v164 offset0:28 offset1:60
	ds_read2st64_b64 v[62:65], v164 offset0:92 offset1:124
	v_and_b32_e32 v166, 15, v0
	v_sub_u32_e32 v168, v0, v166
	v_cvt_f32_u32_e32 v201, v168
	v_lshl_add_u32 v164, v168, 4, v166
	v_lshlrev_b32_e32 v164, 3, v164
	v_mul_f32_e32 v201, 0x39000000, v201
	v_cos_f32_e32 v210, v201
	v_sin_f32_e64 v211, -v201
	s_nop 0
	v_mov_b32_e32 v224, v210
	v_mov_b32_e32 v225, v211
	s_waitcnt lgkmcnt(14)
	v_pk_add_f32 v[202:203], v[2:3], v[6:7]
	v_pk_add_f32 v[2:3], v[2:3], v[6:7] neg_lo:[0,1] neg_hi:[0,1]
	v_pk_add_f32 v[204:205], v[4:5], v[8:9]
	v_pk_add_f32 v[4:5], v[4:5], v[8:9] neg_lo:[0,1] neg_hi:[0,1]
	v_pk_add_f32 v[6:7], v[202:203], v[204:205]
	v_pk_add_f32 v[8:9], v[202:203], v[204:205] neg_lo:[0,1] neg_hi:[0,1]
	v_pk_add_f32 v[202:203], v[2:3], v[4:5] op_sel:[0,1] op_sel_hi:[1,0] neg_hi:[0,1]
	v_pk_add_f32 v[204:205], v[2:3], v[4:5] op_sel:[0,1] op_sel_hi:[1,0] neg_lo:[0,1]
	v_pk_mul_f32 v[206:207], v[210:211], v[210:211] op_sel:[1,1] op_sel_hi:[1,0]
	v_pk_fma_f32 v[212:213], v[210:211], v[210:211], v[206:207] op_sel_hi:[0,1,1] neg_lo:[0,0,1]
	v_pk_mul_f32 v[206:207], v[210:211], v[212:213] op_sel:[1,1] op_sel_hi:[1,0]
	v_pk_fma_f32 v[220:221], v[210:211], v[212:213], v[206:207] op_sel_hi:[0,1,1] neg_lo:[0,0,1]
	v_pk_mul_f32 v[2:3], v[210:211], v[202:203] op_sel:[1,1] op_sel_hi:[1,0]
	v_pk_fma_f32 v[2:3], v[210:211], v[202:203], v[2:3] op_sel_hi:[0,1,1] neg_lo:[0,0,1]
	v_pk_mul_f32 v[4:5], v[212:213], v[8:9] op_sel:[1,1] op_sel_hi:[1,0]
	v_pk_fma_f32 v[4:5], v[212:213], v[8:9], v[4:5] op_sel_hi:[0,1,1] neg_lo:[0,0,1]
	v_pk_mul_f32 v[8:9], v[220:221], v[204:205] op_sel:[1,1] op_sel_hi:[1,0]
	v_pk_fma_f32 v[8:9], v[220:221], v[204:205], v[8:9] op_sel_hi:[0,1,1] neg_lo:[0,0,1]
	v_mul_f32_e32 v210, 0x3f7b14be, v224
	v_mul_f32_e32 v211, 0xbe47c5c2, v224
	v_fmac_f32_e32 v210, 0x3e47c5c2, v225
	v_fmac_f32_e32 v211, 0x3f7b14be, v225
	s_waitcnt lgkmcnt(12)
	v_pk_add_f32 v[202:203], v[10:11], v[14:15]
	v_pk_add_f32 v[10:11], v[10:11], v[14:15] neg_lo:[0,1] neg_hi:[0,1]
	v_pk_add_f32 v[204:205], v[12:13], v[16:17]
	v_pk_add_f32 v[12:13], v[12:13], v[16:17] neg_lo:[0,1] neg_hi:[0,1]
	v_pk_add_f32 v[14:15], v[202:203], v[204:205]
	v_pk_add_f32 v[16:17], v[202:203], v[204:205] neg_lo:[0,1] neg_hi:[0,1]
	v_pk_add_f32 v[202:203], v[10:11], v[12:13] op_sel:[0,1] op_sel_hi:[1,0] neg_hi:[0,1]
	v_pk_add_f32 v[204:205], v[10:11], v[12:13] op_sel:[0,1] op_sel_hi:[1,0] neg_lo:[0,1]
	v_pk_mul_f32 v[206:207], v[210:211], v[210:211] op_sel:[1,1] op_sel_hi:[1,0]
	v_pk_fma_f32 v[212:213], v[210:211], v[210:211], v[206:207] op_sel_hi:[0,1,1] neg_lo:[0,0,1]
	v_pk_mul_f32 v[206:207], v[210:211], v[212:213] op_sel:[1,1] op_sel_hi:[1,0]
	v_pk_fma_f32 v[220:221], v[210:211], v[212:213], v[206:207] op_sel_hi:[0,1,1] neg_lo:[0,0,1]
	v_pk_mul_f32 v[10:11], v[210:211], v[202:203] op_sel:[1,1] op_sel_hi:[1,0]
	v_pk_fma_f32 v[10:11], v[210:211], v[202:203], v[10:11] op_sel_hi:[0,1,1] neg_lo:[0,0,1]
	v_pk_mul_f32 v[12:13], v[212:213], v[16:17] op_sel:[1,1] op_sel_hi:[1,0]
	v_pk_fma_f32 v[12:13], v[212:213], v[16:17], v[12:13] op_sel_hi:[0,1,1] neg_lo:[0,0,1]
	v_pk_mul_f32 v[16:17], v[220:221], v[204:205] op_sel:[1,1] op_sel_hi:[1,0]
	v_pk_fma_f32 v[16:17], v[220:221], v[204:205], v[16:17] op_sel_hi:[0,1,1] neg_lo:[0,0,1]
	v_mul_f32_e32 v210, 0x3f6c835e, v224
	v_mul_f32_e32 v211, 0xbec3ef15, v224
	v_fmac_f32_e32 v210, 0x3ec3ef15, v225
	v_fmac_f32_e32 v211, 0x3f6c835e, v225
	s_waitcnt lgkmcnt(10)
	v_pk_add_f32 v[202:203], v[18:19], v[22:23]
	v_pk_add_f32 v[18:19], v[18:19], v[22:23] neg_lo:[0,1] neg_hi:[0,1]
	v_pk_add_f32 v[204:205], v[20:21], v[24:25]
	v_pk_add_f32 v[20:21], v[20:21], v[24:25] neg_lo:[0,1] neg_hi:[0,1]
	v_pk_add_f32 v[22:23], v[202:203], v[204:205]
	v_pk_add_f32 v[24:25], v[202:203], v[204:205] neg_lo:[0,1] neg_hi:[0,1]
	v_pk_add_f32 v[202:203], v[18:19], v[20:21] op_sel:[0,1] op_sel_hi:[1,0] neg_hi:[0,1]
	v_pk_add_f32 v[204:205], v[18:19], v[20:21] op_sel:[0,1] op_sel_hi:[1,0] neg_lo:[0,1]
	v_pk_mul_f32 v[206:207], v[210:211], v[210:211] op_sel:[1,1] op_sel_hi:[1,0]
	v_pk_fma_f32 v[212:213], v[210:211], v[210:211], v[206:207] op_sel_hi:[0,1,1] neg_lo:[0,0,1]
	v_pk_mul_f32 v[206:207], v[210:211], v[212:213] op_sel:[1,1] op_sel_hi:[1,0]
	v_pk_fma_f32 v[220:221], v[210:211], v[212:213], v[206:207] op_sel_hi:[0,1,1] neg_lo:[0,0,1]
	v_pk_mul_f32 v[18:19], v[210:211], v[202:203] op_sel:[1,1] op_sel_hi:[1,0]
	v_pk_fma_f32 v[18:19], v[210:211], v[202:203], v[18:19] op_sel_hi:[0,1,1] neg_lo:[0,0,1]
	v_pk_mul_f32 v[20:21], v[212:213], v[24:25] op_sel:[1,1] op_sel_hi:[1,0]
	v_pk_fma_f32 v[20:21], v[212:213], v[24:25], v[20:21] op_sel_hi:[0,1,1] neg_lo:[0,0,1]
	v_pk_mul_f32 v[24:25], v[220:221], v[204:205] op_sel:[1,1] op_sel_hi:[1,0]
	v_pk_fma_f32 v[24:25], v[220:221], v[204:205], v[24:25] op_sel_hi:[0,1,1] neg_lo:[0,0,1]
	v_mul_f32_e32 v210, 0x3f54db31, v224
	v_mul_f32_e32 v211, 0xbf0e39da, v224
	v_fmac_f32_e32 v210, 0x3f0e39da, v225
	v_fmac_f32_e32 v211, 0x3f54db31, v225
	s_waitcnt lgkmcnt(8)
; DI f32x2 cmul(f32x2 a, f32x2 b) { return mkf2(a.x * b.x - a.y * b.y, a.x * b.y + a.y * b.x); }
; DI void fft8192(f32x2* buf, const f32x2* __restrict__ tw) {
;     ...
; #pragma unroll
;     for (int e = 0; e < 8; ++e) {
;       const int i = tid + 256 * e;
;       const int q = i & (s - 1);
;       const int ps = i - q;
;       const float rev = (float)ps * (1.f / 8192.f);
;       const f32x2 w1 = mkf2(__builtin_amdgcn_cosf(rev), -__builtin_amdgcn_sinf(rev));
;       const f32x2 w2 = cmul(w1, w1), w3 = cmul(w1, w2);
;       const f32x2 apc = mkf2(a[e].x + c[e].x, a[e].y + c[e].y), amc = mkf2(a[e].x - c[e].x, a[e].y - c[e].y);
;       const f32x2 bpd = mkf2(b[e].x + d[e].x, b[e].y + d[e].y), bmd = mkf2(b[e].x - d[e].x, b[e].y - d[e].y);
;       const int o = 4 * i - 3 * q;
;       buf[SW(o)] = mkf2(apc.x + bpd.x, apc.y + bpd.y);
;       buf[SW(o + s)] = cmul(w1, mkf2(amc.x + bmd.y, amc.y - bmd.x));
;       buf[SW(o + 2 * s)] = cmul(w2, mkf2(apc.x - bpd.x, apc.y - bpd.y));
;       buf[SW(o + 3 * s)] = cmul(w3, mkf2(amc.x - bmd.y, amc.y + bmd.x));
;     }
	v_pk_add_f32 v[202:203], v[26:27], v[30:31]
	v_pk_add_f32 v[26:27], v[26:27], v[30:31] neg_lo:[0,1] neg_hi:[0,1]
	v_pk_add_f32 v[204:205], v[28:29], v[32:33]
	v_pk_add_f32 v[28:29], v[28:29], v[32:33] neg_lo:[0,1] neg_hi:[0,1]
	v_pk_add_f32 v[30:31], v[202:203], v[204:205]
	v_pk_add_f32 v[32:33], v[202:203], v[204:205] neg_lo:[0,1] neg_hi:[0,1]
	v_pk_add_f32 v[202:203], v[26:27], v[28:29] op_sel:[0,1] op_sel_hi:[1,0] neg_hi:[0,1]
	v_pk_add_f32 v[204:205], v[26:27], v[28:29] op_sel:[0,1] op_sel_hi:[1,0] neg_lo:[0,1]
	v_pk_mul_f32 v[206:207], v[210:211], v[210:211] op_sel:[1,1] op_sel_hi:[1,0]
	v_pk_fma_f32 v[212:213], v[210:211], v[210:211], v[206:207] op_sel_hi:[0,1,1] neg_lo:[0,0,1]
	v_pk_mul_f32 v[206:207], v[210:211], v[212:213] op_sel:[1,1] op_sel_hi:[1,0]
	v_pk_fma_f32 v[220:221], v[210:211], v[212:213], v[206:207] op_sel_hi:[0,1,1] neg_lo:[0,0,1]
	v_pk_mul_f32 v[26:27], v[210:211], v[202:203] op_sel:[1,1] op_sel_hi:[1,0]
	v_pk_fma_f32 v[26:27], v[210:211], v[202:203], v[26:27] op_sel_hi:[0,1,1] neg_lo:[0,0,1]
	v_pk_mul_f32 v[28:29], v[212:213], v[32:33] op_sel:[1,1] op_sel_hi:[1,0]
	v_pk_fma_f32 v[28:29], v[212:213], v[32:33], v[28:29] op_sel_hi:[0,1,1] neg_lo:[0,0,1]
	v_pk_mul_f32 v[32:33], v[220:221], v[204:205] op_sel:[1,1] op_sel_hi:[1,0]
	v_pk_fma_f32 v[32:33], v[220:221], v[204:205], v[32:33] op_sel_hi:[0,1,1] neg_lo:[0,0,1]
	v_mul_f32_e32 v210, 0x3f3504f3, v224
	v_mul_f32_e32 v211, 0xbf3504f3, v224
	v_fmac_f32_e32 v210, 0x3f3504f3, v225
	v_fmac_f32_e32 v211, 0x3f3504f3, v225
	s_waitcnt lgkmcnt(6)
	v_pk_add_f32 v[202:203], v[34:35], v[38:39]
	v_pk_add_f32 v[34:35], v[34:35], v[38:39] neg_lo:[0,1] neg_hi:[0,1]
	v_pk_add_f32 v[204:205], v[36:37], v[40:41]
	v_pk_add_f32 v[36:37], v[36:37], v[40:41] neg_lo:[0,1] neg_hi:[0,1]
	v_pk_add_f32 v[38:39], v[202:203], v[204:205]
	v_pk_add_f32 v[40:41], v[202:203], v[204:205] neg_lo:[0,1] neg_hi:[0,1]
	v_pk_add_f32 v[202:203], v[34:35], v[36:37] op_sel:[0,1] op_sel_hi:[1,0] neg_hi:[0,1]
	v_pk_add_f32 v[204:205], v[34:35], v[36:37] op_sel:[0,1] op_sel_hi:[1,0] neg_lo:[0,1]
	v_pk_mul_f32 v[206:207], v[210:211], v[210:211] op_sel:[1,1] op_sel_hi:[1,0]
	v_pk_fma_f32 v[212:213], v[210:211], v[210:211], v[206:207] op_sel_hi:[0,1,1] neg_lo:[0,0,1]
	v_pk_mul_f32 v[206:207], v[210:211], v[212:213] op_sel:[1,1] op_sel_hi:[1,0]
	v_pk_fma_f32 v[220:221], v[210:211], v[212:213], v[206:207] op_sel_hi:[0,1,1] neg_lo:[0,0,1]
	v_pk_mul_f32 v[34:35], v[210:211], v[202:203] op_sel:[1,1] op_sel_hi:[1,0]
	v_pk_fma_f32 v[34:35], v[210:211], v[202:203], v[34:35] op_sel_hi:[0,1,1] neg_lo:[0,0,1]
	v_pk_mul_f32 v[36:37], v[212:213], v[40:41] op_sel:[1,1] op_sel_hi:[1,0]
	v_pk_fma_f32 v[36:37], v[212:213], v[40:41], v[36:37] op_sel_hi:[0,1,1] neg_lo:[0,0,1]
	v_pk_mul_f32 v[40:41], v[220:221], v[204:205] op_sel:[1,1] op_sel_hi:[1,0]
	v_pk_fma_f32 v[40:41], v[220:221], v[204:205], v[40:41] op_sel_hi:[0,1,1] neg_lo:[0,0,1]
	v_mul_f32_e32 v210, 0x3f0e39da, v224
	v_mul_f32_e32 v211, 0xbf54db31, v224
	v_fmac_f32_e32 v210, 0x3f54db31, v225
	v_fmac_f32_e32 v211, 0x3f0e39da, v225
	s_waitcnt lgkmcnt(4)
	v_pk_add_f32 v[202:203], v[42:43], v[46:47]
	v_pk_add_f32 v[42:43], v[42:43], v[46:47] neg_lo:[0,1] neg_hi:[0,1]
	v_pk_add_f32 v[204:205], v[44:45], v[48:49]
	v_pk_add_f32 v[44:45], v[44:45], v[48:49] neg_lo:[0,1] neg_hi:[0,1]
	v_pk_add_f32 v[46:47], v[202:203], v[204:205]
	v_pk_add_f32 v[48:49], v[202:203], v[204:205] neg_lo:[0,1] neg_hi:[0,1]
	v_pk_add_f32 v[202:203], v[42:43], v[44:45] op_sel:[0,1] op_sel_hi:[1,0] neg_hi:[0,1]
	v_pk_add_f32 v[204:205], v[42:43], v[44:45] op_sel:[0,1] op_sel_hi:[1,0] neg_lo:[0,1]
	v_pk_mul_f32 v[206:207], v[210:211], v[210:211] op_sel:[1,1] op_sel_hi:[1,0]
	v_pk_fma_f32 v[212:213], v[210:211], v[210:211], v[206:207] op_sel_hi:[0,1,1] neg_lo:[0,0,1]
	v_pk_mul_f32 v[206:207], v[210:211], v[212:213] op_sel:[1,1] op_sel_hi:[1,0]
	v_pk_fma_f32 v[220:221], v[210:211], v[212:213], v[206:207] op_sel_hi:[0,1,1] neg_lo:[0,0,1]
	v_pk_mul_f32 v[42:43], v[210:211], v[202:203] op_sel:[1,1] op_sel_hi:[1,0]
	v_pk_fma_f32 v[42:43], v[210:211], v[202:203], v[42:43] op_sel_hi:[0,1,1] neg_lo:[0,0,1]
	v_pk_mul_f32 v[44:45], v[212:213], v[48:49] op_sel:[1,1] op_sel_hi:[1,0]
	v_pk_fma_f32 v[44:45], v[212:213], v[48:49], v[44:45] op_sel_hi:[0,1,1] neg_lo:[0,0,1]
	v_pk_mul_f32 v[48:49], v[220:221], v[204:205] op_sel:[1,1] op_sel_hi:[1,0]
	v_pk_fma_f32 v[48:49], v[220:221], v[204:205], v[48:49] op_sel_hi:[0,1,1] neg_lo:[0,0,1]
	v_mul_f32_e32 v210, 0x3ec3ef15, v224
	v_mul_f32_e32 v211, 0xbf6c835e, v224
	v_fmac_f32_e32 v210, 0x3f6c835e, v225
	v_fmac_f32_e32 v211, 0x3ec3ef15, v225
	s_waitcnt lgkmcnt(2)
	v_pk_add_f32 v[202:203], v[50:51], v[54:55]
	v_pk_add_f32 v[50:51], v[50:51], v[54:55] neg_lo:[0,1] neg_hi:[0,1]
	v_pk_add_f32 v[204:205], v[52:53], v[56:57]
	v_pk_add_f32 v[52:53], v[52:53], v[56:57] neg_lo:[0,1] neg_hi:[0,1]
	v_pk_add_f32 v[54:55], v[202:203], v[204:205]
	v_pk_add_f32 v[56:57], v[202:203], v[204:205] neg_lo:[0,1] neg_hi:[0,1]
	v_pk_add_f32 v[202:203], v[50:51], v[52:53] op_sel:[0,1] op_sel_hi:[1,0] neg_hi:[0,1]
	v_pk_add_f32 v[204:205], v[50:51], v[52:53] op_sel:[0,1] op_sel_hi:[1,0] neg_lo:[0,1]
	v_pk_mul_f32 v[206:207], v[210:211], v[210:211] op_sel:[1,1] op_sel_hi:[1,0]
	v_pk_fma_f32 v[212:213], v[210:211], v[210:211], v[206:207] op_sel_hi:[0,1,1] neg_lo:[0,0,1]
	v_pk_mul_f32 v[206:207], v[210:211], v[212:213] op_sel:[1,1] op_sel_hi:[1,0]
	v_pk_fma_f32 v[220:221], v[210:211], v[212:213], v[206:207] op_sel_hi:[0,1,1] neg_lo:[0,0,1]
	v_pk_mul_f32 v[50:51], v[210:211], v[202:203] op_sel:[1,1] op_sel_hi:[1,0]
	v_pk_fma_f32 v[50:51], v[210:211], v[202:203], v[50:51] op_sel_hi:[0,1,1] neg_lo:[0,0,1]
	v_pk_mul_f32 v[52:53], v[212:213], v[56:57] op_sel:[1,1] op_sel_hi:[1,0]
	v_pk_fma_f32 v[52:53], v[212:213], v[56:57], v[52:53] op_sel_hi:[0,1,1] neg_lo:[0,0,1]
	v_pk_mul_f32 v[56:57], v[220:221], v[204:205] op_sel:[1,1] op_sel_hi:[1,0]
	v_pk_fma_f32 v[56:57], v[220:221], v[204:205], v[56:57] op_sel_hi:[0,1,1] neg_lo:[0,0,1]
	v_mul_f32_e32 v210, 0x3e47c5c2, v224
	v_mul_f32_e32 v211, 0xbf7b14be, v224
	v_fmac_f32_e32 v210, 0x3f7b14be, v225
	v_fmac_f32_e32 v211, 0x3e47c5c2, v225
	s_waitcnt lgkmcnt(0)
; DI f32x2 cmul(f32x2 a, f32x2 b) { return mkf2(a.x * b.x - a.y * b.y, a.x * b.y + a.y * b.x); }
; DI void fft8192(f32x2* buf, const f32x2* __restrict__ tw) {
;     ...
; #pragma unroll
;     for (int e = 0; e < 8; ++e) {
;       const int i = tid + 256 * e;
;       const int q = i & (s - 1);
;       const int ps = i - q;
;       const float rev = (float)ps * (1.f / 8192.f);
;       const f32x2 w1 = mkf2(__builtin_amdgcn_cosf(rev), -__builtin_amdgcn_sinf(rev));
;       const f32x2 w2 = cmul(w1, w1), w3 = cmul(w1, w2);
;       const f32x2 apc = mkf2(a[e].x + c[e].x, a[e].y + c[e].y), amc = mkf2(a[e].x - c[e].x, a[e].y - c[e].y);
;       const f32x2 bpd = mkf2(b[e].x + d[e].x, b[e].y + d[e].y), bmd = mkf2(b[e].x - d[e].x, b[e].y - d[e].y);
;       const int o = 4 * i - 3 * q;
;       buf[SW(o)] = mkf2(apc.x + bpd.x, apc.y + bpd.y);
;       buf[SW(o + s)] = cmul(w1, mkf2(amc.x + bmd.y, amc.y - bmd.x));
;       buf[SW(o + 2 * s)] = cmul(w2, mkf2(apc.x - bpd.x, apc.y - bpd.y));
;       buf[SW(o + 3 * s)] = cmul(w3, mkf2(amc.x - bmd.y, amc.y + bmd.x));
;     }
	v_pk_add_f32 v[202:203], v[58:59], v[62:63]
	v_pk_add_f32 v[58:59], v[58:59], v[62:63] neg_lo:[0,1] neg_hi:[0,1]
	v_pk_add_f32 v[204:205], v[60:61], v[64:65]
	v_pk_add_f32 v[60:61], v[60:61], v[64:65] neg_lo:[0,1] neg_hi:[0,1]
	v_pk_add_f32 v[62:63], v[202:203], v[204:205]
	v_pk_add_f32 v[64:65], v[202:203], v[204:205] neg_lo:[0,1] neg_hi:[0,1]
	v_pk_add_f32 v[202:203], v[58:59], v[60:61] op_sel:[0,1] op_sel_hi:[1,0] neg_hi:[0,1]
	v_pk_add_f32 v[204:205], v[58:59], v[60:61] op_sel:[0,1] op_sel_hi:[1,0] neg_lo:[0,1]
	v_pk_mul_f32 v[206:207], v[210:211], v[210:211] op_sel:[1,1] op_sel_hi:[1,0]
	v_pk_fma_f32 v[212:213], v[210:211], v[210:211], v[206:207] op_sel_hi:[0,1,1] neg_lo:[0,0,1]
	v_pk_mul_f32 v[206:207], v[210:211], v[212:213] op_sel:[1,1] op_sel_hi:[1,0]
	v_pk_fma_f32 v[220:221], v[210:211], v[212:213], v[206:207] op_sel_hi:[0,1,1] neg_lo:[0,0,1]
	v_pk_mul_f32 v[58:59], v[210:211], v[202:203] op_sel:[1,1] op_sel_hi:[1,0]
	v_pk_fma_f32 v[58:59], v[210:211], v[202:203], v[58:59] op_sel_hi:[0,1,1] neg_lo:[0,0,1]
	v_pk_mul_f32 v[60:61], v[212:213], v[64:65] op_sel:[1,1] op_sel_hi:[1,0]
	v_pk_fma_f32 v[60:61], v[212:213], v[64:65], v[60:61] op_sel_hi:[0,1,1] neg_lo:[0,0,1]
	v_pk_mul_f32 v[64:65], v[220:221], v[204:205] op_sel:[1,1] op_sel_hi:[1,0]
	v_pk_fma_f32 v[64:65], v[220:221], v[204:205], v[64:65] op_sel_hi:[0,1,1] neg_lo:[0,0,1]
	s_barrier
	v_mul_f32_e32 v214, 4.0, v201
	v_cos_f32_e32 v224, v214
	v_sin_f32_e64 v225, -v214
	s_nop 0
	v_pk_mul_f32 v[206:207], v[224:225], v[224:225] op_sel:[1,1] op_sel_hi:[1,0]
	v_pk_fma_f32 v[226:227], v[224:225], v[224:225], v[206:207] op_sel_hi:[0,1,1] neg_lo:[0,0,1]
	v_pk_mul_f32 v[206:207], v[224:225], v[226:227] op_sel:[1,1] op_sel_hi:[1,0]
	v_pk_fma_f32 v[230:231], v[224:225], v[226:227], v[206:207] op_sel_hi:[0,1,1] neg_lo:[0,0,1]
	v_pk_add_f32 v[202:203], v[6:7], v[38:39]
	v_pk_add_f32 v[6:7], v[6:7], v[38:39] neg_lo:[0,1] neg_hi:[0,1]
	v_pk_add_f32 v[204:205], v[22:23], v[54:55]
	v_pk_add_f32 v[22:23], v[22:23], v[54:55] neg_lo:[0,1] neg_hi:[0,1]
	v_pk_add_f32 v[38:39], v[202:203], v[204:205]
	v_pk_add_f32 v[54:55], v[202:203], v[204:205] neg_lo:[0,1] neg_hi:[0,1]
	v_pk_add_f32 v[202:203], v[6:7], v[22:23] op_sel:[0,1] op_sel_hi:[1,0] neg_hi:[0,1]
	v_pk_add_f32 v[204:205], v[6:7], v[22:23] op_sel:[0,1] op_sel_hi:[1,0] neg_lo:[0,1]
	v_pk_mul_f32 v[6:7], v[224:225], v[202:203] op_sel:[1,1] op_sel_hi:[1,0]
	v_pk_fma_f32 v[6:7], v[224:225], v[202:203], v[6:7] op_sel_hi:[0,1,1] neg_lo:[0,0,1]
	v_pk_mul_f32 v[22:23], v[226:227], v[54:55] op_sel:[1,1] op_sel_hi:[1,0]
	v_pk_fma_f32 v[22:23], v[226:227], v[54:55], v[22:23] op_sel_hi:[0,1,1] neg_lo:[0,0,1]
	v_pk_mul_f32 v[54:55], v[230:231], v[204:205] op_sel:[1,1] op_sel_hi:[1,0]
	v_pk_fma_f32 v[54:55], v[230:231], v[204:205], v[54:55] op_sel_hi:[0,1,1] neg_lo:[0,0,1]
	v_pk_add_f32 v[202:203], v[2:3], v[34:35]
	v_pk_add_f32 v[2:3], v[2:3], v[34:35] neg_lo:[0,1] neg_hi:[0,1]
	v_pk_add_f32 v[204:205], v[18:19], v[50:51]
	v_pk_add_f32 v[18:19], v[18:19], v[50:51] neg_lo:[0,1] neg_hi:[0,1]
	v_pk_add_f32 v[34:35], v[202:203], v[204:205]
	v_pk_add_f32 v[50:51], v[202:203], v[204:205] neg_lo:[0,1] neg_hi:[0,1]
	v_pk_add_f32 v[202:203], v[2:3], v[18:19] op_sel:[0,1] op_sel_hi:[1,0] neg_hi:[0,1]
	v_pk_add_f32 v[204:205], v[2:3], v[18:19] op_sel:[0,1] op_sel_hi:[1,0] neg_lo:[0,1]
	v_pk_mul_f32 v[2:3], v[224:225], v[202:203] op_sel:[1,1] op_sel_hi:[1,0]
	v_pk_fma_f32 v[2:3], v[224:225], v[202:203], v[2:3] op_sel_hi:[0,1,1] neg_lo:[0,0,1]
	v_pk_mul_f32 v[18:19], v[226:227], v[50:51] op_sel:[1,1] op_sel_hi:[1,0]
	v_pk_fma_f32 v[18:19], v[226:227], v[50:51], v[18:19] op_sel_hi:[0,1,1] neg_lo:[0,0,1]
	v_pk_mul_f32 v[50:51], v[230:231], v[204:205] op_sel:[1,1] op_sel_hi:[1,0]
	v_pk_fma_f32 v[50:51], v[230:231], v[204:205], v[50:51] op_sel_hi:[0,1,1] neg_lo:[0,0,1]
	v_pk_add_f32 v[202:203], v[4:5], v[36:37]
	v_pk_add_f32 v[4:5], v[4:5], v[36:37] neg_lo:[0,1] neg_hi:[0,1]
	v_pk_add_f32 v[204:205], v[20:21], v[52:53]
	v_pk_add_f32 v[20:21], v[20:21], v[52:53] neg_lo:[0,1] neg_hi:[0,1]
	v_pk_add_f32 v[36:37], v[202:203], v[204:205]
	v_pk_add_f32 v[52:53], v[202:203], v[204:205] neg_lo:[0,1] neg_hi:[0,1]
	v_pk_add_f32 v[202:203], v[4:5], v[20:21] op_sel:[0,1] op_sel_hi:[1,0] neg_hi:[0,1]
	v_pk_add_f32 v[204:205], v[4:5], v[20:21] op_sel:[0,1] op_sel_hi:[1,0] neg_lo:[0,1]
	v_pk_mul_f32 v[4:5], v[224:225], v[202:203] op_sel:[1,1] op_sel_hi:[1,0]
	v_pk_fma_f32 v[4:5], v[224:225], v[202:203], v[4:5] op_sel_hi:[0,1,1] neg_lo:[0,0,1]
	v_pk_mul_f32 v[20:21], v[226:227], v[52:53] op_sel:[1,1] op_sel_hi:[1,0]
	v_pk_fma_f32 v[20:21], v[226:227], v[52:53], v[20:21] op_sel_hi:[0,1,1] neg_lo:[0,0,1]
	v_pk_mul_f32 v[52:53], v[230:231], v[204:205] op_sel:[1,1] op_sel_hi:[1,0]
	v_pk_fma_f32 v[52:53], v[230:231], v[204:205], v[52:53] op_sel_hi:[0,1,1] neg_lo:[0,0,1]
	v_pk_add_f32 v[202:203], v[8:9], v[40:41]
	v_pk_add_f32 v[8:9], v[8:9], v[40:41] neg_lo:[0,1] neg_hi:[0,1]
	v_pk_add_f32 v[204:205], v[24:25], v[56:57]
	v_pk_add_f32 v[24:25], v[24:25], v[56:57] neg_lo:[0,1] neg_hi:[0,1]
	v_pk_add_f32 v[40:41], v[202:203], v[204:205]
	v_pk_add_f32 v[56:57], v[202:203], v[204:205] neg_lo:[0,1] neg_hi:[0,1]
	v_pk_add_f32 v[202:203], v[8:9], v[24:25] op_sel:[0,1] op_sel_hi:[1,0] neg_hi:[0,1]
	v_pk_add_f32 v[204:205], v[8:9], v[24:25] op_sel:[0,1] op_sel_hi:[1,0] neg_lo:[0,1]
	v_pk_mul_f32 v[8:9], v[224:225], v[202:203] op_sel:[1,1] op_sel_hi:[1,0]
	v_pk_fma_f32 v[8:9], v[224:225], v[202:203], v[8:9] op_sel_hi:[0,1,1] neg_lo:[0,0,1]
	v_pk_mul_f32 v[24:25], v[226:227], v[56:57] op_sel:[1,1] op_sel_hi:[1,0]
	v_pk_fma_f32 v[24:25], v[226:227], v[56:57], v[24:25] op_sel_hi:[0,1,1] neg_lo:[0,0,1]
; DI f32x2 cmul(f32x2 a, f32x2 b) { return mkf2(a.x * b.x - a.y * b.y, a.x * b.y + a.y * b.x); }
; DI void fft8192(f32x2* buf, const f32x2* __restrict__ tw) {
;     ...
; #pragma unroll
;     for (int e = 0; e < 8; ++e) {
;       const int i = tid + 256 * e;
;       const int q = i & (s - 1);
;       const int ps = i - q;
;       const float rev = (float)ps * (1.f / 8192.f);
;       const f32x2 w1 = mkf2(__builtin_amdgcn_cosf(rev), -__builtin_amdgcn_sinf(rev));
;       const f32x2 w2 = cmul(w1, w1), w3 = cmul(w1, w2);
;       const f32x2 apc = mkf2(a[e].x + c[e].x, a[e].y + c[e].y), amc = mkf2(a[e].x - c[e].x, a[e].y - c[e].y);
;       const f32x2 bpd = mkf2(b[e].x + d[e].x, b[e].y + d[e].y), bmd = mkf2(b[e].x - d[e].x, b[e].y - d[e].y);
;       const int o = 4 * i - 3 * q;
;       buf[SW(o)] = mkf2(apc.x + bpd.x, apc.y + bpd.y);
;       buf[SW(o + s)] = cmul(w1, mkf2(amc.x + bmd.y, amc.y - bmd.x));
;       buf[SW(o + 2 * s)] = cmul(w2, mkf2(apc.x - bpd.x, apc.y - bpd.y));
;       buf[SW(o + 3 * s)] = cmul(w3, mkf2(amc.x - bmd.y, amc.y + bmd.x));
;     }
	v_pk_mul_f32 v[56:57], v[230:231], v[204:205] op_sel:[1,1] op_sel_hi:[1,0]
	v_pk_fma_f32 v[56:57], v[230:231], v[204:205], v[56:57] op_sel_hi:[0,1,1] neg_lo:[0,0,1]
	v_mul_f32_e32 v214, 4.0, v201
	v_add_f32_e32 v214, 0x3e000000, v214
	v_cos_f32_e32 v224, v214
	v_sin_f32_e64 v225, -v214
	s_nop 0
	v_pk_mul_f32 v[206:207], v[224:225], v[224:225] op_sel:[1,1] op_sel_hi:[1,0]
	v_pk_fma_f32 v[226:227], v[224:225], v[224:225], v[206:207] op_sel_hi:[0,1,1] neg_lo:[0,0,1]
	v_pk_mul_f32 v[206:207], v[224:225], v[226:227] op_sel:[1,1] op_sel_hi:[1,0]
	v_pk_fma_f32 v[230:231], v[224:225], v[226:227], v[206:207] op_sel_hi:[0,1,1] neg_lo:[0,0,1]
	v_pk_add_f32 v[202:203], v[14:15], v[46:47]
	v_pk_add_f32 v[14:15], v[14:15], v[46:47] neg_lo:[0,1] neg_hi:[0,1]
	v_pk_add_f32 v[204:205], v[30:31], v[62:63]
	v_pk_add_f32 v[30:31], v[30:31], v[62:63] neg_lo:[0,1] neg_hi:[0,1]
	v_pk_add_f32 v[46:47], v[202:203], v[204:205]
	v_pk_add_f32 v[62:63], v[202:203], v[204:205] neg_lo:[0,1] neg_hi:[0,1]
	v_pk_add_f32 v[202:203], v[14:15], v[30:31] op_sel:[0,1] op_sel_hi:[1,0] neg_hi:[0,1]
	v_pk_add_f32 v[204:205], v[14:15], v[30:31] op_sel:[0,1] op_sel_hi:[1,0] neg_lo:[0,1]
	v_pk_mul_f32 v[14:15], v[224:225], v[202:203] op_sel:[1,1] op_sel_hi:[1,0]
	v_pk_fma_f32 v[14:15], v[224:225], v[202:203], v[14:15] op_sel_hi:[0,1,1] neg_lo:[0,0,1]
	v_pk_mul_f32 v[30:31], v[226:227], v[62:63] op_sel:[1,1] op_sel_hi:[1,0]
	v_pk_fma_f32 v[30:31], v[226:227], v[62:63], v[30:31] op_sel_hi:[0,1,1] neg_lo:[0,0,1]
	v_pk_mul_f32 v[62:63], v[230:231], v[204:205] op_sel:[1,1] op_sel_hi:[1,0]
	v_pk_fma_f32 v[62:63], v[230:231], v[204:205], v[62:63] op_sel_hi:[0,1,1] neg_lo:[0,0,1]
	v_pk_add_f32 v[202:203], v[10:11], v[42:43]
	v_pk_add_f32 v[10:11], v[10:11], v[42:43] neg_lo:[0,1] neg_hi:[0,1]
	v_pk_add_f32 v[204:205], v[26:27], v[58:59]
	v_pk_add_f32 v[26:27], v[26:27], v[58:59] neg_lo:[0,1] neg_hi:[0,1]
	v_pk_add_f32 v[42:43], v[202:203], v[204:205]
	v_pk_add_f32 v[58:59], v[202:203], v[204:205] neg_lo:[0,1] neg_hi:[0,1]
	v_pk_add_f32 v[202:203], v[10:11], v[26:27] op_sel:[0,1] op_sel_hi:[1,0] neg_hi:[0,1]
	v_pk_add_f32 v[204:205], v[10:11], v[26:27] op_sel:[0,1] op_sel_hi:[1,0] neg_lo:[0,1]
	v_pk_mul_f32 v[10:11], v[224:225], v[202:203] op_sel:[1,1] op_sel_hi:[1,0]
	v_pk_fma_f32 v[10:11], v[224:225], v[202:203], v[10:11] op_sel_hi:[0,1,1] neg_lo:[0,0,1]
	v_pk_mul_f32 v[26:27], v[226:227], v[58:59] op_sel:[1,1] op_sel_hi:[1,0]
	v_pk_fma_f32 v[26:27], v[226:227], v[58:59], v[26:27] op_sel_hi:[0,1,1] neg_lo:[0,0,1]
	v_pk_mul_f32 v[58:59], v[230:231], v[204:205] op_sel:[1,1] op_sel_hi:[1,0]
	v_pk_fma_f32 v[58:59], v[230:231], v[204:205], v[58:59] op_sel_hi:[0,1,1] neg_lo:[0,0,1]
	v_pk_add_f32 v[202:203], v[12:13], v[44:45]
	v_pk_add_f32 v[12:13], v[12:13], v[44:45] neg_lo:[0,1] neg_hi:[0,1]
	v_pk_add_f32 v[204:205], v[28:29], v[60:61]
	v_pk_add_f32 v[28:29], v[28:29], v[60:61] neg_lo:[0,1] neg_hi:[0,1]
	v_pk_add_f32 v[44:45], v[202:203], v[204:205]
	v_pk_add_f32 v[60:61], v[202:203], v[204:205] neg_lo:[0,1] neg_hi:[0,1]
	v_pk_add_f32 v[202:203], v[12:13], v[28:29] op_sel:[0,1] op_sel_hi:[1,0] neg_hi:[0,1]
	v_pk_add_f32 v[204:205], v[12:13], v[28:29] op_sel:[0,1] op_sel_hi:[1,0] neg_lo:[0,1]
	v_pk_mul_f32 v[12:13], v[224:225], v[202:203] op_sel:[1,1] op_sel_hi:[1,0]
	v_pk_fma_f32 v[12:13], v[224:225], v[202:203], v[12:13] op_sel_hi:[0,1,1] neg_lo:[0,0,1]
	v_pk_mul_f32 v[28:29], v[226:227], v[60:61] op_sel:[1,1] op_sel_hi:[1,0]
	v_pk_fma_f32 v[28:29], v[226:227], v[60:61], v[28:29] op_sel_hi:[0,1,1] neg_lo:[0,0,1]
	v_pk_mul_f32 v[60:61], v[230:231], v[204:205] op_sel:[1,1] op_sel_hi:[1,0]
	v_pk_fma_f32 v[60:61], v[230:231], v[204:205], v[60:61] op_sel_hi:[0,1,1] neg_lo:[0,0,1]
	v_pk_add_f32 v[202:203], v[16:17], v[48:49]
	v_pk_add_f32 v[16:17], v[16:17], v[48:49] neg_lo:[0,1] neg_hi:[0,1]
	v_pk_add_f32 v[204:205], v[32:33], v[64:65]
	v_pk_add_f32 v[32:33], v[32:33], v[64:65] neg_lo:[0,1] neg_hi:[0,1]
	v_pk_add_f32 v[48:49], v[202:203], v[204:205]
	v_pk_add_f32 v[64:65], v[202:203], v[204:205] neg_lo:[0,1] neg_hi:[0,1]
	v_pk_add_f32 v[202:203], v[16:17], v[32:33] op_sel:[0,1] op_sel_hi:[1,0] neg_hi:[0,1]
	v_pk_add_f32 v[204:205], v[16:17], v[32:33] op_sel:[0,1] op_sel_hi:[1,0] neg_lo:[0,1]
	v_pk_mul_f32 v[16:17], v[224:225], v[202:203] op_sel:[1,1] op_sel_hi:[1,0]
	v_pk_fma_f32 v[16:17], v[224:225], v[202:203], v[16:17] op_sel_hi:[0,1,1] neg_lo:[0,0,1]
	v_pk_mul_f32 v[32:33], v[226:227], v[64:65] op_sel:[1,1] op_sel_hi:[1,0]
	v_pk_fma_f32 v[32:33], v[226:227], v[64:65], v[32:33] op_sel_hi:[0,1,1] neg_lo:[0,0,1]
	v_pk_mul_f32 v[64:65], v[230:231], v[204:205] op_sel:[1,1] op_sel_hi:[1,0]
	v_pk_fma_f32 v[64:65], v[230:231], v[204:205], v[64:65] op_sel_hi:[0,1,1] neg_lo:[0,0,1]
	ds_write_b64 v164, v[38:39] offset:0
	v_xor_b32_e32 v156, 0x80, v164
	ds_write_b64 v156, v[34:35] offset:0
	v_xor_b32_e32 v158, 0x128, v164
	ds_write_b64 v158, v[36:37] offset:0
	v_xor_b32_e32 v160, 0x1a8, v164
	ds_write_b64 v160, v[40:41] offset:0
	v_xor_b32_e32 v162, 0x2d0, v164
	ds_write_b64 v162, v[6:7] offset:0
	v_xor_b32_e32 v156, 0x250, v164
	ds_write_b64 v156, v[2:3] offset:0
	v_xor_b32_e32 v158, 0x3f8, v164
	ds_write_b64 v158, v[4:5] offset:0
	v_xor_b32_e32 v160, 0x378, v164
	ds_write_b64 v160, v[8:9] offset:0
	v_xor_b32_e32 v162, 0x400, v164
	ds_write_b64 v162, v[22:23] offset:0
	v_xor_b32_e32 v156, 0x480, v164
	ds_write_b64 v156, v[18:19] offset:0
	v_xor_b32_e32 v158, 0x528, v164
	ds_write_b64 v158, v[20:21] offset:0
	v_xor_b32_e32 v160, 0x5a8, v164
	ds_write_b64 v160, v[24:25] offset:0
	v_xor_b32_e32 v162, 0x6d0, v164
	ds_write_b64 v162, v[54:55] offset:0
	v_xor_b32_e32 v156, 0x650, v164
	ds_write_b64 v156, v[50:51] offset:0
	v_xor_b32_e32 v158, 0x7f8, v164
	ds_write_b64 v158, v[52:53] offset:0
	v_xor_b32_e32 v160, 0x778, v164
	ds_write_b64 v160, v[56:57] offset:0
	ds_write_b64 v164, v[46:47] offset:32768
	v_xor_b32_e32 v162, 0x80, v164
	ds_write_b64 v162, v[42:43] offset:32768
	v_xor_b32_e32 v156, 0x128, v164
	ds_write_b64 v156, v[44:45] offset:32768
	v_xor_b32_e32 v158, 0x1a8, v164
	ds_write_b64 v158, v[48:49] offset:32768
	v_xor_b32_e32 v160, 0x2d0, v164
	ds_write_b64 v160, v[14:15] offset:32768
	v_xor_b32_e32 v162, 0x250, v164
	ds_write_b64 v162, v[10:11] offset:32768
	v_xor_b32_e32 v156, 0x3f8, v164
	ds_write_b64 v156, v[12:13] offset:32768
	v_xor_b32_e32 v158, 0x378, v164
	ds_write_b64 v158, v[16:17] offset:32768
	v_xor_b32_e32 v160, 0x400, v164
	ds_write_b64 v160, v[30:31] offset:32768
	v_xor_b32_e32 v162, 0x480, v164
	ds_write_b64 v162, v[26:27] offset:32768
	v_xor_b32_e32 v156, 0x528, v164
	ds_write_b64 v156, v[28:29] offset:32768
	v_xor_b32_e32 v158, 0x5a8, v164
	ds_write_b64 v158, v[32:33] offset:32768
	v_xor_b32_e32 v160, 0x6d0, v164
	ds_write_b64 v160, v[62:63] offset:32768
	v_xor_b32_e32 v162, 0x650, v164
	ds_write_b64 v162, v[58:59] offset:32768
	v_xor_b32_e32 v156, 0x7f8, v164
	ds_write_b64 v156, v[60:61] offset:32768
	v_xor_b32_e32 v158, 0x778, v164
	ds_write_b64 v158, v[64:65] offset:32768
	s_waitcnt lgkmcnt(0)
	s_barrier
; DI f32x2 cmul(f32x2 a, f32x2 b) { return mkf2(a.x * b.x - a.y * b.y, a.x * b.y + a.y * b.x); }
; DI void fft8192(f32x2* buf, const f32x2* __restrict__ tw) {
;     ...
;     __syncthreads();
; #pragma unroll
;     for (int e = 0; e < 8; ++e) {
;       const int i = tid + 256 * e;
;       const int pi = SW(i);
;       a[e] = buf[pi]; b[e] = buf[pi + 2048]; c[e] = buf[pi + 4096]; d[e] = buf[pi + 6144];
;     }
;     __syncthreads();
; #pragma unroll
;     for (int e = 0; e < 8; ++e) {
;       const int i = tid + 256 * e;
;       const int q = i & (s - 1);
;       const int ps = i - q;
;       const float rev = (float)ps * (1.f / 8192.f);
;       const f32x2 w1 = mkf2(__builtin_amdgcn_cosf(rev), -__builtin_amdgcn_sinf(rev));
;       const f32x2 w2 = cmul(w1, w1), w3 = cmul(w1, w2);
;       const f32x2 apc = mkf2(a[e].x + c[e].x, a[e].y + c[e].y), amc = mkf2(a[e].x - c[e].x, a[e].y - c[e].y);
;       const f32x2 bpd = mkf2(b[e].x + d[e].x, b[e].y + d[e].y), bmd = mkf2(b[e].x - d[e].x, b[e].y - d[e].y);
;       const int o = 4 * i - 3 * q;
;       buf[SW(o)] = mkf2(apc.x + bpd.x, apc.y + bpd.y);
;       buf[SW(o + s)] = cmul(w1, mkf2(amc.x + bmd.y, amc.y - bmd.x));
;       buf[SW(o + 2 * s)] = cmul(w2, mkf2(apc.x - bpd.x, apc.y - bpd.y));
;       buf[SW(o + 3 * s)] = cmul(w3, mkf2(amc.x - bmd.y, amc.y + bmd.x));
;     }
	ds_read2st64_b64 v[2:5], v154 offset0:0 offset1:32
	ds_read2st64_b64 v[6:9], v154 offset0:64 offset1:96
	ds_read2st64_b64 v[10:13], v154 offset0:4 offset1:36
	ds_read2st64_b64 v[14:17], v154 offset0:68 offset1:100
	ds_read2st64_b64 v[18:21], v154 offset0:8 offset1:40
	ds_read2st64_b64 v[22:25], v154 offset0:72 offset1:104
	ds_read2st64_b64 v[26:29], v154 offset0:12 offset1:44
	ds_read2st64_b64 v[30:33], v154 offset0:76 offset1:108
	ds_read2st64_b64 v[34:37], v154 offset0:16 offset1:48
	ds_read2st64_b64 v[38:41], v154 offset0:80 offset1:112
	ds_read2st64_b64 v[42:45], v154 offset0:20 offset1:52
	ds_read2st64_b64 v[46:49], v154 offset0:84 offset1:116
	ds_read2st64_b64 v[50:53], v154 offset0:24 offset1:56
	ds_read2st64_b64 v[54:57], v154 offset0:88 offset1:120
	ds_read2st64_b64 v[58:61], v154 offset0:28 offset1:60
	ds_read2st64_b64 v[62:65], v154 offset0:92 offset1:124
	s_waitcnt lgkmcnt(14)
	v_pk_add_f32 v[202:203], v[2:3], v[6:7]
	v_pk_add_f32 v[2:3], v[2:3], v[6:7] neg_lo:[0,1] neg_hi:[0,1]
	v_pk_add_f32 v[204:205], v[4:5], v[8:9]
	v_pk_add_f32 v[4:5], v[4:5], v[8:9] neg_lo:[0,1] neg_hi:[0,1]
	v_pk_add_f32 v[6:7], v[202:203], v[204:205]
	v_pk_add_f32 v[8:9], v[202:203], v[204:205] neg_lo:[0,1] neg_hi:[0,1]
	v_pk_add_f32 v[202:203], v[2:3], v[4:5] op_sel:[0,1] op_sel_hi:[1,0] neg_hi:[0,1]
	v_pk_add_f32 v[4:5], v[2:3], v[4:5] op_sel:[0,1] op_sel_hi:[1,0] neg_lo:[0,1]
	v_pk_mov_b32 v[2:3], v[202:203], v[202:203] op_sel:[0,1]
	v_mov_b32_e32 v210, 0x3f7b14be
	v_mov_b32_e32 v211, 0xbe47c5c2
	v_mov_b32_e32 v212, 0x3f6c835e
	v_mov_b32_e32 v213, 0xbec3ef15
	v_mov_b32_e32 v220, 0x3f54db31
	v_mov_b32_e32 v221, 0xbf0e39da
	s_waitcnt lgkmcnt(12)
	v_pk_add_f32 v[202:203], v[10:11], v[14:15]
	v_pk_add_f32 v[10:11], v[10:11], v[14:15] neg_lo:[0,1] neg_hi:[0,1]
	v_pk_add_f32 v[204:205], v[12:13], v[16:17]
	v_pk_add_f32 v[12:13], v[12:13], v[16:17] neg_lo:[0,1] neg_hi:[0,1]
	v_pk_add_f32 v[14:15], v[202:203], v[204:205]
	v_pk_add_f32 v[16:17], v[202:203], v[204:205] neg_lo:[0,1] neg_hi:[0,1]
	v_pk_add_f32 v[202:203], v[10:11], v[12:13] op_sel:[0,1] op_sel_hi:[1,0] neg_hi:[0,1]
	v_pk_add_f32 v[204:205], v[10:11], v[12:13] op_sel:[0,1] op_sel_hi:[1,0] neg_lo:[0,1]
	v_pk_mul_f32 v[10:11], v[210:211], v[202:203] op_sel:[1,1] op_sel_hi:[1,0]
	v_pk_fma_f32 v[10:11], v[210:211], v[202:203], v[10:11] op_sel_hi:[0,1,1] neg_lo:[0,0,1]
	v_pk_mul_f32 v[12:13], v[212:213], v[16:17] op_sel:[1,1] op_sel_hi:[1,0]
	v_pk_fma_f32 v[12:13], v[212:213], v[16:17], v[12:13] op_sel_hi:[0,1,1] neg_lo:[0,0,1]
	v_pk_mul_f32 v[16:17], v[220:221], v[204:205] op_sel:[1,1] op_sel_hi:[1,0]
	v_pk_fma_f32 v[16:17], v[220:221], v[204:205], v[16:17] op_sel_hi:[0,1,1] neg_lo:[0,0,1]
	v_mov_b32_e32 v210, 0x3f6c835e
	v_mov_b32_e32 v211, 0xbec3ef15
	v_mov_b32_e32 v212, 0x3f3504f3
	v_mov_b32_e32 v213, 0xbf3504f3
	v_mov_b32_e32 v220, 0x3ec3ef15
	v_mov_b32_e32 v221, 0xbf6c835e
	s_waitcnt lgkmcnt(10)
	v_pk_add_f32 v[202:203], v[18:19], v[22:23]
	v_pk_add_f32 v[18:19], v[18:19], v[22:23] neg_lo:[0,1] neg_hi:[0,1]
	v_pk_add_f32 v[204:205], v[20:21], v[24:25]
	v_pk_add_f32 v[20:21], v[20:21], v[24:25] neg_lo:[0,1] neg_hi:[0,1]
	v_pk_add_f32 v[22:23], v[202:203], v[204:205]
	v_pk_add_f32 v[24:25], v[202:203], v[204:205] neg_lo:[0,1] neg_hi:[0,1]
	v_pk_add_f32 v[202:203], v[18:19], v[20:21] op_sel:[0,1] op_sel_hi:[1,0] neg_hi:[0,1]
	v_pk_add_f32 v[204:205], v[18:19], v[20:21] op_sel:[0,1] op_sel_hi:[1,0] neg_lo:[0,1]
	v_pk_mul_f32 v[18:19], v[210:211], v[202:203] op_sel:[1,1] op_sel_hi:[1,0]
	v_pk_fma_f32 v[18:19], v[210:211], v[202:203], v[18:19] op_sel_hi:[0,1,1] neg_lo:[0,0,1]
	v_pk_mul_f32 v[20:21], v[212:213], v[24:25] op_sel:[1,1] op_sel_hi:[1,0]
	v_pk_fma_f32 v[20:21], v[212:213], v[24:25], v[20:21] op_sel_hi:[0,1,1] neg_lo:[0,0,1]
	v_pk_mul_f32 v[24:25], v[220:221], v[204:205] op_sel:[1,1] op_sel_hi:[1,0]
	v_pk_fma_f32 v[24:25], v[220:221], v[204:205], v[24:25] op_sel_hi:[0,1,1] neg_lo:[0,0,1]
	v_mov_b32_e32 v210, 0x3f54db31
	v_mov_b32_e32 v211, 0xbf0e39da
	v_mov_b32_e32 v212, 0x3ec3ef15
	v_mov_b32_e32 v213, 0xbf6c835e
	v_mov_b32_e32 v220, 0xbe47c5c2
	v_mov_b32_e32 v221, 0xbf7b14be
	s_waitcnt lgkmcnt(8)
	v_pk_add_f32 v[202:203], v[26:27], v[30:31]
	v_pk_add_f32 v[26:27], v[26:27], v[30:31] neg_lo:[0,1] neg_hi:[0,1]
	v_pk_add_f32 v[204:205], v[28:29], v[32:33]
	v_pk_add_f32 v[28:29], v[28:29], v[32:33] neg_lo:[0,1] neg_hi:[0,1]
	v_pk_add_f32 v[30:31], v[202:203], v[204:205]
	v_pk_add_f32 v[32:33], v[202:203], v[204:205] neg_lo:[0,1] neg_hi:[0,1]
	v_pk_add_f32 v[202:203], v[26:27], v[28:29] op_sel:[0,1] op_sel_hi:[1,0] neg_hi:[0,1]
	v_pk_add_f32 v[204:205], v[26:27], v[28:29] op_sel:[0,1] op_sel_hi:[1,0] neg_lo:[0,1]
	v_pk_mul_f32 v[26:27], v[210:211], v[202:203] op_sel:[1,1] op_sel_hi:[1,0]
	v_pk_fma_f32 v[26:27], v[210:211], v[202:203], v[26:27] op_sel_hi:[0,1,1] neg_lo:[0,0,1]
	v_pk_mul_f32 v[28:29], v[212:213], v[32:33] op_sel:[1,1] op_sel_hi:[1,0]
	v_pk_fma_f32 v[28:29], v[212:213], v[32:33], v[28:29] op_sel_hi:[0,1,1] neg_lo:[0,0,1]
	v_pk_mul_f32 v[32:33], v[220:221], v[204:205] op_sel:[1,1] op_sel_hi:[1,0]
	v_pk_fma_f32 v[32:33], v[220:221], v[204:205], v[32:33] op_sel_hi:[0,1,1] neg_lo:[0,0,1]
	v_mov_b32_e32 v210, 0x3f3504f3
	v_mov_b32_e32 v211, 0xbf3504f3
	v_mov_b32_e32 v212, 0x248d3132
	v_mov_b32_e32 v213, 0xbf800000
	v_mov_b32_e32 v220, 0xbf3504f3
	v_mov_b32_e32 v221, 0xbf3504f3
	s_waitcnt lgkmcnt(6)
; DI f32x2 cmul(f32x2 a, f32x2 b) { return mkf2(a.x * b.x - a.y * b.y, a.x * b.y + a.y * b.x); }
; DI void fft8192(f32x2* buf, const f32x2* __restrict__ tw) {
;     ...
; #pragma unroll
;     for (int e = 0; e < 8; ++e) {
;       const int i = tid + 256 * e;
;       const int q = i & (s - 1);
;       const int ps = i - q;
;       const float rev = (float)ps * (1.f / 8192.f);
;       const f32x2 w1 = mkf2(__builtin_amdgcn_cosf(rev), -__builtin_amdgcn_sinf(rev));
;       const f32x2 w2 = cmul(w1, w1), w3 = cmul(w1, w2);
;       const f32x2 apc = mkf2(a[e].x + c[e].x, a[e].y + c[e].y), amc = mkf2(a[e].x - c[e].x, a[e].y - c[e].y);
;       const f32x2 bpd = mkf2(b[e].x + d[e].x, b[e].y + d[e].y), bmd = mkf2(b[e].x - d[e].x, b[e].y - d[e].y);
;       const int o = 4 * i - 3 * q;
;       buf[SW(o)] = mkf2(apc.x + bpd.x, apc.y + bpd.y);
;       buf[SW(o + s)] = cmul(w1, mkf2(amc.x + bmd.y, amc.y - bmd.x));
;       buf[SW(o + 2 * s)] = cmul(w2, mkf2(apc.x - bpd.x, apc.y - bpd.y));
;       buf[SW(o + 3 * s)] = cmul(w3, mkf2(amc.x - bmd.y, amc.y + bmd.x));
;     }
	v_pk_add_f32 v[202:203], v[34:35], v[38:39]
	v_pk_add_f32 v[34:35], v[34:35], v[38:39] neg_lo:[0,1] neg_hi:[0,1]
	v_pk_add_f32 v[204:205], v[36:37], v[40:41]
	v_pk_add_f32 v[36:37], v[36:37], v[40:41] neg_lo:[0,1] neg_hi:[0,1]
	v_pk_add_f32 v[38:39], v[202:203], v[204:205]
	v_pk_add_f32 v[40:41], v[202:203], v[204:205] neg_lo:[0,1] neg_hi:[0,1]
	v_pk_add_f32 v[202:203], v[34:35], v[36:37] op_sel:[0,1] op_sel_hi:[1,0] neg_hi:[0,1]
	v_pk_add_f32 v[204:205], v[34:35], v[36:37] op_sel:[0,1] op_sel_hi:[1,0] neg_lo:[0,1]
	v_pk_mul_f32 v[34:35], v[210:211], v[202:203] op_sel:[1,1] op_sel_hi:[1,0]
	v_pk_fma_f32 v[34:35], v[210:211], v[202:203], v[34:35] op_sel_hi:[0,1,1] neg_lo:[0,0,1]
	v_pk_mul_f32 v[36:37], v[212:213], v[40:41] op_sel:[1,1] op_sel_hi:[1,0]
	v_pk_fma_f32 v[36:37], v[212:213], v[40:41], v[36:37] op_sel_hi:[0,1,1] neg_lo:[0,0,1]
	v_pk_mul_f32 v[40:41], v[220:221], v[204:205] op_sel:[1,1] op_sel_hi:[1,0]
	v_pk_fma_f32 v[40:41], v[220:221], v[204:205], v[40:41] op_sel_hi:[0,1,1] neg_lo:[0,0,1]
	v_mov_b32_e32 v210, 0x3f0e39da
	v_mov_b32_e32 v211, 0xbf54db31
	v_mov_b32_e32 v212, 0xbec3ef15
	v_mov_b32_e32 v213, 0xbf6c835e
	v_mov_b32_e32 v220, 0xbf7b14be
	v_mov_b32_e32 v221, 0xbe47c5c2
	s_waitcnt lgkmcnt(4)
	v_pk_add_f32 v[202:203], v[42:43], v[46:47]
	v_pk_add_f32 v[42:43], v[42:43], v[46:47] neg_lo:[0,1] neg_hi:[0,1]
	v_pk_add_f32 v[204:205], v[44:45], v[48:49]
	v_pk_add_f32 v[44:45], v[44:45], v[48:49] neg_lo:[0,1] neg_hi:[0,1]
	v_pk_add_f32 v[46:47], v[202:203], v[204:205]
	v_pk_add_f32 v[48:49], v[202:203], v[204:205] neg_lo:[0,1] neg_hi:[0,1]
	v_pk_add_f32 v[202:203], v[42:43], v[44:45] op_sel:[0,1] op_sel_hi:[1,0] neg_hi:[0,1]
	v_pk_add_f32 v[204:205], v[42:43], v[44:45] op_sel:[0,1] op_sel_hi:[1,0] neg_lo:[0,1]
	v_pk_mul_f32 v[42:43], v[210:211], v[202:203] op_sel:[1,1] op_sel_hi:[1,0]
	v_pk_fma_f32 v[42:43], v[210:211], v[202:203], v[42:43] op_sel_hi:[0,1,1] neg_lo:[0,0,1]
	v_pk_mul_f32 v[44:45], v[212:213], v[48:49] op_sel:[1,1] op_sel_hi:[1,0]
	v_pk_fma_f32 v[44:45], v[212:213], v[48:49], v[44:45] op_sel_hi:[0,1,1] neg_lo:[0,0,1]
	v_pk_mul_f32 v[48:49], v[220:221], v[204:205] op_sel:[1,1] op_sel_hi:[1,0]
	v_pk_fma_f32 v[48:49], v[220:221], v[204:205], v[48:49] op_sel_hi:[0,1,1] neg_lo:[0,0,1]
	v_mov_b32_e32 v210, 0x3ec3ef15
	v_mov_b32_e32 v211, 0xbf6c835e
	v_mov_b32_e32 v212, 0xbf3504f3
	v_mov_b32_e32 v213, 0xbf3504f3
	v_mov_b32_e32 v220, 0xbf6c835e
	v_mov_b32_e32 v221, 0x3ec3ef15
	s_waitcnt lgkmcnt(2)
	v_pk_add_f32 v[202:203], v[50:51], v[54:55]
	v_pk_add_f32 v[50:51], v[50:51], v[54:55] neg_lo:[0,1] neg_hi:[0,1]
	v_pk_add_f32 v[204:205], v[52:53], v[56:57]
	v_pk_add_f32 v[52:53], v[52:53], v[56:57] neg_lo:[0,1] neg_hi:[0,1]
	v_pk_add_f32 v[54:55], v[202:203], v[204:205]
	v_pk_add_f32 v[56:57], v[202:203], v[204:205] neg_lo:[0,1] neg_hi:[0,1]
	v_pk_add_f32 v[202:203], v[50:51], v[52:53] op_sel:[0,1] op_sel_hi:[1,0] neg_hi:[0,1]
	v_pk_add_f32 v[204:205], v[50:51], v[52:53] op_sel:[0,1] op_sel_hi:[1,0] neg_lo:[0,1]
	v_pk_mul_f32 v[50:51], v[210:211], v[202:203] op_sel:[1,1] op_sel_hi:[1,0]
	v_pk_fma_f32 v[50:51], v[210:211], v[202:203], v[50:51] op_sel_hi:[0,1,1] neg_lo:[0,0,1]
	v_pk_mul_f32 v[52:53], v[212:213], v[56:57] op_sel:[1,1] op_sel_hi:[1,0]
	v_pk_fma_f32 v[52:53], v[212:213], v[56:57], v[52:53] op_sel_hi:[0,1,1] neg_lo:[0,0,1]
	v_pk_mul_f32 v[56:57], v[220:221], v[204:205] op_sel:[1,1] op_sel_hi:[1,0]
	v_pk_fma_f32 v[56:57], v[220:221], v[204:205], v[56:57] op_sel_hi:[0,1,1] neg_lo:[0,0,1]
	v_mov_b32_e32 v210, 0x3e47c5c2
	v_mov_b32_e32 v211, 0xbf7b14be
	v_mov_b32_e32 v212, 0xbf6c835e
	v_mov_b32_e32 v213, 0xbec3ef15
	v_mov_b32_e32 v220, 0xbf0e39da
	v_mov_b32_e32 v221, 0x3f54db31
	s_waitcnt lgkmcnt(0)
	v_pk_add_f32 v[202:203], v[58:59], v[62:63]
	v_pk_add_f32 v[58:59], v[58:59], v[62:63] neg_lo:[0,1] neg_hi:[0,1]
	v_pk_add_f32 v[204:205], v[60:61], v[64:65]
	v_pk_add_f32 v[60:61], v[60:61], v[64:65] neg_lo:[0,1] neg_hi:[0,1]
	v_pk_add_f32 v[62:63], v[202:203], v[204:205]
	v_pk_add_f32 v[64:65], v[202:203], v[204:205] neg_lo:[0,1] neg_hi:[0,1]
	v_pk_add_f32 v[202:203], v[58:59], v[60:61] op_sel:[0,1] op_sel_hi:[1,0] neg_hi:[0,1]
	v_pk_add_f32 v[204:205], v[58:59], v[60:61] op_sel:[0,1] op_sel_hi:[1,0] neg_lo:[0,1]
	v_pk_mul_f32 v[58:59], v[210:211], v[202:203] op_sel:[1,1] op_sel_hi:[1,0]
	v_pk_fma_f32 v[58:59], v[210:211], v[202:203], v[58:59] op_sel_hi:[0,1,1] neg_lo:[0,0,1]
	v_pk_mul_f32 v[60:61], v[212:213], v[64:65] op_sel:[1,1] op_sel_hi:[1,0]
	v_pk_fma_f32 v[60:61], v[212:213], v[64:65], v[60:61] op_sel_hi:[0,1,1] neg_lo:[0,0,1]
	v_pk_mul_f32 v[64:65], v[220:221], v[204:205] op_sel:[1,1] op_sel_hi:[1,0]
	v_pk_fma_f32 v[64:65], v[220:221], v[204:205], v[64:65] op_sel_hi:[0,1,1] neg_lo:[0,0,1]
	s_barrier
; DI f32x2 cmul(f32x2 a, f32x2 b) { return mkf2(a.x * b.x - a.y * b.y, a.x * b.y + a.y * b.x); }
; DI void fft8192(f32x2* buf, const f32x2* __restrict__ tw) {
;     ...
; #pragma unroll
;     for (int e = 0; e < 8; ++e) {
;       const int i = tid + 256 * e;
;       const int q = i & (s - 1);
;       const int ps = i - q;
;       const float rev = (float)ps * (1.f / 8192.f);
;       const f32x2 w1 = mkf2(__builtin_amdgcn_cosf(rev), -__builtin_amdgcn_sinf(rev));
;       const f32x2 w2 = cmul(w1, w1), w3 = cmul(w1, w2);
;       const f32x2 apc = mkf2(a[e].x + c[e].x, a[e].y + c[e].y), amc = mkf2(a[e].x - c[e].x, a[e].y - c[e].y);
;       const f32x2 bpd = mkf2(b[e].x + d[e].x, b[e].y + d[e].y), bmd = mkf2(b[e].x - d[e].x, b[e].y - d[e].y);
;       const int o = 4 * i - 3 * q;
;       buf[SW(o)] = mkf2(apc.x + bpd.x, apc.y + bpd.y);
;       buf[SW(o + s)] = cmul(w1, mkf2(amc.x + bmd.y, amc.y - bmd.x));
;       buf[SW(o + 2 * s)] = cmul(w2, mkf2(apc.x - bpd.x, apc.y - bpd.y));
;       buf[SW(o + 3 * s)] = cmul(w3, mkf2(amc.x - bmd.y, amc.y + bmd.x));
;     }
	v_pk_add_f32 v[202:203], v[6:7], v[38:39]
	v_pk_add_f32 v[6:7], v[6:7], v[38:39] neg_lo:[0,1] neg_hi:[0,1]
	v_pk_add_f32 v[204:205], v[22:23], v[54:55]
	v_pk_add_f32 v[22:23], v[22:23], v[54:55] neg_lo:[0,1] neg_hi:[0,1]
	v_pk_add_f32 v[38:39], v[202:203], v[204:205]
	v_pk_add_f32 v[54:55], v[202:203], v[204:205] neg_lo:[0,1] neg_hi:[0,1]
	v_pk_add_f32 v[202:203], v[6:7], v[22:23] op_sel:[0,1] op_sel_hi:[1,0] neg_hi:[0,1]
	v_pk_add_f32 v[22:23], v[6:7], v[22:23] op_sel:[0,1] op_sel_hi:[1,0] neg_lo:[0,1]
	v_pk_mov_b32 v[6:7], v[202:203], v[202:203] op_sel:[0,1]
	v_pk_add_f32 v[202:203], v[2:3], v[34:35]
	v_pk_add_f32 v[2:3], v[2:3], v[34:35] neg_lo:[0,1] neg_hi:[0,1]
	v_pk_add_f32 v[204:205], v[18:19], v[50:51]
	v_pk_add_f32 v[18:19], v[18:19], v[50:51] neg_lo:[0,1] neg_hi:[0,1]
	v_pk_add_f32 v[34:35], v[202:203], v[204:205]
	v_pk_add_f32 v[50:51], v[202:203], v[204:205] neg_lo:[0,1] neg_hi:[0,1]
	v_pk_add_f32 v[202:203], v[2:3], v[18:19] op_sel:[0,1] op_sel_hi:[1,0] neg_hi:[0,1]
	v_pk_add_f32 v[18:19], v[2:3], v[18:19] op_sel:[0,1] op_sel_hi:[1,0] neg_lo:[0,1]
	v_pk_mov_b32 v[2:3], v[202:203], v[202:203] op_sel:[0,1]
	v_pk_add_f32 v[202:203], v[8:9], v[36:37]
	v_pk_add_f32 v[8:9], v[8:9], v[36:37] neg_lo:[0,1] neg_hi:[0,1]
	v_pk_add_f32 v[204:205], v[20:21], v[52:53]
	v_pk_add_f32 v[20:21], v[20:21], v[52:53] neg_lo:[0,1] neg_hi:[0,1]
	v_pk_add_f32 v[36:37], v[202:203], v[204:205]
	v_pk_add_f32 v[52:53], v[202:203], v[204:205] neg_lo:[0,1] neg_hi:[0,1]
	v_pk_add_f32 v[202:203], v[8:9], v[20:21] op_sel:[0,1] op_sel_hi:[1,0] neg_hi:[0,1]
	v_pk_add_f32 v[20:21], v[8:9], v[20:21] op_sel:[0,1] op_sel_hi:[1,0] neg_lo:[0,1]
	v_pk_mov_b32 v[8:9], v[202:203], v[202:203] op_sel:[0,1]
	v_pk_add_f32 v[202:203], v[4:5], v[40:41]
	v_pk_add_f32 v[4:5], v[4:5], v[40:41] neg_lo:[0,1] neg_hi:[0,1]
	v_pk_add_f32 v[204:205], v[24:25], v[56:57]
	v_pk_add_f32 v[24:25], v[24:25], v[56:57] neg_lo:[0,1] neg_hi:[0,1]
	v_pk_add_f32 v[40:41], v[202:203], v[204:205]
	v_pk_add_f32 v[56:57], v[202:203], v[204:205] neg_lo:[0,1] neg_hi:[0,1]
	v_pk_add_f32 v[202:203], v[4:5], v[24:25] op_sel:[0,1] op_sel_hi:[1,0] neg_hi:[0,1]
	v_pk_add_f32 v[24:25], v[4:5], v[24:25] op_sel:[0,1] op_sel_hi:[1,0] neg_lo:[0,1]
	v_pk_mov_b32 v[4:5], v[202:203], v[202:203] op_sel:[0,1]
	v_mov_b32_e32 v224, 0x3f3504f3
	v_mov_b32_e32 v225, 0xbf3504f3
	v_mov_b32_e32 v226, 0x248d3132
	v_mov_b32_e32 v227, 0xbf800000
	v_mov_b32_e32 v230, 0xbf3504f3
	v_mov_b32_e32 v231, 0xbf3504f3
	v_pk_add_f32 v[202:203], v[14:15], v[46:47]
	v_pk_add_f32 v[14:15], v[14:15], v[46:47] neg_lo:[0,1] neg_hi:[0,1]
	v_pk_add_f32 v[204:205], v[30:31], v[62:63]
	v_pk_add_f32 v[30:31], v[30:31], v[62:63] neg_lo:[0,1] neg_hi:[0,1]
	v_pk_add_f32 v[46:47], v[202:203], v[204:205]
	v_pk_add_f32 v[62:63], v[202:203], v[204:205] neg_lo:[0,1] neg_hi:[0,1]
	v_pk_add_f32 v[202:203], v[14:15], v[30:31] op_sel:[0,1] op_sel_hi:[1,0] neg_hi:[0,1]
	v_pk_add_f32 v[204:205], v[14:15], v[30:31] op_sel:[0,1] op_sel_hi:[1,0] neg_lo:[0,1]
	v_pk_mul_f32 v[14:15], v[224:225], v[202:203] op_sel:[1,1] op_sel_hi:[1,0]
	v_pk_fma_f32 v[14:15], v[224:225], v[202:203], v[14:15] op_sel_hi:[0,1,1] neg_lo:[0,0,1]
	v_pk_mul_f32 v[30:31], v[226:227], v[62:63] op_sel:[1,1] op_sel_hi:[1,0]
	v_pk_fma_f32 v[30:31], v[226:227], v[62:63], v[30:31] op_sel_hi:[0,1,1] neg_lo:[0,0,1]
	v_pk_mul_f32 v[62:63], v[230:231], v[204:205] op_sel:[1,1] op_sel_hi:[1,0]
	v_pk_fma_f32 v[62:63], v[230:231], v[204:205], v[62:63] op_sel_hi:[0,1,1] neg_lo:[0,0,1]
	v_pk_add_f32 v[202:203], v[10:11], v[42:43]
	v_pk_add_f32 v[10:11], v[10:11], v[42:43] neg_lo:[0,1] neg_hi:[0,1]
	v_pk_add_f32 v[204:205], v[26:27], v[58:59]
	v_pk_add_f32 v[26:27], v[26:27], v[58:59] neg_lo:[0,1] neg_hi:[0,1]
	v_pk_add_f32 v[42:43], v[202:203], v[204:205]
	v_pk_add_f32 v[58:59], v[202:203], v[204:205] neg_lo:[0,1] neg_hi:[0,1]
	v_pk_add_f32 v[202:203], v[10:11], v[26:27] op_sel:[0,1] op_sel_hi:[1,0] neg_hi:[0,1]
	v_pk_add_f32 v[204:205], v[10:11], v[26:27] op_sel:[0,1] op_sel_hi:[1,0] neg_lo:[0,1]
	v_pk_mul_f32 v[10:11], v[224:225], v[202:203] op_sel:[1,1] op_sel_hi:[1,0]
	v_pk_fma_f32 v[10:11], v[224:225], v[202:203], v[10:11] op_sel_hi:[0,1,1] neg_lo:[0,0,1]
	v_pk_mul_f32 v[26:27], v[226:227], v[58:59] op_sel:[1,1] op_sel_hi:[1,0]
	v_pk_fma_f32 v[26:27], v[226:227], v[58:59], v[26:27] op_sel_hi:[0,1,1] neg_lo:[0,0,1]
	v_pk_mul_f32 v[58:59], v[230:231], v[204:205] op_sel:[1,1] op_sel_hi:[1,0]
	v_pk_fma_f32 v[58:59], v[230:231], v[204:205], v[58:59] op_sel_hi:[0,1,1] neg_lo:[0,0,1]
	v_pk_add_f32 v[202:203], v[12:13], v[44:45]
	v_pk_add_f32 v[12:13], v[12:13], v[44:45] neg_lo:[0,1] neg_hi:[0,1]
	v_pk_add_f32 v[204:205], v[28:29], v[60:61]
	v_pk_add_f32 v[28:29], v[28:29], v[60:61] neg_lo:[0,1] neg_hi:[0,1]
	v_pk_add_f32 v[44:45], v[202:203], v[204:205]
	v_pk_add_f32 v[60:61], v[202:203], v[204:205] neg_lo:[0,1] neg_hi:[0,1]
	v_pk_add_f32 v[202:203], v[12:13], v[28:29] op_sel:[0,1] op_sel_hi:[1,0] neg_hi:[0,1]
	v_pk_add_f32 v[204:205], v[12:13], v[28:29] op_sel:[0,1] op_sel_hi:[1,0] neg_lo:[0,1]
	v_pk_mul_f32 v[12:13], v[224:225], v[202:203] op_sel:[1,1] op_sel_hi:[1,0]
	v_pk_fma_f32 v[12:13], v[224:225], v[202:203], v[12:13] op_sel_hi:[0,1,1] neg_lo:[0,0,1]
	v_pk_mul_f32 v[28:29], v[226:227], v[60:61] op_sel:[1,1] op_sel_hi:[1,0]
	v_pk_fma_f32 v[28:29], v[226:227], v[60:61], v[28:29] op_sel_hi:[0,1,1] neg_lo:[0,0,1]
	v_pk_mul_f32 v[60:61], v[230:231], v[204:205] op_sel:[1,1] op_sel_hi:[1,0]
	v_pk_fma_f32 v[60:61], v[230:231], v[204:205], v[60:61] op_sel_hi:[0,1,1] neg_lo:[0,0,1]
	v_pk_add_f32 v[202:203], v[16:17], v[48:49]
	v_pk_add_f32 v[16:17], v[16:17], v[48:49] neg_lo:[0,1] neg_hi:[0,1]
; DI f32x2 cmul(f32x2 a, f32x2 b) { return mkf2(a.x * b.x - a.y * b.y, a.x * b.y + a.y * b.x); }
; DI void fft8192(f32x2* buf, const f32x2* __restrict__ tw) {
;     ...
; #pragma unroll
;     for (int e = 0; e < 16; ++e) {
;       const int pi = SW(tid + 256 * e);
;       buf[pi] = mkf2(a[e].x + b[e].x, a[e].y + b[e].y);
;       buf[pi + 4096] = mkf2(a[e].x - b[e].x, a[e].y - b[e].y);
;     }
; DI void hyena_unit(KP p, int l, int c, char* smem) {
;     ...
;       for (int j = 0; j < 32; ++j) {
;         const int f = tid + 256 * j;
;         f32x2 z = cmul(buf[SW(f)], KF[j]);
;         buf[SW(f)] = mkf2(z.x, -z.y);
;       }
	v_pk_add_f32 v[204:205], v[32:33], v[64:65]
	v_pk_add_f32 v[32:33], v[32:33], v[64:65] neg_lo:[0,1] neg_hi:[0,1]
	v_pk_add_f32 v[48:49], v[202:203], v[204:205]
	v_pk_add_f32 v[64:65], v[202:203], v[204:205] neg_lo:[0,1] neg_hi:[0,1]
	v_pk_add_f32 v[202:203], v[16:17], v[32:33] op_sel:[0,1] op_sel_hi:[1,0] neg_hi:[0,1]
	v_pk_add_f32 v[204:205], v[16:17], v[32:33] op_sel:[0,1] op_sel_hi:[1,0] neg_lo:[0,1]
	v_pk_mul_f32 v[16:17], v[224:225], v[202:203] op_sel:[1,1] op_sel_hi:[1,0]
	v_pk_fma_f32 v[16:17], v[224:225], v[202:203], v[16:17] op_sel_hi:[0,1,1] neg_lo:[0,0,1]
	v_pk_mul_f32 v[32:33], v[226:227], v[64:65] op_sel:[1,1] op_sel_hi:[1,0]
	v_pk_fma_f32 v[32:33], v[226:227], v[64:65], v[32:33] op_sel_hi:[0,1,1] neg_lo:[0,0,1]
	v_pk_mul_f32 v[64:65], v[230:231], v[204:205] op_sel:[1,1] op_sel_hi:[1,0]
	v_pk_fma_f32 v[64:65], v[230:231], v[204:205], v[64:65] op_sel_hi:[0,1,1] neg_lo:[0,0,1]
	v_pk_add_f32 v[202:203], v[38:39], v[46:47]
	v_pk_add_f32 v[46:47], v[38:39], v[46:47] neg_lo:[0,1] neg_hi:[0,1]
	v_pk_mul_f32 v[38:39], v[78:79], v[202:203] op_sel:[1,1] op_sel_hi:[1,0]
	v_pk_fma_f32 v[202:203], v[78:79], v[202:203], v[38:39] op_sel_hi:[0,1,1] neg_lo:[0,0,1] neg_hi:[1,0,1]
	v_pk_mul_f32 v[38:39], v[110:111], v[46:47] op_sel:[1,1] op_sel_hi:[1,0]
	v_pk_fma_f32 v[46:47], v[110:111], v[46:47], v[38:39] op_sel_hi:[0,1,1] neg_lo:[0,0,1] neg_hi:[1,0,1]
	v_pk_add_f32 v[204:205], v[34:35], v[42:43]
	v_pk_add_f32 v[42:43], v[34:35], v[42:43] neg_lo:[0,1] neg_hi:[0,1]
	v_pk_mul_f32 v[34:35], v[80:81], v[204:205] op_sel:[1,1] op_sel_hi:[1,0]
	v_pk_fma_f32 v[204:205], v[80:81], v[204:205], v[34:35] op_sel_hi:[0,1,1] neg_lo:[0,0,1] neg_hi:[1,0,1]
	v_pk_mul_f32 v[34:35], v[112:113], v[42:43] op_sel:[1,1] op_sel_hi:[1,0]
	v_pk_fma_f32 v[42:43], v[112:113], v[42:43], v[34:35] op_sel_hi:[0,1,1] neg_lo:[0,0,1] neg_hi:[1,0,1]
	v_pk_add_f32 v[206:207], v[36:37], v[44:45]
	v_pk_add_f32 v[44:45], v[36:37], v[44:45] neg_lo:[0,1] neg_hi:[0,1]
	v_pk_mul_f32 v[36:37], v[82:83], v[206:207] op_sel:[1,1] op_sel_hi:[1,0]
	v_pk_fma_f32 v[206:207], v[82:83], v[206:207], v[36:37] op_sel_hi:[0,1,1] neg_lo:[0,0,1] neg_hi:[1,0,1]
	v_pk_mul_f32 v[36:37], v[114:115], v[44:45] op_sel:[1,1] op_sel_hi:[1,0]
	v_pk_fma_f32 v[44:45], v[114:115], v[44:45], v[36:37] op_sel_hi:[0,1,1] neg_lo:[0,0,1] neg_hi:[1,0,1]
	v_pk_add_f32 v[208:209], v[40:41], v[48:49]
	v_pk_add_f32 v[48:49], v[40:41], v[48:49] neg_lo:[0,1] neg_hi:[0,1]
	v_pk_mul_f32 v[40:41], v[84:85], v[208:209] op_sel:[1,1] op_sel_hi:[1,0]
	v_pk_fma_f32 v[208:209], v[84:85], v[208:209], v[40:41] op_sel_hi:[0,1,1] neg_lo:[0,0,1] neg_hi:[1,0,1]
	v_pk_mul_f32 v[40:41], v[116:117], v[48:49] op_sel:[1,1] op_sel_hi:[1,0]
	v_pk_fma_f32 v[48:49], v[116:117], v[48:49], v[40:41] op_sel_hi:[0,1,1] neg_lo:[0,0,1] neg_hi:[1,0,1]
	v_pk_add_f32 v[210:211], v[6:7], v[14:15]
	v_pk_add_f32 v[14:15], v[6:7], v[14:15] neg_lo:[0,1] neg_hi:[0,1]
	v_pk_mul_f32 v[6:7], v[86:87], v[210:211] op_sel:[1,1] op_sel_hi:[1,0]
	v_pk_fma_f32 v[210:211], v[86:87], v[210:211], v[6:7] op_sel_hi:[0,1,1] neg_lo:[0,0,1] neg_hi:[1,0,1]
	v_pk_mul_f32 v[6:7], v[118:119], v[14:15] op_sel:[1,1] op_sel_hi:[1,0]
	v_pk_fma_f32 v[14:15], v[118:119], v[14:15], v[6:7] op_sel_hi:[0,1,1] neg_lo:[0,0,1] neg_hi:[1,0,1]
	v_pk_add_f32 v[212:213], v[2:3], v[10:11]
	v_pk_add_f32 v[10:11], v[2:3], v[10:11] neg_lo:[0,1] neg_hi:[0,1]
	v_pk_mul_f32 v[2:3], v[88:89], v[212:213] op_sel:[1,1] op_sel_hi:[1,0]
	v_pk_fma_f32 v[212:213], v[88:89], v[212:213], v[2:3] op_sel_hi:[0,1,1] neg_lo:[0,0,1] neg_hi:[1,0,1]
	v_pk_mul_f32 v[2:3], v[120:121], v[10:11] op_sel:[1,1] op_sel_hi:[1,0]
	v_pk_fma_f32 v[10:11], v[120:121], v[10:11], v[2:3] op_sel_hi:[0,1,1] neg_lo:[0,0,1] neg_hi:[1,0,1]
	v_pk_add_f32 v[220:221], v[8:9], v[12:13]
	v_pk_add_f32 v[12:13], v[8:9], v[12:13] neg_lo:[0,1] neg_hi:[0,1]
	v_pk_mul_f32 v[8:9], v[90:91], v[220:221] op_sel:[1,1] op_sel_hi:[1,0]
	v_pk_fma_f32 v[220:221], v[90:91], v[220:221], v[8:9] op_sel_hi:[0,1,1] neg_lo:[0,0,1] neg_hi:[1,0,1]
	v_pk_mul_f32 v[8:9], v[122:123], v[12:13] op_sel:[1,1] op_sel_hi:[1,0]
	v_pk_fma_f32 v[12:13], v[122:123], v[12:13], v[8:9] op_sel_hi:[0,1,1] neg_lo:[0,0,1] neg_hi:[1,0,1]
	v_pk_add_f32 v[224:225], v[4:5], v[16:17]
	v_pk_add_f32 v[16:17], v[4:5], v[16:17] neg_lo:[0,1] neg_hi:[0,1]
	v_pk_mul_f32 v[4:5], v[92:93], v[224:225] op_sel:[1,1] op_sel_hi:[1,0]
	v_pk_fma_f32 v[224:225], v[92:93], v[224:225], v[4:5] op_sel_hi:[0,1,1] neg_lo:[0,0,1] neg_hi:[1,0,1]
	v_pk_mul_f32 v[4:5], v[124:125], v[16:17] op_sel:[1,1] op_sel_hi:[1,0]
	v_pk_fma_f32 v[16:17], v[124:125], v[16:17], v[4:5] op_sel_hi:[0,1,1] neg_lo:[0,0,1] neg_hi:[1,0,1]
	v_pk_add_f32 v[226:227], v[54:55], v[30:31]
	v_pk_add_f32 v[30:31], v[54:55], v[30:31] neg_lo:[0,1] neg_hi:[0,1]
	v_pk_mul_f32 v[54:55], v[94:95], v[226:227] op_sel:[1,1] op_sel_hi:[1,0]
	v_pk_fma_f32 v[226:227], v[94:95], v[226:227], v[54:55] op_sel_hi:[0,1,1] neg_lo:[0,0,1] neg_hi:[1,0,1]
	v_pk_mul_f32 v[54:55], v[126:127], v[30:31] op_sel:[1,1] op_sel_hi:[1,0]
	v_pk_fma_f32 v[30:31], v[126:127], v[30:31], v[54:55] op_sel_hi:[0,1,1] neg_lo:[0,0,1] neg_hi:[1,0,1]
	v_pk_add_f32 v[230:231], v[50:51], v[26:27]
	v_pk_add_f32 v[26:27], v[50:51], v[26:27] neg_lo:[0,1] neg_hi:[0,1]
	v_pk_mul_f32 v[50:51], v[96:97], v[230:231] op_sel:[1,1] op_sel_hi:[1,0]
	v_pk_fma_f32 v[230:231], v[96:97], v[230:231], v[50:51] op_sel_hi:[0,1,1] neg_lo:[0,0,1] neg_hi:[1,0,1]
	v_pk_mul_f32 v[50:51], v[128:129], v[26:27] op_sel:[1,1] op_sel_hi:[1,0]
	v_pk_fma_f32 v[26:27], v[128:129], v[26:27], v[50:51] op_sel_hi:[0,1,1] neg_lo:[0,0,1] neg_hi:[1,0,1]
	v_pk_add_f32 v[232:233], v[52:53], v[28:29]
	v_pk_add_f32 v[28:29], v[52:53], v[28:29] neg_lo:[0,1] neg_hi:[0,1]
; DI f32x2 cmul(f32x2 a, f32x2 b) { return mkf2(a.x * b.x - a.y * b.y, a.x * b.y + a.y * b.x); }
; DI void fft8192(f32x2* buf, const f32x2* __restrict__ tw) {
;     ...
;     __syncthreads();
; #pragma unroll
;     for (int e = 0; e < 8; ++e) {
;       const int i = tid + 256 * e;
;       const int pi = SW(i);
;       a[e] = buf[pi]; b[e] = buf[pi + 2048]; c[e] = buf[pi + 4096]; d[e] = buf[pi + 6144];
;     }
;     __syncthreads();
; #pragma unroll
;     for (int e = 0; e < 8; ++e) {
;       const int i = tid + 256 * e;
;       const int q = i & (s - 1);
;       const int ps = i - q;
;       const float rev = (float)ps * (1.f / 8192.f);
;       const f32x2 w1 = mkf2(__builtin_amdgcn_cosf(rev), -__builtin_amdgcn_sinf(rev));
; DI void hyena_unit(KP p, int l, int c, char* smem) {
;     ...
;       for (int j = 0; j < 32; ++j) {
;         const int f = tid + 256 * j;
;         f32x2 z = cmul(buf[SW(f)], KF[j]);
;         buf[SW(f)] = mkf2(z.x, -z.y);
;       }
	v_pk_mul_f32 v[52:53], v[98:99], v[232:233] op_sel:[1,1] op_sel_hi:[1,0]
	v_pk_fma_f32 v[232:233], v[98:99], v[232:233], v[52:53] op_sel_hi:[0,1,1] neg_lo:[0,0,1] neg_hi:[1,0,1]
	v_pk_mul_f32 v[52:53], v[130:131], v[28:29] op_sel:[1,1] op_sel_hi:[1,0]
	v_pk_fma_f32 v[28:29], v[130:131], v[28:29], v[52:53] op_sel_hi:[0,1,1] neg_lo:[0,0,1] neg_hi:[1,0,1]
	v_pk_add_f32 v[236:237], v[56:57], v[32:33]
	v_pk_add_f32 v[32:33], v[56:57], v[32:33] neg_lo:[0,1] neg_hi:[0,1]
	v_pk_mul_f32 v[56:57], v[100:101], v[236:237] op_sel:[1,1] op_sel_hi:[1,0]
	v_pk_fma_f32 v[236:237], v[100:101], v[236:237], v[56:57] op_sel_hi:[0,1,1] neg_lo:[0,0,1] neg_hi:[1,0,1]
	v_pk_mul_f32 v[56:57], v[132:133], v[32:33] op_sel:[1,1] op_sel_hi:[1,0]
	v_pk_fma_f32 v[32:33], v[132:133], v[32:33], v[56:57] op_sel_hi:[0,1,1] neg_lo:[0,0,1] neg_hi:[1,0,1]
	v_pk_add_f32 v[238:239], v[22:23], v[62:63]
	v_pk_add_f32 v[62:63], v[22:23], v[62:63] neg_lo:[0,1] neg_hi:[0,1]
	v_pk_mul_f32 v[22:23], v[102:103], v[238:239] op_sel:[1,1] op_sel_hi:[1,0]
	v_pk_fma_f32 v[238:239], v[102:103], v[238:239], v[22:23] op_sel_hi:[0,1,1] neg_lo:[0,0,1] neg_hi:[1,0,1]
	v_pk_mul_f32 v[22:23], v[134:135], v[62:63] op_sel:[1,1] op_sel_hi:[1,0]
	v_pk_fma_f32 v[62:63], v[134:135], v[62:63], v[22:23] op_sel_hi:[0,1,1] neg_lo:[0,0,1] neg_hi:[1,0,1]
	v_pk_add_f32 v[240:241], v[18:19], v[58:59]
	v_pk_add_f32 v[58:59], v[18:19], v[58:59] neg_lo:[0,1] neg_hi:[0,1]
	v_pk_mul_f32 v[18:19], v[104:105], v[240:241] op_sel:[1,1] op_sel_hi:[1,0]
	v_pk_fma_f32 v[240:241], v[104:105], v[240:241], v[18:19] op_sel_hi:[0,1,1] neg_lo:[0,0,1] neg_hi:[1,0,1]
	v_pk_mul_f32 v[18:19], v[136:137], v[58:59] op_sel:[1,1] op_sel_hi:[1,0]
	v_pk_fma_f32 v[58:59], v[136:137], v[58:59], v[18:19] op_sel_hi:[0,1,1] neg_lo:[0,0,1] neg_hi:[1,0,1]
	v_pk_add_f32 v[244:245], v[20:21], v[60:61]
	v_pk_add_f32 v[60:61], v[20:21], v[60:61] neg_lo:[0,1] neg_hi:[0,1]
	v_pk_mul_f32 v[20:21], v[106:107], v[244:245] op_sel:[1,1] op_sel_hi:[1,0]
	v_pk_fma_f32 v[244:245], v[106:107], v[244:245], v[20:21] op_sel_hi:[0,1,1] neg_lo:[0,0,1] neg_hi:[1,0,1]
	v_pk_mul_f32 v[20:21], v[138:139], v[60:61] op_sel:[1,1] op_sel_hi:[1,0]
	v_pk_fma_f32 v[60:61], v[138:139], v[60:61], v[20:21] op_sel_hi:[0,1,1] neg_lo:[0,0,1] neg_hi:[1,0,1]
	v_pk_add_f32 v[246:247], v[24:25], v[64:65]
	v_pk_add_f32 v[64:65], v[24:25], v[64:65] neg_lo:[0,1] neg_hi:[0,1]
	v_pk_mul_f32 v[24:25], v[108:109], v[246:247] op_sel:[1,1] op_sel_hi:[1,0]
	v_pk_fma_f32 v[246:247], v[108:109], v[246:247], v[24:25] op_sel_hi:[0,1,1] neg_lo:[0,0,1] neg_hi:[1,0,1]
	v_pk_mul_f32 v[24:25], v[140:141], v[64:65] op_sel:[1,1] op_sel_hi:[1,0]
	v_pk_fma_f32 v[64:65], v[140:141], v[64:65], v[24:25] op_sel_hi:[0,1,1] neg_lo:[0,0,1] neg_hi:[1,0,1]
	ds_write2st64_b64 v154, v[202:203], v[46:47] offset0:0 offset1:64
	ds_write2st64_b64 v154, v[204:205], v[42:43] offset0:4 offset1:68
	ds_write2st64_b64 v154, v[206:207], v[44:45] offset0:8 offset1:72
	ds_write2st64_b64 v154, v[208:209], v[48:49] offset0:12 offset1:76
	ds_write2st64_b64 v154, v[210:211], v[14:15] offset0:16 offset1:80
	ds_write2st64_b64 v154, v[212:213], v[10:11] offset0:20 offset1:84
	ds_write2st64_b64 v154, v[220:221], v[12:13] offset0:24 offset1:88
	ds_write2st64_b64 v154, v[224:225], v[16:17] offset0:28 offset1:92
	ds_write2st64_b64 v154, v[226:227], v[30:31] offset0:32 offset1:96
	ds_write2st64_b64 v154, v[230:231], v[26:27] offset0:36 offset1:100
	ds_write2st64_b64 v154, v[232:233], v[28:29] offset0:40 offset1:104
	ds_write2st64_b64 v154, v[236:237], v[32:33] offset0:44 offset1:108
	ds_write2st64_b64 v154, v[238:239], v[62:63] offset0:48 offset1:112
	ds_write2st64_b64 v154, v[240:241], v[58:59] offset0:52 offset1:116
	ds_write2st64_b64 v154, v[244:245], v[60:61] offset0:56 offset1:120
	ds_write2st64_b64 v154, v[246:247], v[64:65] offset0:60 offset1:124
	v_bfe_i32 v166, v0, 5, 1
	v_bfe_i32 v168, v0, 6, 1
	v_and_b32_e32 v166, 5, v166
	v_and_b32_e32 v168, 26, v168
	v_xor_b32_e32 v166, v166, v168
	v_xor_b32_e32 v166, v166, v0
	v_lshlrev_b32_e32 v154, 3, v166
	s_waitcnt lgkmcnt(0)
	s_barrier
	ds_read2st64_b64 v[2:5], v154 offset0:0 offset1:32
	ds_read2st64_b64 v[6:9], v154 offset0:64 offset1:96
	ds_read2st64_b64 v[10:13], v154 offset0:4 offset1:36
	ds_read2st64_b64 v[14:17], v154 offset0:68 offset1:100
	ds_read2st64_b64 v[18:21], v154 offset0:8 offset1:40
	ds_read2st64_b64 v[22:25], v154 offset0:72 offset1:104
	ds_read2st64_b64 v[26:29], v154 offset0:12 offset1:44
	ds_read2st64_b64 v[30:33], v154 offset0:76 offset1:108
	ds_read2st64_b64 v[34:37], v154 offset0:16 offset1:48
	ds_read2st64_b64 v[38:41], v154 offset0:80 offset1:112
	ds_read2st64_b64 v[42:45], v154 offset0:20 offset1:52
	ds_read2st64_b64 v[46:49], v154 offset0:84 offset1:116
	ds_read2st64_b64 v[50:53], v154 offset0:24 offset1:56
	ds_read2st64_b64 v[54:57], v154 offset0:88 offset1:120
	ds_read2st64_b64 v[58:61], v154 offset0:28 offset1:60
	ds_read2st64_b64 v[62:65], v154 offset0:92 offset1:124
	v_cvt_f32_u32_e32 v201, v0
	v_and_b32_e32 v166, 15, v0
	v_lshlrev_b32_e32 v166, 3, v166
	v_lshl_add_u32 v164, v0, 7, v166
	v_mul_f32_e32 v201, 0x39000000, v201
	v_cos_f32_e32 v210, v201
	v_sin_f32_e64 v211, -v201
	s_nop 0
	v_mov_b32_e32 v224, v210
	v_mov_b32_e32 v225, v211
	s_waitcnt lgkmcnt(14)
; DI f32x2 cmul(f32x2 a, f32x2 b) { return mkf2(a.x * b.x - a.y * b.y, a.x * b.y + a.y * b.x); }
; DI void fft8192(f32x2* buf, const f32x2* __restrict__ tw) {
;     ...
; #pragma unroll
;     for (int e = 0; e < 8; ++e) {
;       const int i = tid + 256 * e;
;       const int q = i & (s - 1);
;       const int ps = i - q;
;       const float rev = (float)ps * (1.f / 8192.f);
;       const f32x2 w1 = mkf2(__builtin_amdgcn_cosf(rev), -__builtin_amdgcn_sinf(rev));
;       const f32x2 w2 = cmul(w1, w1), w3 = cmul(w1, w2);
;       const f32x2 apc = mkf2(a[e].x + c[e].x, a[e].y + c[e].y), amc = mkf2(a[e].x - c[e].x, a[e].y - c[e].y);
;       const f32x2 bpd = mkf2(b[e].x + d[e].x, b[e].y + d[e].y), bmd = mkf2(b[e].x - d[e].x, b[e].y - d[e].y);
;       const int o = 4 * i - 3 * q;
;       buf[SW(o)] = mkf2(apc.x + bpd.x, apc.y + bpd.y);
;       buf[SW(o + s)] = cmul(w1, mkf2(amc.x + bmd.y, amc.y - bmd.x));
;       buf[SW(o + 2 * s)] = cmul(w2, mkf2(apc.x - bpd.x, apc.y - bpd.y));
;       buf[SW(o + 3 * s)] = cmul(w3, mkf2(amc.x - bmd.y, amc.y + bmd.x));
;     }
	v_pk_add_f32 v[202:203], v[2:3], v[6:7]
	v_pk_add_f32 v[2:3], v[2:3], v[6:7] neg_lo:[0,1] neg_hi:[0,1]
	v_pk_add_f32 v[204:205], v[4:5], v[8:9]
	v_pk_add_f32 v[4:5], v[4:5], v[8:9] neg_lo:[0,1] neg_hi:[0,1]
	v_pk_add_f32 v[6:7], v[202:203], v[204:205]
	v_pk_add_f32 v[8:9], v[202:203], v[204:205] neg_lo:[0,1] neg_hi:[0,1]
	v_pk_add_f32 v[202:203], v[2:3], v[4:5] op_sel:[0,1] op_sel_hi:[1,0] neg_hi:[0,1]
	v_pk_add_f32 v[204:205], v[2:3], v[4:5] op_sel:[0,1] op_sel_hi:[1,0] neg_lo:[0,1]
	v_pk_mul_f32 v[206:207], v[210:211], v[210:211] op_sel:[1,1] op_sel_hi:[1,0]
	v_pk_fma_f32 v[212:213], v[210:211], v[210:211], v[206:207] op_sel_hi:[0,1,1] neg_lo:[0,0,1]
	v_pk_mul_f32 v[206:207], v[210:211], v[212:213] op_sel:[1,1] op_sel_hi:[1,0]
	v_pk_fma_f32 v[220:221], v[210:211], v[212:213], v[206:207] op_sel_hi:[0,1,1] neg_lo:[0,0,1]
	v_pk_mul_f32 v[2:3], v[210:211], v[202:203] op_sel:[1,1] op_sel_hi:[1,0]
	v_pk_fma_f32 v[2:3], v[210:211], v[202:203], v[2:3] op_sel_hi:[0,1,1] neg_lo:[0,0,1]
	v_pk_mul_f32 v[4:5], v[212:213], v[8:9] op_sel:[1,1] op_sel_hi:[1,0]
	v_pk_fma_f32 v[4:5], v[212:213], v[8:9], v[4:5] op_sel_hi:[0,1,1] neg_lo:[0,0,1]
	v_pk_mul_f32 v[8:9], v[220:221], v[204:205] op_sel:[1,1] op_sel_hi:[1,0]
	v_pk_fma_f32 v[8:9], v[220:221], v[204:205], v[8:9] op_sel_hi:[0,1,1] neg_lo:[0,0,1]
	v_mul_f32_e32 v210, 0x3f7b14be, v224
	v_mul_f32_e32 v211, 0xbe47c5c2, v224
	v_fmac_f32_e32 v210, 0x3e47c5c2, v225
	v_fmac_f32_e32 v211, 0x3f7b14be, v225
	s_waitcnt lgkmcnt(12)
	v_pk_add_f32 v[202:203], v[10:11], v[14:15]
	v_pk_add_f32 v[10:11], v[10:11], v[14:15] neg_lo:[0,1] neg_hi:[0,1]
	v_pk_add_f32 v[204:205], v[12:13], v[16:17]
	v_pk_add_f32 v[12:13], v[12:13], v[16:17] neg_lo:[0,1] neg_hi:[0,1]
	v_pk_add_f32 v[14:15], v[202:203], v[204:205]
	v_pk_add_f32 v[16:17], v[202:203], v[204:205] neg_lo:[0,1] neg_hi:[0,1]
	v_pk_add_f32 v[202:203], v[10:11], v[12:13] op_sel:[0,1] op_sel_hi:[1,0] neg_hi:[0,1]
	v_pk_add_f32 v[204:205], v[10:11], v[12:13] op_sel:[0,1] op_sel_hi:[1,0] neg_lo:[0,1]
	v_pk_mul_f32 v[206:207], v[210:211], v[210:211] op_sel:[1,1] op_sel_hi:[1,0]
	v_pk_fma_f32 v[212:213], v[210:211], v[210:211], v[206:207] op_sel_hi:[0,1,1] neg_lo:[0,0,1]
	v_pk_mul_f32 v[206:207], v[210:211], v[212:213] op_sel:[1,1] op_sel_hi:[1,0]
	v_pk_fma_f32 v[220:221], v[210:211], v[212:213], v[206:207] op_sel_hi:[0,1,1] neg_lo:[0,0,1]
	v_pk_mul_f32 v[10:11], v[210:211], v[202:203] op_sel:[1,1] op_sel_hi:[1,0]
	v_pk_fma_f32 v[10:11], v[210:211], v[202:203], v[10:11] op_sel_hi:[0,1,1] neg_lo:[0,0,1]
	v_pk_mul_f32 v[12:13], v[212:213], v[16:17] op_sel:[1,1] op_sel_hi:[1,0]
	v_pk_fma_f32 v[12:13], v[212:213], v[16:17], v[12:13] op_sel_hi:[0,1,1] neg_lo:[0,0,1]
	v_pk_mul_f32 v[16:17], v[220:221], v[204:205] op_sel:[1,1] op_sel_hi:[1,0]
	v_pk_fma_f32 v[16:17], v[220:221], v[204:205], v[16:17] op_sel_hi:[0,1,1] neg_lo:[0,0,1]
	v_mul_f32_e32 v210, 0x3f6c835e, v224
	v_mul_f32_e32 v211, 0xbec3ef15, v224
	v_fmac_f32_e32 v210, 0x3ec3ef15, v225
	v_fmac_f32_e32 v211, 0x3f6c835e, v225
	s_waitcnt lgkmcnt(10)
	v_pk_add_f32 v[202:203], v[18:19], v[22:23]
	v_pk_add_f32 v[18:19], v[18:19], v[22:23] neg_lo:[0,1] neg_hi:[0,1]
	v_pk_add_f32 v[204:205], v[20:21], v[24:25]
	v_pk_add_f32 v[20:21], v[20:21], v[24:25] neg_lo:[0,1] neg_hi:[0,1]
	v_pk_add_f32 v[22:23], v[202:203], v[204:205]
	v_pk_add_f32 v[24:25], v[202:203], v[204:205] neg_lo:[0,1] neg_hi:[0,1]
	v_pk_add_f32 v[202:203], v[18:19], v[20:21] op_sel:[0,1] op_sel_hi:[1,0] neg_hi:[0,1]
	v_pk_add_f32 v[204:205], v[18:19], v[20:21] op_sel:[0,1] op_sel_hi:[1,0] neg_lo:[0,1]
	v_pk_mul_f32 v[206:207], v[210:211], v[210:211] op_sel:[1,1] op_sel_hi:[1,0]
	v_pk_fma_f32 v[212:213], v[210:211], v[210:211], v[206:207] op_sel_hi:[0,1,1] neg_lo:[0,0,1]
	v_pk_mul_f32 v[206:207], v[210:211], v[212:213] op_sel:[1,1] op_sel_hi:[1,0]
	v_pk_fma_f32 v[220:221], v[210:211], v[212:213], v[206:207] op_sel_hi:[0,1,1] neg_lo:[0,0,1]
	v_pk_mul_f32 v[18:19], v[210:211], v[202:203] op_sel:[1,1] op_sel_hi:[1,0]
	v_pk_fma_f32 v[18:19], v[210:211], v[202:203], v[18:19] op_sel_hi:[0,1,1] neg_lo:[0,0,1]
	v_pk_mul_f32 v[20:21], v[212:213], v[24:25] op_sel:[1,1] op_sel_hi:[1,0]
	v_pk_fma_f32 v[20:21], v[212:213], v[24:25], v[20:21] op_sel_hi:[0,1,1] neg_lo:[0,0,1]
	v_pk_mul_f32 v[24:25], v[220:221], v[204:205] op_sel:[1,1] op_sel_hi:[1,0]
	v_pk_fma_f32 v[24:25], v[220:221], v[204:205], v[24:25] op_sel_hi:[0,1,1] neg_lo:[0,0,1]
	v_mul_f32_e32 v210, 0x3f54db31, v224
	v_mul_f32_e32 v211, 0xbf0e39da, v224
	v_fmac_f32_e32 v210, 0x3f0e39da, v225
	v_fmac_f32_e32 v211, 0x3f54db31, v225
	s_waitcnt lgkmcnt(8)
	v_pk_add_f32 v[202:203], v[26:27], v[30:31]
	v_pk_add_f32 v[26:27], v[26:27], v[30:31] neg_lo:[0,1] neg_hi:[0,1]
	v_pk_add_f32 v[204:205], v[28:29], v[32:33]
	v_pk_add_f32 v[28:29], v[28:29], v[32:33] neg_lo:[0,1] neg_hi:[0,1]
	v_pk_add_f32 v[30:31], v[202:203], v[204:205]
	v_pk_add_f32 v[32:33], v[202:203], v[204:205] neg_lo:[0,1] neg_hi:[0,1]
	v_pk_add_f32 v[202:203], v[26:27], v[28:29] op_sel:[0,1] op_sel_hi:[1,0] neg_hi:[0,1]
	v_pk_add_f32 v[204:205], v[26:27], v[28:29] op_sel:[0,1] op_sel_hi:[1,0] neg_lo:[0,1]
	v_pk_mul_f32 v[206:207], v[210:211], v[210:211] op_sel:[1,1] op_sel_hi:[1,0]
	v_pk_fma_f32 v[212:213], v[210:211], v[210:211], v[206:207] op_sel_hi:[0,1,1] neg_lo:[0,0,1]
	v_pk_mul_f32 v[206:207], v[210:211], v[212:213] op_sel:[1,1] op_sel_hi:[1,0]
	v_pk_fma_f32 v[220:221], v[210:211], v[212:213], v[206:207] op_sel_hi:[0,1,1] neg_lo:[0,0,1]
	v_pk_mul_f32 v[26:27], v[210:211], v[202:203] op_sel:[1,1] op_sel_hi:[1,0]
	v_pk_fma_f32 v[26:27], v[210:211], v[202:203], v[26:27] op_sel_hi:[0,1,1] neg_lo:[0,0,1]
	v_pk_mul_f32 v[28:29], v[212:213], v[32:33] op_sel:[1,1] op_sel_hi:[1,0]
	v_pk_fma_f32 v[28:29], v[212:213], v[32:33], v[28:29] op_sel_hi:[0,1,1] neg_lo:[0,0,1]
	v_pk_mul_f32 v[32:33], v[220:221], v[204:205] op_sel:[1,1] op_sel_hi:[1,0]
	v_pk_fma_f32 v[32:33], v[220:221], v[204:205], v[32:33] op_sel_hi:[0,1,1] neg_lo:[0,0,1]
	v_mul_f32_e32 v210, 0x3f3504f3, v224
	v_mul_f32_e32 v211, 0xbf3504f3, v224
	v_fmac_f32_e32 v210, 0x3f3504f3, v225
	v_fmac_f32_e32 v211, 0x3f3504f3, v225
	s_waitcnt lgkmcnt(6)
; DI f32x2 cmul(f32x2 a, f32x2 b) { return mkf2(a.x * b.x - a.y * b.y, a.x * b.y + a.y * b.x); }
; DI void fft8192(f32x2* buf, const f32x2* __restrict__ tw) {
;     ...
; #pragma unroll
;     for (int e = 0; e < 8; ++e) {
;       const int i = tid + 256 * e;
;       const int q = i & (s - 1);
;       const int ps = i - q;
;       const float rev = (float)ps * (1.f / 8192.f);
;       const f32x2 w1 = mkf2(__builtin_amdgcn_cosf(rev), -__builtin_amdgcn_sinf(rev));
;       const f32x2 w2 = cmul(w1, w1), w3 = cmul(w1, w2);
;       const f32x2 apc = mkf2(a[e].x + c[e].x, a[e].y + c[e].y), amc = mkf2(a[e].x - c[e].x, a[e].y - c[e].y);
;       const f32x2 bpd = mkf2(b[e].x + d[e].x, b[e].y + d[e].y), bmd = mkf2(b[e].x - d[e].x, b[e].y - d[e].y);
;       const int o = 4 * i - 3 * q;
;       buf[SW(o)] = mkf2(apc.x + bpd.x, apc.y + bpd.y);
;       buf[SW(o + s)] = cmul(w1, mkf2(amc.x + bmd.y, amc.y - bmd.x));
;       buf[SW(o + 2 * s)] = cmul(w2, mkf2(apc.x - bpd.x, apc.y - bpd.y));
;       buf[SW(o + 3 * s)] = cmul(w3, mkf2(amc.x - bmd.y, amc.y + bmd.x));
;     }
	v_pk_add_f32 v[202:203], v[34:35], v[38:39]
	v_pk_add_f32 v[34:35], v[34:35], v[38:39] neg_lo:[0,1] neg_hi:[0,1]
	v_pk_add_f32 v[204:205], v[36:37], v[40:41]
	v_pk_add_f32 v[36:37], v[36:37], v[40:41] neg_lo:[0,1] neg_hi:[0,1]
	v_pk_add_f32 v[38:39], v[202:203], v[204:205]
	v_pk_add_f32 v[40:41], v[202:203], v[204:205] neg_lo:[0,1] neg_hi:[0,1]
	v_pk_add_f32 v[202:203], v[34:35], v[36:37] op_sel:[0,1] op_sel_hi:[1,0] neg_hi:[0,1]
	v_pk_add_f32 v[204:205], v[34:35], v[36:37] op_sel:[0,1] op_sel_hi:[1,0] neg_lo:[0,1]
	v_pk_mul_f32 v[206:207], v[210:211], v[210:211] op_sel:[1,1] op_sel_hi:[1,0]
	v_pk_fma_f32 v[212:213], v[210:211], v[210:211], v[206:207] op_sel_hi:[0,1,1] neg_lo:[0,0,1]
	v_pk_mul_f32 v[206:207], v[210:211], v[212:213] op_sel:[1,1] op_sel_hi:[1,0]
	v_pk_fma_f32 v[220:221], v[210:211], v[212:213], v[206:207] op_sel_hi:[0,1,1] neg_lo:[0,0,1]
	v_pk_mul_f32 v[34:35], v[210:211], v[202:203] op_sel:[1,1] op_sel_hi:[1,0]
	v_pk_fma_f32 v[34:35], v[210:211], v[202:203], v[34:35] op_sel_hi:[0,1,1] neg_lo:[0,0,1]
	v_pk_mul_f32 v[36:37], v[212:213], v[40:41] op_sel:[1,1] op_sel_hi:[1,0]
	v_pk_fma_f32 v[36:37], v[212:213], v[40:41], v[36:37] op_sel_hi:[0,1,1] neg_lo:[0,0,1]
	v_pk_mul_f32 v[40:41], v[220:221], v[204:205] op_sel:[1,1] op_sel_hi:[1,0]
	v_pk_fma_f32 v[40:41], v[220:221], v[204:205], v[40:41] op_sel_hi:[0,1,1] neg_lo:[0,0,1]
	v_mul_f32_e32 v210, 0x3f0e39da, v224
	v_mul_f32_e32 v211, 0xbf54db31, v224
	v_fmac_f32_e32 v210, 0x3f54db31, v225
	v_fmac_f32_e32 v211, 0x3f0e39da, v225
	s_waitcnt lgkmcnt(4)
	v_pk_add_f32 v[202:203], v[42:43], v[46:47]
	v_pk_add_f32 v[42:43], v[42:43], v[46:47] neg_lo:[0,1] neg_hi:[0,1]
	v_pk_add_f32 v[204:205], v[44:45], v[48:49]
	v_pk_add_f32 v[44:45], v[44:45], v[48:49] neg_lo:[0,1] neg_hi:[0,1]
	v_pk_add_f32 v[46:47], v[202:203], v[204:205]
	v_pk_add_f32 v[48:49], v[202:203], v[204:205] neg_lo:[0,1] neg_hi:[0,1]
	v_pk_add_f32 v[202:203], v[42:43], v[44:45] op_sel:[0,1] op_sel_hi:[1,0] neg_hi:[0,1]
	v_pk_add_f32 v[204:205], v[42:43], v[44:45] op_sel:[0,1] op_sel_hi:[1,0] neg_lo:[0,1]
	v_pk_mul_f32 v[206:207], v[210:211], v[210:211] op_sel:[1,1] op_sel_hi:[1,0]
	v_pk_fma_f32 v[212:213], v[210:211], v[210:211], v[206:207] op_sel_hi:[0,1,1] neg_lo:[0,0,1]
	v_pk_mul_f32 v[206:207], v[210:211], v[212:213] op_sel:[1,1] op_sel_hi:[1,0]
	v_pk_fma_f32 v[220:221], v[210:211], v[212:213], v[206:207] op_sel_hi:[0,1,1] neg_lo:[0,0,1]
	v_pk_mul_f32 v[42:43], v[210:211], v[202:203] op_sel:[1,1] op_sel_hi:[1,0]
	v_pk_fma_f32 v[42:43], v[210:211], v[202:203], v[42:43] op_sel_hi:[0,1,1] neg_lo:[0,0,1]
	v_pk_mul_f32 v[44:45], v[212:213], v[48:49] op_sel:[1,1] op_sel_hi:[1,0]
	v_pk_fma_f32 v[44:45], v[212:213], v[48:49], v[44:45] op_sel_hi:[0,1,1] neg_lo:[0,0,1]
	v_pk_mul_f32 v[48:49], v[220:221], v[204:205] op_sel:[1,1] op_sel_hi:[1,0]
	v_pk_fma_f32 v[48:49], v[220:221], v[204:205], v[48:49] op_sel_hi:[0,1,1] neg_lo:[0,0,1]
	v_mul_f32_e32 v210, 0x3ec3ef15, v224
	v_mul_f32_e32 v211, 0xbf6c835e, v224
	v_fmac_f32_e32 v210, 0x3f6c835e, v225
	v_fmac_f32_e32 v211, 0x3ec3ef15, v225
	s_waitcnt lgkmcnt(2)
	v_pk_add_f32 v[202:203], v[50:51], v[54:55]
	v_pk_add_f32 v[50:51], v[50:51], v[54:55] neg_lo:[0,1] neg_hi:[0,1]
	v_pk_add_f32 v[204:205], v[52:53], v[56:57]
	v_pk_add_f32 v[52:53], v[52:53], v[56:57] neg_lo:[0,1] neg_hi:[0,1]
	v_pk_add_f32 v[54:55], v[202:203], v[204:205]
	v_pk_add_f32 v[56:57], v[202:203], v[204:205] neg_lo:[0,1] neg_hi:[0,1]
	v_pk_add_f32 v[202:203], v[50:51], v[52:53] op_sel:[0,1] op_sel_hi:[1,0] neg_hi:[0,1]
	v_pk_add_f32 v[204:205], v[50:51], v[52:53] op_sel:[0,1] op_sel_hi:[1,0] neg_lo:[0,1]
	v_pk_mul_f32 v[206:207], v[210:211], v[210:211] op_sel:[1,1] op_sel_hi:[1,0]
	v_pk_fma_f32 v[212:213], v[210:211], v[210:211], v[206:207] op_sel_hi:[0,1,1] neg_lo:[0,0,1]
	v_pk_mul_f32 v[206:207], v[210:211], v[212:213] op_sel:[1,1] op_sel_hi:[1,0]
	v_pk_fma_f32 v[220:221], v[210:211], v[212:213], v[206:207] op_sel_hi:[0,1,1] neg_lo:[0,0,1]
	v_pk_mul_f32 v[50:51], v[210:211], v[202:203] op_sel:[1,1] op_sel_hi:[1,0]
	v_pk_fma_f32 v[50:51], v[210:211], v[202:203], v[50:51] op_sel_hi:[0,1,1] neg_lo:[0,0,1]
	v_pk_mul_f32 v[52:53], v[212:213], v[56:57] op_sel:[1,1] op_sel_hi:[1,0]
	v_pk_fma_f32 v[52:53], v[212:213], v[56:57], v[52:53] op_sel_hi:[0,1,1] neg_lo:[0,0,1]
	v_pk_mul_f32 v[56:57], v[220:221], v[204:205] op_sel:[1,1] op_sel_hi:[1,0]
	v_pk_fma_f32 v[56:57], v[220:221], v[204:205], v[56:57] op_sel_hi:[0,1,1] neg_lo:[0,0,1]
	v_mul_f32_e32 v210, 0x3e47c5c2, v224
	v_mul_f32_e32 v211, 0xbf7b14be, v224
	v_fmac_f32_e32 v210, 0x3f7b14be, v225
	v_fmac_f32_e32 v211, 0x3e47c5c2, v225
	s_waitcnt lgkmcnt(0)
	v_pk_add_f32 v[202:203], v[58:59], v[62:63]
	v_pk_add_f32 v[58:59], v[58:59], v[62:63] neg_lo:[0,1] neg_hi:[0,1]
	v_pk_add_f32 v[204:205], v[60:61], v[64:65]
	v_pk_add_f32 v[60:61], v[60:61], v[64:65] neg_lo:[0,1] neg_hi:[0,1]
	v_pk_add_f32 v[62:63], v[202:203], v[204:205]
	v_pk_add_f32 v[64:65], v[202:203], v[204:205] neg_lo:[0,1] neg_hi:[0,1]
	v_pk_add_f32 v[202:203], v[58:59], v[60:61] op_sel:[0,1] op_sel_hi:[1,0] neg_hi:[0,1]
	v_pk_add_f32 v[204:205], v[58:59], v[60:61] op_sel:[0,1] op_sel_hi:[1,0] neg_lo:[0,1]
	v_pk_mul_f32 v[206:207], v[210:211], v[210:211] op_sel:[1,1] op_sel_hi:[1,0]
	v_pk_fma_f32 v[212:213], v[210:211], v[210:211], v[206:207] op_sel_hi:[0,1,1] neg_lo:[0,0,1]
	v_pk_mul_f32 v[206:207], v[210:211], v[212:213] op_sel:[1,1] op_sel_hi:[1,0]
	v_pk_fma_f32 v[220:221], v[210:211], v[212:213], v[206:207] op_sel_hi:[0,1,1] neg_lo:[0,0,1]
	v_pk_mul_f32 v[58:59], v[210:211], v[202:203] op_sel:[1,1] op_sel_hi:[1,0]
	v_pk_fma_f32 v[58:59], v[210:211], v[202:203], v[58:59] op_sel_hi:[0,1,1] neg_lo:[0,0,1]
	v_pk_mul_f32 v[60:61], v[212:213], v[64:65] op_sel:[1,1] op_sel_hi:[1,0]
	v_pk_fma_f32 v[60:61], v[212:213], v[64:65], v[60:61] op_sel_hi:[0,1,1] neg_lo:[0,0,1]
	v_pk_mul_f32 v[64:65], v[220:221], v[204:205] op_sel:[1,1] op_sel_hi:[1,0]
	v_pk_fma_f32 v[64:65], v[220:221], v[204:205], v[64:65] op_sel_hi:[0,1,1] neg_lo:[0,0,1]
	s_barrier
; DI f32x2 cmul(f32x2 a, f32x2 b) { return mkf2(a.x * b.x - a.y * b.y, a.x * b.y + a.y * b.x); }
; DI void fft8192(f32x2* buf, const f32x2* __restrict__ tw) {
;     ...
; #pragma unroll
;     for (int e = 0; e < 8; ++e) {
;       const int i = tid + 256 * e;
;       const int q = i & (s - 1);
;       const int ps = i - q;
;       const float rev = (float)ps * (1.f / 8192.f);
;       const f32x2 w1 = mkf2(__builtin_amdgcn_cosf(rev), -__builtin_amdgcn_sinf(rev));
;       const f32x2 w2 = cmul(w1, w1), w3 = cmul(w1, w2);
;       const f32x2 apc = mkf2(a[e].x + c[e].x, a[e].y + c[e].y), amc = mkf2(a[e].x - c[e].x, a[e].y - c[e].y);
;       const f32x2 bpd = mkf2(b[e].x + d[e].x, b[e].y + d[e].y), bmd = mkf2(b[e].x - d[e].x, b[e].y - d[e].y);
;       const int o = 4 * i - 3 * q;
;       buf[SW(o)] = mkf2(apc.x + bpd.x, apc.y + bpd.y);
;       buf[SW(o + s)] = cmul(w1, mkf2(amc.x + bmd.y, amc.y - bmd.x));
;       buf[SW(o + 2 * s)] = cmul(w2, mkf2(apc.x - bpd.x, apc.y - bpd.y));
;       buf[SW(o + 3 * s)] = cmul(w3, mkf2(amc.x - bmd.y, amc.y + bmd.x));
;     }
	v_mul_f32_e32 v214, 4.0, v201
	v_cos_f32_e32 v224, v214
	v_sin_f32_e64 v225, -v214
	s_nop 0
	v_pk_mul_f32 v[206:207], v[224:225], v[224:225] op_sel:[1,1] op_sel_hi:[1,0]
	v_pk_fma_f32 v[226:227], v[224:225], v[224:225], v[206:207] op_sel_hi:[0,1,1] neg_lo:[0,0,1]
	v_pk_mul_f32 v[206:207], v[224:225], v[226:227] op_sel:[1,1] op_sel_hi:[1,0]
	v_pk_fma_f32 v[230:231], v[224:225], v[226:227], v[206:207] op_sel_hi:[0,1,1] neg_lo:[0,0,1]
	v_pk_add_f32 v[202:203], v[6:7], v[38:39]
	v_pk_add_f32 v[6:7], v[6:7], v[38:39] neg_lo:[0,1] neg_hi:[0,1]
	v_pk_add_f32 v[204:205], v[22:23], v[54:55]
	v_pk_add_f32 v[22:23], v[22:23], v[54:55] neg_lo:[0,1] neg_hi:[0,1]
	v_pk_add_f32 v[38:39], v[202:203], v[204:205]
	v_pk_add_f32 v[54:55], v[202:203], v[204:205] neg_lo:[0,1] neg_hi:[0,1]
	v_pk_add_f32 v[202:203], v[6:7], v[22:23] op_sel:[0,1] op_sel_hi:[1,0] neg_hi:[0,1]
	v_pk_add_f32 v[204:205], v[6:7], v[22:23] op_sel:[0,1] op_sel_hi:[1,0] neg_lo:[0,1]
	v_pk_mul_f32 v[6:7], v[224:225], v[202:203] op_sel:[1,1] op_sel_hi:[1,0]
	v_pk_fma_f32 v[6:7], v[224:225], v[202:203], v[6:7] op_sel_hi:[0,1,1] neg_lo:[0,0,1]
	v_pk_mul_f32 v[22:23], v[226:227], v[54:55] op_sel:[1,1] op_sel_hi:[1,0]
	v_pk_fma_f32 v[22:23], v[226:227], v[54:55], v[22:23] op_sel_hi:[0,1,1] neg_lo:[0,0,1]
	v_pk_mul_f32 v[54:55], v[230:231], v[204:205] op_sel:[1,1] op_sel_hi:[1,0]
	v_pk_fma_f32 v[54:55], v[230:231], v[204:205], v[54:55] op_sel_hi:[0,1,1] neg_lo:[0,0,1]
	v_pk_add_f32 v[202:203], v[2:3], v[34:35]
	v_pk_add_f32 v[2:3], v[2:3], v[34:35] neg_lo:[0,1] neg_hi:[0,1]
	v_pk_add_f32 v[204:205], v[18:19], v[50:51]
	v_pk_add_f32 v[18:19], v[18:19], v[50:51] neg_lo:[0,1] neg_hi:[0,1]
	v_pk_add_f32 v[34:35], v[202:203], v[204:205]
	v_pk_add_f32 v[50:51], v[202:203], v[204:205] neg_lo:[0,1] neg_hi:[0,1]
	v_pk_add_f32 v[202:203], v[2:3], v[18:19] op_sel:[0,1] op_sel_hi:[1,0] neg_hi:[0,1]
	v_pk_add_f32 v[204:205], v[2:3], v[18:19] op_sel:[0,1] op_sel_hi:[1,0] neg_lo:[0,1]
	v_pk_mul_f32 v[2:3], v[224:225], v[202:203] op_sel:[1,1] op_sel_hi:[1,0]
	v_pk_fma_f32 v[2:3], v[224:225], v[202:203], v[2:3] op_sel_hi:[0,1,1] neg_lo:[0,0,1]
	v_pk_mul_f32 v[18:19], v[226:227], v[50:51] op_sel:[1,1] op_sel_hi:[1,0]
	v_pk_fma_f32 v[18:19], v[226:227], v[50:51], v[18:19] op_sel_hi:[0,1,1] neg_lo:[0,0,1]
	v_pk_mul_f32 v[50:51], v[230:231], v[204:205] op_sel:[1,1] op_sel_hi:[1,0]
	v_pk_fma_f32 v[50:51], v[230:231], v[204:205], v[50:51] op_sel_hi:[0,1,1] neg_lo:[0,0,1]
	v_pk_add_f32 v[202:203], v[4:5], v[36:37]
	v_pk_add_f32 v[4:5], v[4:5], v[36:37] neg_lo:[0,1] neg_hi:[0,1]
	v_pk_add_f32 v[204:205], v[20:21], v[52:53]
	v_pk_add_f32 v[20:21], v[20:21], v[52:53] neg_lo:[0,1] neg_hi:[0,1]
	v_pk_add_f32 v[36:37], v[202:203], v[204:205]
	v_pk_add_f32 v[52:53], v[202:203], v[204:205] neg_lo:[0,1] neg_hi:[0,1]
	v_pk_add_f32 v[202:203], v[4:5], v[20:21] op_sel:[0,1] op_sel_hi:[1,0] neg_hi:[0,1]
	v_pk_add_f32 v[204:205], v[4:5], v[20:21] op_sel:[0,1] op_sel_hi:[1,0] neg_lo:[0,1]
	v_pk_mul_f32 v[4:5], v[224:225], v[202:203] op_sel:[1,1] op_sel_hi:[1,0]
	v_pk_fma_f32 v[4:5], v[224:225], v[202:203], v[4:5] op_sel_hi:[0,1,1] neg_lo:[0,0,1]
	v_pk_mul_f32 v[20:21], v[226:227], v[52:53] op_sel:[1,1] op_sel_hi:[1,0]
	v_pk_fma_f32 v[20:21], v[226:227], v[52:53], v[20:21] op_sel_hi:[0,1,1] neg_lo:[0,0,1]
	v_pk_mul_f32 v[52:53], v[230:231], v[204:205] op_sel:[1,1] op_sel_hi:[1,0]
	v_pk_fma_f32 v[52:53], v[230:231], v[204:205], v[52:53] op_sel_hi:[0,1,1] neg_lo:[0,0,1]
	v_pk_add_f32 v[202:203], v[8:9], v[40:41]
	v_pk_add_f32 v[8:9], v[8:9], v[40:41] neg_lo:[0,1] neg_hi:[0,1]
	v_pk_add_f32 v[204:205], v[24:25], v[56:57]
	v_pk_add_f32 v[24:25], v[24:25], v[56:57] neg_lo:[0,1] neg_hi:[0,1]
	v_pk_add_f32 v[40:41], v[202:203], v[204:205]
	v_pk_add_f32 v[56:57], v[202:203], v[204:205] neg_lo:[0,1] neg_hi:[0,1]
	v_pk_add_f32 v[202:203], v[8:9], v[24:25] op_sel:[0,1] op_sel_hi:[1,0] neg_hi:[0,1]
	v_pk_add_f32 v[204:205], v[8:9], v[24:25] op_sel:[0,1] op_sel_hi:[1,0] neg_lo:[0,1]
	v_pk_mul_f32 v[8:9], v[224:225], v[202:203] op_sel:[1,1] op_sel_hi:[1,0]
	v_pk_fma_f32 v[8:9], v[224:225], v[202:203], v[8:9] op_sel_hi:[0,1,1] neg_lo:[0,0,1]
	v_pk_mul_f32 v[24:25], v[226:227], v[56:57] op_sel:[1,1] op_sel_hi:[1,0]
	v_pk_fma_f32 v[24:25], v[226:227], v[56:57], v[24:25] op_sel_hi:[0,1,1] neg_lo:[0,0,1]
	v_pk_mul_f32 v[56:57], v[230:231], v[204:205] op_sel:[1,1] op_sel_hi:[1,0]
	v_pk_fma_f32 v[56:57], v[230:231], v[204:205], v[56:57] op_sel_hi:[0,1,1] neg_lo:[0,0,1]
	v_mul_f32_e32 v214, 4.0, v201
	v_add_f32_e32 v214, 0x3e000000, v214
	v_cos_f32_e32 v224, v214
	v_sin_f32_e64 v225, -v214
	s_nop 0
	v_pk_mul_f32 v[206:207], v[224:225], v[224:225] op_sel:[1,1] op_sel_hi:[1,0]
	v_pk_fma_f32 v[226:227], v[224:225], v[224:225], v[206:207] op_sel_hi:[0,1,1] neg_lo:[0,0,1]
	v_pk_mul_f32 v[206:207], v[224:225], v[226:227] op_sel:[1,1] op_sel_hi:[1,0]
	v_pk_fma_f32 v[230:231], v[224:225], v[226:227], v[206:207] op_sel_hi:[0,1,1] neg_lo:[0,0,1]
	v_pk_add_f32 v[202:203], v[14:15], v[46:47]
	v_pk_add_f32 v[14:15], v[14:15], v[46:47] neg_lo:[0,1] neg_hi:[0,1]
	v_pk_add_f32 v[204:205], v[30:31], v[62:63]
	v_pk_add_f32 v[30:31], v[30:31], v[62:63] neg_lo:[0,1] neg_hi:[0,1]
	v_pk_add_f32 v[46:47], v[202:203], v[204:205]
	v_pk_add_f32 v[62:63], v[202:203], v[204:205] neg_lo:[0,1] neg_hi:[0,1]
	v_pk_add_f32 v[202:203], v[14:15], v[30:31] op_sel:[0,1] op_sel_hi:[1,0] neg_hi:[0,1]
	v_pk_add_f32 v[204:205], v[14:15], v[30:31] op_sel:[0,1] op_sel_hi:[1,0] neg_lo:[0,1]
	v_pk_mul_f32 v[14:15], v[224:225], v[202:203] op_sel:[1,1] op_sel_hi:[1,0]
	v_pk_fma_f32 v[14:15], v[224:225], v[202:203], v[14:15] op_sel_hi:[0,1,1] neg_lo:[0,0,1]
	v_pk_mul_f32 v[30:31], v[226:227], v[62:63] op_sel:[1,1] op_sel_hi:[1,0]
; DI f32x2 cmul(f32x2 a, f32x2 b) { return mkf2(a.x * b.x - a.y * b.y, a.x * b.y + a.y * b.x); }
; DI void fft8192(f32x2* buf, const f32x2* __restrict__ tw) {
;     ...
; #pragma unroll
;     for (int e = 0; e < 8; ++e) {
;       const int i = tid + 256 * e;
;       const int q = i & (s - 1);
;       const int ps = i - q;
;       const float rev = (float)ps * (1.f / 8192.f);
;       const f32x2 w1 = mkf2(__builtin_amdgcn_cosf(rev), -__builtin_amdgcn_sinf(rev));
;       const f32x2 w2 = cmul(w1, w1), w3 = cmul(w1, w2);
;       const f32x2 apc = mkf2(a[e].x + c[e].x, a[e].y + c[e].y), amc = mkf2(a[e].x - c[e].x, a[e].y - c[e].y);
;       const f32x2 bpd = mkf2(b[e].x + d[e].x, b[e].y + d[e].y), bmd = mkf2(b[e].x - d[e].x, b[e].y - d[e].y);
;       const int o = 4 * i - 3 * q;
;       buf[SW(o)] = mkf2(apc.x + bpd.x, apc.y + bpd.y);
;       buf[SW(o + s)] = cmul(w1, mkf2(amc.x + bmd.y, amc.y - bmd.x));
;       buf[SW(o + 2 * s)] = cmul(w2, mkf2(apc.x - bpd.x, apc.y - bpd.y));
;       buf[SW(o + 3 * s)] = cmul(w3, mkf2(amc.x - bmd.y, amc.y + bmd.x));
;     }
	v_pk_fma_f32 v[30:31], v[226:227], v[62:63], v[30:31] op_sel_hi:[0,1,1] neg_lo:[0,0,1]
	v_pk_mul_f32 v[62:63], v[230:231], v[204:205] op_sel:[1,1] op_sel_hi:[1,0]
	v_pk_fma_f32 v[62:63], v[230:231], v[204:205], v[62:63] op_sel_hi:[0,1,1] neg_lo:[0,0,1]
	v_pk_add_f32 v[202:203], v[10:11], v[42:43]
	v_pk_add_f32 v[10:11], v[10:11], v[42:43] neg_lo:[0,1] neg_hi:[0,1]
	v_pk_add_f32 v[204:205], v[26:27], v[58:59]
	v_pk_add_f32 v[26:27], v[26:27], v[58:59] neg_lo:[0,1] neg_hi:[0,1]
	v_pk_add_f32 v[42:43], v[202:203], v[204:205]
	v_pk_add_f32 v[58:59], v[202:203], v[204:205] neg_lo:[0,1] neg_hi:[0,1]
	v_pk_add_f32 v[202:203], v[10:11], v[26:27] op_sel:[0,1] op_sel_hi:[1,0] neg_hi:[0,1]
	v_pk_add_f32 v[204:205], v[10:11], v[26:27] op_sel:[0,1] op_sel_hi:[1,0] neg_lo:[0,1]
	v_pk_mul_f32 v[10:11], v[224:225], v[202:203] op_sel:[1,1] op_sel_hi:[1,0]
	v_pk_fma_f32 v[10:11], v[224:225], v[202:203], v[10:11] op_sel_hi:[0,1,1] neg_lo:[0,0,1]
	v_pk_mul_f32 v[26:27], v[226:227], v[58:59] op_sel:[1,1] op_sel_hi:[1,0]
	v_pk_fma_f32 v[26:27], v[226:227], v[58:59], v[26:27] op_sel_hi:[0,1,1] neg_lo:[0,0,1]
	v_pk_mul_f32 v[58:59], v[230:231], v[204:205] op_sel:[1,1] op_sel_hi:[1,0]
	v_pk_fma_f32 v[58:59], v[230:231], v[204:205], v[58:59] op_sel_hi:[0,1,1] neg_lo:[0,0,1]
	v_pk_add_f32 v[202:203], v[12:13], v[44:45]
	v_pk_add_f32 v[12:13], v[12:13], v[44:45] neg_lo:[0,1] neg_hi:[0,1]
	v_pk_add_f32 v[204:205], v[28:29], v[60:61]
	v_pk_add_f32 v[28:29], v[28:29], v[60:61] neg_lo:[0,1] neg_hi:[0,1]
	v_pk_add_f32 v[44:45], v[202:203], v[204:205]
	v_pk_add_f32 v[60:61], v[202:203], v[204:205] neg_lo:[0,1] neg_hi:[0,1]
	v_pk_add_f32 v[202:203], v[12:13], v[28:29] op_sel:[0,1] op_sel_hi:[1,0] neg_hi:[0,1]
	v_pk_add_f32 v[204:205], v[12:13], v[28:29] op_sel:[0,1] op_sel_hi:[1,0] neg_lo:[0,1]
	v_pk_mul_f32 v[12:13], v[224:225], v[202:203] op_sel:[1,1] op_sel_hi:[1,0]
	v_pk_fma_f32 v[12:13], v[224:225], v[202:203], v[12:13] op_sel_hi:[0,1,1] neg_lo:[0,0,1]
	v_pk_mul_f32 v[28:29], v[226:227], v[60:61] op_sel:[1,1] op_sel_hi:[1,0]
	v_pk_fma_f32 v[28:29], v[226:227], v[60:61], v[28:29] op_sel_hi:[0,1,1] neg_lo:[0,0,1]
	v_pk_mul_f32 v[60:61], v[230:231], v[204:205] op_sel:[1,1] op_sel_hi:[1,0]
	v_pk_fma_f32 v[60:61], v[230:231], v[204:205], v[60:61] op_sel_hi:[0,1,1] neg_lo:[0,0,1]
	v_pk_add_f32 v[202:203], v[16:17], v[48:49]
	v_pk_add_f32 v[16:17], v[16:17], v[48:49] neg_lo:[0,1] neg_hi:[0,1]
	v_pk_add_f32 v[204:205], v[32:33], v[64:65]
	v_pk_add_f32 v[32:33], v[32:33], v[64:65] neg_lo:[0,1] neg_hi:[0,1]
	v_pk_add_f32 v[48:49], v[202:203], v[204:205]
	v_pk_add_f32 v[64:65], v[202:203], v[204:205] neg_lo:[0,1] neg_hi:[0,1]
	v_pk_add_f32 v[202:203], v[16:17], v[32:33] op_sel:[0,1] op_sel_hi:[1,0] neg_hi:[0,1]
	v_pk_add_f32 v[204:205], v[16:17], v[32:33] op_sel:[0,1] op_sel_hi:[1,0] neg_lo:[0,1]
	v_pk_mul_f32 v[16:17], v[224:225], v[202:203] op_sel:[1,1] op_sel_hi:[1,0]
	v_pk_fma_f32 v[16:17], v[224:225], v[202:203], v[16:17] op_sel_hi:[0,1,1] neg_lo:[0,0,1]
	v_pk_mul_f32 v[32:33], v[226:227], v[64:65] op_sel:[1,1] op_sel_hi:[1,0]
	v_pk_fma_f32 v[32:33], v[226:227], v[64:65], v[32:33] op_sel_hi:[0,1,1] neg_lo:[0,0,1]
	v_pk_mul_f32 v[64:65], v[230:231], v[204:205] op_sel:[1,1] op_sel_hi:[1,0]
	v_pk_fma_f32 v[64:65], v[230:231], v[204:205], v[64:65] op_sel_hi:[0,1,1] neg_lo:[0,0,1]
	ds_write_b64 v164, v[38:39] offset:0
	v_xor_b32_e32 v156, 8, v164
	ds_write_b64 v156, v[34:35] offset:0
	v_xor_b32_e32 v158, 16, v164
	ds_write_b64 v158, v[36:37] offset:0
	v_xor_b32_e32 v160, 24, v164
	ds_write_b64 v160, v[40:41] offset:0
	v_xor_b32_e32 v162, 32, v164
	ds_write_b64 v162, v[6:7] offset:0
	v_xor_b32_e32 v156, 40, v164
	ds_write_b64 v156, v[2:3] offset:0
	v_xor_b32_e32 v158, 48, v164
	ds_write_b64 v158, v[4:5] offset:0
	v_xor_b32_e32 v160, 56, v164
	ds_write_b64 v160, v[8:9] offset:0
	v_xor_b32_e32 v162, 64, v164
	ds_write_b64 v162, v[22:23] offset:0
	v_xor_b32_e32 v156, 0x48, v164
	ds_write_b64 v156, v[18:19] offset:0
	v_xor_b32_e32 v158, 0x50, v164
	ds_write_b64 v158, v[20:21] offset:0
	v_xor_b32_e32 v160, 0x58, v164
	ds_write_b64 v160, v[24:25] offset:0
	v_xor_b32_e32 v162, 0x60, v164
	ds_write_b64 v162, v[54:55] offset:0
	v_xor_b32_e32 v156, 0x68, v164
	ds_write_b64 v156, v[50:51] offset:0
	v_xor_b32_e32 v158, 0x70, v164
	ds_write_b64 v158, v[52:53] offset:0
	v_xor_b32_e32 v160, 0x78, v164
	ds_write_b64 v160, v[56:57] offset:0
	ds_write_b64 v164, v[46:47] offset:32768
	v_xor_b32_e32 v162, 8, v164
	ds_write_b64 v162, v[42:43] offset:32768
	v_xor_b32_e32 v156, 16, v164
	ds_write_b64 v156, v[44:45] offset:32768
	v_xor_b32_e32 v158, 24, v164
	ds_write_b64 v158, v[48:49] offset:32768
	v_xor_b32_e32 v160, 32, v164
	ds_write_b64 v160, v[14:15] offset:32768
	v_xor_b32_e32 v162, 40, v164
	ds_write_b64 v162, v[10:11] offset:32768
	v_xor_b32_e32 v156, 48, v164
	ds_write_b64 v156, v[12:13] offset:32768
	v_xor_b32_e32 v158, 56, v164
	ds_write_b64 v158, v[16:17] offset:32768
	v_xor_b32_e32 v160, 64, v164
	ds_write_b64 v160, v[30:31] offset:32768
	v_xor_b32_e32 v162, 0x48, v164
	ds_write_b64 v162, v[26:27] offset:32768
	v_xor_b32_e32 v156, 0x50, v164
	ds_write_b64 v156, v[28:29] offset:32768
	v_xor_b32_e32 v158, 0x58, v164
	ds_write_b64 v158, v[32:33] offset:32768
	v_xor_b32_e32 v160, 0x60, v164
	ds_write_b64 v160, v[62:63] offset:32768
	v_xor_b32_e32 v162, 0x68, v164
	ds_write_b64 v162, v[58:59] offset:32768
	v_xor_b32_e32 v156, 0x70, v164
	ds_write_b64 v156, v[60:61] offset:32768
	v_xor_b32_e32 v158, 0x78, v164
	ds_write_b64 v158, v[64:65] offset:32768
	s_waitcnt lgkmcnt(0)
	s_barrier
; DI f32x2 cmul(f32x2 a, f32x2 b) { return mkf2(a.x * b.x - a.y * b.y, a.x * b.y + a.y * b.x); }
; DI void fft8192(f32x2* buf, const f32x2* __restrict__ tw) {
;     ...
;   for (int ls = 0; ls < 12; ls += 2) {
;     const int s = 1 << ls;
;     f32x2 a[8], b[8], c[8], d[8];
;     __syncthreads();
; #pragma unroll
;     for (int e = 0; e < 8; ++e) {
;       const int i = tid + 256 * e;
;       const int pi = SW(i);
;       a[e] = buf[pi]; b[e] = buf[pi + 2048]; c[e] = buf[pi + 4096]; d[e] = buf[pi + 6144];
;     }
;     __syncthreads();
; #pragma unroll
;     for (int e = 0; e < 8; ++e) {
;       const int i = tid + 256 * e;
;       const int q = i & (s - 1);
;       const int ps = i - q;
;       const float rev = (float)ps * (1.f / 8192.f);
;       const f32x2 w1 = mkf2(__builtin_amdgcn_cosf(rev), -__builtin_amdgcn_sinf(rev));
;       const f32x2 w2 = cmul(w1, w1), w3 = cmul(w1, w2);
;       const f32x2 apc = mkf2(a[e].x + c[e].x, a[e].y + c[e].y), amc = mkf2(a[e].x - c[e].x, a[e].y - c[e].y);
;       const f32x2 bpd = mkf2(b[e].x + d[e].x, b[e].y + d[e].y), bmd = mkf2(b[e].x - d[e].x, b[e].y - d[e].y);
;       const int o = 4 * i - 3 * q;
;       buf[SW(o)] = mkf2(apc.x + bpd.x, apc.y + bpd.y);
;       buf[SW(o + s)] = cmul(w1, mkf2(amc.x + bmd.y, amc.y - bmd.x));
;       buf[SW(o + 2 * s)] = cmul(w2, mkf2(apc.x - bpd.x, apc.y - bpd.y));
;       buf[SW(o + 3 * s)] = cmul(w3, mkf2(amc.x - bmd.y, amc.y + bmd.x));
;     }
	v_bfe_i32 v166, v0, 4, 4
	v_and_b32_e32 v166, 15, v166
	v_xor_b32_e32 v166, v166, v0
	v_lshlrev_b32_e32 v164, 3, v166
	ds_read2st64_b64 v[2:5], v164 offset0:0 offset1:32
	ds_read2st64_b64 v[6:9], v164 offset0:64 offset1:96
	ds_read2st64_b64 v[10:13], v164 offset0:4 offset1:36
	ds_read2st64_b64 v[14:17], v164 offset0:68 offset1:100
	ds_read2st64_b64 v[18:21], v164 offset0:8 offset1:40
	ds_read2st64_b64 v[22:25], v164 offset0:72 offset1:104
	ds_read2st64_b64 v[26:29], v164 offset0:12 offset1:44
	ds_read2st64_b64 v[30:33], v164 offset0:76 offset1:108
	ds_read2st64_b64 v[34:37], v164 offset0:16 offset1:48
	ds_read2st64_b64 v[38:41], v164 offset0:80 offset1:112
	ds_read2st64_b64 v[42:45], v164 offset0:20 offset1:52
	ds_read2st64_b64 v[46:49], v164 offset0:84 offset1:116
	ds_read2st64_b64 v[50:53], v164 offset0:24 offset1:56
	ds_read2st64_b64 v[54:57], v164 offset0:88 offset1:120
	ds_read2st64_b64 v[58:61], v164 offset0:28 offset1:60
	ds_read2st64_b64 v[62:65], v164 offset0:92 offset1:124
	v_and_b32_e32 v166, 15, v0
	v_sub_u32_e32 v168, v0, v166
	v_cvt_f32_u32_e32 v201, v168
	v_lshl_add_u32 v164, v168, 4, v166
	v_lshlrev_b32_e32 v164, 3, v164
	v_mul_f32_e32 v201, 0x39000000, v201
	v_cos_f32_e32 v210, v201
	v_sin_f32_e64 v211, -v201
	s_nop 0
	v_mov_b32_e32 v224, v210
	v_mov_b32_e32 v225, v211
	s_waitcnt lgkmcnt(14)
	v_pk_add_f32 v[202:203], v[2:3], v[6:7]
	v_pk_add_f32 v[2:3], v[2:3], v[6:7] neg_lo:[0,1] neg_hi:[0,1]
	v_pk_add_f32 v[204:205], v[4:5], v[8:9]
	v_pk_add_f32 v[4:5], v[4:5], v[8:9] neg_lo:[0,1] neg_hi:[0,1]
	v_pk_add_f32 v[6:7], v[202:203], v[204:205]
	v_pk_add_f32 v[8:9], v[202:203], v[204:205] neg_lo:[0,1] neg_hi:[0,1]
	v_pk_add_f32 v[202:203], v[2:3], v[4:5] op_sel:[0,1] op_sel_hi:[1,0] neg_hi:[0,1]
	v_pk_add_f32 v[204:205], v[2:3], v[4:5] op_sel:[0,1] op_sel_hi:[1,0] neg_lo:[0,1]
	v_pk_mul_f32 v[206:207], v[210:211], v[210:211] op_sel:[1,1] op_sel_hi:[1,0]
	v_pk_fma_f32 v[212:213], v[210:211], v[210:211], v[206:207] op_sel_hi:[0,1,1] neg_lo:[0,0,1]
	v_pk_mul_f32 v[206:207], v[210:211], v[212:213] op_sel:[1,1] op_sel_hi:[1,0]
	v_pk_fma_f32 v[220:221], v[210:211], v[212:213], v[206:207] op_sel_hi:[0,1,1] neg_lo:[0,0,1]
	v_pk_mul_f32 v[2:3], v[210:211], v[202:203] op_sel:[1,1] op_sel_hi:[1,0]
	v_pk_fma_f32 v[2:3], v[210:211], v[202:203], v[2:3] op_sel_hi:[0,1,1] neg_lo:[0,0,1]
	v_pk_mul_f32 v[4:5], v[212:213], v[8:9] op_sel:[1,1] op_sel_hi:[1,0]
	v_pk_fma_f32 v[4:5], v[212:213], v[8:9], v[4:5] op_sel_hi:[0,1,1] neg_lo:[0,0,1]
	v_pk_mul_f32 v[8:9], v[220:221], v[204:205] op_sel:[1,1] op_sel_hi:[1,0]
	v_pk_fma_f32 v[8:9], v[220:221], v[204:205], v[8:9] op_sel_hi:[0,1,1] neg_lo:[0,0,1]
	v_mul_f32_e32 v210, 0x3f7b14be, v224
	v_mul_f32_e32 v211, 0xbe47c5c2, v224
	v_fmac_f32_e32 v210, 0x3e47c5c2, v225
	v_fmac_f32_e32 v211, 0x3f7b14be, v225
	s_waitcnt lgkmcnt(12)
	v_pk_add_f32 v[202:203], v[10:11], v[14:15]
	v_pk_add_f32 v[10:11], v[10:11], v[14:15] neg_lo:[0,1] neg_hi:[0,1]
	v_pk_add_f32 v[204:205], v[12:13], v[16:17]
	v_pk_add_f32 v[12:13], v[12:13], v[16:17] neg_lo:[0,1] neg_hi:[0,1]
	v_pk_add_f32 v[14:15], v[202:203], v[204:205]
	v_pk_add_f32 v[16:17], v[202:203], v[204:205] neg_lo:[0,1] neg_hi:[0,1]
	v_pk_add_f32 v[202:203], v[10:11], v[12:13] op_sel:[0,1] op_sel_hi:[1,0] neg_hi:[0,1]
	v_pk_add_f32 v[204:205], v[10:11], v[12:13] op_sel:[0,1] op_sel_hi:[1,0] neg_lo:[0,1]
	v_pk_mul_f32 v[206:207], v[210:211], v[210:211] op_sel:[1,1] op_sel_hi:[1,0]
	v_pk_fma_f32 v[212:213], v[210:211], v[210:211], v[206:207] op_sel_hi:[0,1,1] neg_lo:[0,0,1]
	v_pk_mul_f32 v[206:207], v[210:211], v[212:213] op_sel:[1,1] op_sel_hi:[1,0]
	v_pk_fma_f32 v[220:221], v[210:211], v[212:213], v[206:207] op_sel_hi:[0,1,1] neg_lo:[0,0,1]
	v_pk_mul_f32 v[10:11], v[210:211], v[202:203] op_sel:[1,1] op_sel_hi:[1,0]
	v_pk_fma_f32 v[10:11], v[210:211], v[202:203], v[10:11] op_sel_hi:[0,1,1] neg_lo:[0,0,1]
	v_pk_mul_f32 v[12:13], v[212:213], v[16:17] op_sel:[1,1] op_sel_hi:[1,0]
	v_pk_fma_f32 v[12:13], v[212:213], v[16:17], v[12:13] op_sel_hi:[0,1,1] neg_lo:[0,0,1]
	v_pk_mul_f32 v[16:17], v[220:221], v[204:205] op_sel:[1,1] op_sel_hi:[1,0]
	v_pk_fma_f32 v[16:17], v[220:221], v[204:205], v[16:17] op_sel_hi:[0,1,1] neg_lo:[0,0,1]
	v_mul_f32_e32 v210, 0x3f6c835e, v224
	v_mul_f32_e32 v211, 0xbec3ef15, v224
	v_fmac_f32_e32 v210, 0x3ec3ef15, v225
	v_fmac_f32_e32 v211, 0x3f6c835e, v225
	s_waitcnt lgkmcnt(10)
	v_pk_add_f32 v[202:203], v[18:19], v[22:23]
	v_pk_add_f32 v[18:19], v[18:19], v[22:23] neg_lo:[0,1] neg_hi:[0,1]
	v_pk_add_f32 v[204:205], v[20:21], v[24:25]
	v_pk_add_f32 v[20:21], v[20:21], v[24:25] neg_lo:[0,1] neg_hi:[0,1]
	v_pk_add_f32 v[22:23], v[202:203], v[204:205]
	v_pk_add_f32 v[24:25], v[202:203], v[204:205] neg_lo:[0,1] neg_hi:[0,1]
	v_pk_add_f32 v[202:203], v[18:19], v[20:21] op_sel:[0,1] op_sel_hi:[1,0] neg_hi:[0,1]
	v_pk_add_f32 v[204:205], v[18:19], v[20:21] op_sel:[0,1] op_sel_hi:[1,0] neg_lo:[0,1]
	v_pk_mul_f32 v[206:207], v[210:211], v[210:211] op_sel:[1,1] op_sel_hi:[1,0]
	v_pk_fma_f32 v[212:213], v[210:211], v[210:211], v[206:207] op_sel_hi:[0,1,1] neg_lo:[0,0,1]
	v_pk_mul_f32 v[206:207], v[210:211], v[212:213] op_sel:[1,1] op_sel_hi:[1,0]
	v_pk_fma_f32 v[220:221], v[210:211], v[212:213], v[206:207] op_sel_hi:[0,1,1] neg_lo:[0,0,1]
	v_pk_mul_f32 v[18:19], v[210:211], v[202:203] op_sel:[1,1] op_sel_hi:[1,0]
	v_pk_fma_f32 v[18:19], v[210:211], v[202:203], v[18:19] op_sel_hi:[0,1,1] neg_lo:[0,0,1]
	v_pk_mul_f32 v[20:21], v[212:213], v[24:25] op_sel:[1,1] op_sel_hi:[1,0]
	v_pk_fma_f32 v[20:21], v[212:213], v[24:25], v[20:21] op_sel_hi:[0,1,1] neg_lo:[0,0,1]
	v_pk_mul_f32 v[24:25], v[220:221], v[204:205] op_sel:[1,1] op_sel_hi:[1,0]
	v_pk_fma_f32 v[24:25], v[220:221], v[204:205], v[24:25] op_sel_hi:[0,1,1] neg_lo:[0,0,1]
	v_mul_f32_e32 v210, 0x3f54db31, v224
	v_mul_f32_e32 v211, 0xbf0e39da, v224
	v_fmac_f32_e32 v210, 0x3f0e39da, v225
	v_fmac_f32_e32 v211, 0x3f54db31, v225
	s_waitcnt lgkmcnt(8)
; DI f32x2 cmul(f32x2 a, f32x2 b) { return mkf2(a.x * b.x - a.y * b.y, a.x * b.y + a.y * b.x); }
; DI void fft8192(f32x2* buf, const f32x2* __restrict__ tw) {
;     ...
; #pragma unroll
;     for (int e = 0; e < 8; ++e) {
;       const int i = tid + 256 * e;
;       const int q = i & (s - 1);
;       const int ps = i - q;
;       const float rev = (float)ps * (1.f / 8192.f);
;       const f32x2 w1 = mkf2(__builtin_amdgcn_cosf(rev), -__builtin_amdgcn_sinf(rev));
;       const f32x2 w2 = cmul(w1, w1), w3 = cmul(w1, w2);
;       const f32x2 apc = mkf2(a[e].x + c[e].x, a[e].y + c[e].y), amc = mkf2(a[e].x - c[e].x, a[e].y - c[e].y);
;       const f32x2 bpd = mkf2(b[e].x + d[e].x, b[e].y + d[e].y), bmd = mkf2(b[e].x - d[e].x, b[e].y - d[e].y);
;       const int o = 4 * i - 3 * q;
;       buf[SW(o)] = mkf2(apc.x + bpd.x, apc.y + bpd.y);
;       buf[SW(o + s)] = cmul(w1, mkf2(amc.x + bmd.y, amc.y - bmd.x));
;       buf[SW(o + 2 * s)] = cmul(w2, mkf2(apc.x - bpd.x, apc.y - bpd.y));
;       buf[SW(o + 3 * s)] = cmul(w3, mkf2(amc.x - bmd.y, amc.y + bmd.x));
;     }
	v_pk_add_f32 v[202:203], v[26:27], v[30:31]
	v_pk_add_f32 v[26:27], v[26:27], v[30:31] neg_lo:[0,1] neg_hi:[0,1]
	v_pk_add_f32 v[204:205], v[28:29], v[32:33]
	v_pk_add_f32 v[28:29], v[28:29], v[32:33] neg_lo:[0,1] neg_hi:[0,1]
	v_pk_add_f32 v[30:31], v[202:203], v[204:205]
	v_pk_add_f32 v[32:33], v[202:203], v[204:205] neg_lo:[0,1] neg_hi:[0,1]
	v_pk_add_f32 v[202:203], v[26:27], v[28:29] op_sel:[0,1] op_sel_hi:[1,0] neg_hi:[0,1]
	v_pk_add_f32 v[204:205], v[26:27], v[28:29] op_sel:[0,1] op_sel_hi:[1,0] neg_lo:[0,1]
	v_pk_mul_f32 v[206:207], v[210:211], v[210:211] op_sel:[1,1] op_sel_hi:[1,0]
	v_pk_fma_f32 v[212:213], v[210:211], v[210:211], v[206:207] op_sel_hi:[0,1,1] neg_lo:[0,0,1]
	v_pk_mul_f32 v[206:207], v[210:211], v[212:213] op_sel:[1,1] op_sel_hi:[1,0]
	v_pk_fma_f32 v[220:221], v[210:211], v[212:213], v[206:207] op_sel_hi:[0,1,1] neg_lo:[0,0,1]
	v_pk_mul_f32 v[26:27], v[210:211], v[202:203] op_sel:[1,1] op_sel_hi:[1,0]
	v_pk_fma_f32 v[26:27], v[210:211], v[202:203], v[26:27] op_sel_hi:[0,1,1] neg_lo:[0,0,1]
	v_pk_mul_f32 v[28:29], v[212:213], v[32:33] op_sel:[1,1] op_sel_hi:[1,0]
	v_pk_fma_f32 v[28:29], v[212:213], v[32:33], v[28:29] op_sel_hi:[0,1,1] neg_lo:[0,0,1]
	v_pk_mul_f32 v[32:33], v[220:221], v[204:205] op_sel:[1,1] op_sel_hi:[1,0]
	v_pk_fma_f32 v[32:33], v[220:221], v[204:205], v[32:33] op_sel_hi:[0,1,1] neg_lo:[0,0,1]
	v_mul_f32_e32 v210, 0x3f3504f3, v224
	v_mul_f32_e32 v211, 0xbf3504f3, v224
	v_fmac_f32_e32 v210, 0x3f3504f3, v225
	v_fmac_f32_e32 v211, 0x3f3504f3, v225
	s_waitcnt lgkmcnt(6)
	v_pk_add_f32 v[202:203], v[34:35], v[38:39]
	v_pk_add_f32 v[34:35], v[34:35], v[38:39] neg_lo:[0,1] neg_hi:[0,1]
	v_pk_add_f32 v[204:205], v[36:37], v[40:41]
	v_pk_add_f32 v[36:37], v[36:37], v[40:41] neg_lo:[0,1] neg_hi:[0,1]
	v_pk_add_f32 v[38:39], v[202:203], v[204:205]
	v_pk_add_f32 v[40:41], v[202:203], v[204:205] neg_lo:[0,1] neg_hi:[0,1]
	v_pk_add_f32 v[202:203], v[34:35], v[36:37] op_sel:[0,1] op_sel_hi:[1,0] neg_hi:[0,1]
	v_pk_add_f32 v[204:205], v[34:35], v[36:37] op_sel:[0,1] op_sel_hi:[1,0] neg_lo:[0,1]
	v_pk_mul_f32 v[206:207], v[210:211], v[210:211] op_sel:[1,1] op_sel_hi:[1,0]
	v_pk_fma_f32 v[212:213], v[210:211], v[210:211], v[206:207] op_sel_hi:[0,1,1] neg_lo:[0,0,1]
	v_pk_mul_f32 v[206:207], v[210:211], v[212:213] op_sel:[1,1] op_sel_hi:[1,0]
	v_pk_fma_f32 v[220:221], v[210:211], v[212:213], v[206:207] op_sel_hi:[0,1,1] neg_lo:[0,0,1]
	v_pk_mul_f32 v[34:35], v[210:211], v[202:203] op_sel:[1,1] op_sel_hi:[1,0]
	v_pk_fma_f32 v[34:35], v[210:211], v[202:203], v[34:35] op_sel_hi:[0,1,1] neg_lo:[0,0,1]
	v_pk_mul_f32 v[36:37], v[212:213], v[40:41] op_sel:[1,1] op_sel_hi:[1,0]
	v_pk_fma_f32 v[36:37], v[212:213], v[40:41], v[36:37] op_sel_hi:[0,1,1] neg_lo:[0,0,1]
	v_pk_mul_f32 v[40:41], v[220:221], v[204:205] op_sel:[1,1] op_sel_hi:[1,0]
	v_pk_fma_f32 v[40:41], v[220:221], v[204:205], v[40:41] op_sel_hi:[0,1,1] neg_lo:[0,0,1]
	v_mul_f32_e32 v210, 0x3f0e39da, v224
	v_mul_f32_e32 v211, 0xbf54db31, v224
	v_fmac_f32_e32 v210, 0x3f54db31, v225
	v_fmac_f32_e32 v211, 0x3f0e39da, v225
	s_waitcnt lgkmcnt(4)
	v_pk_add_f32 v[202:203], v[42:43], v[46:47]
	v_pk_add_f32 v[42:43], v[42:43], v[46:47] neg_lo:[0,1] neg_hi:[0,1]
	v_pk_add_f32 v[204:205], v[44:45], v[48:49]
	v_pk_add_f32 v[44:45], v[44:45], v[48:49] neg_lo:[0,1] neg_hi:[0,1]
	v_pk_add_f32 v[46:47], v[202:203], v[204:205]
	v_pk_add_f32 v[48:49], v[202:203], v[204:205] neg_lo:[0,1] neg_hi:[0,1]
	v_pk_add_f32 v[202:203], v[42:43], v[44:45] op_sel:[0,1] op_sel_hi:[1,0] neg_hi:[0,1]
	v_pk_add_f32 v[204:205], v[42:43], v[44:45] op_sel:[0,1] op_sel_hi:[1,0] neg_lo:[0,1]
	v_pk_mul_f32 v[206:207], v[210:211], v[210:211] op_sel:[1,1] op_sel_hi:[1,0]
	v_pk_fma_f32 v[212:213], v[210:211], v[210:211], v[206:207] op_sel_hi:[0,1,1] neg_lo:[0,0,1]
	v_pk_mul_f32 v[206:207], v[210:211], v[212:213] op_sel:[1,1] op_sel_hi:[1,0]
	v_pk_fma_f32 v[220:221], v[210:211], v[212:213], v[206:207] op_sel_hi:[0,1,1] neg_lo:[0,0,1]
	v_pk_mul_f32 v[42:43], v[210:211], v[202:203] op_sel:[1,1] op_sel_hi:[1,0]
	v_pk_fma_f32 v[42:43], v[210:211], v[202:203], v[42:43] op_sel_hi:[0,1,1] neg_lo:[0,0,1]
	v_pk_mul_f32 v[44:45], v[212:213], v[48:49] op_sel:[1,1] op_sel_hi:[1,0]
	v_pk_fma_f32 v[44:45], v[212:213], v[48:49], v[44:45] op_sel_hi:[0,1,1] neg_lo:[0,0,1]
	v_pk_mul_f32 v[48:49], v[220:221], v[204:205] op_sel:[1,1] op_sel_hi:[1,0]
	v_pk_fma_f32 v[48:49], v[220:221], v[204:205], v[48:49] op_sel_hi:[0,1,1] neg_lo:[0,0,1]
	v_mul_f32_e32 v210, 0x3ec3ef15, v224
	v_mul_f32_e32 v211, 0xbf6c835e, v224
	v_fmac_f32_e32 v210, 0x3f6c835e, v225
	v_fmac_f32_e32 v211, 0x3ec3ef15, v225
	s_waitcnt lgkmcnt(2)
	v_pk_add_f32 v[202:203], v[50:51], v[54:55]
	v_pk_add_f32 v[50:51], v[50:51], v[54:55] neg_lo:[0,1] neg_hi:[0,1]
	v_pk_add_f32 v[204:205], v[52:53], v[56:57]
	v_pk_add_f32 v[52:53], v[52:53], v[56:57] neg_lo:[0,1] neg_hi:[0,1]
	v_pk_add_f32 v[54:55], v[202:203], v[204:205]
	v_pk_add_f32 v[56:57], v[202:203], v[204:205] neg_lo:[0,1] neg_hi:[0,1]
	v_pk_add_f32 v[202:203], v[50:51], v[52:53] op_sel:[0,1] op_sel_hi:[1,0] neg_hi:[0,1]
	v_pk_add_f32 v[204:205], v[50:51], v[52:53] op_sel:[0,1] op_sel_hi:[1,0] neg_lo:[0,1]
	v_pk_mul_f32 v[206:207], v[210:211], v[210:211] op_sel:[1,1] op_sel_hi:[1,0]
	v_pk_fma_f32 v[212:213], v[210:211], v[210:211], v[206:207] op_sel_hi:[0,1,1] neg_lo:[0,0,1]
	v_pk_mul_f32 v[206:207], v[210:211], v[212:213] op_sel:[1,1] op_sel_hi:[1,0]
	v_pk_fma_f32 v[220:221], v[210:211], v[212:213], v[206:207] op_sel_hi:[0,1,1] neg_lo:[0,0,1]
	v_pk_mul_f32 v[50:51], v[210:211], v[202:203] op_sel:[1,1] op_sel_hi:[1,0]
	v_pk_fma_f32 v[50:51], v[210:211], v[202:203], v[50:51] op_sel_hi:[0,1,1] neg_lo:[0,0,1]
	v_pk_mul_f32 v[52:53], v[212:213], v[56:57] op_sel:[1,1] op_sel_hi:[1,0]
	v_pk_fma_f32 v[52:53], v[212:213], v[56:57], v[52:53] op_sel_hi:[0,1,1] neg_lo:[0,0,1]
	v_pk_mul_f32 v[56:57], v[220:221], v[204:205] op_sel:[1,1] op_sel_hi:[1,0]
	v_pk_fma_f32 v[56:57], v[220:221], v[204:205], v[56:57] op_sel_hi:[0,1,1] neg_lo:[0,0,1]
	v_mul_f32_e32 v210, 0x3e47c5c2, v224
	v_mul_f32_e32 v211, 0xbf7b14be, v224
	v_fmac_f32_e32 v210, 0x3f7b14be, v225
	v_fmac_f32_e32 v211, 0x3e47c5c2, v225
	s_waitcnt lgkmcnt(0)
; DI f32x2 cmul(f32x2 a, f32x2 b) { return mkf2(a.x * b.x - a.y * b.y, a.x * b.y + a.y * b.x); }
; DI void fft8192(f32x2* buf, const f32x2* __restrict__ tw) {
;     ...
;     __syncthreads();
; #pragma unroll
;     for (int e = 0; e < 8; ++e) {
;       const int i = tid + 256 * e;
;       const int pi = SW(i);
;       a[e] = buf[pi]; b[e] = buf[pi + 2048]; c[e] = buf[pi + 4096]; d[e] = buf[pi + 6144];
;     }
;     __syncthreads();
; #pragma unroll
;     for (int e = 0; e < 8; ++e) {
;       const int i = tid + 256 * e;
;       const int q = i & (s - 1);
;       const int ps = i - q;
;       const float rev = (float)ps * (1.f / 8192.f);
;       const f32x2 w1 = mkf2(__builtin_amdgcn_cosf(rev), -__builtin_amdgcn_sinf(rev));
;       const f32x2 w2 = cmul(w1, w1), w3 = cmul(w1, w2);
;       const f32x2 apc = mkf2(a[e].x + c[e].x, a[e].y + c[e].y), amc = mkf2(a[e].x - c[e].x, a[e].y - c[e].y);
;       const f32x2 bpd = mkf2(b[e].x + d[e].x, b[e].y + d[e].y), bmd = mkf2(b[e].x - d[e].x, b[e].y - d[e].y);
;       const int o = 4 * i - 3 * q;
;       buf[SW(o)] = mkf2(apc.x + bpd.x, apc.y + bpd.y);
;       buf[SW(o + s)] = cmul(w1, mkf2(amc.x + bmd.y, amc.y - bmd.x));
;       buf[SW(o + 2 * s)] = cmul(w2, mkf2(apc.x - bpd.x, apc.y - bpd.y));
;       buf[SW(o + 3 * s)] = cmul(w3, mkf2(amc.x - bmd.y, amc.y + bmd.x));
;     }
	v_pk_add_f32 v[202:203], v[58:59], v[62:63]
	v_pk_add_f32 v[58:59], v[58:59], v[62:63] neg_lo:[0,1] neg_hi:[0,1]
	v_pk_add_f32 v[204:205], v[60:61], v[64:65]
	v_pk_add_f32 v[60:61], v[60:61], v[64:65] neg_lo:[0,1] neg_hi:[0,1]
	v_pk_add_f32 v[62:63], v[202:203], v[204:205]
	v_pk_add_f32 v[64:65], v[202:203], v[204:205] neg_lo:[0,1] neg_hi:[0,1]
	v_pk_add_f32 v[202:203], v[58:59], v[60:61] op_sel:[0,1] op_sel_hi:[1,0] neg_hi:[0,1]
	v_pk_add_f32 v[204:205], v[58:59], v[60:61] op_sel:[0,1] op_sel_hi:[1,0] neg_lo:[0,1]
	v_pk_mul_f32 v[206:207], v[210:211], v[210:211] op_sel:[1,1] op_sel_hi:[1,0]
	v_pk_fma_f32 v[212:213], v[210:211], v[210:211], v[206:207] op_sel_hi:[0,1,1] neg_lo:[0,0,1]
	v_pk_mul_f32 v[206:207], v[210:211], v[212:213] op_sel:[1,1] op_sel_hi:[1,0]
	v_pk_fma_f32 v[220:221], v[210:211], v[212:213], v[206:207] op_sel_hi:[0,1,1] neg_lo:[0,0,1]
	v_pk_mul_f32 v[58:59], v[210:211], v[202:203] op_sel:[1,1] op_sel_hi:[1,0]
	v_pk_fma_f32 v[58:59], v[210:211], v[202:203], v[58:59] op_sel_hi:[0,1,1] neg_lo:[0,0,1]
	v_pk_mul_f32 v[60:61], v[212:213], v[64:65] op_sel:[1,1] op_sel_hi:[1,0]
	v_pk_fma_f32 v[60:61], v[212:213], v[64:65], v[60:61] op_sel_hi:[0,1,1] neg_lo:[0,0,1]
	v_pk_mul_f32 v[64:65], v[220:221], v[204:205] op_sel:[1,1] op_sel_hi:[1,0]
	v_pk_fma_f32 v[64:65], v[220:221], v[204:205], v[64:65] op_sel_hi:[0,1,1] neg_lo:[0,0,1]
	s_barrier
	v_mul_f32_e32 v214, 4.0, v201
	v_cos_f32_e32 v224, v214
	v_sin_f32_e64 v225, -v214
	s_nop 0
	v_pk_mul_f32 v[206:207], v[224:225], v[224:225] op_sel:[1,1] op_sel_hi:[1,0]
	v_pk_fma_f32 v[226:227], v[224:225], v[224:225], v[206:207] op_sel_hi:[0,1,1] neg_lo:[0,0,1]
	v_pk_mul_f32 v[206:207], v[224:225], v[226:227] op_sel:[1,1] op_sel_hi:[1,0]
	v_pk_fma_f32 v[230:231], v[224:225], v[226:227], v[206:207] op_sel_hi:[0,1,1] neg_lo:[0,0,1]
	v_pk_add_f32 v[202:203], v[6:7], v[38:39]
	v_pk_add_f32 v[6:7], v[6:7], v[38:39] neg_lo:[0,1] neg_hi:[0,1]
	v_pk_add_f32 v[204:205], v[22:23], v[54:55]
	v_pk_add_f32 v[22:23], v[22:23], v[54:55] neg_lo:[0,1] neg_hi:[0,1]
	v_pk_add_f32 v[38:39], v[202:203], v[204:205]
	v_pk_add_f32 v[54:55], v[202:203], v[204:205] neg_lo:[0,1] neg_hi:[0,1]
	v_pk_add_f32 v[202:203], v[6:7], v[22:23] op_sel:[0,1] op_sel_hi:[1,0] neg_hi:[0,1]
	v_pk_add_f32 v[204:205], v[6:7], v[22:23] op_sel:[0,1] op_sel_hi:[1,0] neg_lo:[0,1]
	v_pk_mul_f32 v[6:7], v[224:225], v[202:203] op_sel:[1,1] op_sel_hi:[1,0]
	v_pk_fma_f32 v[6:7], v[224:225], v[202:203], v[6:7] op_sel_hi:[0,1,1] neg_lo:[0,0,1]
	v_pk_mul_f32 v[22:23], v[226:227], v[54:55] op_sel:[1,1] op_sel_hi:[1,0]
	v_pk_fma_f32 v[22:23], v[226:227], v[54:55], v[22:23] op_sel_hi:[0,1,1] neg_lo:[0,0,1]
	v_pk_mul_f32 v[54:55], v[230:231], v[204:205] op_sel:[1,1] op_sel_hi:[1,0]
	v_pk_fma_f32 v[54:55], v[230:231], v[204:205], v[54:55] op_sel_hi:[0,1,1] neg_lo:[0,0,1]
	v_pk_add_f32 v[202:203], v[2:3], v[34:35]
	v_pk_add_f32 v[2:3], v[2:3], v[34:35] neg_lo:[0,1] neg_hi:[0,1]
	v_pk_add_f32 v[204:205], v[18:19], v[50:51]
	v_pk_add_f32 v[18:19], v[18:19], v[50:51] neg_lo:[0,1] neg_hi:[0,1]
	v_pk_add_f32 v[34:35], v[202:203], v[204:205]
	v_pk_add_f32 v[50:51], v[202:203], v[204:205] neg_lo:[0,1] neg_hi:[0,1]
	v_pk_add_f32 v[202:203], v[2:3], v[18:19] op_sel:[0,1] op_sel_hi:[1,0] neg_hi:[0,1]
	v_pk_add_f32 v[204:205], v[2:3], v[18:19] op_sel:[0,1] op_sel_hi:[1,0] neg_lo:[0,1]
	v_pk_mul_f32 v[2:3], v[224:225], v[202:203] op_sel:[1,1] op_sel_hi:[1,0]
	v_pk_fma_f32 v[2:3], v[224:225], v[202:203], v[2:3] op_sel_hi:[0,1,1] neg_lo:[0,0,1]
	v_pk_mul_f32 v[18:19], v[226:227], v[50:51] op_sel:[1,1] op_sel_hi:[1,0]
	v_pk_fma_f32 v[18:19], v[226:227], v[50:51], v[18:19] op_sel_hi:[0,1,1] neg_lo:[0,0,1]
	v_pk_mul_f32 v[50:51], v[230:231], v[204:205] op_sel:[1,1] op_sel_hi:[1,0]
	v_pk_fma_f32 v[50:51], v[230:231], v[204:205], v[50:51] op_sel_hi:[0,1,1] neg_lo:[0,0,1]
	v_pk_add_f32 v[202:203], v[4:5], v[36:37]
	v_pk_add_f32 v[4:5], v[4:5], v[36:37] neg_lo:[0,1] neg_hi:[0,1]
	v_pk_add_f32 v[204:205], v[20:21], v[52:53]
	v_pk_add_f32 v[20:21], v[20:21], v[52:53] neg_lo:[0,1] neg_hi:[0,1]
	v_pk_add_f32 v[36:37], v[202:203], v[204:205]
	v_pk_add_f32 v[52:53], v[202:203], v[204:205] neg_lo:[0,1] neg_hi:[0,1]
	v_pk_add_f32 v[202:203], v[4:5], v[20:21] op_sel:[0,1] op_sel_hi:[1,0] neg_hi:[0,1]
	v_pk_add_f32 v[204:205], v[4:5], v[20:21] op_sel:[0,1] op_sel_hi:[1,0] neg_lo:[0,1]
	v_pk_mul_f32 v[4:5], v[224:225], v[202:203] op_sel:[1,1] op_sel_hi:[1,0]
	v_pk_fma_f32 v[4:5], v[224:225], v[202:203], v[4:5] op_sel_hi:[0,1,1] neg_lo:[0,0,1]
	v_pk_mul_f32 v[20:21], v[226:227], v[52:53] op_sel:[1,1] op_sel_hi:[1,0]
	v_pk_fma_f32 v[20:21], v[226:227], v[52:53], v[20:21] op_sel_hi:[0,1,1] neg_lo:[0,0,1]
	v_pk_mul_f32 v[52:53], v[230:231], v[204:205] op_sel:[1,1] op_sel_hi:[1,0]
	v_pk_fma_f32 v[52:53], v[230:231], v[204:205], v[52:53] op_sel_hi:[0,1,1] neg_lo:[0,0,1]
	v_pk_add_f32 v[202:203], v[8:9], v[40:41]
	v_pk_add_f32 v[8:9], v[8:9], v[40:41] neg_lo:[0,1] neg_hi:[0,1]
	v_pk_add_f32 v[204:205], v[24:25], v[56:57]
	v_pk_add_f32 v[24:25], v[24:25], v[56:57] neg_lo:[0,1] neg_hi:[0,1]
	v_pk_add_f32 v[40:41], v[202:203], v[204:205]
	v_pk_add_f32 v[56:57], v[202:203], v[204:205] neg_lo:[0,1] neg_hi:[0,1]
	v_pk_add_f32 v[202:203], v[8:9], v[24:25] op_sel:[0,1] op_sel_hi:[1,0] neg_hi:[0,1]
	v_pk_add_f32 v[204:205], v[8:9], v[24:25] op_sel:[0,1] op_sel_hi:[1,0] neg_lo:[0,1]
	v_pk_mul_f32 v[8:9], v[224:225], v[202:203] op_sel:[1,1] op_sel_hi:[1,0]
	v_pk_fma_f32 v[8:9], v[224:225], v[202:203], v[8:9] op_sel_hi:[0,1,1] neg_lo:[0,0,1]
	v_pk_mul_f32 v[24:25], v[226:227], v[56:57] op_sel:[1,1] op_sel_hi:[1,0]
	v_pk_fma_f32 v[24:25], v[226:227], v[56:57], v[24:25] op_sel_hi:[0,1,1] neg_lo:[0,0,1]
; DI f32x2 cmul(f32x2 a, f32x2 b) { return mkf2(a.x * b.x - a.y * b.y, a.x * b.y + a.y * b.x); }
; DI void fft8192(f32x2* buf, const f32x2* __restrict__ tw) {
;     ...
; #pragma unroll
;     for (int e = 0; e < 8; ++e) {
;       const int i = tid + 256 * e;
;       const int q = i & (s - 1);
;       const int ps = i - q;
;       const float rev = (float)ps * (1.f / 8192.f);
;       const f32x2 w1 = mkf2(__builtin_amdgcn_cosf(rev), -__builtin_amdgcn_sinf(rev));
;       const f32x2 w2 = cmul(w1, w1), w3 = cmul(w1, w2);
;       const f32x2 apc = mkf2(a[e].x + c[e].x, a[e].y + c[e].y), amc = mkf2(a[e].x - c[e].x, a[e].y - c[e].y);
;       const f32x2 bpd = mkf2(b[e].x + d[e].x, b[e].y + d[e].y), bmd = mkf2(b[e].x - d[e].x, b[e].y - d[e].y);
;       const int o = 4 * i - 3 * q;
;       buf[SW(o)] = mkf2(apc.x + bpd.x, apc.y + bpd.y);
;       buf[SW(o + s)] = cmul(w1, mkf2(amc.x + bmd.y, amc.y - bmd.x));
;       buf[SW(o + 2 * s)] = cmul(w2, mkf2(apc.x - bpd.x, apc.y - bpd.y));
;       buf[SW(o + 3 * s)] = cmul(w3, mkf2(amc.x - bmd.y, amc.y + bmd.x));
;     }
	v_pk_mul_f32 v[56:57], v[230:231], v[204:205] op_sel:[1,1] op_sel_hi:[1,0]
	v_pk_fma_f32 v[56:57], v[230:231], v[204:205], v[56:57] op_sel_hi:[0,1,1] neg_lo:[0,0,1]
	v_mul_f32_e32 v214, 4.0, v201
	v_add_f32_e32 v214, 0x3e000000, v214
	v_cos_f32_e32 v224, v214
	v_sin_f32_e64 v225, -v214
	s_nop 0
	v_pk_mul_f32 v[206:207], v[224:225], v[224:225] op_sel:[1,1] op_sel_hi:[1,0]
	v_pk_fma_f32 v[226:227], v[224:225], v[224:225], v[206:207] op_sel_hi:[0,1,1] neg_lo:[0,0,1]
	v_pk_mul_f32 v[206:207], v[224:225], v[226:227] op_sel:[1,1] op_sel_hi:[1,0]
	v_pk_fma_f32 v[230:231], v[224:225], v[226:227], v[206:207] op_sel_hi:[0,1,1] neg_lo:[0,0,1]
	v_pk_add_f32 v[202:203], v[14:15], v[46:47]
	v_pk_add_f32 v[14:15], v[14:15], v[46:47] neg_lo:[0,1] neg_hi:[0,1]
	v_pk_add_f32 v[204:205], v[30:31], v[62:63]
	v_pk_add_f32 v[30:31], v[30:31], v[62:63] neg_lo:[0,1] neg_hi:[0,1]
	v_pk_add_f32 v[46:47], v[202:203], v[204:205]
	v_pk_add_f32 v[62:63], v[202:203], v[204:205] neg_lo:[0,1] neg_hi:[0,1]
	v_pk_add_f32 v[202:203], v[14:15], v[30:31] op_sel:[0,1] op_sel_hi:[1,0] neg_hi:[0,1]
	v_pk_add_f32 v[204:205], v[14:15], v[30:31] op_sel:[0,1] op_sel_hi:[1,0] neg_lo:[0,1]
	v_pk_mul_f32 v[14:15], v[224:225], v[202:203] op_sel:[1,1] op_sel_hi:[1,0]
	v_pk_fma_f32 v[14:15], v[224:225], v[202:203], v[14:15] op_sel_hi:[0,1,1] neg_lo:[0,0,1]
	v_pk_mul_f32 v[30:31], v[226:227], v[62:63] op_sel:[1,1] op_sel_hi:[1,0]
	v_pk_fma_f32 v[30:31], v[226:227], v[62:63], v[30:31] op_sel_hi:[0,1,1] neg_lo:[0,0,1]
	v_pk_mul_f32 v[62:63], v[230:231], v[204:205] op_sel:[1,1] op_sel_hi:[1,0]
	v_pk_fma_f32 v[62:63], v[230:231], v[204:205], v[62:63] op_sel_hi:[0,1,1] neg_lo:[0,0,1]
	v_pk_add_f32 v[202:203], v[10:11], v[42:43]
	v_pk_add_f32 v[10:11], v[10:11], v[42:43] neg_lo:[0,1] neg_hi:[0,1]
	v_pk_add_f32 v[204:205], v[26:27], v[58:59]
	v_pk_add_f32 v[26:27], v[26:27], v[58:59] neg_lo:[0,1] neg_hi:[0,1]
	v_pk_add_f32 v[42:43], v[202:203], v[204:205]
	v_pk_add_f32 v[58:59], v[202:203], v[204:205] neg_lo:[0,1] neg_hi:[0,1]
	v_pk_add_f32 v[202:203], v[10:11], v[26:27] op_sel:[0,1] op_sel_hi:[1,0] neg_hi:[0,1]
	v_pk_add_f32 v[204:205], v[10:11], v[26:27] op_sel:[0,1] op_sel_hi:[1,0] neg_lo:[0,1]
	v_pk_mul_f32 v[10:11], v[224:225], v[202:203] op_sel:[1,1] op_sel_hi:[1,0]
	v_pk_fma_f32 v[10:11], v[224:225], v[202:203], v[10:11] op_sel_hi:[0,1,1] neg_lo:[0,0,1]
	v_pk_mul_f32 v[26:27], v[226:227], v[58:59] op_sel:[1,1] op_sel_hi:[1,0]
	v_pk_fma_f32 v[26:27], v[226:227], v[58:59], v[26:27] op_sel_hi:[0,1,1] neg_lo:[0,0,1]
	v_pk_mul_f32 v[58:59], v[230:231], v[204:205] op_sel:[1,1] op_sel_hi:[1,0]
	v_pk_fma_f32 v[58:59], v[230:231], v[204:205], v[58:59] op_sel_hi:[0,1,1] neg_lo:[0,0,1]
	v_pk_add_f32 v[202:203], v[12:13], v[44:45]
	v_pk_add_f32 v[12:13], v[12:13], v[44:45] neg_lo:[0,1] neg_hi:[0,1]
	v_pk_add_f32 v[204:205], v[28:29], v[60:61]
	v_pk_add_f32 v[28:29], v[28:29], v[60:61] neg_lo:[0,1] neg_hi:[0,1]
	v_pk_add_f32 v[44:45], v[202:203], v[204:205]
	v_pk_add_f32 v[60:61], v[202:203], v[204:205] neg_lo:[0,1] neg_hi:[0,1]
	v_pk_add_f32 v[202:203], v[12:13], v[28:29] op_sel:[0,1] op_sel_hi:[1,0] neg_hi:[0,1]
	v_pk_add_f32 v[204:205], v[12:13], v[28:29] op_sel:[0,1] op_sel_hi:[1,0] neg_lo:[0,1]
	v_pk_mul_f32 v[12:13], v[224:225], v[202:203] op_sel:[1,1] op_sel_hi:[1,0]
	v_pk_fma_f32 v[12:13], v[224:225], v[202:203], v[12:13] op_sel_hi:[0,1,1] neg_lo:[0,0,1]
	v_pk_mul_f32 v[28:29], v[226:227], v[60:61] op_sel:[1,1] op_sel_hi:[1,0]
	v_pk_fma_f32 v[28:29], v[226:227], v[60:61], v[28:29] op_sel_hi:[0,1,1] neg_lo:[0,0,1]
	v_pk_mul_f32 v[60:61], v[230:231], v[204:205] op_sel:[1,1] op_sel_hi:[1,0]
	v_pk_fma_f32 v[60:61], v[230:231], v[204:205], v[60:61] op_sel_hi:[0,1,1] neg_lo:[0,0,1]
	v_pk_add_f32 v[202:203], v[16:17], v[48:49]
	v_pk_add_f32 v[16:17], v[16:17], v[48:49] neg_lo:[0,1] neg_hi:[0,1]
	v_pk_add_f32 v[204:205], v[32:33], v[64:65]
	v_pk_add_f32 v[32:33], v[32:33], v[64:65] neg_lo:[0,1] neg_hi:[0,1]
	v_pk_add_f32 v[48:49], v[202:203], v[204:205]
	v_pk_add_f32 v[64:65], v[202:203], v[204:205] neg_lo:[0,1] neg_hi:[0,1]
	v_pk_add_f32 v[202:203], v[16:17], v[32:33] op_sel:[0,1] op_sel_hi:[1,0] neg_hi:[0,1]
	v_pk_add_f32 v[204:205], v[16:17], v[32:33] op_sel:[0,1] op_sel_hi:[1,0] neg_lo:[0,1]
	v_pk_mul_f32 v[16:17], v[224:225], v[202:203] op_sel:[1,1] op_sel_hi:[1,0]
	v_pk_fma_f32 v[16:17], v[224:225], v[202:203], v[16:17] op_sel_hi:[0,1,1] neg_lo:[0,0,1]
	v_pk_mul_f32 v[32:33], v[226:227], v[64:65] op_sel:[1,1] op_sel_hi:[1,0]
	v_pk_fma_f32 v[32:33], v[226:227], v[64:65], v[32:33] op_sel_hi:[0,1,1] neg_lo:[0,0,1]
	v_pk_mul_f32 v[64:65], v[230:231], v[204:205] op_sel:[1,1] op_sel_hi:[1,0]
	v_pk_fma_f32 v[64:65], v[230:231], v[204:205], v[64:65] op_sel_hi:[0,1,1] neg_lo:[0,0,1]
	ds_write_b64 v164, v[38:39] offset:0
	v_xor_b32_e32 v156, 0x80, v164
	ds_write_b64 v156, v[34:35] offset:0
	v_xor_b32_e32 v158, 0x128, v164
	ds_write_b64 v158, v[36:37] offset:0
	v_xor_b32_e32 v160, 0x1a8, v164
	ds_write_b64 v160, v[40:41] offset:0
	v_xor_b32_e32 v162, 0x2d0, v164
	ds_write_b64 v162, v[6:7] offset:0
	v_xor_b32_e32 v156, 0x250, v164
	ds_write_b64 v156, v[2:3] offset:0
	v_xor_b32_e32 v158, 0x3f8, v164
	ds_write_b64 v158, v[4:5] offset:0
	v_xor_b32_e32 v160, 0x378, v164
	ds_write_b64 v160, v[8:9] offset:0
	v_xor_b32_e32 v162, 0x400, v164
	ds_write_b64 v162, v[22:23] offset:0
	v_xor_b32_e32 v156, 0x480, v164
	ds_write_b64 v156, v[18:19] offset:0
	v_xor_b32_e32 v158, 0x528, v164
	ds_write_b64 v158, v[20:21] offset:0
	v_xor_b32_e32 v160, 0x5a8, v164
	ds_write_b64 v160, v[24:25] offset:0
	v_xor_b32_e32 v162, 0x6d0, v164
	ds_write_b64 v162, v[54:55] offset:0
	v_xor_b32_e32 v156, 0x650, v164
	ds_write_b64 v156, v[50:51] offset:0
	v_xor_b32_e32 v158, 0x7f8, v164
	ds_write_b64 v158, v[52:53] offset:0
	v_xor_b32_e32 v160, 0x778, v164
	ds_write_b64 v160, v[56:57] offset:0
	ds_write_b64 v164, v[46:47] offset:32768
	v_xor_b32_e32 v162, 0x80, v164
	ds_write_b64 v162, v[42:43] offset:32768
	v_xor_b32_e32 v156, 0x128, v164
	ds_write_b64 v156, v[44:45] offset:32768
	v_xor_b32_e32 v158, 0x1a8, v164
	ds_write_b64 v158, v[48:49] offset:32768
	v_xor_b32_e32 v160, 0x2d0, v164
	ds_write_b64 v160, v[14:15] offset:32768
	v_xor_b32_e32 v162, 0x250, v164
	ds_write_b64 v162, v[10:11] offset:32768
	v_xor_b32_e32 v156, 0x3f8, v164
	ds_write_b64 v156, v[12:13] offset:32768
	v_xor_b32_e32 v158, 0x378, v164
	ds_write_b64 v158, v[16:17] offset:32768
	v_xor_b32_e32 v160, 0x400, v164
	ds_write_b64 v160, v[30:31] offset:32768
	v_xor_b32_e32 v162, 0x480, v164
	ds_write_b64 v162, v[26:27] offset:32768
	v_xor_b32_e32 v156, 0x528, v164
	ds_write_b64 v156, v[28:29] offset:32768
	v_xor_b32_e32 v158, 0x5a8, v164
	ds_write_b64 v158, v[32:33] offset:32768
	v_xor_b32_e32 v160, 0x6d0, v164
	ds_write_b64 v160, v[62:63] offset:32768
	v_xor_b32_e32 v162, 0x650, v164
	ds_write_b64 v162, v[58:59] offset:32768
	v_xor_b32_e32 v156, 0x7f8, v164
	ds_write_b64 v156, v[60:61] offset:32768
	v_xor_b32_e32 v158, 0x778, v164
	ds_write_b64 v158, v[64:65] offset:32768
	s_waitcnt lgkmcnt(0)
	s_barrier
; DI f32x2 cmul(f32x2 a, f32x2 b) { return mkf2(a.x * b.x - a.y * b.y, a.x * b.y + a.y * b.x); }
; DI void fft8192(f32x2* buf, const f32x2* __restrict__ tw) {
;     ...
;     __syncthreads();
; #pragma unroll
;     for (int e = 0; e < 8; ++e) {
;       const int i = tid + 256 * e;
;       const int pi = SW(i);
;       a[e] = buf[pi]; b[e] = buf[pi + 2048]; c[e] = buf[pi + 4096]; d[e] = buf[pi + 6144];
;     }
;     __syncthreads();
; #pragma unroll
;     for (int e = 0; e < 8; ++e) {
;       const int i = tid + 256 * e;
;       const int q = i & (s - 1);
;       const int ps = i - q;
;       const float rev = (float)ps * (1.f / 8192.f);
;       const f32x2 w1 = mkf2(__builtin_amdgcn_cosf(rev), -__builtin_amdgcn_sinf(rev));
;       const f32x2 w2 = cmul(w1, w1), w3 = cmul(w1, w2);
;       const f32x2 apc = mkf2(a[e].x + c[e].x, a[e].y + c[e].y), amc = mkf2(a[e].x - c[e].x, a[e].y - c[e].y);
;       const f32x2 bpd = mkf2(b[e].x + d[e].x, b[e].y + d[e].y), bmd = mkf2(b[e].x - d[e].x, b[e].y - d[e].y);
;       const int o = 4 * i - 3 * q;
;       buf[SW(o)] = mkf2(apc.x + bpd.x, apc.y + bpd.y);
;       buf[SW(o + s)] = cmul(w1, mkf2(amc.x + bmd.y, amc.y - bmd.x));
;       buf[SW(o + 2 * s)] = cmul(w2, mkf2(apc.x - bpd.x, apc.y - bpd.y));
;       buf[SW(o + 3 * s)] = cmul(w3, mkf2(amc.x - bmd.y, amc.y + bmd.x));
;     }
	ds_read2st64_b64 v[2:5], v154 offset0:0 offset1:32
	ds_read2st64_b64 v[6:9], v154 offset0:64 offset1:96
	ds_read2st64_b64 v[10:13], v154 offset0:4 offset1:36
	ds_read2st64_b64 v[14:17], v154 offset0:68 offset1:100
	ds_read2st64_b64 v[18:21], v154 offset0:8 offset1:40
	ds_read2st64_b64 v[22:25], v154 offset0:72 offset1:104
	ds_read2st64_b64 v[26:29], v154 offset0:12 offset1:44
	ds_read2st64_b64 v[30:33], v154 offset0:76 offset1:108
	ds_read2st64_b64 v[34:37], v154 offset0:16 offset1:48
	ds_read2st64_b64 v[38:41], v154 offset0:80 offset1:112
	ds_read2st64_b64 v[42:45], v154 offset0:20 offset1:52
	ds_read2st64_b64 v[46:49], v154 offset0:84 offset1:116
	ds_read2st64_b64 v[50:53], v154 offset0:24 offset1:56
	ds_read2st64_b64 v[54:57], v154 offset0:88 offset1:120
	ds_read2st64_b64 v[58:61], v154 offset0:28 offset1:60
	ds_read2st64_b64 v[62:65], v154 offset0:92 offset1:124
	s_waitcnt lgkmcnt(14)
	v_pk_add_f32 v[202:203], v[2:3], v[6:7]
	v_pk_add_f32 v[2:3], v[2:3], v[6:7] neg_lo:[0,1] neg_hi:[0,1]
	v_pk_add_f32 v[204:205], v[4:5], v[8:9]
	v_pk_add_f32 v[4:5], v[4:5], v[8:9] neg_lo:[0,1] neg_hi:[0,1]
	v_pk_add_f32 v[6:7], v[202:203], v[204:205]
	v_pk_add_f32 v[8:9], v[202:203], v[204:205] neg_lo:[0,1] neg_hi:[0,1]
	v_pk_add_f32 v[202:203], v[2:3], v[4:5] op_sel:[0,1] op_sel_hi:[1,0] neg_hi:[0,1]
	v_pk_add_f32 v[4:5], v[2:3], v[4:5] op_sel:[0,1] op_sel_hi:[1,0] neg_lo:[0,1]
	v_pk_mov_b32 v[2:3], v[202:203], v[202:203] op_sel:[0,1]
	v_mov_b32_e32 v210, 0x3f7b14be
	v_mov_b32_e32 v211, 0xbe47c5c2
	v_mov_b32_e32 v212, 0x3f6c835e
	v_mov_b32_e32 v213, 0xbec3ef15
	v_mov_b32_e32 v220, 0x3f54db31
	v_mov_b32_e32 v221, 0xbf0e39da
	s_waitcnt lgkmcnt(12)
	v_pk_add_f32 v[202:203], v[10:11], v[14:15]
	v_pk_add_f32 v[10:11], v[10:11], v[14:15] neg_lo:[0,1] neg_hi:[0,1]
	v_pk_add_f32 v[204:205], v[12:13], v[16:17]
	v_pk_add_f32 v[12:13], v[12:13], v[16:17] neg_lo:[0,1] neg_hi:[0,1]
	v_pk_add_f32 v[14:15], v[202:203], v[204:205]
	v_pk_add_f32 v[16:17], v[202:203], v[204:205] neg_lo:[0,1] neg_hi:[0,1]
	v_pk_add_f32 v[202:203], v[10:11], v[12:13] op_sel:[0,1] op_sel_hi:[1,0] neg_hi:[0,1]
	v_pk_add_f32 v[204:205], v[10:11], v[12:13] op_sel:[0,1] op_sel_hi:[1,0] neg_lo:[0,1]
	v_pk_mul_f32 v[10:11], v[210:211], v[202:203] op_sel:[1,1] op_sel_hi:[1,0]
	v_pk_fma_f32 v[10:11], v[210:211], v[202:203], v[10:11] op_sel_hi:[0,1,1] neg_lo:[0,0,1]
	v_pk_mul_f32 v[12:13], v[212:213], v[16:17] op_sel:[1,1] op_sel_hi:[1,0]
	v_pk_fma_f32 v[12:13], v[212:213], v[16:17], v[12:13] op_sel_hi:[0,1,1] neg_lo:[0,0,1]
	v_pk_mul_f32 v[16:17], v[220:221], v[204:205] op_sel:[1,1] op_sel_hi:[1,0]
	v_pk_fma_f32 v[16:17], v[220:221], v[204:205], v[16:17] op_sel_hi:[0,1,1] neg_lo:[0,0,1]
	v_mov_b32_e32 v210, 0x3f6c835e
	v_mov_b32_e32 v211, 0xbec3ef15
	v_mov_b32_e32 v212, 0x3f3504f3
	v_mov_b32_e32 v213, 0xbf3504f3
	v_mov_b32_e32 v220, 0x3ec3ef15
	v_mov_b32_e32 v221, 0xbf6c835e
	s_waitcnt lgkmcnt(10)
	v_pk_add_f32 v[202:203], v[18:19], v[22:23]
	v_pk_add_f32 v[18:19], v[18:19], v[22:23] neg_lo:[0,1] neg_hi:[0,1]
	v_pk_add_f32 v[204:205], v[20:21], v[24:25]
	v_pk_add_f32 v[20:21], v[20:21], v[24:25] neg_lo:[0,1] neg_hi:[0,1]
	v_pk_add_f32 v[22:23], v[202:203], v[204:205]
	v_pk_add_f32 v[24:25], v[202:203], v[204:205] neg_lo:[0,1] neg_hi:[0,1]
	v_pk_add_f32 v[202:203], v[18:19], v[20:21] op_sel:[0,1] op_sel_hi:[1,0] neg_hi:[0,1]
	v_pk_add_f32 v[204:205], v[18:19], v[20:21] op_sel:[0,1] op_sel_hi:[1,0] neg_lo:[0,1]
	v_pk_mul_f32 v[18:19], v[210:211], v[202:203] op_sel:[1,1] op_sel_hi:[1,0]
	v_pk_fma_f32 v[18:19], v[210:211], v[202:203], v[18:19] op_sel_hi:[0,1,1] neg_lo:[0,0,1]
	v_pk_mul_f32 v[20:21], v[212:213], v[24:25] op_sel:[1,1] op_sel_hi:[1,0]
	v_pk_fma_f32 v[20:21], v[212:213], v[24:25], v[20:21] op_sel_hi:[0,1,1] neg_lo:[0,0,1]
	v_pk_mul_f32 v[24:25], v[220:221], v[204:205] op_sel:[1,1] op_sel_hi:[1,0]
	v_pk_fma_f32 v[24:25], v[220:221], v[204:205], v[24:25] op_sel_hi:[0,1,1] neg_lo:[0,0,1]
	v_mov_b32_e32 v210, 0x3f54db31
	v_mov_b32_e32 v211, 0xbf0e39da
	v_mov_b32_e32 v212, 0x3ec3ef15
	v_mov_b32_e32 v213, 0xbf6c835e
	v_mov_b32_e32 v220, 0xbe47c5c2
	v_mov_b32_e32 v221, 0xbf7b14be
	s_waitcnt lgkmcnt(8)
	v_pk_add_f32 v[202:203], v[26:27], v[30:31]
	v_pk_add_f32 v[26:27], v[26:27], v[30:31] neg_lo:[0,1] neg_hi:[0,1]
	v_pk_add_f32 v[204:205], v[28:29], v[32:33]
	v_pk_add_f32 v[28:29], v[28:29], v[32:33] neg_lo:[0,1] neg_hi:[0,1]
	v_pk_add_f32 v[30:31], v[202:203], v[204:205]
	v_pk_add_f32 v[32:33], v[202:203], v[204:205] neg_lo:[0,1] neg_hi:[0,1]
	v_pk_add_f32 v[202:203], v[26:27], v[28:29] op_sel:[0,1] op_sel_hi:[1,0] neg_hi:[0,1]
	v_pk_add_f32 v[204:205], v[26:27], v[28:29] op_sel:[0,1] op_sel_hi:[1,0] neg_lo:[0,1]
	v_pk_mul_f32 v[26:27], v[210:211], v[202:203] op_sel:[1,1] op_sel_hi:[1,0]
	v_pk_fma_f32 v[26:27], v[210:211], v[202:203], v[26:27] op_sel_hi:[0,1,1] neg_lo:[0,0,1]
	v_pk_mul_f32 v[28:29], v[212:213], v[32:33] op_sel:[1,1] op_sel_hi:[1,0]
	v_pk_fma_f32 v[28:29], v[212:213], v[32:33], v[28:29] op_sel_hi:[0,1,1] neg_lo:[0,0,1]
	v_pk_mul_f32 v[32:33], v[220:221], v[204:205] op_sel:[1,1] op_sel_hi:[1,0]
	v_pk_fma_f32 v[32:33], v[220:221], v[204:205], v[32:33] op_sel_hi:[0,1,1] neg_lo:[0,0,1]
	v_mov_b32_e32 v210, 0x3f3504f3
	v_mov_b32_e32 v211, 0xbf3504f3
	v_mov_b32_e32 v212, 0x248d3132
	v_mov_b32_e32 v213, 0xbf800000
	v_mov_b32_e32 v220, 0xbf3504f3
	v_mov_b32_e32 v221, 0xbf3504f3
	s_waitcnt lgkmcnt(6)
; DI f32x2 cmul(f32x2 a, f32x2 b) { return mkf2(a.x * b.x - a.y * b.y, a.x * b.y + a.y * b.x); }
; DI void fft8192(f32x2* buf, const f32x2* __restrict__ tw) {
;     ...
; #pragma unroll
;     for (int e = 0; e < 8; ++e) {
;       const int i = tid + 256 * e;
;       const int q = i & (s - 1);
;       const int ps = i - q;
;       const float rev = (float)ps * (1.f / 8192.f);
;       const f32x2 w1 = mkf2(__builtin_amdgcn_cosf(rev), -__builtin_amdgcn_sinf(rev));
;       const f32x2 w2 = cmul(w1, w1), w3 = cmul(w1, w2);
;       const f32x2 apc = mkf2(a[e].x + c[e].x, a[e].y + c[e].y), amc = mkf2(a[e].x - c[e].x, a[e].y - c[e].y);
;       const f32x2 bpd = mkf2(b[e].x + d[e].x, b[e].y + d[e].y), bmd = mkf2(b[e].x - d[e].x, b[e].y - d[e].y);
;       const int o = 4 * i - 3 * q;
;       buf[SW(o)] = mkf2(apc.x + bpd.x, apc.y + bpd.y);
;       buf[SW(o + s)] = cmul(w1, mkf2(amc.x + bmd.y, amc.y - bmd.x));
;       buf[SW(o + 2 * s)] = cmul(w2, mkf2(apc.x - bpd.x, apc.y - bpd.y));
;       buf[SW(o + 3 * s)] = cmul(w3, mkf2(amc.x - bmd.y, amc.y + bmd.x));
;     }
	v_pk_add_f32 v[202:203], v[34:35], v[38:39]
	v_pk_add_f32 v[34:35], v[34:35], v[38:39] neg_lo:[0,1] neg_hi:[0,1]
	v_pk_add_f32 v[204:205], v[36:37], v[40:41]
	v_pk_add_f32 v[36:37], v[36:37], v[40:41] neg_lo:[0,1] neg_hi:[0,1]
	v_pk_add_f32 v[38:39], v[202:203], v[204:205]
	v_pk_add_f32 v[40:41], v[202:203], v[204:205] neg_lo:[0,1] neg_hi:[0,1]
	v_pk_add_f32 v[202:203], v[34:35], v[36:37] op_sel:[0,1] op_sel_hi:[1,0] neg_hi:[0,1]
	v_pk_add_f32 v[204:205], v[34:35], v[36:37] op_sel:[0,1] op_sel_hi:[1,0] neg_lo:[0,1]
	v_pk_mul_f32 v[34:35], v[210:211], v[202:203] op_sel:[1,1] op_sel_hi:[1,0]
	v_pk_fma_f32 v[34:35], v[210:211], v[202:203], v[34:35] op_sel_hi:[0,1,1] neg_lo:[0,0,1]
	v_pk_mul_f32 v[36:37], v[212:213], v[40:41] op_sel:[1,1] op_sel_hi:[1,0]
	v_pk_fma_f32 v[36:37], v[212:213], v[40:41], v[36:37] op_sel_hi:[0,1,1] neg_lo:[0,0,1]
	v_pk_mul_f32 v[40:41], v[220:221], v[204:205] op_sel:[1,1] op_sel_hi:[1,0]
	v_pk_fma_f32 v[40:41], v[220:221], v[204:205], v[40:41] op_sel_hi:[0,1,1] neg_lo:[0,0,1]
	v_mov_b32_e32 v210, 0x3f0e39da
	v_mov_b32_e32 v211, 0xbf54db31
	v_mov_b32_e32 v212, 0xbec3ef15
	v_mov_b32_e32 v213, 0xbf6c835e
	v_mov_b32_e32 v220, 0xbf7b14be
	v_mov_b32_e32 v221, 0xbe47c5c2
	s_waitcnt lgkmcnt(4)
	v_pk_add_f32 v[202:203], v[42:43], v[46:47]
	v_pk_add_f32 v[42:43], v[42:43], v[46:47] neg_lo:[0,1] neg_hi:[0,1]
	v_pk_add_f32 v[204:205], v[44:45], v[48:49]
	v_pk_add_f32 v[44:45], v[44:45], v[48:49] neg_lo:[0,1] neg_hi:[0,1]
	v_pk_add_f32 v[46:47], v[202:203], v[204:205]
	v_pk_add_f32 v[48:49], v[202:203], v[204:205] neg_lo:[0,1] neg_hi:[0,1]
	v_pk_add_f32 v[202:203], v[42:43], v[44:45] op_sel:[0,1] op_sel_hi:[1,0] neg_hi:[0,1]
	v_pk_add_f32 v[204:205], v[42:43], v[44:45] op_sel:[0,1] op_sel_hi:[1,0] neg_lo:[0,1]
	v_pk_mul_f32 v[42:43], v[210:211], v[202:203] op_sel:[1,1] op_sel_hi:[1,0]
	v_pk_fma_f32 v[42:43], v[210:211], v[202:203], v[42:43] op_sel_hi:[0,1,1] neg_lo:[0,0,1]
	v_pk_mul_f32 v[44:45], v[212:213], v[48:49] op_sel:[1,1] op_sel_hi:[1,0]
	v_pk_fma_f32 v[44:45], v[212:213], v[48:49], v[44:45] op_sel_hi:[0,1,1] neg_lo:[0,0,1]
	v_pk_mul_f32 v[48:49], v[220:221], v[204:205] op_sel:[1,1] op_sel_hi:[1,0]
	v_pk_fma_f32 v[48:49], v[220:221], v[204:205], v[48:49] op_sel_hi:[0,1,1] neg_lo:[0,0,1]
	v_mov_b32_e32 v210, 0x3ec3ef15
	v_mov_b32_e32 v211, 0xbf6c835e
	v_mov_b32_e32 v212, 0xbf3504f3
	v_mov_b32_e32 v213, 0xbf3504f3
	v_mov_b32_e32 v220, 0xbf6c835e
	v_mov_b32_e32 v221, 0x3ec3ef15
	s_waitcnt lgkmcnt(2)
	v_pk_add_f32 v[202:203], v[50:51], v[54:55]
	v_pk_add_f32 v[50:51], v[50:51], v[54:55] neg_lo:[0,1] neg_hi:[0,1]
	v_pk_add_f32 v[204:205], v[52:53], v[56:57]
	v_pk_add_f32 v[52:53], v[52:53], v[56:57] neg_lo:[0,1] neg_hi:[0,1]
	v_pk_add_f32 v[54:55], v[202:203], v[204:205]
	v_pk_add_f32 v[56:57], v[202:203], v[204:205] neg_lo:[0,1] neg_hi:[0,1]
	v_pk_add_f32 v[202:203], v[50:51], v[52:53] op_sel:[0,1] op_sel_hi:[1,0] neg_hi:[0,1]
	v_pk_add_f32 v[204:205], v[50:51], v[52:53] op_sel:[0,1] op_sel_hi:[1,0] neg_lo:[0,1]
	v_pk_mul_f32 v[50:51], v[210:211], v[202:203] op_sel:[1,1] op_sel_hi:[1,0]
	v_pk_fma_f32 v[50:51], v[210:211], v[202:203], v[50:51] op_sel_hi:[0,1,1] neg_lo:[0,0,1]
	v_pk_mul_f32 v[52:53], v[212:213], v[56:57] op_sel:[1,1] op_sel_hi:[1,0]
	v_pk_fma_f32 v[52:53], v[212:213], v[56:57], v[52:53] op_sel_hi:[0,1,1] neg_lo:[0,0,1]
	v_pk_mul_f32 v[56:57], v[220:221], v[204:205] op_sel:[1,1] op_sel_hi:[1,0]
	v_pk_fma_f32 v[56:57], v[220:221], v[204:205], v[56:57] op_sel_hi:[0,1,1] neg_lo:[0,0,1]
	v_mov_b32_e32 v210, 0x3e47c5c2
	v_mov_b32_e32 v211, 0xbf7b14be
	v_mov_b32_e32 v212, 0xbf6c835e
	v_mov_b32_e32 v213, 0xbec3ef15
	v_mov_b32_e32 v220, 0xbf0e39da
	v_mov_b32_e32 v221, 0x3f54db31
	s_waitcnt lgkmcnt(0)
	v_pk_add_f32 v[202:203], v[58:59], v[62:63]
	v_pk_add_f32 v[58:59], v[58:59], v[62:63] neg_lo:[0,1] neg_hi:[0,1]
	v_pk_add_f32 v[204:205], v[60:61], v[64:65]
	v_pk_add_f32 v[60:61], v[60:61], v[64:65] neg_lo:[0,1] neg_hi:[0,1]
	v_pk_add_f32 v[62:63], v[202:203], v[204:205]
	v_pk_add_f32 v[64:65], v[202:203], v[204:205] neg_lo:[0,1] neg_hi:[0,1]
	v_pk_add_f32 v[202:203], v[58:59], v[60:61] op_sel:[0,1] op_sel_hi:[1,0] neg_hi:[0,1]
	v_pk_add_f32 v[204:205], v[58:59], v[60:61] op_sel:[0,1] op_sel_hi:[1,0] neg_lo:[0,1]
	v_pk_mul_f32 v[58:59], v[210:211], v[202:203] op_sel:[1,1] op_sel_hi:[1,0]
	v_pk_fma_f32 v[58:59], v[210:211], v[202:203], v[58:59] op_sel_hi:[0,1,1] neg_lo:[0,0,1]
	v_pk_mul_f32 v[60:61], v[212:213], v[64:65] op_sel:[1,1] op_sel_hi:[1,0]
	v_pk_fma_f32 v[60:61], v[212:213], v[64:65], v[60:61] op_sel_hi:[0,1,1] neg_lo:[0,0,1]
	v_pk_mul_f32 v[64:65], v[220:221], v[204:205] op_sel:[1,1] op_sel_hi:[1,0]
	v_pk_fma_f32 v[64:65], v[220:221], v[204:205], v[64:65] op_sel_hi:[0,1,1] neg_lo:[0,0,1]
	s_barrier
; DI f32x2 cmul(f32x2 a, f32x2 b) { return mkf2(a.x * b.x - a.y * b.y, a.x * b.y + a.y * b.x); }
; DI void fft8192(f32x2* buf, const f32x2* __restrict__ tw) {
;     ...
; #pragma unroll
;     for (int e = 0; e < 8; ++e) {
;       const int i = tid + 256 * e;
;       const int q = i & (s - 1);
;       const int ps = i - q;
;       const float rev = (float)ps * (1.f / 8192.f);
;       const f32x2 w1 = mkf2(__builtin_amdgcn_cosf(rev), -__builtin_amdgcn_sinf(rev));
;       const f32x2 w2 = cmul(w1, w1), w3 = cmul(w1, w2);
;       const f32x2 apc = mkf2(a[e].x + c[e].x, a[e].y + c[e].y), amc = mkf2(a[e].x - c[e].x, a[e].y - c[e].y);
;       const f32x2 bpd = mkf2(b[e].x + d[e].x, b[e].y + d[e].y), bmd = mkf2(b[e].x - d[e].x, b[e].y - d[e].y);
;       const int o = 4 * i - 3 * q;
;       buf[SW(o)] = mkf2(apc.x + bpd.x, apc.y + bpd.y);
;       buf[SW(o + s)] = cmul(w1, mkf2(amc.x + bmd.y, amc.y - bmd.x));
;       buf[SW(o + 2 * s)] = cmul(w2, mkf2(apc.x - bpd.x, apc.y - bpd.y));
;       buf[SW(o + 3 * s)] = cmul(w3, mkf2(amc.x - bmd.y, amc.y + bmd.x));
;     }
	v_pk_add_f32 v[202:203], v[6:7], v[38:39]
	v_pk_add_f32 v[6:7], v[6:7], v[38:39] neg_lo:[0,1] neg_hi:[0,1]
	v_pk_add_f32 v[204:205], v[22:23], v[54:55]
	v_pk_add_f32 v[22:23], v[22:23], v[54:55] neg_lo:[0,1] neg_hi:[0,1]
	v_pk_add_f32 v[38:39], v[202:203], v[204:205]
	v_pk_add_f32 v[54:55], v[202:203], v[204:205] neg_lo:[0,1] neg_hi:[0,1]
	v_pk_add_f32 v[202:203], v[6:7], v[22:23] op_sel:[0,1] op_sel_hi:[1,0] neg_hi:[0,1]
	v_pk_add_f32 v[22:23], v[6:7], v[22:23] op_sel:[0,1] op_sel_hi:[1,0] neg_lo:[0,1]
	v_pk_mov_b32 v[6:7], v[202:203], v[202:203] op_sel:[0,1]
	v_pk_add_f32 v[202:203], v[2:3], v[34:35]
	v_pk_add_f32 v[2:3], v[2:3], v[34:35] neg_lo:[0,1] neg_hi:[0,1]
	v_pk_add_f32 v[204:205], v[18:19], v[50:51]
	v_pk_add_f32 v[18:19], v[18:19], v[50:51] neg_lo:[0,1] neg_hi:[0,1]
	v_pk_add_f32 v[34:35], v[202:203], v[204:205]
	v_pk_add_f32 v[50:51], v[202:203], v[204:205] neg_lo:[0,1] neg_hi:[0,1]
	v_pk_add_f32 v[202:203], v[2:3], v[18:19] op_sel:[0,1] op_sel_hi:[1,0] neg_hi:[0,1]
	v_pk_add_f32 v[18:19], v[2:3], v[18:19] op_sel:[0,1] op_sel_hi:[1,0] neg_lo:[0,1]
	v_pk_mov_b32 v[2:3], v[202:203], v[202:203] op_sel:[0,1]
	v_pk_add_f32 v[202:203], v[8:9], v[36:37]
	v_pk_add_f32 v[8:9], v[8:9], v[36:37] neg_lo:[0,1] neg_hi:[0,1]
	v_pk_add_f32 v[204:205], v[20:21], v[52:53]
	v_pk_add_f32 v[20:21], v[20:21], v[52:53] neg_lo:[0,1] neg_hi:[0,1]
	v_pk_add_f32 v[36:37], v[202:203], v[204:205]
	v_pk_add_f32 v[52:53], v[202:203], v[204:205] neg_lo:[0,1] neg_hi:[0,1]
	v_pk_add_f32 v[202:203], v[8:9], v[20:21] op_sel:[0,1] op_sel_hi:[1,0] neg_hi:[0,1]
	v_pk_add_f32 v[20:21], v[8:9], v[20:21] op_sel:[0,1] op_sel_hi:[1,0] neg_lo:[0,1]
	v_pk_mov_b32 v[8:9], v[202:203], v[202:203] op_sel:[0,1]
	v_pk_add_f32 v[202:203], v[4:5], v[40:41]
	v_pk_add_f32 v[4:5], v[4:5], v[40:41] neg_lo:[0,1] neg_hi:[0,1]
	v_pk_add_f32 v[204:205], v[24:25], v[56:57]
	v_pk_add_f32 v[24:25], v[24:25], v[56:57] neg_lo:[0,1] neg_hi:[0,1]
	v_pk_add_f32 v[40:41], v[202:203], v[204:205]
	v_pk_add_f32 v[56:57], v[202:203], v[204:205] neg_lo:[0,1] neg_hi:[0,1]
	v_pk_add_f32 v[202:203], v[4:5], v[24:25] op_sel:[0,1] op_sel_hi:[1,0] neg_hi:[0,1]
	v_pk_add_f32 v[24:25], v[4:5], v[24:25] op_sel:[0,1] op_sel_hi:[1,0] neg_lo:[0,1]
	v_pk_mov_b32 v[4:5], v[202:203], v[202:203] op_sel:[0,1]
	v_mov_b32_e32 v224, 0x3f3504f3
	v_mov_b32_e32 v225, 0xbf3504f3
	v_mov_b32_e32 v226, 0x248d3132
	v_mov_b32_e32 v227, 0xbf800000
	v_mov_b32_e32 v230, 0xbf3504f3
	v_mov_b32_e32 v231, 0xbf3504f3
	v_pk_add_f32 v[202:203], v[14:15], v[46:47]
	v_pk_add_f32 v[14:15], v[14:15], v[46:47] neg_lo:[0,1] neg_hi:[0,1]
	v_pk_add_f32 v[204:205], v[30:31], v[62:63]
	v_pk_add_f32 v[30:31], v[30:31], v[62:63] neg_lo:[0,1] neg_hi:[0,1]
	v_pk_add_f32 v[46:47], v[202:203], v[204:205]
	v_pk_add_f32 v[62:63], v[202:203], v[204:205] neg_lo:[0,1] neg_hi:[0,1]
	v_pk_add_f32 v[202:203], v[14:15], v[30:31] op_sel:[0,1] op_sel_hi:[1,0] neg_hi:[0,1]
	v_pk_add_f32 v[204:205], v[14:15], v[30:31] op_sel:[0,1] op_sel_hi:[1,0] neg_lo:[0,1]
	v_pk_mul_f32 v[14:15], v[224:225], v[202:203] op_sel:[1,1] op_sel_hi:[1,0]
	v_pk_fma_f32 v[14:15], v[224:225], v[202:203], v[14:15] op_sel_hi:[0,1,1] neg_lo:[0,0,1]
	v_pk_mul_f32 v[30:31], v[226:227], v[62:63] op_sel:[1,1] op_sel_hi:[1,0]
	v_pk_fma_f32 v[30:31], v[226:227], v[62:63], v[30:31] op_sel_hi:[0,1,1] neg_lo:[0,0,1]
	v_pk_mul_f32 v[62:63], v[230:231], v[204:205] op_sel:[1,1] op_sel_hi:[1,0]
	v_pk_fma_f32 v[62:63], v[230:231], v[204:205], v[62:63] op_sel_hi:[0,1,1] neg_lo:[0,0,1]
	v_pk_add_f32 v[202:203], v[10:11], v[42:43]
	v_pk_add_f32 v[10:11], v[10:11], v[42:43] neg_lo:[0,1] neg_hi:[0,1]
	v_pk_add_f32 v[204:205], v[26:27], v[58:59]
	v_pk_add_f32 v[26:27], v[26:27], v[58:59] neg_lo:[0,1] neg_hi:[0,1]
	v_pk_add_f32 v[42:43], v[202:203], v[204:205]
	v_pk_add_f32 v[58:59], v[202:203], v[204:205] neg_lo:[0,1] neg_hi:[0,1]
	v_pk_add_f32 v[202:203], v[10:11], v[26:27] op_sel:[0,1] op_sel_hi:[1,0] neg_hi:[0,1]
	v_pk_add_f32 v[204:205], v[10:11], v[26:27] op_sel:[0,1] op_sel_hi:[1,0] neg_lo:[0,1]
	v_pk_mul_f32 v[10:11], v[224:225], v[202:203] op_sel:[1,1] op_sel_hi:[1,0]
	v_pk_fma_f32 v[10:11], v[224:225], v[202:203], v[10:11] op_sel_hi:[0,1,1] neg_lo:[0,0,1]
	v_pk_mul_f32 v[26:27], v[226:227], v[58:59] op_sel:[1,1] op_sel_hi:[1,0]
	v_pk_fma_f32 v[26:27], v[226:227], v[58:59], v[26:27] op_sel_hi:[0,1,1] neg_lo:[0,0,1]
	v_pk_mul_f32 v[58:59], v[230:231], v[204:205] op_sel:[1,1] op_sel_hi:[1,0]
	v_pk_fma_f32 v[58:59], v[230:231], v[204:205], v[58:59] op_sel_hi:[0,1,1] neg_lo:[0,0,1]
	v_pk_add_f32 v[202:203], v[12:13], v[44:45]
	v_pk_add_f32 v[12:13], v[12:13], v[44:45] neg_lo:[0,1] neg_hi:[0,1]
	v_pk_add_f32 v[204:205], v[28:29], v[60:61]
	v_pk_add_f32 v[28:29], v[28:29], v[60:61] neg_lo:[0,1] neg_hi:[0,1]
	v_pk_add_f32 v[44:45], v[202:203], v[204:205]
	v_pk_add_f32 v[60:61], v[202:203], v[204:205] neg_lo:[0,1] neg_hi:[0,1]
	v_pk_add_f32 v[202:203], v[12:13], v[28:29] op_sel:[0,1] op_sel_hi:[1,0] neg_hi:[0,1]
	v_pk_add_f32 v[204:205], v[12:13], v[28:29] op_sel:[0,1] op_sel_hi:[1,0] neg_lo:[0,1]
	v_pk_mul_f32 v[12:13], v[224:225], v[202:203] op_sel:[1,1] op_sel_hi:[1,0]
	v_pk_fma_f32 v[12:13], v[224:225], v[202:203], v[12:13] op_sel_hi:[0,1,1] neg_lo:[0,0,1]
	v_pk_mul_f32 v[28:29], v[226:227], v[60:61] op_sel:[1,1] op_sel_hi:[1,0]
	v_pk_fma_f32 v[28:29], v[226:227], v[60:61], v[28:29] op_sel_hi:[0,1,1] neg_lo:[0,0,1]
	v_pk_mul_f32 v[60:61], v[230:231], v[204:205] op_sel:[1,1] op_sel_hi:[1,0]
	v_pk_fma_f32 v[60:61], v[230:231], v[204:205], v[60:61] op_sel_hi:[0,1,1] neg_lo:[0,0,1]
	v_pk_add_f32 v[202:203], v[16:17], v[48:49]
	v_pk_add_f32 v[16:17], v[16:17], v[48:49] neg_lo:[0,1] neg_hi:[0,1]
; DI void fft8192(f32x2* buf, const f32x2* __restrict__ tw) {
;     ...
;   {
;     f32x2 a[16], b[16];
;     __syncthreads();
; #pragma unroll
;     for (int e = 0; e < 16; ++e) { const int pi = SW(tid + 256 * e); a[e] = buf[pi]; b[e] = buf[pi + 4096]; }
;     __syncthreads();
; #pragma unroll
;     for (int e = 0; e < 16; ++e) {
;       const int pi = SW(tid + 256 * e);
;       buf[pi] = mkf2(a[e].x + b[e].x, a[e].y + b[e].y);
;       buf[pi + 4096] = mkf2(a[e].x - b[e].x, a[e].y - b[e].y);
;     }
;     __syncthreads();
;   }
; DI void hyena_unit(KP p, int l, int c, char* smem) {
;     ...
;       const u16* g0 = Zhy + (size_t)(b0 * 1536 + gcol) * 4096;
;       const u16* g1 = Zhy + (size_t)(b1 * 1536 + gcol) * 4096;
; #pragma unroll 4
;       for (int jj = 0; jj < 16; ++jj) {
;         const int t = tid + 256 * jj;
;         const f32x2 r = buf[SW(t)];
;         const float y0 = r.x * (1.f / 8192.f), y1 = -r.y * (1.f / 8192.f);
;         const float x0 = sconv3(g0, t, 4096, gw0, gw1, gw2, gb), x1 = sconv3(g1, t, 4096, gw0, gw1, gw2, gb);
;         if (o == 0) { r0[t] = f2bf(x0 * y0); r1[t] = f2bf(x1 * y1); }
;         else { y0p[t] = f2bf(x0 * y0); y1p[t] = f2bf(x1 * y1); }
;       }
	v_pk_add_f32 v[204:205], v[32:33], v[64:65]
	v_pk_add_f32 v[32:33], v[32:33], v[64:65] neg_lo:[0,1] neg_hi:[0,1]
	v_pk_add_f32 v[48:49], v[202:203], v[204:205]
	v_pk_add_f32 v[64:65], v[202:203], v[204:205] neg_lo:[0,1] neg_hi:[0,1]
	v_pk_add_f32 v[202:203], v[16:17], v[32:33] op_sel:[0,1] op_sel_hi:[1,0] neg_hi:[0,1]
	v_pk_add_f32 v[204:205], v[16:17], v[32:33] op_sel:[0,1] op_sel_hi:[1,0] neg_lo:[0,1]
	v_pk_mul_f32 v[16:17], v[224:225], v[202:203] op_sel:[1,1] op_sel_hi:[1,0]
	v_pk_fma_f32 v[16:17], v[224:225], v[202:203], v[16:17] op_sel_hi:[0,1,1] neg_lo:[0,0,1]
	v_pk_mul_f32 v[32:33], v[226:227], v[64:65] op_sel:[1,1] op_sel_hi:[1,0]
	v_pk_fma_f32 v[32:33], v[226:227], v[64:65], v[32:33] op_sel_hi:[0,1,1] neg_lo:[0,0,1]
	v_pk_mul_f32 v[64:65], v[230:231], v[204:205] op_sel:[1,1] op_sel_hi:[1,0]
	v_pk_fma_f32 v[64:65], v[230:231], v[204:205], v[64:65] op_sel_hi:[0,1,1] neg_lo:[0,0,1]
	v_pk_add_f32 v[202:203], v[38:39], v[46:47]
	v_pk_add_f32 v[204:205], v[34:35], v[42:43]
	v_pk_add_f32 v[206:207], v[36:37], v[44:45]
	v_pk_add_f32 v[208:209], v[40:41], v[48:49]
	v_pk_add_f32 v[210:211], v[6:7], v[14:15]
	v_pk_add_f32 v[212:213], v[2:3], v[10:11]
	v_pk_add_f32 v[220:221], v[8:9], v[12:13]
	v_pk_add_f32 v[224:225], v[4:5], v[16:17]
	v_pk_add_f32 v[226:227], v[54:55], v[30:31]
	v_pk_add_f32 v[230:231], v[50:51], v[26:27]
	v_pk_add_f32 v[232:233], v[52:53], v[28:29]
	v_pk_add_f32 v[236:237], v[56:57], v[32:33]
	v_pk_add_f32 v[238:239], v[22:23], v[62:63]
	v_pk_add_f32 v[240:241], v[18:19], v[58:59]
	v_pk_add_f32 v[244:245], v[20:21], v[60:61]
	v_pk_add_f32 v[246:247], v[24:25], v[64:65]
	ds_write_b64 v154, v[202:203] offset:0
	ds_write_b64 v154, v[204:205] offset:2048
	ds_write_b64 v154, v[206:207] offset:4096
	ds_write_b64 v154, v[208:209] offset:6144
	ds_write_b64 v154, v[210:211] offset:8192
	ds_write_b64 v154, v[212:213] offset:10240
	ds_write_b64 v154, v[220:221] offset:12288
	ds_write_b64 v154, v[224:225] offset:14336
	ds_write_b64 v154, v[226:227] offset:16384
	ds_write_b64 v154, v[230:231] offset:18432
	ds_write_b64 v154, v[232:233] offset:20480
	ds_write_b64 v154, v[236:237] offset:22528
	ds_write_b64 v154, v[238:239] offset:24576
	ds_write_b64 v154, v[240:241] offset:26624
	ds_write_b64 v154, v[244:245] offset:28672
	ds_write_b64 v154, v[246:247] offset:30720
	s_lshl_b32 s2, s83, 11
	s_lshl_b32 s4, s78, 10
	s_sub_i32 s2, s28, s2
	s_sub_i32 s4, s6, s4
	s_ashr_i32 s3, s2, 31
	s_ashr_i32 s5, s4, 31
	s_lshl_b64 s[2:3], s[2:3], 13
	s_lshl_b64 s[4:5], s[4:5], 13
	s_add_u32 s8, s55, s2
	s_addc_u32 s9, s81, s3
	s_add_u32 s10, s55, s4
	s_addc_u32 s11, s81, s5
	s_add_i32 s2, s82, s21
	s_ashr_i32 s3, s2, 31
	s_lshl_b64 s[2:3], s[2:3], 13
	s_add_u32 s6, s80, s2
	s_addc_u32 s7, s76, s3
	s_add_i32 s4, s29, s21
	s_ashr_i32 s5, s4, 31
	s_lshl_b64 s[4:5], s[4:5], 13
	s_add_u32 s12, s80, s4
	s_addc_u32 s13, s76, s5
	s_and_b64 s[4:5], s[96:97], exec
	s_cselect_b32 s5, s25, s9
	s_cselect_b32 s4, s24, s8
	s_cselect_b32 s9, s27, s11
	s_cselect_b32 s8, s26, s10
	v_lshl_add_u64 v[4:5], s[4:5], 0, v[68:69]
	s_add_i32 s4, s77, s82
	s_ashr_i32 s5, s4, 31
	s_lshl_b64 s[4:5], s[4:5], 13
	v_lshl_add_u64 v[2:3], s[8:9], 0, v[68:69]
	v_lshl_add_u64 v[6:7], v[70:71], 0, s[4:5]
	v_lshl_add_u64 v[8:9], v[70:71], 0, s[2:3]
	s_mov_b64 s[22:23], 0
	v_mov_b32_e32 v198, v66
	s_waitcnt lgkmcnt(0)
	s_barrier
	v_lshlrev_b32_e32 v201, 1, v66
	v_xor_b32_e32 v203, v66, v155
	v_add_u32_e32 v202, 0x1000, v201
	v_lshlrev_b32_e32 v203, 3, v203
	s_mov_b64 s[8:9], 0x1000
	v_lshl_add_u64 v[204:205], v[4:5], 0, s[8:9]
	v_lshl_add_u64 v[206:207], v[2:3], 0, s[8:9]
	v_cmp_eq_u32_e64 s[8:9], 0, v66
	v_cmp_eq_u32_e32 vcc, 0xff, v66
	s_mov_b64 s[10:11], vcc
	ds_read_b64 v[224:225], v203
	ds_read_b64 v[226:227], v203 offset:2048
	ds_read_b64 v[230:231], v203 offset:4096
	ds_read_b64 v[232:233], v203 offset:6144
	ds_read_b64 v[236:237], v203 offset:8192
	ds_read_b64 v[238:239], v203 offset:10240
	ds_read_b64 v[240:241], v203 offset:12288
	ds_read_b64 v[244:245], v203 offset:14336
	global_load_ushort v10, v201, s[6:7] offset:-2
	global_load_ushort v11, v201, s[6:7] offset:0
	global_load_ushort v12, v201, s[6:7] offset:2
	global_load_ushort v13, v201, s[12:13] offset:-2
	global_load_ushort v14, v201, s[12:13] offset:0
	global_load_ushort v15, v201, s[12:13] offset:2
	global_load_ushort v16, v201, s[6:7] offset:510
	global_load_ushort v17, v201, s[6:7] offset:512
	global_load_ushort v18, v201, s[6:7] offset:514
	global_load_ushort v19, v201, s[12:13] offset:510
	global_load_ushort v20, v201, s[12:13] offset:512
	global_load_ushort v21, v201, s[12:13] offset:514
	global_load_ushort v22, v201, s[6:7] offset:1022
	global_load_ushort v23, v201, s[6:7] offset:1024
	global_load_ushort v24, v201, s[6:7] offset:1026
	global_load_ushort v25, v201, s[12:13] offset:1022
	global_load_ushort v26, v201, s[12:13] offset:1024
	global_load_ushort v27, v201, s[12:13] offset:1026
	global_load_ushort v28, v201, s[6:7] offset:1534
	global_load_ushort v29, v201, s[6:7] offset:1536
	global_load_ushort v30, v201, s[6:7] offset:1538
	global_load_ushort v31, v201, s[12:13] offset:1534
	global_load_ushort v32, v201, s[12:13] offset:1536
	global_load_ushort v34, v201, s[12:13] offset:1538
	global_load_ushort v35, v201, s[6:7] offset:2046
	global_load_ushort v36, v201, s[6:7] offset:2048
	global_load_ushort v37, v201, s[6:7] offset:2050
	global_load_ushort v38, v201, s[12:13] offset:2046
	global_load_ushort v39, v201, s[12:13] offset:2048
	global_load_ushort v40, v201, s[12:13] offset:2050
	global_load_ushort v41, v201, s[6:7] offset:2558
	global_load_ushort v42, v201, s[6:7] offset:2560
	global_load_ushort v43, v201, s[6:7] offset:2562
	global_load_ushort v44, v201, s[12:13] offset:2558
	global_load_ushort v45, v201, s[12:13] offset:2560
	global_load_ushort v46, v201, s[12:13] offset:2562
	global_load_ushort v47, v201, s[6:7] offset:3070
	global_load_ushort v48, v201, s[6:7] offset:3072
	global_load_ushort v49, v201, s[6:7] offset:3074
	global_load_ushort v50, v201, s[12:13] offset:3070
	global_load_ushort v51, v201, s[12:13] offset:3072
	global_load_ushort v52, v201, s[12:13] offset:3074
	global_load_ushort v53, v201, s[6:7] offset:3582
	global_load_ushort v54, v201, s[6:7] offset:3584
	global_load_ushort v55, v201, s[6:7] offset:3586
	global_load_ushort v56, v201, s[12:13] offset:3582
	global_load_ushort v57, v201, s[12:13] offset:3584
	global_load_ushort v58, v201, s[12:13] offset:3586
	s_waitcnt vmcnt(42)
; DI float bf2f(u16 v) { return __uint_as_float(((unsigned)v) << 16); }
; DI float sconv3(const u16* row, int t, int n, float w0, float w1, float w2, float bias) {
;   float xm = (t > 0) ? bf2f(row[t - 1]) : 0.f, x0 = bf2f(row[t]), xp = (t + 1 < n) ? bf2f(row[t + 1]) : 0.f;
;   return w0 * xm + w1 * x0 + w2 * xp + bias;
; DI void hyena_unit(KP p, int l, int c, char* smem) {
;     ...
; #pragma unroll 4
;       for (int jj = 0; jj < 16; ++jj) {
;         const int t = tid + 256 * jj;
;         const f32x2 r = buf[SW(t)];
;         const float y0 = r.x * (1.f / 8192.f), y1 = -r.y * (1.f / 8192.f);
;         const float x0 = sconv3(g0, t, 4096, gw0, gw1, gw2, gb), x1 = sconv3(g1, t, 4096, gw0, gw1, gw2, gb);
;         if (o == 0) { r0[t] = f2bf(x0 * y0); r1[t] = f2bf(x1 * y1); }
;         else { y0p[t] = f2bf(x0 * y0); y1p[t] = f2bf(x1 * y1); }
;       }
	s_waitcnt lgkmcnt(0)
	v_cndmask_b32_e64 v10, v10, 0, s[8:9]
	v_cndmask_b32_e64 v13, v13, 0, s[8:9]
	v_lshlrev_b32_e32 v10, 16, v10
	v_lshlrev_b32_e32 v11, 16, v11
	v_lshlrev_b32_e32 v12, 16, v12
	v_lshlrev_b32_e32 v13, 16, v13
	v_lshlrev_b32_e32 v14, 16, v14
	v_lshlrev_b32_e32 v15, 16, v15
	v_mul_f32_e32 v11, v196, v11
	v_mul_f32_e32 v14, v196, v14
	v_fmac_f32_e32 v11, v74, v10
	v_fmac_f32_e32 v14, v74, v13
	v_fmac_f32_e32 v11, v75, v12
	v_fmac_f32_e32 v14, v75, v15
	v_mul_f32_e32 v10, 0x39000000, v224
	v_mul_f32_e32 v13, 0xb9000000, v225
	v_add_f32_e32 v11, v195, v11
	v_add_f32_e32 v14, v195, v14
	v_mul_f32_e32 v10, v10, v11
	v_mul_f32_e32 v13, v13, v14
	v_cvt_pk_bf16_f32 v10, v10, v10
	v_cvt_pk_bf16_f32 v13, v13, v13
	global_store_short v[4:5], v10, off
	global_store_short v[2:3], v13, off
	s_waitcnt vmcnt(38)
	v_lshlrev_b32_e32 v16, 16, v16
	v_lshlrev_b32_e32 v17, 16, v17
	v_lshlrev_b32_e32 v18, 16, v18
	v_lshlrev_b32_e32 v19, 16, v19
	v_lshlrev_b32_e32 v20, 16, v20
	v_lshlrev_b32_e32 v21, 16, v21
	v_mul_f32_e32 v17, v196, v17
	v_mul_f32_e32 v20, v196, v20
	v_fmac_f32_e32 v17, v74, v16
	v_fmac_f32_e32 v20, v74, v19
	v_fmac_f32_e32 v17, v75, v18
	v_fmac_f32_e32 v20, v75, v21
	v_mul_f32_e32 v16, 0x39000000, v226
	v_mul_f32_e32 v19, 0xb9000000, v227
	v_add_f32_e32 v17, v195, v17
	v_add_f32_e32 v20, v195, v20
	v_mul_f32_e32 v16, v16, v17
	v_mul_f32_e32 v19, v19, v20
	v_cvt_pk_bf16_f32 v16, v16, v16
	v_cvt_pk_bf16_f32 v19, v19, v19
	global_store_short v[4:5], v16, off offset:512
	global_store_short v[2:3], v19, off offset:512
	s_waitcnt vmcnt(34)
	v_lshlrev_b32_e32 v22, 16, v22
	v_lshlrev_b32_e32 v23, 16, v23
	v_lshlrev_b32_e32 v24, 16, v24
	v_lshlrev_b32_e32 v25, 16, v25
	v_lshlrev_b32_e32 v26, 16, v26
	v_lshlrev_b32_e32 v27, 16, v27
	v_mul_f32_e32 v23, v196, v23
	v_mul_f32_e32 v26, v196, v26
	v_fmac_f32_e32 v23, v74, v22
	v_fmac_f32_e32 v26, v74, v25
	v_fmac_f32_e32 v23, v75, v24
	v_fmac_f32_e32 v26, v75, v27
	v_mul_f32_e32 v22, 0x39000000, v230
	v_mul_f32_e32 v25, 0xb9000000, v231
	v_add_f32_e32 v23, v195, v23
	v_add_f32_e32 v26, v195, v26
	v_mul_f32_e32 v22, v22, v23
	v_mul_f32_e32 v25, v25, v26
	v_cvt_pk_bf16_f32 v22, v22, v22
	v_cvt_pk_bf16_f32 v25, v25, v25
	global_store_short v[4:5], v22, off offset:1024
	global_store_short v[2:3], v25, off offset:1024
	s_waitcnt vmcnt(30)
	v_lshlrev_b32_e32 v28, 16, v28
	v_lshlrev_b32_e32 v29, 16, v29
	v_lshlrev_b32_e32 v30, 16, v30
	v_lshlrev_b32_e32 v31, 16, v31
	v_lshlrev_b32_e32 v32, 16, v32
	v_lshlrev_b32_e32 v34, 16, v34
	v_mul_f32_e32 v29, v196, v29
	v_mul_f32_e32 v32, v196, v32
	v_fmac_f32_e32 v29, v74, v28
	v_fmac_f32_e32 v32, v74, v31
	v_fmac_f32_e32 v29, v75, v30
	v_fmac_f32_e32 v32, v75, v34
	v_mul_f32_e32 v28, 0x39000000, v232
	v_mul_f32_e32 v31, 0xb9000000, v233
	v_add_f32_e32 v29, v195, v29
	v_add_f32_e32 v32, v195, v32
	v_mul_f32_e32 v28, v28, v29
	v_mul_f32_e32 v31, v31, v32
	v_cvt_pk_bf16_f32 v28, v28, v28
	v_cvt_pk_bf16_f32 v31, v31, v31
	global_store_short v[4:5], v28, off offset:1536
	global_store_short v[2:3], v31, off offset:1536
	s_waitcnt vmcnt(26)
	v_lshlrev_b32_e32 v35, 16, v35
	v_lshlrev_b32_e32 v36, 16, v36
	v_lshlrev_b32_e32 v37, 16, v37
	v_lshlrev_b32_e32 v38, 16, v38
	v_lshlrev_b32_e32 v39, 16, v39
	v_lshlrev_b32_e32 v40, 16, v40
	v_mul_f32_e32 v36, v196, v36
	v_mul_f32_e32 v39, v196, v39
	v_fmac_f32_e32 v36, v74, v35
	v_fmac_f32_e32 v39, v74, v38
	v_fmac_f32_e32 v36, v75, v37
	v_fmac_f32_e32 v39, v75, v40
	v_mul_f32_e32 v35, 0x39000000, v236
	v_mul_f32_e32 v38, 0xb9000000, v237
	v_add_f32_e32 v36, v195, v36
	v_add_f32_e32 v39, v195, v39
	v_mul_f32_e32 v35, v35, v36
	v_mul_f32_e32 v38, v38, v39
	v_cvt_pk_bf16_f32 v35, v35, v35
	v_cvt_pk_bf16_f32 v38, v38, v38
	global_store_short v[4:5], v35, off offset:2048
	global_store_short v[2:3], v38, off offset:2048
	s_waitcnt vmcnt(22)
	v_lshlrev_b32_e32 v41, 16, v41
	v_lshlrev_b32_e32 v42, 16, v42
	v_lshlrev_b32_e32 v43, 16, v43
	v_lshlrev_b32_e32 v44, 16, v44
	v_lshlrev_b32_e32 v45, 16, v45
	v_lshlrev_b32_e32 v46, 16, v46
	v_mul_f32_e32 v42, v196, v42
	v_mul_f32_e32 v45, v196, v45
	v_fmac_f32_e32 v42, v74, v41
	v_fmac_f32_e32 v45, v74, v44
	v_fmac_f32_e32 v42, v75, v43
	v_fmac_f32_e32 v45, v75, v46
	v_mul_f32_e32 v41, 0x39000000, v238
	v_mul_f32_e32 v44, 0xb9000000, v239
	v_add_f32_e32 v42, v195, v42
	v_add_f32_e32 v45, v195, v45
	v_mul_f32_e32 v41, v41, v42
	v_mul_f32_e32 v44, v44, v45
	v_cvt_pk_bf16_f32 v41, v41, v41
	v_cvt_pk_bf16_f32 v44, v44, v44
	global_store_short v[4:5], v41, off offset:2560
	global_store_short v[2:3], v44, off offset:2560
	s_waitcnt vmcnt(18)
	v_lshlrev_b32_e32 v47, 16, v47
	v_lshlrev_b32_e32 v48, 16, v48
	v_lshlrev_b32_e32 v49, 16, v49
	v_lshlrev_b32_e32 v50, 16, v50
	v_lshlrev_b32_e32 v51, 16, v51
	v_lshlrev_b32_e32 v52, 16, v52
	v_mul_f32_e32 v48, v196, v48
	v_mul_f32_e32 v51, v196, v51
	v_fmac_f32_e32 v48, v74, v47
	v_fmac_f32_e32 v51, v74, v50
	v_fmac_f32_e32 v48, v75, v49
	v_fmac_f32_e32 v51, v75, v52
	v_mul_f32_e32 v47, 0x39000000, v240
	v_mul_f32_e32 v50, 0xb9000000, v241
	v_add_f32_e32 v48, v195, v48
	v_add_f32_e32 v51, v195, v51
	v_mul_f32_e32 v47, v47, v48
	v_mul_f32_e32 v50, v50, v51
	v_cvt_pk_bf16_f32 v47, v47, v47
	v_cvt_pk_bf16_f32 v50, v50, v50
	global_store_short v[4:5], v47, off offset:3072
	global_store_short v[2:3], v50, off offset:3072
	s_waitcnt vmcnt(14)
; DI float bf2f(u16 v) { return __uint_as_float(((unsigned)v) << 16); }
; DI float sconv3(const u16* row, int t, int n, float w0, float w1, float w2, float bias) {
;   float xm = (t > 0) ? bf2f(row[t - 1]) : 0.f, x0 = bf2f(row[t]), xp = (t + 1 < n) ? bf2f(row[t + 1]) : 0.f;
;   return w0 * xm + w1 * x0 + w2 * xp + bias;
; DI void hyena_unit(KP p, int l, int c, char* smem) {
;     ...
; #pragma unroll 4
;       for (int jj = 0; jj < 16; ++jj) {
;         const int t = tid + 256 * jj;
;         const f32x2 r = buf[SW(t)];
;         const float y0 = r.x * (1.f / 8192.f), y1 = -r.y * (1.f / 8192.f);
;         const float x0 = sconv3(g0, t, 4096, gw0, gw1, gw2, gb), x1 = sconv3(g1, t, 4096, gw0, gw1, gw2, gb);
;         if (o == 0) { r0[t] = f2bf(x0 * y0); r1[t] = f2bf(x1 * y1); }
;         else { y0p[t] = f2bf(x0 * y0); y1p[t] = f2bf(x1 * y1); }
;       }
	v_lshlrev_b32_e32 v53, 16, v53
	v_lshlrev_b32_e32 v54, 16, v54
	v_lshlrev_b32_e32 v55, 16, v55
	v_lshlrev_b32_e32 v56, 16, v56
	v_lshlrev_b32_e32 v57, 16, v57
	v_lshlrev_b32_e32 v58, 16, v58
	v_mul_f32_e32 v54, v196, v54
	v_mul_f32_e32 v57, v196, v57
	v_fmac_f32_e32 v54, v74, v53
	v_fmac_f32_e32 v57, v74, v56
	v_fmac_f32_e32 v54, v75, v55
	v_fmac_f32_e32 v57, v75, v58
	v_mul_f32_e32 v53, 0x39000000, v244
	v_mul_f32_e32 v56, 0xb9000000, v245
	v_add_f32_e32 v54, v195, v54
	v_add_f32_e32 v57, v195, v57
	v_mul_f32_e32 v53, v53, v54
	v_mul_f32_e32 v56, v56, v57
	v_cvt_pk_bf16_f32 v53, v53, v53
	v_cvt_pk_bf16_f32 v56, v56, v56
	global_store_short v[4:5], v53, off offset:3584
	global_store_short v[2:3], v56, off offset:3584
	ds_read_b64 v[224:225], v203 offset:16384
	ds_read_b64 v[226:227], v203 offset:18432
	ds_read_b64 v[230:231], v203 offset:20480
	ds_read_b64 v[232:233], v203 offset:22528
	ds_read_b64 v[236:237], v203 offset:24576
	ds_read_b64 v[238:239], v203 offset:26624
	ds_read_b64 v[240:241], v203 offset:28672
	ds_read_b64 v[244:245], v203 offset:30720
	global_load_ushort v10, v202, s[6:7] offset:-2
	global_load_ushort v11, v202, s[6:7] offset:0
	global_load_ushort v12, v202, s[6:7] offset:2
	global_load_ushort v13, v202, s[12:13] offset:-2
	global_load_ushort v14, v202, s[12:13] offset:0
	global_load_ushort v15, v202, s[12:13] offset:2
	global_load_ushort v16, v202, s[6:7] offset:510
	global_load_ushort v17, v202, s[6:7] offset:512
	global_load_ushort v18, v202, s[6:7] offset:514
	global_load_ushort v19, v202, s[12:13] offset:510
	global_load_ushort v20, v202, s[12:13] offset:512
	global_load_ushort v21, v202, s[12:13] offset:514
	global_load_ushort v22, v202, s[6:7] offset:1022
	global_load_ushort v23, v202, s[6:7] offset:1024
	global_load_ushort v24, v202, s[6:7] offset:1026
	global_load_ushort v25, v202, s[12:13] offset:1022
	global_load_ushort v26, v202, s[12:13] offset:1024
	global_load_ushort v27, v202, s[12:13] offset:1026
	global_load_ushort v28, v202, s[6:7] offset:1534
	global_load_ushort v29, v202, s[6:7] offset:1536
	global_load_ushort v30, v202, s[6:7] offset:1538
	global_load_ushort v31, v202, s[12:13] offset:1534
	global_load_ushort v32, v202, s[12:13] offset:1536
	global_load_ushort v34, v202, s[12:13] offset:1538
	global_load_ushort v35, v202, s[6:7] offset:2046
	global_load_ushort v36, v202, s[6:7] offset:2048
	global_load_ushort v37, v202, s[6:7] offset:2050
	global_load_ushort v38, v202, s[12:13] offset:2046
	global_load_ushort v39, v202, s[12:13] offset:2048
	global_load_ushort v40, v202, s[12:13] offset:2050
	global_load_ushort v41, v202, s[6:7] offset:2558
	global_load_ushort v42, v202, s[6:7] offset:2560
	global_load_ushort v43, v202, s[6:7] offset:2562
	global_load_ushort v44, v202, s[12:13] offset:2558
	global_load_ushort v45, v202, s[12:13] offset:2560
	global_load_ushort v46, v202, s[12:13] offset:2562
	global_load_ushort v47, v202, s[6:7] offset:3070
	global_load_ushort v48, v202, s[6:7] offset:3072
	global_load_ushort v49, v202, s[6:7] offset:3074
	global_load_ushort v50, v202, s[12:13] offset:3070
	global_load_ushort v51, v202, s[12:13] offset:3072
	global_load_ushort v52, v202, s[12:13] offset:3074
	global_load_ushort v53, v202, s[6:7] offset:3582
	global_load_ushort v54, v202, s[6:7] offset:3584
	global_load_ushort v55, v202, s[6:7] offset:3586
	global_load_ushort v56, v202, s[12:13] offset:3582
	global_load_ushort v57, v202, s[12:13] offset:3584
	global_load_ushort v58, v202, s[12:13] offset:3586
	s_waitcnt vmcnt(42)
	s_waitcnt lgkmcnt(0)
	v_lshlrev_b32_e32 v10, 16, v10
	v_lshlrev_b32_e32 v11, 16, v11
	v_lshlrev_b32_e32 v12, 16, v12
	v_lshlrev_b32_e32 v13, 16, v13
	v_lshlrev_b32_e32 v14, 16, v14
	v_lshlrev_b32_e32 v15, 16, v15
	v_mul_f32_e32 v11, v196, v11
	v_mul_f32_e32 v14, v196, v14
	v_fmac_f32_e32 v11, v74, v10
	v_fmac_f32_e32 v14, v74, v13
	v_fmac_f32_e32 v11, v75, v12
	v_fmac_f32_e32 v14, v75, v15
	v_mul_f32_e32 v10, 0x39000000, v224
	v_mul_f32_e32 v13, 0xb9000000, v225
	v_add_f32_e32 v11, v195, v11
	v_add_f32_e32 v14, v195, v14
	v_mul_f32_e32 v10, v10, v11
	v_mul_f32_e32 v13, v13, v14
	v_cvt_pk_bf16_f32 v10, v10, v10
	v_cvt_pk_bf16_f32 v13, v13, v13
	global_store_short v[204:205], v10, off
	global_store_short v[206:207], v13, off
	s_waitcnt vmcnt(38)
	v_lshlrev_b32_e32 v16, 16, v16
	v_lshlrev_b32_e32 v17, 16, v17
	v_lshlrev_b32_e32 v18, 16, v18
	v_lshlrev_b32_e32 v19, 16, v19
	v_lshlrev_b32_e32 v20, 16, v20
	v_lshlrev_b32_e32 v21, 16, v21
	v_mul_f32_e32 v17, v196, v17
	v_mul_f32_e32 v20, v196, v20
	v_fmac_f32_e32 v17, v74, v16
	v_fmac_f32_e32 v20, v74, v19
	v_fmac_f32_e32 v17, v75, v18
	v_fmac_f32_e32 v20, v75, v21
	v_mul_f32_e32 v16, 0x39000000, v226
	v_mul_f32_e32 v19, 0xb9000000, v227
	v_add_f32_e32 v17, v195, v17
	v_add_f32_e32 v20, v195, v20
	v_mul_f32_e32 v16, v16, v17
	v_mul_f32_e32 v19, v19, v20
	v_cvt_pk_bf16_f32 v16, v16, v16
	v_cvt_pk_bf16_f32 v19, v19, v19
	global_store_short v[204:205], v16, off offset:512
	global_store_short v[206:207], v19, off offset:512
	s_waitcnt vmcnt(34)
; DI float bf2f(u16 v) { return __uint_as_float(((unsigned)v) << 16); }
; DI float sconv3(const u16* row, int t, int n, float w0, float w1, float w2, float bias) {
;   float xm = (t > 0) ? bf2f(row[t - 1]) : 0.f, x0 = bf2f(row[t]), xp = (t + 1 < n) ? bf2f(row[t + 1]) : 0.f;
;   return w0 * xm + w1 * x0 + w2 * xp + bias;
; DI void hyena_unit(KP p, int l, int c, char* smem) {
;     ...
; #pragma unroll 4
;       for (int jj = 0; jj < 16; ++jj) {
;         const int t = tid + 256 * jj;
;         const f32x2 r = buf[SW(t)];
;         const float y0 = r.x * (1.f / 8192.f), y1 = -r.y * (1.f / 8192.f);
;         const float x0 = sconv3(g0, t, 4096, gw0, gw1, gw2, gb), x1 = sconv3(g1, t, 4096, gw0, gw1, gw2, gb);
;         if (o == 0) { r0[t] = f2bf(x0 * y0); r1[t] = f2bf(x1 * y1); }
;         else { y0p[t] = f2bf(x0 * y0); y1p[t] = f2bf(x1 * y1); }
;       }
	v_lshlrev_b32_e32 v22, 16, v22
	v_lshlrev_b32_e32 v23, 16, v23
	v_lshlrev_b32_e32 v24, 16, v24
	v_lshlrev_b32_e32 v25, 16, v25
	v_lshlrev_b32_e32 v26, 16, v26
	v_lshlrev_b32_e32 v27, 16, v27
	v_mul_f32_e32 v23, v196, v23
	v_mul_f32_e32 v26, v196, v26
	v_fmac_f32_e32 v23, v74, v22
	v_fmac_f32_e32 v26, v74, v25
	v_fmac_f32_e32 v23, v75, v24
	v_fmac_f32_e32 v26, v75, v27
	v_mul_f32_e32 v22, 0x39000000, v230
	v_mul_f32_e32 v25, 0xb9000000, v231
	v_add_f32_e32 v23, v195, v23
	v_add_f32_e32 v26, v195, v26
	v_mul_f32_e32 v22, v22, v23
	v_mul_f32_e32 v25, v25, v26
	v_cvt_pk_bf16_f32 v22, v22, v22
	v_cvt_pk_bf16_f32 v25, v25, v25
	global_store_short v[204:205], v22, off offset:1024
	global_store_short v[206:207], v25, off offset:1024
	s_waitcnt vmcnt(30)
	v_lshlrev_b32_e32 v28, 16, v28
	v_lshlrev_b32_e32 v29, 16, v29
	v_lshlrev_b32_e32 v30, 16, v30
	v_lshlrev_b32_e32 v31, 16, v31
	v_lshlrev_b32_e32 v32, 16, v32
	v_lshlrev_b32_e32 v34, 16, v34
	v_mul_f32_e32 v29, v196, v29
	v_mul_f32_e32 v32, v196, v32
	v_fmac_f32_e32 v29, v74, v28
	v_fmac_f32_e32 v32, v74, v31
	v_fmac_f32_e32 v29, v75, v30
	v_fmac_f32_e32 v32, v75, v34
	v_mul_f32_e32 v28, 0x39000000, v232
	v_mul_f32_e32 v31, 0xb9000000, v233
	v_add_f32_e32 v29, v195, v29
	v_add_f32_e32 v32, v195, v32
	v_mul_f32_e32 v28, v28, v29
	v_mul_f32_e32 v31, v31, v32
	v_cvt_pk_bf16_f32 v28, v28, v28
	v_cvt_pk_bf16_f32 v31, v31, v31
	global_store_short v[204:205], v28, off offset:1536
	global_store_short v[206:207], v31, off offset:1536
	s_waitcnt vmcnt(26)
	v_lshlrev_b32_e32 v35, 16, v35
	v_lshlrev_b32_e32 v36, 16, v36
	v_lshlrev_b32_e32 v37, 16, v37
	v_lshlrev_b32_e32 v38, 16, v38
	v_lshlrev_b32_e32 v39, 16, v39
	v_lshlrev_b32_e32 v40, 16, v40
	v_mul_f32_e32 v36, v196, v36
	v_mul_f32_e32 v39, v196, v39
	v_fmac_f32_e32 v36, v74, v35
	v_fmac_f32_e32 v39, v74, v38
	v_fmac_f32_e32 v36, v75, v37
	v_fmac_f32_e32 v39, v75, v40
	v_mul_f32_e32 v35, 0x39000000, v236
	v_mul_f32_e32 v38, 0xb9000000, v237
	v_add_f32_e32 v36, v195, v36
	v_add_f32_e32 v39, v195, v39
	v_mul_f32_e32 v35, v35, v36
	v_mul_f32_e32 v38, v38, v39
	v_cvt_pk_bf16_f32 v35, v35, v35
	v_cvt_pk_bf16_f32 v38, v38, v38
	global_store_short v[204:205], v35, off offset:2048
	global_store_short v[206:207], v38, off offset:2048
	s_waitcnt vmcnt(22)
	v_lshlrev_b32_e32 v41, 16, v41
	v_lshlrev_b32_e32 v42, 16, v42
	v_lshlrev_b32_e32 v43, 16, v43
	v_lshlrev_b32_e32 v44, 16, v44
	v_lshlrev_b32_e32 v45, 16, v45
	v_lshlrev_b32_e32 v46, 16, v46
	v_mul_f32_e32 v42, v196, v42
	v_mul_f32_e32 v45, v196, v45
	v_fmac_f32_e32 v42, v74, v41
	v_fmac_f32_e32 v45, v74, v44
	v_fmac_f32_e32 v42, v75, v43
	v_fmac_f32_e32 v45, v75, v46
	v_mul_f32_e32 v41, 0x39000000, v238
	v_mul_f32_e32 v44, 0xb9000000, v239
	v_add_f32_e32 v42, v195, v42
	v_add_f32_e32 v45, v195, v45
	v_mul_f32_e32 v41, v41, v42
	v_mul_f32_e32 v44, v44, v45
	v_cvt_pk_bf16_f32 v41, v41, v41
	v_cvt_pk_bf16_f32 v44, v44, v44
	global_store_short v[204:205], v41, off offset:2560
	global_store_short v[206:207], v44, off offset:2560
	s_waitcnt vmcnt(18)
	v_lshlrev_b32_e32 v47, 16, v47
	v_lshlrev_b32_e32 v48, 16, v48
	v_lshlrev_b32_e32 v49, 16, v49
	v_lshlrev_b32_e32 v50, 16, v50
	v_lshlrev_b32_e32 v51, 16, v51
	v_lshlrev_b32_e32 v52, 16, v52
	v_mul_f32_e32 v48, v196, v48
	v_mul_f32_e32 v51, v196, v51
	v_fmac_f32_e32 v48, v74, v47
	v_fmac_f32_e32 v51, v74, v50
	v_fmac_f32_e32 v48, v75, v49
	v_fmac_f32_e32 v51, v75, v52
	v_mul_f32_e32 v47, 0x39000000, v240
	v_mul_f32_e32 v50, 0xb9000000, v241
	v_add_f32_e32 v48, v195, v48
	v_add_f32_e32 v51, v195, v51
	v_mul_f32_e32 v47, v47, v48
	v_mul_f32_e32 v50, v50, v51
	v_cvt_pk_bf16_f32 v47, v47, v47
	v_cvt_pk_bf16_f32 v50, v50, v50
	global_store_short v[204:205], v47, off offset:3072
	global_store_short v[206:207], v50, off offset:3072
	s_waitcnt vmcnt(14)
	v_cndmask_b32_e64 v55, v55, 0, s[10:11]
	v_cndmask_b32_e64 v58, v58, 0, s[10:11]
	v_lshlrev_b32_e32 v53, 16, v53
	v_lshlrev_b32_e32 v54, 16, v54
	v_lshlrev_b32_e32 v55, 16, v55
	v_lshlrev_b32_e32 v56, 16, v56
	v_lshlrev_b32_e32 v57, 16, v57
	v_lshlrev_b32_e32 v58, 16, v58
	v_mul_f32_e32 v54, v196, v54
	v_mul_f32_e32 v57, v196, v57
	v_fmac_f32_e32 v54, v74, v53
	v_fmac_f32_e32 v57, v74, v56
	v_fmac_f32_e32 v54, v75, v55
	v_fmac_f32_e32 v57, v75, v58
	v_mul_f32_e32 v53, 0x39000000, v244
	v_mul_f32_e32 v56, 0xb9000000, v245
	v_add_f32_e32 v54, v195, v54
	v_add_f32_e32 v57, v195, v57
	v_mul_f32_e32 v53, v53, v54
	v_mul_f32_e32 v56, v56, v57
	v_cvt_pk_bf16_f32 v53, v53, v53
	v_cvt_pk_bf16_f32 v56, v56, v56
	global_store_short v[204:205], v53, off offset:3584
	global_store_short v[206:207], v56, off offset:3584
	s_branch .LBB0_936
